# dilated pass-B gate loads issued before the key loop into spare registers (hides one exposed load latency per task); dead twiddle-address instructions removed from FFT pass loops
# speedup vs baseline: 1.0112x; 1.0036x over previous
; #define LAS __attribute__((address_space(3)))
; __device__ __forceinline__ int otid() { int t = threadIdx.x; asm volatile("" : "+v"(t)); return t; }
; template <int LR, bool INV> __device__ __forceinline__ void fft_pass(ldsf2 buf, int base, int stride, int twi) {
;     constexpr int R = 1 << LR; cf x[R];
;     const v2f wv = ((ldsf2)((LAS unsigned char*)buf + 139264))[twi];
; #pragma unroll
;     for (int m = 0; m < R; ++m) { const v2f v = buf[base + m * stride]; x[m] = cf{v.x, v.y}; }
;     const cf w{wv.x, wv.y};
;     if (INV) dit_reg<LR>(x, w); else dif_reg<LR>(x, w);
; #pragma unroll
;     for (int m = 0; m < R; ++m) buf[base + m * stride] = mkv2(x[m].x, x[m].y);
; __device__ __forceinline__ void fft_fwd_abc(ldsf2 buf) {
;     const int tid = otid(); const int wv = tid >> 6, l = tid & 63;
; #pragma unroll 1
;     for (int u = 0; u < 2; ++u) { const int bf = tid + NT * u; fft_pass<3, false>(buf, bf + (bf >> 4), 1088, bf); }
.LBB0_347:
	v_add_u32_e32 v72, s0, v68
	v_ashrrev_i32_e32 v69, 4, v72
	v_lshl_add_u32 v72, v72, 3, 0
	v_lshl_add_u32 v69, v69, 3, v72
	ds_read2st64_b64 v[72:75], v69 offset1:17
	ds_read2st64_b64 v[76:79], v69 offset0:68 offset1:85
	ds_read2st64_b64 v[80:83], v69 offset0:34 offset1:51
	ds_read2st64_b64 v[84:87], v69 offset0:102 offset1:119
	s_movk_i32 s0, 0x200
	v_add_u32_e32 v112, s0, v68
	v_ashrrev_i32_e32 v114, 4, v112
	v_lshl_add_u32 v112, v112, 3, 0
	v_lshl_add_u32 v114, v114, 3, v112
	ds_read2st64_b64 v[120:123], v114 offset1:17
	ds_read2st64_b64 v[124:127], v114 offset0:68 offset1:85
	ds_read2st64_b64 v[128:131], v114 offset0:34 offset1:51
	ds_read2st64_b64 v[132:135], v114 offset0:102 offset1:119
	s_waitcnt lgkmcnt(4)
	v_pk_add_f32 v[90:91], v[232:233], v[232:233] op_sel:[0,1] op_sel_hi:[1,0] neg_lo:[0,0] neg_hi:[0,1]
	s_nop 0
	v_pk_mul_f32 v[92:93], v[90:91], s[16:17] op_sel:[0,0] op_sel_hi:[1,0]
	v_pk_mul_f32 v[94:95], v[90:91], s[16:17] op_sel:[1,0] op_sel_hi:[0,0] neg_lo:[0,0] neg_hi:[1,0]
	v_pk_add_f32 v[100:101], v[72:73], v[76:77] neg_lo:[0,1] neg_hi:[0,1]
	v_pk_add_f32 v[102:103], v[74:75], v[78:79] neg_lo:[0,1] neg_hi:[0,1]
	v_pk_add_f32 v[104:105], v[80:81], v[84:85] neg_lo:[0,1] neg_hi:[0,1]
	v_pk_add_f32 v[106:107], v[82:83], v[86:87] neg_lo:[0,1] neg_hi:[0,1]
	v_pk_add_f32 v[72:73], v[72:73], v[76:77]
	v_pk_add_f32 v[74:75], v[74:75], v[78:79]
	v_pk_add_f32 v[80:81], v[80:81], v[84:85]
	v_pk_add_f32 v[82:83], v[82:83], v[86:87]
	v_pk_mul_f32 v[76:77], v[100:101], v[232:233] op_sel:[1,1] op_sel_hi:[1,0]
	v_pk_mul_f32 v[78:79], v[102:103], v[92:93] op_sel:[1,1] op_sel_hi:[1,0]
	v_pk_mul_f32 v[84:85], v[104:105], v[232:233] op_sel:[1,0] op_sel_hi:[1,1]
	v_pk_mul_f32 v[86:87], v[106:107], v[94:95] op_sel:[1,1] op_sel_hi:[1,0]
	v_pk_fma_f32 v[76:77], v[100:101], v[232:233], v[76:77] op_sel:[0,0,0] op_sel_hi:[0,1,1] neg_lo:[0,0,1] neg_hi:[0,0,0]
	v_pk_fma_f32 v[78:79], v[102:103], v[92:93], v[78:79] op_sel:[0,0,0] op_sel_hi:[0,1,1] neg_lo:[0,0,1] neg_hi:[0,0,0]
	v_pk_fma_f32 v[84:85], v[104:105], v[232:233], v[84:85] op_sel:[0,1,0] op_sel_hi:[0,0,1] neg_lo:[0,0,0] neg_hi:[0,1,0]
	v_pk_fma_f32 v[86:87], v[106:107], v[94:95], v[86:87] op_sel:[0,0,0] op_sel_hi:[0,1,1] neg_lo:[0,0,1] neg_hi:[0,0,0]
	v_pk_add_f32 v[100:101], v[72:73], v[80:81] neg_lo:[0,1] neg_hi:[0,1]
	v_pk_add_f32 v[102:103], v[74:75], v[82:83] neg_lo:[0,1] neg_hi:[0,1]
	v_pk_add_f32 v[104:105], v[76:77], v[84:85] neg_lo:[0,1] neg_hi:[0,1]
	v_pk_add_f32 v[106:107], v[78:79], v[86:87] neg_lo:[0,1] neg_hi:[0,1]
	v_pk_add_f32 v[72:73], v[72:73], v[80:81]
	v_pk_add_f32 v[74:75], v[74:75], v[82:83]
	v_pk_add_f32 v[76:77], v[76:77], v[84:85]
	v_pk_add_f32 v[78:79], v[78:79], v[86:87]
	v_pk_mul_f32 v[80:81], v[100:101], v[234:235] op_sel:[1,1] op_sel_hi:[1,0]
	v_pk_mul_f32 v[82:83], v[102:103], v[234:235] op_sel:[1,0] op_sel_hi:[1,1]
	v_pk_mul_f32 v[84:85], v[104:105], v[234:235] op_sel:[1,1] op_sel_hi:[1,0]
	v_pk_mul_f32 v[86:87], v[106:107], v[234:235] op_sel:[1,0] op_sel_hi:[1,1]
	v_pk_fma_f32 v[80:81], v[100:101], v[234:235], v[80:81] op_sel:[0,0,0] op_sel_hi:[0,1,1] neg_lo:[0,0,1] neg_hi:[0,0,0]
	v_pk_fma_f32 v[82:83], v[102:103], v[234:235], v[82:83] op_sel:[0,1,0] op_sel_hi:[0,0,1] neg_lo:[0,0,0] neg_hi:[0,1,0]
	v_pk_fma_f32 v[84:85], v[104:105], v[234:235], v[84:85] op_sel:[0,0,0] op_sel_hi:[0,1,1] neg_lo:[0,0,1] neg_hi:[0,0,0]
	v_pk_fma_f32 v[86:87], v[106:107], v[234:235], v[86:87] op_sel:[0,1,0] op_sel_hi:[0,0,1] neg_lo:[0,0,0] neg_hi:[0,1,0]
	v_pk_add_f32 v[100:101], v[72:73], v[74:75] neg_lo:[0,1] neg_hi:[0,1]
	v_pk_add_f32 v[102:103], v[80:81], v[82:83] neg_lo:[0,1] neg_hi:[0,1]
	v_pk_add_f32 v[104:105], v[76:77], v[78:79] neg_lo:[0,1] neg_hi:[0,1]
	v_pk_add_f32 v[106:107], v[84:85], v[86:87] neg_lo:[0,1] neg_hi:[0,1]
	v_pk_add_f32 v[72:73], v[72:73], v[74:75]
	v_pk_add_f32 v[80:81], v[80:81], v[82:83]
	v_pk_add_f32 v[76:77], v[76:77], v[78:79]
	v_pk_add_f32 v[84:85], v[84:85], v[86:87]
	v_pk_mul_f32 v[74:75], v[100:101], v[236:237] op_sel:[1,1] op_sel_hi:[1,0]
	v_pk_mul_f32 v[82:83], v[102:103], v[236:237] op_sel:[1,1] op_sel_hi:[1,0]
	v_pk_mul_f32 v[78:79], v[104:105], v[236:237] op_sel:[1,1] op_sel_hi:[1,0]
	v_pk_mul_f32 v[86:87], v[106:107], v[236:237] op_sel:[1,1] op_sel_hi:[1,0]
	v_pk_fma_f32 v[74:75], v[100:101], v[236:237], v[74:75] op_sel:[0,0,0] op_sel_hi:[0,1,1] neg_lo:[0,0,1] neg_hi:[0,0,0]
	v_pk_fma_f32 v[82:83], v[102:103], v[236:237], v[82:83] op_sel:[0,0,0] op_sel_hi:[0,1,1] neg_lo:[0,0,1] neg_hi:[0,0,0]
	v_pk_fma_f32 v[78:79], v[104:105], v[236:237], v[78:79] op_sel:[0,0,0] op_sel_hi:[0,1,1] neg_lo:[0,0,1] neg_hi:[0,0,0]
	v_pk_fma_f32 v[86:87], v[106:107], v[236:237], v[86:87] op_sel:[0,0,0] op_sel_hi:[0,1,1] neg_lo:[0,0,1] neg_hi:[0,0,0]
	ds_write2st64_b64 v69, v[72:73], v[74:75] offset1:17
	ds_write2st64_b64 v69, v[80:81], v[82:83] offset0:34 offset1:51
	ds_write2st64_b64 v69, v[76:77], v[78:79] offset0:68 offset1:85
	ds_write2st64_b64 v69, v[84:85], v[86:87] offset0:102 offset1:119
	s_waitcnt lgkmcnt(4)
; __device__ __forceinline__ void lds_barrier() { asm volatile("s_waitcnt lgkmcnt(0)\n\ts_barrier" ::: "memory"); }
; __device__ __forceinline__ void fft_fwd_abc(ldsf2 buf) {
;     ...
;     for (int u = 0; u < 2; ++u) { const int bf = tid + NT * u; fft_pass<3, false>(buf, bf + (bf >> 4), 1088, bf); }
;     lds_barrier();
; #pragma unroll 1
;     for (int u = 0; u < 2; ++u) { const int o = l + 64 * u, e0 = wv * 1024 + o; fft_pass<3, false>(buf, e0 + (e0 >> 4), 136, o * 8); }
	v_pk_add_f32 v[148:149], v[240:241], v[240:241] op_sel:[0,1] op_sel_hi:[1,0] neg_lo:[0,0] neg_hi:[0,1]
	s_nop 0
	v_pk_mul_f32 v[150:151], v[148:149], s[16:17] op_sel:[0,0] op_sel_hi:[1,0]
	v_pk_mul_f32 v[152:153], v[148:149], s[16:17] op_sel:[1,0] op_sel_hi:[0,0] neg_lo:[0,0] neg_hi:[1,0]
	v_pk_add_f32 v[158:159], v[120:121], v[124:125] neg_lo:[0,1] neg_hi:[0,1]
	v_pk_add_f32 v[160:161], v[122:123], v[126:127] neg_lo:[0,1] neg_hi:[0,1]
	v_pk_add_f32 v[162:163], v[128:129], v[132:133] neg_lo:[0,1] neg_hi:[0,1]
	v_pk_add_f32 v[164:165], v[130:131], v[134:135] neg_lo:[0,1] neg_hi:[0,1]
	v_pk_add_f32 v[120:121], v[120:121], v[124:125]
	v_pk_add_f32 v[122:123], v[122:123], v[126:127]
	v_pk_add_f32 v[128:129], v[128:129], v[132:133]
	v_pk_add_f32 v[130:131], v[130:131], v[134:135]
	v_pk_mul_f32 v[124:125], v[158:159], v[240:241] op_sel:[1,1] op_sel_hi:[1,0]
	v_pk_mul_f32 v[126:127], v[160:161], v[150:151] op_sel:[1,1] op_sel_hi:[1,0]
	v_pk_mul_f32 v[132:133], v[162:163], v[240:241] op_sel:[1,0] op_sel_hi:[1,1]
	v_pk_mul_f32 v[134:135], v[164:165], v[152:153] op_sel:[1,1] op_sel_hi:[1,0]
	v_pk_fma_f32 v[124:125], v[158:159], v[240:241], v[124:125] op_sel:[0,0,0] op_sel_hi:[0,1,1] neg_lo:[0,0,1] neg_hi:[0,0,0]
	v_pk_fma_f32 v[126:127], v[160:161], v[150:151], v[126:127] op_sel:[0,0,0] op_sel_hi:[0,1,1] neg_lo:[0,0,1] neg_hi:[0,0,0]
	v_pk_fma_f32 v[132:133], v[162:163], v[240:241], v[132:133] op_sel:[0,1,0] op_sel_hi:[0,0,1] neg_lo:[0,0,0] neg_hi:[0,1,0]
	v_pk_fma_f32 v[134:135], v[164:165], v[152:153], v[134:135] op_sel:[0,0,0] op_sel_hi:[0,1,1] neg_lo:[0,0,1] neg_hi:[0,0,0]
	v_pk_add_f32 v[158:159], v[120:121], v[128:129] neg_lo:[0,1] neg_hi:[0,1]
	v_pk_add_f32 v[160:161], v[122:123], v[130:131] neg_lo:[0,1] neg_hi:[0,1]
	v_pk_add_f32 v[162:163], v[124:125], v[132:133] neg_lo:[0,1] neg_hi:[0,1]
	v_pk_add_f32 v[164:165], v[126:127], v[134:135] neg_lo:[0,1] neg_hi:[0,1]
	v_pk_add_f32 v[120:121], v[120:121], v[128:129]
	v_pk_add_f32 v[122:123], v[122:123], v[130:131]
	v_pk_add_f32 v[124:125], v[124:125], v[132:133]
	v_pk_add_f32 v[126:127], v[126:127], v[134:135]
	v_pk_mul_f32 v[128:129], v[158:159], v[242:243] op_sel:[1,1] op_sel_hi:[1,0]
	v_pk_mul_f32 v[130:131], v[160:161], v[242:243] op_sel:[1,0] op_sel_hi:[1,1]
	v_pk_mul_f32 v[132:133], v[162:163], v[242:243] op_sel:[1,1] op_sel_hi:[1,0]
	v_pk_mul_f32 v[134:135], v[164:165], v[242:243] op_sel:[1,0] op_sel_hi:[1,1]
	v_pk_fma_f32 v[128:129], v[158:159], v[242:243], v[128:129] op_sel:[0,0,0] op_sel_hi:[0,1,1] neg_lo:[0,0,1] neg_hi:[0,0,0]
	v_pk_fma_f32 v[130:131], v[160:161], v[242:243], v[130:131] op_sel:[0,1,0] op_sel_hi:[0,0,1] neg_lo:[0,0,0] neg_hi:[0,1,0]
	v_pk_fma_f32 v[132:133], v[162:163], v[242:243], v[132:133] op_sel:[0,0,0] op_sel_hi:[0,1,1] neg_lo:[0,0,1] neg_hi:[0,0,0]
	v_pk_fma_f32 v[134:135], v[164:165], v[242:243], v[134:135] op_sel:[0,1,0] op_sel_hi:[0,0,1] neg_lo:[0,0,0] neg_hi:[0,1,0]
	v_pk_add_f32 v[158:159], v[120:121], v[122:123] neg_lo:[0,1] neg_hi:[0,1]
	v_pk_add_f32 v[160:161], v[128:129], v[130:131] neg_lo:[0,1] neg_hi:[0,1]
	v_pk_add_f32 v[162:163], v[124:125], v[126:127] neg_lo:[0,1] neg_hi:[0,1]
	v_pk_add_f32 v[164:165], v[132:133], v[134:135] neg_lo:[0,1] neg_hi:[0,1]
	v_pk_add_f32 v[120:121], v[120:121], v[122:123]
	v_pk_add_f32 v[128:129], v[128:129], v[130:131]
	v_pk_add_f32 v[124:125], v[124:125], v[126:127]
	v_pk_add_f32 v[132:133], v[132:133], v[134:135]
	v_pk_mul_f32 v[122:123], v[158:159], v[244:245] op_sel:[1,1] op_sel_hi:[1,0]
	v_pk_mul_f32 v[130:131], v[160:161], v[244:245] op_sel:[1,1] op_sel_hi:[1,0]
	v_pk_mul_f32 v[126:127], v[162:163], v[244:245] op_sel:[1,1] op_sel_hi:[1,0]
	v_pk_mul_f32 v[134:135], v[164:165], v[244:245] op_sel:[1,1] op_sel_hi:[1,0]
	v_pk_fma_f32 v[122:123], v[158:159], v[244:245], v[122:123] op_sel:[0,0,0] op_sel_hi:[0,1,1] neg_lo:[0,0,1] neg_hi:[0,0,0]
	v_pk_fma_f32 v[130:131], v[160:161], v[244:245], v[130:131] op_sel:[0,0,0] op_sel_hi:[0,1,1] neg_lo:[0,0,1] neg_hi:[0,0,0]
	v_pk_fma_f32 v[126:127], v[162:163], v[244:245], v[126:127] op_sel:[0,0,0] op_sel_hi:[0,1,1] neg_lo:[0,0,1] neg_hi:[0,0,0]
	v_pk_fma_f32 v[134:135], v[164:165], v[244:245], v[134:135] op_sel:[0,0,0] op_sel_hi:[0,1,1] neg_lo:[0,0,1] neg_hi:[0,0,0]
	ds_write2st64_b64 v114, v[120:121], v[122:123] offset1:17
	ds_write2st64_b64 v114, v[128:129], v[130:131] offset0:34 offset1:51
	ds_write2st64_b64 v114, v[124:125], v[126:127] offset0:68 offset1:85
	ds_write2st64_b64 v114, v[132:133], v[134:135] offset0:102 offset1:119
	s_mov_b64 s[6:7], 0
	s_waitcnt lgkmcnt(0)
	s_barrier
	v_lshlrev_b32_e32 v72, 4, v68
	v_and_b32_e32 v69, 63, v68
	v_and_b32_e32 v72, 0xfffffc00, v72
	s_mov_b32 s0, 0
	s_mov_b64 s[6:7], -1
; #define LAS __attribute__((address_space(3)))
; template <int LR, bool INV> __device__ __forceinline__ void fft_pass(ldsf2 buf, int base, int stride, int twi) {
;     constexpr int R = 1 << LR; cf x[R];
;     const v2f wv = ((ldsf2)((LAS unsigned char*)buf + 139264))[twi];
; #pragma unroll
;     for (int m = 0; m < R; ++m) { const v2f v = buf[base + m * stride]; x[m] = cf{v.x, v.y}; }
;     const cf w{wv.x, wv.y};
;     if (INV) dit_reg<LR>(x, w); else dif_reg<LR>(x, w);
; #pragma unroll
;     for (int m = 0; m < R; ++m) buf[base + m * stride] = mkv2(x[m].x, x[m].y);
; __device__ __forceinline__ void fft_fwd_abc(ldsf2 buf) {
;     ...
;     for (int u = 0; u < 2; ++u) { const int o = l + 64 * u, e0 = wv * 1024 + o; fft_pass<3, false>(buf, e0 + (e0 >> 4), 136, o * 8); }
.LBB0_349:
	v_or_b32_e32 v74, s0, v69
	v_or_b32_e32 v73, v74, v72
	v_ashrrev_i32_e32 v75, 4, v73
	v_lshlrev_b32_e32 v73, 3, v73
	v_lshlrev_b32_e32 v74, 3, v75
	v_add3_u32 v73, 0, v73, v74
	v_add_u32_e32 v113, 0x800, v73
	ds_read2_b64 v[74:77], v73 offset1:136
	v_add_u32_e32 v118, 0x1000, v73
	v_add_u32_e32 v119, 0x1800, v73
	ds_read2_b64 v[78:81], v113 offset0:16 offset1:152
	ds_read2_b64 v[82:85], v118 offset0:32 offset1:168
	ds_read2_b64 v[86:89], v119 offset0:48 offset1:184
	s_mov_b32 s0, 64
	v_or_b32_e32 v120, s0, v69
	v_or_b32_e32 v122, v120, v72
	v_ashrrev_i32_e32 v124, 4, v122
	v_lshlrev_b32_e32 v122, 3, v122
	v_lshlrev_b32_e32 v120, 3, v124
	v_add3_u32 v122, 0, v122, v120
	v_add_u32_e32 v128, 0x800, v122
	ds_read2_b64 v[130:133], v122 offset1:136
	v_add_u32_e32 v134, 0x1000, v122
	v_add_u32_e32 v148, 0x1800, v122
	ds_read2_b64 v[150:153], v128 offset0:16 offset1:152
	ds_read2_b64 v[154:157], v134 offset0:32 offset1:168
	ds_read2_b64 v[158:161], v148 offset0:48 offset1:184
	s_waitcnt lgkmcnt(4)
	v_pk_add_f32 v[92:93], v[214:215], v[214:215] op_sel:[0,1] op_sel_hi:[1,0] neg_lo:[0,0] neg_hi:[0,1]
	s_nop 0
	v_pk_mul_f32 v[94:95], v[92:93], s[16:17] op_sel:[0,0] op_sel_hi:[1,0]
	v_pk_mul_f32 v[96:97], v[92:93], s[16:17] op_sel:[1,0] op_sel_hi:[0,0] neg_lo:[0,0] neg_hi:[1,0]
	v_pk_add_f32 v[102:103], v[74:75], v[82:83] neg_lo:[0,1] neg_hi:[0,1]
	v_pk_add_f32 v[104:105], v[76:77], v[84:85] neg_lo:[0,1] neg_hi:[0,1]
	v_pk_add_f32 v[106:107], v[78:79], v[86:87] neg_lo:[0,1] neg_hi:[0,1]
	v_pk_add_f32 v[108:109], v[80:81], v[88:89] neg_lo:[0,1] neg_hi:[0,1]
	v_pk_add_f32 v[74:75], v[74:75], v[82:83]
	v_pk_add_f32 v[76:77], v[76:77], v[84:85]
	v_pk_add_f32 v[78:79], v[78:79], v[86:87]
	v_pk_add_f32 v[80:81], v[80:81], v[88:89]
	v_pk_mul_f32 v[82:83], v[102:103], v[214:215] op_sel:[1,1] op_sel_hi:[1,0]
	v_pk_mul_f32 v[84:85], v[104:105], v[94:95] op_sel:[1,1] op_sel_hi:[1,0]
	v_pk_mul_f32 v[86:87], v[106:107], v[214:215] op_sel:[1,0] op_sel_hi:[1,1]
	v_pk_mul_f32 v[88:89], v[108:109], v[96:97] op_sel:[1,1] op_sel_hi:[1,0]
	v_pk_fma_f32 v[82:83], v[102:103], v[214:215], v[82:83] op_sel:[0,0,0] op_sel_hi:[0,1,1] neg_lo:[0,0,1] neg_hi:[0,0,0]
	v_pk_fma_f32 v[84:85], v[104:105], v[94:95], v[84:85] op_sel:[0,0,0] op_sel_hi:[0,1,1] neg_lo:[0,0,1] neg_hi:[0,0,0]
	v_pk_fma_f32 v[86:87], v[106:107], v[214:215], v[86:87] op_sel:[0,1,0] op_sel_hi:[0,0,1] neg_lo:[0,0,0] neg_hi:[0,1,0]
	v_pk_fma_f32 v[88:89], v[108:109], v[96:97], v[88:89] op_sel:[0,0,0] op_sel_hi:[0,1,1] neg_lo:[0,0,1] neg_hi:[0,0,0]
	v_pk_add_f32 v[102:103], v[74:75], v[78:79] neg_lo:[0,1] neg_hi:[0,1]
	v_pk_add_f32 v[104:105], v[76:77], v[80:81] neg_lo:[0,1] neg_hi:[0,1]
	v_pk_add_f32 v[106:107], v[82:83], v[86:87] neg_lo:[0,1] neg_hi:[0,1]
	v_pk_add_f32 v[108:109], v[84:85], v[88:89] neg_lo:[0,1] neg_hi:[0,1]
	v_pk_add_f32 v[74:75], v[74:75], v[78:79]
	v_pk_add_f32 v[76:77], v[76:77], v[80:81]
	v_pk_add_f32 v[82:83], v[82:83], v[86:87]
	v_pk_add_f32 v[84:85], v[84:85], v[88:89]
	v_pk_mul_f32 v[78:79], v[102:103], v[216:217] op_sel:[1,1] op_sel_hi:[1,0]
	v_pk_mul_f32 v[80:81], v[104:105], v[216:217] op_sel:[1,0] op_sel_hi:[1,1]
	v_pk_mul_f32 v[86:87], v[106:107], v[216:217] op_sel:[1,1] op_sel_hi:[1,0]
	v_pk_mul_f32 v[88:89], v[108:109], v[216:217] op_sel:[1,0] op_sel_hi:[1,1]
	v_pk_fma_f32 v[78:79], v[102:103], v[216:217], v[78:79] op_sel:[0,0,0] op_sel_hi:[0,1,1] neg_lo:[0,0,1] neg_hi:[0,0,0]
	v_pk_fma_f32 v[80:81], v[104:105], v[216:217], v[80:81] op_sel:[0,1,0] op_sel_hi:[0,0,1] neg_lo:[0,0,0] neg_hi:[0,1,0]
	v_pk_fma_f32 v[86:87], v[106:107], v[216:217], v[86:87] op_sel:[0,0,0] op_sel_hi:[0,1,1] neg_lo:[0,0,1] neg_hi:[0,0,0]
	v_pk_fma_f32 v[88:89], v[108:109], v[216:217], v[88:89] op_sel:[0,1,0] op_sel_hi:[0,0,1] neg_lo:[0,0,0] neg_hi:[0,1,0]
	v_pk_add_f32 v[102:103], v[74:75], v[76:77] neg_lo:[0,1] neg_hi:[0,1]
	v_pk_add_f32 v[104:105], v[78:79], v[80:81] neg_lo:[0,1] neg_hi:[0,1]
	v_pk_add_f32 v[106:107], v[82:83], v[84:85] neg_lo:[0,1] neg_hi:[0,1]
	v_pk_add_f32 v[108:109], v[86:87], v[88:89] neg_lo:[0,1] neg_hi:[0,1]
	v_pk_add_f32 v[74:75], v[74:75], v[76:77]
	v_pk_add_f32 v[78:79], v[78:79], v[80:81]
	v_pk_add_f32 v[82:83], v[82:83], v[84:85]
	v_pk_add_f32 v[86:87], v[86:87], v[88:89]
	v_pk_mul_f32 v[76:77], v[102:103], v[218:219] op_sel:[1,1] op_sel_hi:[1,0]
	v_pk_mul_f32 v[80:81], v[104:105], v[218:219] op_sel:[1,1] op_sel_hi:[1,0]
	v_pk_mul_f32 v[84:85], v[106:107], v[218:219] op_sel:[1,1] op_sel_hi:[1,0]
	v_pk_mul_f32 v[88:89], v[108:109], v[218:219] op_sel:[1,1] op_sel_hi:[1,0]
	v_pk_fma_f32 v[76:77], v[102:103], v[218:219], v[76:77] op_sel:[0,0,0] op_sel_hi:[0,1,1] neg_lo:[0,0,1] neg_hi:[0,0,0]
	v_pk_fma_f32 v[80:81], v[104:105], v[218:219], v[80:81] op_sel:[0,0,0] op_sel_hi:[0,1,1] neg_lo:[0,0,1] neg_hi:[0,0,0]
	v_pk_fma_f32 v[84:85], v[106:107], v[218:219], v[84:85] op_sel:[0,0,0] op_sel_hi:[0,1,1] neg_lo:[0,0,1] neg_hi:[0,0,0]
	v_pk_fma_f32 v[88:89], v[108:109], v[218:219], v[88:89] op_sel:[0,0,0] op_sel_hi:[0,1,1] neg_lo:[0,0,1] neg_hi:[0,0,0]
	ds_write2_b64 v73, v[74:75], v[76:77] offset1:136
	ds_write2_b64 v113, v[78:79], v[80:81] offset0:16 offset1:152
	ds_write2_b64 v118, v[82:83], v[84:85] offset0:32 offset1:168
	ds_write2_b64 v119, v[86:87], v[88:89] offset0:48 offset1:184
	s_waitcnt lgkmcnt(4)
; __device__ __forceinline__ void wave_lds_fence() { asm volatile("s_waitcnt lgkmcnt(0)" ::: "memory"); }
; __device__ __forceinline__ void fft_fwd_abc(ldsf2 buf) {
;     ...
;     for (int u = 0; u < 2; ++u) { const int o = l + 64 * u, e0 = wv * 1024 + o; fft_pass<3, false>(buf, e0 + (e0 >> 4), 136, o * 8); }
;     wave_lds_fence();
; #pragma unroll 1
;     for (int u = 0; u < 2; ++u) { const int j = l + 64 * u, o = j & 15, e0 = wv * 1024 + (j >> 4) * 128 + o; fft_pass<3, false>(buf, e0 + (e0 >> 4), 17, o * 64); }
	v_pk_add_f32 v[162:163], v[220:221], v[220:221] op_sel:[0,1] op_sel_hi:[1,0] neg_lo:[0,0] neg_hi:[0,1]
	s_nop 0
	v_pk_mul_f32 v[164:165], v[162:163], s[16:17] op_sel:[0,0] op_sel_hi:[1,0]
	v_pk_mul_f32 v[166:167], v[162:163], s[16:17] op_sel:[1,0] op_sel_hi:[0,0] neg_lo:[0,0] neg_hi:[1,0]
	v_pk_add_f32 v[172:173], v[130:131], v[154:155] neg_lo:[0,1] neg_hi:[0,1]
	v_pk_add_f32 v[174:175], v[132:133], v[156:157] neg_lo:[0,1] neg_hi:[0,1]
	v_pk_add_f32 v[188:189], v[150:151], v[158:159] neg_lo:[0,1] neg_hi:[0,1]
	v_pk_add_f32 v[190:191], v[152:153], v[160:161] neg_lo:[0,1] neg_hi:[0,1]
	v_pk_add_f32 v[130:131], v[130:131], v[154:155]
	v_pk_add_f32 v[132:133], v[132:133], v[156:157]
	v_pk_add_f32 v[150:151], v[150:151], v[158:159]
	v_pk_add_f32 v[152:153], v[152:153], v[160:161]
	v_pk_mul_f32 v[154:155], v[172:173], v[220:221] op_sel:[1,1] op_sel_hi:[1,0]
	v_pk_mul_f32 v[156:157], v[174:175], v[164:165] op_sel:[1,1] op_sel_hi:[1,0]
	v_pk_mul_f32 v[158:159], v[188:189], v[220:221] op_sel:[1,0] op_sel_hi:[1,1]
	v_pk_mul_f32 v[160:161], v[190:191], v[166:167] op_sel:[1,1] op_sel_hi:[1,0]
	v_pk_fma_f32 v[154:155], v[172:173], v[220:221], v[154:155] op_sel:[0,0,0] op_sel_hi:[0,1,1] neg_lo:[0,0,1] neg_hi:[0,0,0]
	v_pk_fma_f32 v[156:157], v[174:175], v[164:165], v[156:157] op_sel:[0,0,0] op_sel_hi:[0,1,1] neg_lo:[0,0,1] neg_hi:[0,0,0]
	v_pk_fma_f32 v[158:159], v[188:189], v[220:221], v[158:159] op_sel:[0,1,0] op_sel_hi:[0,0,1] neg_lo:[0,0,0] neg_hi:[0,1,0]
	v_pk_fma_f32 v[160:161], v[190:191], v[166:167], v[160:161] op_sel:[0,0,0] op_sel_hi:[0,1,1] neg_lo:[0,0,1] neg_hi:[0,0,0]
	v_pk_add_f32 v[172:173], v[130:131], v[150:151] neg_lo:[0,1] neg_hi:[0,1]
	v_pk_add_f32 v[174:175], v[132:133], v[152:153] neg_lo:[0,1] neg_hi:[0,1]
	v_pk_add_f32 v[188:189], v[154:155], v[158:159] neg_lo:[0,1] neg_hi:[0,1]
	v_pk_add_f32 v[190:191], v[156:157], v[160:161] neg_lo:[0,1] neg_hi:[0,1]
	v_pk_add_f32 v[130:131], v[130:131], v[150:151]
	v_pk_add_f32 v[132:133], v[132:133], v[152:153]
	v_pk_add_f32 v[154:155], v[154:155], v[158:159]
	v_pk_add_f32 v[156:157], v[156:157], v[160:161]
	v_pk_mul_f32 v[150:151], v[172:173], v[222:223] op_sel:[1,1] op_sel_hi:[1,0]
	v_pk_mul_f32 v[152:153], v[174:175], v[222:223] op_sel:[1,0] op_sel_hi:[1,1]
	v_pk_mul_f32 v[158:159], v[188:189], v[222:223] op_sel:[1,1] op_sel_hi:[1,0]
	v_pk_mul_f32 v[160:161], v[190:191], v[222:223] op_sel:[1,0] op_sel_hi:[1,1]
	v_pk_fma_f32 v[150:151], v[172:173], v[222:223], v[150:151] op_sel:[0,0,0] op_sel_hi:[0,1,1] neg_lo:[0,0,1] neg_hi:[0,0,0]
	v_pk_fma_f32 v[152:153], v[174:175], v[222:223], v[152:153] op_sel:[0,1,0] op_sel_hi:[0,0,1] neg_lo:[0,0,0] neg_hi:[0,1,0]
	v_pk_fma_f32 v[158:159], v[188:189], v[222:223], v[158:159] op_sel:[0,0,0] op_sel_hi:[0,1,1] neg_lo:[0,0,1] neg_hi:[0,0,0]
	v_pk_fma_f32 v[160:161], v[190:191], v[222:223], v[160:161] op_sel:[0,1,0] op_sel_hi:[0,0,1] neg_lo:[0,0,0] neg_hi:[0,1,0]
	v_pk_add_f32 v[172:173], v[130:131], v[132:133] neg_lo:[0,1] neg_hi:[0,1]
	v_pk_add_f32 v[174:175], v[150:151], v[152:153] neg_lo:[0,1] neg_hi:[0,1]
	v_pk_add_f32 v[188:189], v[154:155], v[156:157] neg_lo:[0,1] neg_hi:[0,1]
	v_pk_add_f32 v[190:191], v[158:159], v[160:161] neg_lo:[0,1] neg_hi:[0,1]
	v_pk_add_f32 v[130:131], v[130:131], v[132:133]
	v_pk_add_f32 v[150:151], v[150:151], v[152:153]
	v_pk_add_f32 v[154:155], v[154:155], v[156:157]
	v_pk_add_f32 v[158:159], v[158:159], v[160:161]
	v_pk_mul_f32 v[132:133], v[172:173], v[224:225] op_sel:[1,1] op_sel_hi:[1,0]
	v_pk_mul_f32 v[152:153], v[174:175], v[224:225] op_sel:[1,1] op_sel_hi:[1,0]
	v_pk_mul_f32 v[156:157], v[188:189], v[224:225] op_sel:[1,1] op_sel_hi:[1,0]
	v_pk_mul_f32 v[160:161], v[190:191], v[224:225] op_sel:[1,1] op_sel_hi:[1,0]
	v_pk_fma_f32 v[132:133], v[172:173], v[224:225], v[132:133] op_sel:[0,0,0] op_sel_hi:[0,1,1] neg_lo:[0,0,1] neg_hi:[0,0,0]
	v_pk_fma_f32 v[152:153], v[174:175], v[224:225], v[152:153] op_sel:[0,0,0] op_sel_hi:[0,1,1] neg_lo:[0,0,1] neg_hi:[0,0,0]
	v_pk_fma_f32 v[156:157], v[188:189], v[224:225], v[156:157] op_sel:[0,0,0] op_sel_hi:[0,1,1] neg_lo:[0,0,1] neg_hi:[0,0,0]
	v_pk_fma_f32 v[160:161], v[190:191], v[224:225], v[160:161] op_sel:[0,0,0] op_sel_hi:[0,1,1] neg_lo:[0,0,1] neg_hi:[0,0,0]
	ds_write2_b64 v122, v[130:131], v[132:133] offset1:136
	ds_write2_b64 v128, v[150:151], v[152:153] offset0:16 offset1:152
	ds_write2_b64 v134, v[154:155], v[156:157] offset0:32 offset1:168
	ds_write2_b64 v148, v[158:159], v[160:161] offset0:48 offset1:184
	s_mov_b64 s[6:7], 0
	v_and_b32_e32 v68, 15, v68
	s_waitcnt lgkmcnt(0)
	v_lshlrev_b32_e32 v69, 3, v69
	v_lshlrev_b32_e32 v73, 9, v68
	v_and_or_b32 v69, v69, s90, v72
	v_add_u32_e32 v72, 0, v73
	v_lshl_add_u32 v68, v68, 3, 0
	s_mov_b32 s0, 0
	s_mov_b64 s[6:7], -1
; #define LAS __attribute__((address_space(3)))
; template <int LR, bool INV> __device__ __forceinline__ void fft_pass(ldsf2 buf, int base, int stride, int twi) {
;     constexpr int R = 1 << LR; cf x[R];
;     const v2f wv = ((ldsf2)((LAS unsigned char*)buf + 139264))[twi];
; #pragma unroll
;     for (int m = 0; m < R; ++m) { const v2f v = buf[base + m * stride]; x[m] = cf{v.x, v.y}; }
;     const cf w{wv.x, wv.y};
;     if (INV) dit_reg<LR>(x, w); else dif_reg<LR>(x, w);
; #pragma unroll
;     for (int m = 0; m < R; ++m) buf[base + m * stride] = mkv2(x[m].x, x[m].y);
; __device__ __forceinline__ void fft_fwd_abc(ldsf2 buf) {
;     ...
;     for (int u = 0; u < 2; ++u) { const int j = l + 64 * u, o = j & 15, e0 = wv * 1024 + (j >> 4) * 128 + o; fft_pass<3, false>(buf, e0 + (e0 >> 4), 17, o * 64); }
.LBB0_351:
	v_or_b32_e32 v73, s0, v69
	v_lshlrev_b32_e32 v74, 3, v73
	v_ashrrev_i32_e32 v73, 1, v73
	v_add3_u32 v73, v68, v74, v73
	ds_read2_b64 v[74:77], v73 offset1:17
	ds_read2_b64 v[78:81], v73 offset0:34 offset1:51
	ds_read2_b64 v[82:85], v73 offset0:68 offset1:85
	ds_read2_b64 v[86:89], v73 offset0:102 offset1:119
	s_movk_i32 s0, 0x200
	v_or_b32_e32 v118, s0, v69
	v_lshlrev_b32_e32 v122, 3, v118
	v_ashrrev_i32_e32 v118, 1, v118
	v_add3_u32 v118, v68, v122, v118
	ds_read2_b64 v[124:127], v118 offset1:17
	ds_read2_b64 v[128:131], v118 offset0:34 offset1:51
	ds_read2_b64 v[132:135], v118 offset0:68 offset1:85
	ds_read2_b64 v[148:151], v118 offset0:102 offset1:119
	s_waitcnt lgkmcnt(4)
	v_pk_add_f32 v[102:103], v[74:75], v[82:83] neg_lo:[0,1] neg_hi:[0,1]
	v_pk_add_f32 v[104:105], v[76:77], v[84:85] neg_lo:[0,1] neg_hi:[0,1]
	v_pk_add_f32 v[106:107], v[78:79], v[86:87] neg_lo:[0,1] neg_hi:[0,1]
	v_pk_add_f32 v[108:109], v[80:81], v[88:89] neg_lo:[0,1] neg_hi:[0,1]
	v_pk_add_f32 v[74:75], v[74:75], v[82:83]
	v_pk_add_f32 v[76:77], v[76:77], v[84:85]
	v_pk_add_f32 v[78:79], v[78:79], v[86:87]
	v_pk_add_f32 v[80:81], v[80:81], v[88:89]
	v_pk_mul_f32 v[82:83], v[102:103], v[204:205] op_sel:[1,1] op_sel_hi:[1,0]
	v_pk_mul_f32 v[84:85], v[104:105], v[210:211] op_sel:[1,1] op_sel_hi:[1,0]
	v_pk_mul_f32 v[86:87], v[106:107], v[204:205] op_sel:[1,0] op_sel_hi:[1,1]
	v_pk_mul_f32 v[88:89], v[108:109], v[212:213] op_sel:[1,1] op_sel_hi:[1,0]
	v_pk_fma_f32 v[82:83], v[102:103], v[204:205], v[82:83] op_sel:[0,0,0] op_sel_hi:[0,1,1] neg_lo:[0,0,1] neg_hi:[0,0,0]
	v_pk_fma_f32 v[84:85], v[104:105], v[210:211], v[84:85] op_sel:[0,0,0] op_sel_hi:[0,1,1] neg_lo:[0,0,1] neg_hi:[0,0,0]
	v_pk_fma_f32 v[86:87], v[106:107], v[204:205], v[86:87] op_sel:[0,1,0] op_sel_hi:[0,0,1] neg_lo:[0,0,0] neg_hi:[0,1,0]
	v_pk_fma_f32 v[88:89], v[108:109], v[212:213], v[88:89] op_sel:[0,0,0] op_sel_hi:[0,1,1] neg_lo:[0,0,1] neg_hi:[0,0,0]
	v_pk_add_f32 v[102:103], v[74:75], v[78:79] neg_lo:[0,1] neg_hi:[0,1]
	v_pk_add_f32 v[104:105], v[76:77], v[80:81] neg_lo:[0,1] neg_hi:[0,1]
	v_pk_add_f32 v[106:107], v[82:83], v[86:87] neg_lo:[0,1] neg_hi:[0,1]
	v_pk_add_f32 v[108:109], v[84:85], v[88:89] neg_lo:[0,1] neg_hi:[0,1]
	v_pk_add_f32 v[74:75], v[74:75], v[78:79]
	v_pk_add_f32 v[76:77], v[76:77], v[80:81]
	v_pk_add_f32 v[82:83], v[82:83], v[86:87]
	v_pk_add_f32 v[84:85], v[84:85], v[88:89]
	v_pk_mul_f32 v[78:79], v[102:103], v[206:207] op_sel:[1,1] op_sel_hi:[1,0]
	v_pk_mul_f32 v[80:81], v[104:105], v[206:207] op_sel:[1,0] op_sel_hi:[1,1]
	v_pk_mul_f32 v[86:87], v[106:107], v[206:207] op_sel:[1,1] op_sel_hi:[1,0]
	v_pk_mul_f32 v[88:89], v[108:109], v[206:207] op_sel:[1,0] op_sel_hi:[1,1]
	v_pk_fma_f32 v[78:79], v[102:103], v[206:207], v[78:79] op_sel:[0,0,0] op_sel_hi:[0,1,1] neg_lo:[0,0,1] neg_hi:[0,0,0]
	v_pk_fma_f32 v[80:81], v[104:105], v[206:207], v[80:81] op_sel:[0,1,0] op_sel_hi:[0,0,1] neg_lo:[0,0,0] neg_hi:[0,1,0]
	v_pk_fma_f32 v[86:87], v[106:107], v[206:207], v[86:87] op_sel:[0,0,0] op_sel_hi:[0,1,1] neg_lo:[0,0,1] neg_hi:[0,0,0]
	v_pk_fma_f32 v[88:89], v[108:109], v[206:207], v[88:89] op_sel:[0,1,0] op_sel_hi:[0,0,1] neg_lo:[0,0,0] neg_hi:[0,1,0]
	v_pk_add_f32 v[102:103], v[74:75], v[76:77] neg_lo:[0,1] neg_hi:[0,1]
	v_pk_add_f32 v[104:105], v[78:79], v[80:81] neg_lo:[0,1] neg_hi:[0,1]
	v_pk_add_f32 v[106:107], v[82:83], v[84:85] neg_lo:[0,1] neg_hi:[0,1]
	v_pk_add_f32 v[108:109], v[86:87], v[88:89] neg_lo:[0,1] neg_hi:[0,1]
	v_pk_add_f32 v[74:75], v[74:75], v[76:77]
	v_pk_add_f32 v[78:79], v[78:79], v[80:81]
	v_pk_add_f32 v[82:83], v[82:83], v[84:85]
	v_pk_add_f32 v[86:87], v[86:87], v[88:89]
	v_pk_mul_f32 v[76:77], v[102:103], v[208:209] op_sel:[1,1] op_sel_hi:[1,0]
	v_pk_mul_f32 v[80:81], v[104:105], v[208:209] op_sel:[1,1] op_sel_hi:[1,0]
	v_pk_mul_f32 v[84:85], v[106:107], v[208:209] op_sel:[1,1] op_sel_hi:[1,0]
	v_pk_mul_f32 v[88:89], v[108:109], v[208:209] op_sel:[1,1] op_sel_hi:[1,0]
	v_pk_fma_f32 v[76:77], v[102:103], v[208:209], v[76:77] op_sel:[0,0,0] op_sel_hi:[0,1,1] neg_lo:[0,0,1] neg_hi:[0,0,0]
	v_pk_fma_f32 v[80:81], v[104:105], v[208:209], v[80:81] op_sel:[0,0,0] op_sel_hi:[0,1,1] neg_lo:[0,0,1] neg_hi:[0,0,0]
	v_pk_fma_f32 v[84:85], v[106:107], v[208:209], v[84:85] op_sel:[0,0,0] op_sel_hi:[0,1,1] neg_lo:[0,0,1] neg_hi:[0,0,0]
	v_pk_fma_f32 v[88:89], v[108:109], v[208:209], v[88:89] op_sel:[0,0,0] op_sel_hi:[0,1,1] neg_lo:[0,0,1] neg_hi:[0,0,0]
	ds_write2_b64 v73, v[74:75], v[76:77] offset1:17
	ds_write2_b64 v73, v[78:79], v[80:81] offset0:34 offset1:51
	ds_write2_b64 v73, v[82:83], v[84:85] offset0:68 offset1:85
	ds_write2_b64 v73, v[86:87], v[88:89] offset0:102 offset1:119
	s_waitcnt lgkmcnt(4)
; __device__ __forceinline__ int otid() { int t = threadIdx.x; asm volatile("" : "+v"(t)); return t; }
; __device__ __forceinline__ void wave_lds_fence() { asm volatile("s_waitcnt lgkmcnt(0)" ::: "memory"); }
; __device__ __forceinline__ void fft_fwd_abc(ldsf2 buf) {
;     ...
;     for (int u = 0; u < 2; ++u) { const int j = l + 64 * u, o = j & 15, e0 = wv * 1024 + (j >> 4) * 128 + o; fft_pass<3, false>(buf, e0 + (e0 >> 4), 17, o * 64); }
;     wave_lds_fence();
; __device__ __forceinline__ void fft_conv(ldsf2 buf, const LAS unsigned* spec) {
;     ...
;     { const int tid = otid(); cf x[16];
; #pragma unroll
;       for (int m = 0; m < 16; ++m) { const v2f v = buf[tid * 17 + m]; x[m] = cf{v.x, v.y}; }
;       dif_reg<4>(x, cf{1.0f, 0.0f});
; #pragma unroll
;       for (int m = 0; m < 16; ++m) { const h2_t hv = __builtin_bit_cast(h2_t, spec[tid * 17 + m]); x[m] = cmul(x[m], cf{(float)hv.x, (float)hv.y}); }
	v_pk_add_f32 v[162:163], v[124:125], v[132:133] neg_lo:[0,1] neg_hi:[0,1]
	v_pk_add_f32 v[164:165], v[126:127], v[134:135] neg_lo:[0,1] neg_hi:[0,1]
	v_pk_add_f32 v[166:167], v[128:129], v[148:149] neg_lo:[0,1] neg_hi:[0,1]
	v_pk_add_f32 v[168:169], v[130:131], v[150:151] neg_lo:[0,1] neg_hi:[0,1]
	v_pk_add_f32 v[124:125], v[124:125], v[132:133]
	v_pk_add_f32 v[126:127], v[126:127], v[134:135]
	v_pk_add_f32 v[128:129], v[128:129], v[148:149]
	v_pk_add_f32 v[130:131], v[130:131], v[150:151]
	v_pk_mul_f32 v[132:133], v[162:163], v[204:205] op_sel:[1,1] op_sel_hi:[1,0]
	v_pk_mul_f32 v[134:135], v[164:165], v[210:211] op_sel:[1,1] op_sel_hi:[1,0]
	v_pk_mul_f32 v[148:149], v[166:167], v[204:205] op_sel:[1,0] op_sel_hi:[1,1]
	v_pk_mul_f32 v[150:151], v[168:169], v[212:213] op_sel:[1,1] op_sel_hi:[1,0]
	v_pk_fma_f32 v[132:133], v[162:163], v[204:205], v[132:133] op_sel:[0,0,0] op_sel_hi:[0,1,1] neg_lo:[0,0,1] neg_hi:[0,0,0]
	v_pk_fma_f32 v[134:135], v[164:165], v[210:211], v[134:135] op_sel:[0,0,0] op_sel_hi:[0,1,1] neg_lo:[0,0,1] neg_hi:[0,0,0]
	v_pk_fma_f32 v[148:149], v[166:167], v[204:205], v[148:149] op_sel:[0,1,0] op_sel_hi:[0,0,1] neg_lo:[0,0,0] neg_hi:[0,1,0]
	v_pk_fma_f32 v[150:151], v[168:169], v[212:213], v[150:151] op_sel:[0,0,0] op_sel_hi:[0,1,1] neg_lo:[0,0,1] neg_hi:[0,0,0]
	v_pk_add_f32 v[162:163], v[124:125], v[128:129] neg_lo:[0,1] neg_hi:[0,1]
	v_pk_add_f32 v[164:165], v[126:127], v[130:131] neg_lo:[0,1] neg_hi:[0,1]
	v_pk_add_f32 v[166:167], v[132:133], v[148:149] neg_lo:[0,1] neg_hi:[0,1]
	v_pk_add_f32 v[168:169], v[134:135], v[150:151] neg_lo:[0,1] neg_hi:[0,1]
	v_pk_add_f32 v[124:125], v[124:125], v[128:129]
	v_pk_add_f32 v[126:127], v[126:127], v[130:131]
	v_pk_add_f32 v[132:133], v[132:133], v[148:149]
	v_pk_add_f32 v[134:135], v[134:135], v[150:151]
	v_pk_mul_f32 v[128:129], v[162:163], v[206:207] op_sel:[1,1] op_sel_hi:[1,0]
	v_pk_mul_f32 v[130:131], v[164:165], v[206:207] op_sel:[1,0] op_sel_hi:[1,1]
	v_pk_mul_f32 v[148:149], v[166:167], v[206:207] op_sel:[1,1] op_sel_hi:[1,0]
	v_pk_mul_f32 v[150:151], v[168:169], v[206:207] op_sel:[1,0] op_sel_hi:[1,1]
	v_pk_fma_f32 v[128:129], v[162:163], v[206:207], v[128:129] op_sel:[0,0,0] op_sel_hi:[0,1,1] neg_lo:[0,0,1] neg_hi:[0,0,0]
	v_pk_fma_f32 v[130:131], v[164:165], v[206:207], v[130:131] op_sel:[0,1,0] op_sel_hi:[0,0,1] neg_lo:[0,0,0] neg_hi:[0,1,0]
	v_pk_fma_f32 v[148:149], v[166:167], v[206:207], v[148:149] op_sel:[0,0,0] op_sel_hi:[0,1,1] neg_lo:[0,0,1] neg_hi:[0,0,0]
	v_pk_fma_f32 v[150:151], v[168:169], v[206:207], v[150:151] op_sel:[0,1,0] op_sel_hi:[0,0,1] neg_lo:[0,0,0] neg_hi:[0,1,0]
	v_pk_add_f32 v[162:163], v[124:125], v[126:127] neg_lo:[0,1] neg_hi:[0,1]
	v_pk_add_f32 v[164:165], v[128:129], v[130:131] neg_lo:[0,1] neg_hi:[0,1]
	v_pk_add_f32 v[166:167], v[132:133], v[134:135] neg_lo:[0,1] neg_hi:[0,1]
	v_pk_add_f32 v[168:169], v[148:149], v[150:151] neg_lo:[0,1] neg_hi:[0,1]
	v_pk_add_f32 v[124:125], v[124:125], v[126:127]
	v_pk_add_f32 v[128:129], v[128:129], v[130:131]
	v_pk_add_f32 v[132:133], v[132:133], v[134:135]
	v_pk_add_f32 v[148:149], v[148:149], v[150:151]
	v_pk_mul_f32 v[126:127], v[162:163], v[208:209] op_sel:[1,1] op_sel_hi:[1,0]
	v_pk_mul_f32 v[130:131], v[164:165], v[208:209] op_sel:[1,1] op_sel_hi:[1,0]
	v_pk_mul_f32 v[134:135], v[166:167], v[208:209] op_sel:[1,1] op_sel_hi:[1,0]
	v_pk_mul_f32 v[150:151], v[168:169], v[208:209] op_sel:[1,1] op_sel_hi:[1,0]
	v_pk_fma_f32 v[126:127], v[162:163], v[208:209], v[126:127] op_sel:[0,0,0] op_sel_hi:[0,1,1] neg_lo:[0,0,1] neg_hi:[0,0,0]
	v_pk_fma_f32 v[130:131], v[164:165], v[208:209], v[130:131] op_sel:[0,0,0] op_sel_hi:[0,1,1] neg_lo:[0,0,1] neg_hi:[0,0,0]
	v_pk_fma_f32 v[134:135], v[166:167], v[208:209], v[134:135] op_sel:[0,0,0] op_sel_hi:[0,1,1] neg_lo:[0,0,1] neg_hi:[0,0,0]
	v_pk_fma_f32 v[150:151], v[168:169], v[208:209], v[150:151] op_sel:[0,0,0] op_sel_hi:[0,1,1] neg_lo:[0,0,1] neg_hi:[0,0,0]
	ds_write2_b64 v118, v[124:125], v[126:127] offset1:17
	ds_write2_b64 v118, v[128:129], v[130:131] offset0:34 offset1:51
	ds_write2_b64 v118, v[132:133], v[134:135] offset0:68 offset1:85
	ds_write2_b64 v118, v[148:149], v[150:151] offset0:102 offset1:119
	s_mov_b64 s[6:7], 0
	v_mov_b32_e32 v158, v195
	s_movk_i32 s0, 0x88
	s_waitcnt lgkmcnt(0)
	s_mov_b32 s86, s63
	v_mul_lo_u32 v68, v158, s0
	v_add_u32_e32 v147, 0, v68
	ds_read2_b64 v[72:75], v147 offset1:1
	ds_read2_b64 v[76:79], v147 offset0:2 offset1:3
	ds_read2_b64 v[90:93], v147 offset0:4 offset1:5
	ds_read2_b64 v[94:97], v147 offset0:6 offset1:7
	ds_read2_b64 v[98:101], v147 offset0:8 offset1:9
	ds_read2_b64 v[102:105], v147 offset0:10 offset1:11
	ds_read2_b64 v[118:121], v147 offset0:12 offset1:13
	ds_read2_b64 v[126:129], v147 offset0:14 offset1:15
	s_mov_b32 s6, s63
	s_mov_b32 s7, s16
	s_mov_b32 s17, s5
	s_mov_b32 s0, s16
	s_mov_b32 s1, s4
	s_mov_b32 s0, s63
	s_mov_b32 s1, s5
	s_mov_b32 s0, s87
	s_mov_b32 s1, s4
	s_mov_b32 s1, s5
	s_mov_b32 s35, s4
	s_mov_b32 s12, s63
	s_movk_i32 s0, 0x44
	v_mul_lo_u32 v106, v158, s0
	v_add_u32_e32 v106, 0, v106
	v_add_u32_e32 v106, 0x11000, v106
	ds_read2_b32 v[156:157], v106 offset1:1
	ds_read2_b32 v[158:159], v106 offset0:2 offset1:3
	ds_read2_b32 v[160:161], v106 offset0:4 offset1:5
	ds_read2_b32 v[162:163], v106 offset0:6 offset1:7
	ds_read2_b32 v[164:165], v106 offset0:8 offset1:9
	ds_read2_b32 v[134:135], v106 offset0:10 offset1:11
	ds_read2_b32 v[130:131], v106 offset0:12 offset1:13
	ds_read2_b32 v[168:169], v106 offset0:14 offset1:15
	s_mov_b32 s0, s5
	s_mov_b64 s[6:7], -1
	s_mov_b32 s35, s13
	s_mov_b32 s0, s13
	s_waitcnt lgkmcnt(8)
; __device__ __forceinline__ int otid() { int t = threadIdx.x; asm volatile("" : "+v"(t)); return t; }
; __device__ __forceinline__ cf twc(cf ws, int k16) { if (k16 == 0) return ws; if (k16 == 4) return cf{ws.y, -ws.x}; return cmul(ws, cf{c16(k16), -s16(k16)}); }
; template <int LR> __device__ __forceinline__ void dif_reg(cf (&x)[1 << LR], cf w) {
;     constexpr int R = 1 << LR; cf ws = w;
; #pragma unroll
;     for (int s = 0; s < LR; ++s) { const int half = R >> (s + 1);
; #pragma unroll
;         for (int m0 = 0; m0 < R; m0 += 2 * half)
; #pragma unroll
;             for (int mm = 0; mm < half; ++mm) { const int ia = m0 + mm, ib = ia + half; const cf a = x[ia], b = x[ib];
;                 x[ia] = cf{a.x + b.x, a.y + b.y}; const cf d{a.x - b.x, a.y - b.y};
;                 x[ib] = cmul(d, twc(ws, (mm << s) * (16 / R))); }
;         ws = cmul(ws, ws); }
; }
; __device__ __forceinline__ void fft_conv(ldsf2 buf, const LAS unsigned* spec) {
;     ...
;     { const int tid = otid(); cf x[16];
; #pragma unroll
;       for (int m = 0; m < 16; ++m) { const v2f v = buf[tid * 17 + m]; x[m] = cf{v.x, v.y}; }
;       dif_reg<4>(x, cf{1.0f, 0.0f});
	v_pk_add_f32 v[80:81], v[72:73], v[98:99]
	v_pk_add_f32 v[82:83], v[74:75], v[100:101]
	v_pk_add_f32 v[84:85], v[76:77], v[102:103]
	v_pk_add_f32 v[86:87], v[78:79], v[104:105]
	v_pk_add_f32 v[72:73], v[72:73], v[98:99] neg_lo:[0,1] neg_hi:[0,1]
	v_pk_add_f32 v[74:75], v[74:75], v[100:101] neg_lo:[0,1] neg_hi:[0,1]
	v_pk_add_f32 v[76:77], v[76:77], v[102:103] neg_lo:[0,1] neg_hi:[0,1]
	v_pk_add_f32 v[78:79], v[78:79], v[104:105] neg_lo:[0,1] neg_hi:[0,1]
	v_pk_mul_f32 v[100:101], v[74:75], s[4:5] op_sel:[1,1] op_sel_hi:[1,0] neg_lo:[0,1] neg_hi:[0,0]
	v_pk_mul_f32 v[102:103], v[76:77], s[16:17] op_sel:[1,0] op_sel_hi:[1,0] neg_lo:[0,1] neg_hi:[0,0]
	v_pk_mul_f32 v[104:105], v[78:79], s[4:5] op_sel:[1,0] op_sel_hi:[1,1] neg_lo:[0,1] neg_hi:[0,0]
	v_pk_fma_f32 v[100:101], v[74:75], s[4:5], v[100:101] op_sel:[0,0,0] op_sel_hi:[0,1,1] neg_lo:[0,0,1] neg_hi:[0,1,0]
	v_pk_fma_f32 v[102:103], v[76:77], s[16:17], v[102:103] op_sel:[0,0,0] op_sel_hi:[0,0,1] neg_lo:[0,0,1] neg_hi:[0,1,0]
	v_pk_fma_f32 v[104:105], v[78:79], s[4:5], v[104:105] op_sel:[0,1,0] op_sel_hi:[0,0,1] neg_lo:[0,0,1] neg_hi:[0,1,0]
	v_pk_add_f32 v[88:89], v[90:91], v[118:119]
	v_pk_add_f32 v[108:109], v[92:93], v[120:121]
	v_pk_add_f32 v[110:111], v[94:95], v[126:127]
	v_pk_add_f32 v[112:113], v[96:97], v[128:129]
	v_pk_add_f32 v[90:91], v[90:91], v[118:119] op_sel:[1,1] op_sel_hi:[0,0] neg_lo:[0,1] neg_hi:[1,0]
	v_pk_add_f32 v[92:93], v[92:93], v[120:121] neg_lo:[0,1] neg_hi:[0,1]
	v_pk_add_f32 v[94:95], v[94:95], v[126:127] neg_lo:[0,1] neg_hi:[0,1]
	v_pk_add_f32 v[96:97], v[96:97], v[128:129] neg_lo:[0,1] neg_hi:[0,1]
	v_pk_mul_f32 v[120:121], v[92:93], s[4:5] op_sel:[1,0] op_sel_hi:[1,1] neg_lo:[0,1] neg_hi:[0,1]
	v_pk_mul_f32 v[126:127], v[94:95], s[16:17] op_sel:[1,0] op_sel_hi:[1,0] neg_lo:[0,1] neg_hi:[0,1]
	v_pk_mul_f32 v[128:129], v[96:97], s[4:5] op_sel:[1,1] op_sel_hi:[1,0] neg_lo:[0,1] neg_hi:[0,1]
	v_pk_fma_f32 v[120:121], v[92:93], s[4:5], v[120:121] op_sel:[0,1,0] op_sel_hi:[0,0,1] neg_lo:[0,1,1] neg_hi:[0,1,0]
	v_pk_fma_f32 v[126:127], v[94:95], s[16:17], v[126:127] op_sel:[0,0,0] op_sel_hi:[0,0,1] neg_lo:[0,1,1] neg_hi:[0,1,0]
	v_pk_fma_f32 v[128:129], v[96:97], s[4:5], v[128:129] op_sel:[0,0,0] op_sel_hi:[0,1,1] neg_lo:[0,1,1] neg_hi:[0,1,0]
	v_pk_add_f32 v[114:115], v[80:81], v[88:89]
	v_pk_add_f32 v[116:117], v[82:83], v[108:109]
	v_pk_add_f32 v[122:123], v[84:85], v[110:111]
	v_pk_add_f32 v[124:125], v[86:87], v[112:113]
	v_pk_add_f32 v[80:81], v[80:81], v[88:89] neg_lo:[0,1] neg_hi:[0,1]
	v_pk_add_f32 v[82:83], v[82:83], v[108:109] neg_lo:[0,1] neg_hi:[0,1]
	v_pk_add_f32 v[84:85], v[84:85], v[110:111] op_sel:[1,1] op_sel_hi:[0,0] neg_lo:[0,1] neg_hi:[1,0]
	v_pk_add_f32 v[86:87], v[86:87], v[112:113] neg_lo:[0,1] neg_hi:[0,1]
	v_pk_mul_f32 v[108:109], v[82:83], s[16:17] op_sel:[1,0] op_sel_hi:[1,0] neg_lo:[0,1] neg_hi:[0,0]
	v_pk_mul_f32 v[112:113], v[86:87], s[16:17] op_sel:[1,0] op_sel_hi:[1,0] neg_lo:[0,1] neg_hi:[0,1]
	v_pk_fma_f32 v[108:109], v[82:83], s[16:17], v[108:109] op_sel:[0,0,0] op_sel_hi:[0,0,1] neg_lo:[0,0,1] neg_hi:[0,1,0]
	v_pk_fma_f32 v[112:113], v[86:87], s[16:17], v[112:113] op_sel:[0,0,0] op_sel_hi:[0,0,1] neg_lo:[0,1,1] neg_hi:[0,1,0]
	v_pk_add_f32 v[132:133], v[72:73], v[90:91]
	v_pk_add_f32 v[148:149], v[100:101], v[120:121]
	v_pk_add_f32 v[150:151], v[102:103], v[126:127]
	v_pk_add_f32 v[152:153], v[104:105], v[128:129]
	v_pk_add_f32 v[72:73], v[72:73], v[90:91] neg_lo:[0,1] neg_hi:[0,1]
	v_pk_add_f32 v[100:101], v[100:101], v[120:121] neg_lo:[0,1] neg_hi:[0,1]
	v_pk_add_f32 v[102:103], v[102:103], v[126:127] op_sel:[1,1] op_sel_hi:[0,0] neg_lo:[0,1] neg_hi:[1,0]
	v_pk_add_f32 v[104:105], v[104:105], v[128:129] neg_lo:[0,1] neg_hi:[0,1]
	v_pk_mul_f32 v[120:121], v[100:101], s[16:17] op_sel:[1,0] op_sel_hi:[1,0] neg_lo:[0,1] neg_hi:[0,0]
	v_pk_mul_f32 v[128:129], v[104:105], s[16:17] op_sel:[1,0] op_sel_hi:[1,0] neg_lo:[0,1] neg_hi:[0,1]
	v_pk_fma_f32 v[120:121], v[100:101], s[16:17], v[120:121] op_sel:[0,0,0] op_sel_hi:[0,0,1] neg_lo:[0,0,1] neg_hi:[0,1,0]
	v_pk_fma_f32 v[128:129], v[104:105], s[16:17], v[128:129] op_sel:[0,0,0] op_sel_hi:[0,0,1] neg_lo:[0,1,1] neg_hi:[0,1,0]
	v_pk_add_f32 v[154:155], v[114:115], v[122:123]
	v_pk_add_f32 v[166:167], v[116:117], v[124:125]
	v_pk_add_f32 v[98:99], v[80:81], v[84:85]
	v_pk_add_f32 v[74:75], v[108:109], v[112:113]
	v_pk_add_f32 v[114:115], v[114:115], v[122:123] neg_lo:[0,1] neg_hi:[0,1]
	v_pk_add_f32 v[116:117], v[116:117], v[124:125] op_sel:[1,1] op_sel_hi:[0,0] neg_lo:[0,1] neg_hi:[1,0]
	v_pk_add_f32 v[80:81], v[80:81], v[84:85] neg_lo:[0,1] neg_hi:[0,1]
	v_pk_add_f32 v[108:109], v[108:109], v[112:113] op_sel:[1,1] op_sel_hi:[0,0] neg_lo:[0,1] neg_hi:[1,0]
	v_pk_add_f32 v[76:77], v[132:133], v[150:151]
	v_pk_add_f32 v[78:79], v[148:149], v[152:153]
	v_pk_add_f32 v[118:119], v[72:73], v[102:103]
	v_pk_add_f32 v[92:93], v[120:121], v[128:129]
	v_pk_add_f32 v[132:133], v[132:133], v[150:151] neg_lo:[0,1] neg_hi:[0,1]
	v_pk_add_f32 v[148:149], v[148:149], v[152:153] op_sel:[1,1] op_sel_hi:[0,0] neg_lo:[0,1] neg_hi:[1,0]
	v_pk_add_f32 v[72:73], v[72:73], v[102:103] neg_lo:[0,1] neg_hi:[0,1]
	v_pk_add_f32 v[120:121], v[120:121], v[128:129] op_sel:[1,1] op_sel_hi:[0,0] neg_lo:[0,1] neg_hi:[1,0]
	v_pk_add_f32 v[94:95], v[154:155], v[166:167]
	v_pk_add_f32 v[96:97], v[114:115], v[116:117]
	v_pk_add_f32 v[88:89], v[98:99], v[74:75]
	v_pk_add_f32 v[82:83], v[80:81], v[108:109]
	v_pk_add_f32 v[154:155], v[154:155], v[166:167] neg_lo:[0,1] neg_hi:[0,1]
	v_pk_add_f32 v[114:115], v[114:115], v[116:117] neg_lo:[0,1] neg_hi:[0,1]
	v_pk_add_f32 v[98:99], v[98:99], v[74:75] neg_lo:[0,1] neg_hi:[0,1]
	v_pk_add_f32 v[80:81], v[80:81], v[108:109] neg_lo:[0,1] neg_hi:[0,1]
	v_pk_add_f32 v[110:111], v[76:77], v[78:79]
	v_pk_add_f32 v[86:87], v[132:133], v[148:149]
	v_pk_add_f32 v[90:91], v[118:119], v[92:93]
	v_pk_add_f32 v[100:101], v[72:73], v[120:121]
	v_pk_add_f32 v[76:77], v[76:77], v[78:79] neg_lo:[0,1] neg_hi:[0,1]
	v_pk_add_f32 v[132:133], v[132:133], v[148:149] neg_lo:[0,1] neg_hi:[0,1]
	v_pk_add_f32 v[118:119], v[118:119], v[92:93] neg_lo:[0,1] neg_hi:[0,1]
	v_pk_add_f32 v[72:73], v[72:73], v[120:121] neg_lo:[0,1] neg_hi:[0,1]
	s_waitcnt lgkmcnt(0)
; __device__ __forceinline__ cf twc(cf ws, int k16) { if (k16 == 0) return ws; if (k16 == 4) return cf{ws.y, -ws.x}; return cmul(ws, cf{c16(k16), -s16(k16)}); }
; template <int LR> __device__ __forceinline__ void dit_reg(cf (&x)[1 << LR], cf w) {
;     constexpr int R = 1 << LR; cf wsv[LR]; wsv[0] = w;
; #pragma unroll
;     for (int s = 1; s < LR; ++s) wsv[s] = cmul(wsv[s - 1], wsv[s - 1]);
; #pragma unroll
;     for (int s = LR - 1; s >= 0; --s) { const int half = R >> (s + 1);
; #pragma unroll
;         for (int m0 = 0; m0 < R; m0 += 2 * half)
; #pragma unroll
;             for (int mm = 0; mm < half; ++mm) { const int ia = m0 + mm, ib = ia + half; const cf a = x[ia];
;                 const cf b = cmulc(x[ib], twc(wsv[s], (mm << s) * (16 / R)));
;                 x[ia] = cf{a.x + b.x, a.y + b.y}; x[ib] = cf{a.x - b.x, a.y - b.y}; } }
; __device__ __forceinline__ void fft_conv(ldsf2 buf, const LAS unsigned* spec) {
;     ...
;       for (int m = 0; m < 16; ++m) { const h2_t hv = __builtin_bit_cast(h2_t, spec[tid * 17 + m]); x[m] = cmul(x[m], cf{(float)hv.x, (float)hv.y}); }
;       dit_reg<4>(x, cf{1.0f, 0.0f});
	v_cvt_f32_f16_e32 v126, v156
	v_cvt_f32_f16_e32 v122, v157
	v_cvt_f32_f16_e32 v84, v158
	v_cvt_f32_f16_e32 v150, v159
	v_cvt_f32_f16_sdwa v127, v156 dst_sel:DWORD dst_unused:UNUSED_PAD src0_sel:WORD_1
	v_cvt_f32_f16_sdwa v123, v157 dst_sel:DWORD dst_unused:UNUSED_PAD src0_sel:WORD_1
	v_cvt_f32_f16_sdwa v85, v158 dst_sel:DWORD dst_unused:UNUSED_PAD src0_sel:WORD_1
	v_cvt_f32_f16_sdwa v151, v159 dst_sel:DWORD dst_unused:UNUSED_PAD src0_sel:WORD_1
	v_pk_mul_f32 v[104:105], v[94:95], v[126:127] op_sel:[1,1] op_sel_hi:[1,0]
	v_pk_mul_f32 v[124:125], v[154:155], v[122:123] op_sel:[1,1] op_sel_hi:[1,0]
	v_pk_mul_f32 v[112:113], v[96:97], v[84:85] op_sel:[1,1] op_sel_hi:[1,0]
	v_pk_mul_f32 v[152:153], v[114:115], v[150:151] op_sel:[1,1] op_sel_hi:[1,0]
	v_pk_fma_f32 v[126:127], v[94:95], v[126:127], v[104:105] op_sel:[0,0,0] op_sel_hi:[0,1,1] neg_lo:[0,0,1] neg_hi:[0,0,0]
	v_pk_fma_f32 v[122:123], v[154:155], v[122:123], v[124:125] op_sel:[0,0,0] op_sel_hi:[0,1,1] neg_lo:[0,0,1] neg_hi:[0,0,0]
	v_pk_fma_f32 v[84:85], v[96:97], v[84:85], v[112:113] op_sel:[0,0,0] op_sel_hi:[0,1,1] neg_lo:[0,0,1] neg_hi:[0,0,0]
	v_pk_fma_f32 v[150:151], v[114:115], v[150:151], v[152:153] op_sel:[0,0,0] op_sel_hi:[0,1,1] neg_lo:[0,0,1] neg_hi:[0,0,0]
	v_cvt_f32_f16_e32 v102, v160
	v_cvt_f32_f16_e32 v166, v161
	v_cvt_f32_f16_e32 v74, v162
	v_cvt_f32_f16_e32 v78, v163
	v_cvt_f32_f16_sdwa v103, v160 dst_sel:DWORD dst_unused:UNUSED_PAD src0_sel:WORD_1
	v_cvt_f32_f16_sdwa v167, v161 dst_sel:DWORD dst_unused:UNUSED_PAD src0_sel:WORD_1
	v_cvt_f32_f16_sdwa v75, v162 dst_sel:DWORD dst_unused:UNUSED_PAD src0_sel:WORD_1
	v_cvt_f32_f16_sdwa v79, v163 dst_sel:DWORD dst_unused:UNUSED_PAD src0_sel:WORD_1
	v_pk_mul_f32 v[128:129], v[88:89], v[102:103] op_sel:[1,1] op_sel_hi:[1,0]
	v_pk_mul_f32 v[116:117], v[98:99], v[166:167] op_sel:[1,1] op_sel_hi:[1,0]
	v_pk_mul_f32 v[108:109], v[82:83], v[74:75] op_sel:[1,1] op_sel_hi:[1,0]
	v_pk_mul_f32 v[148:149], v[80:81], v[78:79] op_sel:[1,1] op_sel_hi:[1,0]
	v_pk_fma_f32 v[102:103], v[88:89], v[102:103], v[128:129] op_sel:[0,0,0] op_sel_hi:[0,1,1] neg_lo:[0,0,1] neg_hi:[0,0,0]
	v_pk_fma_f32 v[166:167], v[98:99], v[166:167], v[116:117] op_sel:[0,0,0] op_sel_hi:[0,1,1] neg_lo:[0,0,1] neg_hi:[0,0,0]
	v_pk_fma_f32 v[74:75], v[82:83], v[74:75], v[108:109] op_sel:[0,0,0] op_sel_hi:[0,1,1] neg_lo:[0,0,1] neg_hi:[0,0,0]
	v_pk_fma_f32 v[78:79], v[80:81], v[78:79], v[148:149] op_sel:[0,0,0] op_sel_hi:[0,1,1] neg_lo:[0,0,1] neg_hi:[0,0,0]
	v_cvt_f32_f16_e32 v92, v164
	v_cvt_f32_f16_e32 v104, v165
	v_cvt_f32_f16_e32 v124, v134
	v_cvt_f32_f16_e32 v112, v135
	v_cvt_f32_f16_sdwa v93, v164 dst_sel:DWORD dst_unused:UNUSED_PAD src0_sel:WORD_1
	v_cvt_f32_f16_sdwa v105, v165 dst_sel:DWORD dst_unused:UNUSED_PAD src0_sel:WORD_1
	v_cvt_f32_f16_sdwa v125, v134 dst_sel:DWORD dst_unused:UNUSED_PAD src0_sel:WORD_1
	v_cvt_f32_f16_sdwa v113, v135 dst_sel:DWORD dst_unused:UNUSED_PAD src0_sel:WORD_1
	v_pk_mul_f32 v[120:121], v[110:111], v[92:93] op_sel:[1,1] op_sel_hi:[1,0]
	v_pk_mul_f32 v[94:95], v[76:77], v[104:105] op_sel:[1,1] op_sel_hi:[1,0]
	v_pk_mul_f32 v[154:155], v[86:87], v[124:125] op_sel:[1,1] op_sel_hi:[1,0]
	v_pk_mul_f32 v[96:97], v[132:133], v[112:113] op_sel:[1,1] op_sel_hi:[1,0]
	v_pk_fma_f32 v[92:93], v[110:111], v[92:93], v[120:121] op_sel:[0,0,0] op_sel_hi:[0,1,1] neg_lo:[0,0,1] neg_hi:[0,0,0]
	v_pk_fma_f32 v[104:105], v[76:77], v[104:105], v[94:95] op_sel:[0,0,0] op_sel_hi:[0,1,1] neg_lo:[0,0,1] neg_hi:[0,0,0]
	v_pk_fma_f32 v[124:125], v[86:87], v[124:125], v[154:155] op_sel:[0,0,0] op_sel_hi:[0,1,1] neg_lo:[0,0,1] neg_hi:[0,0,0]
	v_pk_fma_f32 v[112:113], v[132:133], v[112:113], v[96:97] op_sel:[0,0,0] op_sel_hi:[0,1,1] neg_lo:[0,0,1] neg_hi:[0,0,0]
	v_cvt_f32_f16_e32 v152, v130
	v_cvt_f32_f16_e32 v128, v131
	v_cvt_f32_f16_e32 v116, v168
	v_cvt_f32_f16_e32 v108, v169
	v_cvt_f32_f16_sdwa v153, v130 dst_sel:DWORD dst_unused:UNUSED_PAD src0_sel:WORD_1
	v_cvt_f32_f16_sdwa v129, v131 dst_sel:DWORD dst_unused:UNUSED_PAD src0_sel:WORD_1
	v_cvt_f32_f16_sdwa v117, v168 dst_sel:DWORD dst_unused:UNUSED_PAD src0_sel:WORD_1
	v_cvt_f32_f16_sdwa v109, v169 dst_sel:DWORD dst_unused:UNUSED_PAD src0_sel:WORD_1
	v_pk_mul_f32 v[114:115], v[90:91], v[152:153] op_sel:[1,1] op_sel_hi:[1,0]
	v_pk_mul_f32 v[88:89], v[118:119], v[128:129] op_sel:[1,1] op_sel_hi:[1,0]
	v_pk_mul_f32 v[98:99], v[100:101], v[116:117] op_sel:[1,1] op_sel_hi:[1,0]
	v_pk_mul_f32 v[82:83], v[72:73], v[108:109] op_sel:[1,1] op_sel_hi:[1,0]
	v_pk_fma_f32 v[152:153], v[90:91], v[152:153], v[114:115] op_sel:[0,0,0] op_sel_hi:[0,1,1] neg_lo:[0,0,1] neg_hi:[0,0,0]
	v_pk_fma_f32 v[128:129], v[118:119], v[128:129], v[88:89] op_sel:[0,0,0] op_sel_hi:[0,1,1] neg_lo:[0,0,1] neg_hi:[0,0,0]
	v_pk_fma_f32 v[116:117], v[100:101], v[116:117], v[98:99] op_sel:[0,0,0] op_sel_hi:[0,1,1] neg_lo:[0,0,1] neg_hi:[0,0,0]
	v_pk_fma_f32 v[108:109], v[72:73], v[108:109], v[82:83] op_sel:[0,0,0] op_sel_hi:[0,1,1] neg_lo:[0,0,1] neg_hi:[0,0,0]
	v_pk_add_f32 v[148:149], v[126:127], v[122:123]
	v_pk_add_f32 v[80:81], v[84:85], v[150:151]
	v_pk_add_f32 v[120:121], v[102:103], v[166:167]
	v_pk_add_f32 v[110:111], v[74:75], v[78:79]
	v_pk_add_f32 v[126:127], v[126:127], v[122:123] neg_lo:[0,1] neg_hi:[0,1]
	v_pk_add_f32 v[84:85], v[84:85], v[150:151] neg_lo:[0,1] neg_hi:[0,1]
	v_pk_add_f32 v[102:103], v[102:103], v[166:167] neg_lo:[0,1] neg_hi:[0,1]
	v_pk_add_f32 v[74:75], v[74:75], v[78:79] neg_lo:[0,1] neg_hi:[0,1]
	v_pk_add_f32 v[94:95], v[92:93], v[104:105]
	v_pk_add_f32 v[76:77], v[124:125], v[112:113]
	v_pk_add_f32 v[154:155], v[152:153], v[128:129]
	v_pk_add_f32 v[86:87], v[116:117], v[108:109]
; __device__ __forceinline__ cf twc(cf ws, int k16) { if (k16 == 0) return ws; if (k16 == 4) return cf{ws.y, -ws.x}; return cmul(ws, cf{c16(k16), -s16(k16)}); }
; __device__ __forceinline__ void wave_lds_fence() { asm volatile("s_waitcnt lgkmcnt(0)" ::: "memory"); }
; template <int LR> __device__ __forceinline__ void dit_reg(cf (&x)[1 << LR], cf w) {
;     constexpr int R = 1 << LR; cf wsv[LR]; wsv[0] = w;
; #pragma unroll
;     for (int s = 1; s < LR; ++s) wsv[s] = cmul(wsv[s - 1], wsv[s - 1]);
; #pragma unroll
;     for (int s = LR - 1; s >= 0; --s) { const int half = R >> (s + 1);
; #pragma unroll
;         for (int m0 = 0; m0 < R; m0 += 2 * half)
; #pragma unroll
;             for (int mm = 0; mm < half; ++mm) { const int ia = m0 + mm, ib = ia + half; const cf a = x[ia];
;                 const cf b = cmulc(x[ib], twc(wsv[s], (mm << s) * (16 / R)));
;                 x[ia] = cf{a.x + b.x, a.y + b.y}; x[ib] = cf{a.x - b.x, a.y - b.y}; } }
; __device__ __forceinline__ void fft_conv(ldsf2 buf, const LAS unsigned* spec) {
;     ...
; #pragma unroll
;       for (int m = 0; m < 16; ++m) buf[tid * 17 + m] = mkv2(x[m].x, x[m].y); }
;     wave_lds_fence();
	v_pk_add_f32 v[92:93], v[92:93], v[104:105] neg_lo:[0,1] neg_hi:[0,1]
	v_pk_add_f32 v[124:125], v[124:125], v[112:113] neg_lo:[0,1] neg_hi:[0,1]
	v_pk_add_f32 v[152:153], v[152:153], v[128:129] neg_lo:[0,1] neg_hi:[0,1]
	v_pk_add_f32 v[116:117], v[116:117], v[108:109] neg_lo:[0,1] neg_hi:[0,1]
	v_pk_add_f32 v[96:97], v[148:149], v[80:81]
	v_pk_add_f32 v[132:133], v[126:127], v[84:85] op_sel:[0,1] op_sel_hi:[1,0] neg_lo:[0,1] neg_hi:[0,0]
	v_pk_add_f32 v[114:115], v[120:121], v[110:111]
	v_pk_add_f32 v[90:91], v[102:103], v[74:75] op_sel:[0,1] op_sel_hi:[1,0] neg_lo:[0,1] neg_hi:[0,0]
	v_pk_add_f32 v[148:149], v[148:149], v[80:81] neg_lo:[0,1] neg_hi:[0,1]
	v_pk_add_f32 v[126:127], v[126:127], v[84:85] op_sel:[0,1] op_sel_hi:[1,0] neg_lo:[0,0] neg_hi:[0,1]
	v_pk_add_f32 v[120:121], v[120:121], v[110:111] neg_lo:[0,1] neg_hi:[0,1]
	v_pk_add_f32 v[102:103], v[102:103], v[74:75] op_sel:[0,1] op_sel_hi:[1,0] neg_lo:[0,0] neg_hi:[0,1]
	v_pk_add_f32 v[88:89], v[94:95], v[76:77]
	v_pk_add_f32 v[118:119], v[92:93], v[124:125] op_sel:[0,1] op_sel_hi:[1,0] neg_lo:[0,1] neg_hi:[0,0]
	v_pk_add_f32 v[98:99], v[154:155], v[86:87]
	v_pk_add_f32 v[100:101], v[152:153], v[116:117] op_sel:[0,1] op_sel_hi:[1,0] neg_lo:[0,1] neg_hi:[0,0]
	v_pk_add_f32 v[94:95], v[94:95], v[76:77] neg_lo:[0,1] neg_hi:[0,1]
	v_pk_add_f32 v[92:93], v[92:93], v[124:125] op_sel:[0,1] op_sel_hi:[1,0] neg_lo:[0,0] neg_hi:[0,1]
	v_pk_add_f32 v[154:155], v[154:155], v[86:87] neg_lo:[0,1] neg_hi:[0,1]
	v_pk_add_f32 v[152:153], v[152:153], v[116:117] op_sel:[0,1] op_sel_hi:[1,0] neg_lo:[0,0] neg_hi:[0,1]
	v_pk_add_f32 v[82:83], v[96:97], v[114:115]
	v_pk_mul_f32 v[72:73], v[90:91], s[16:17] op_sel:[1,0] op_sel_hi:[1,0] neg_lo:[0,1] neg_hi:[0,0]
	v_pk_add_f32 v[122:123], v[148:149], v[120:121] op_sel:[0,1] op_sel_hi:[1,0] neg_lo:[0,1] neg_hi:[0,0]
	v_pk_mul_f32 v[150:151], v[102:103], s[16:17] op_sel:[1,0] op_sel_hi:[1,0] neg_lo:[0,1] neg_hi:[0,1]
	v_pk_add_f32 v[96:97], v[96:97], v[114:115] neg_lo:[0,1] neg_hi:[0,1]
	v_pk_fma_f32 v[72:73], v[90:91], s[16:17], v[72:73] op_sel:[0,0,0] op_sel_hi:[0,0,1] neg_lo:[0,0,0] neg_hi:[0,0,0]
	v_pk_add_f32 v[148:149], v[148:149], v[120:121] op_sel:[0,1] op_sel_hi:[1,0] neg_lo:[0,0] neg_hi:[0,1]
	v_pk_fma_f32 v[150:151], v[102:103], s[16:17], v[150:151] op_sel:[0,0,0] op_sel_hi:[0,0,1] neg_lo:[0,1,0] neg_hi:[0,0,0]
	v_pk_add_f32 v[90:91], v[132:133], v[72:73] neg_lo:[0,1] neg_hi:[0,1]
	v_pk_add_f32 v[102:103], v[126:127], v[150:151] neg_lo:[0,1] neg_hi:[0,1]
	v_pk_add_f32 v[132:133], v[132:133], v[72:73]
	v_pk_add_f32 v[126:127], v[126:127], v[150:151]
	v_pk_add_f32 v[166:167], v[88:89], v[98:99]
	v_pk_mul_f32 v[78:79], v[100:101], s[16:17] op_sel:[1,0] op_sel_hi:[1,0] neg_lo:[0,1] neg_hi:[0,0]
	v_pk_add_f32 v[104:105], v[94:95], v[154:155] op_sel:[0,1] op_sel_hi:[1,0] neg_lo:[0,1] neg_hi:[0,0]
	v_pk_mul_f32 v[112:113], v[152:153], s[16:17] op_sel:[1,0] op_sel_hi:[1,0] neg_lo:[0,1] neg_hi:[0,1]
	v_pk_add_f32 v[88:89], v[88:89], v[98:99] neg_lo:[0,1] neg_hi:[0,1]
	v_pk_fma_f32 v[78:79], v[100:101], s[16:17], v[78:79] op_sel:[0,0,0] op_sel_hi:[0,0,1] neg_lo:[0,0,0] neg_hi:[0,0,0]
	v_pk_add_f32 v[94:95], v[94:95], v[154:155] op_sel:[0,1] op_sel_hi:[1,0] neg_lo:[0,0] neg_hi:[0,1]
	v_pk_fma_f32 v[112:113], v[152:153], s[16:17], v[112:113] op_sel:[0,0,0] op_sel_hi:[0,0,1] neg_lo:[0,1,0] neg_hi:[0,0,0]
	v_pk_add_f32 v[100:101], v[118:119], v[78:79] neg_lo:[0,1] neg_hi:[0,1]
	v_pk_add_f32 v[152:153], v[92:93], v[112:113] neg_lo:[0,1] neg_hi:[0,1]
	v_pk_add_f32 v[118:119], v[118:119], v[78:79]
	v_pk_add_f32 v[92:93], v[92:93], v[112:113]
	v_pk_add_f32 v[128:129], v[82:83], v[166:167]
	v_pk_mul_f32 v[108:109], v[118:119], s[4:5] op_sel:[1,1] op_sel_hi:[1,0] neg_lo:[0,1] neg_hi:[0,0]
	v_pk_mul_f32 v[80:81], v[104:105], s[16:17] op_sel:[1,0] op_sel_hi:[1,0] neg_lo:[0,1] neg_hi:[0,0]
	v_pk_mul_f32 v[84:85], v[92:93], s[4:5] op_sel:[1,0] op_sel_hi:[1,1] neg_lo:[0,1] neg_hi:[0,0]
	v_pk_add_f32 v[82:83], v[82:83], v[166:167] neg_lo:[0,1] neg_hi:[0,1]
	v_pk_fma_f32 v[108:109], v[118:119], s[4:5], v[108:109] op_sel:[0,0,0] op_sel_hi:[0,1,1] neg_lo:[0,0,0] neg_hi:[0,0,0]
	v_pk_fma_f32 v[80:81], v[104:105], s[16:17], v[80:81] op_sel:[0,0,0] op_sel_hi:[0,0,1] neg_lo:[0,0,0] neg_hi:[0,0,0]
	v_pk_fma_f32 v[84:85], v[92:93], s[4:5], v[84:85] op_sel:[0,1,0] op_sel_hi:[0,0,1] neg_lo:[0,0,0] neg_hi:[0,0,0]
	v_pk_add_f32 v[118:119], v[132:133], v[108:109] neg_lo:[0,1] neg_hi:[0,1]
	v_pk_add_f32 v[104:105], v[122:123], v[80:81] neg_lo:[0,1] neg_hi:[0,1]
	v_pk_add_f32 v[92:93], v[126:127], v[84:85] neg_lo:[0,1] neg_hi:[0,1]
	v_pk_add_f32 v[132:133], v[132:133], v[108:109]
	v_pk_add_f32 v[122:123], v[122:123], v[80:81]
	v_pk_add_f32 v[126:127], v[126:127], v[84:85]
	v_pk_add_f32 v[110:111], v[96:97], v[88:89] op_sel:[0,1] op_sel_hi:[1,0] neg_lo:[0,1] neg_hi:[0,0]
	v_pk_mul_f32 v[74:75], v[100:101], s[4:5] op_sel:[1,0] op_sel_hi:[1,1] neg_lo:[0,1] neg_hi:[0,1]
	v_pk_mul_f32 v[76:77], v[94:95], s[16:17] op_sel:[1,0] op_sel_hi:[1,0] neg_lo:[0,1] neg_hi:[0,1]
	v_pk_mul_f32 v[124:125], v[152:153], s[4:5] op_sel:[1,1] op_sel_hi:[1,0] neg_lo:[0,1] neg_hi:[0,1]
	v_pk_add_f32 v[96:97], v[96:97], v[88:89] op_sel:[0,1] op_sel_hi:[1,0] neg_lo:[0,0] neg_hi:[0,1]
	v_pk_fma_f32 v[74:75], v[100:101], s[4:5], v[74:75] op_sel:[0,1,0] op_sel_hi:[0,0,1] neg_lo:[0,1,0] neg_hi:[0,0,0]
	v_pk_fma_f32 v[76:77], v[94:95], s[16:17], v[76:77] op_sel:[0,0,0] op_sel_hi:[0,0,1] neg_lo:[0,1,0] neg_hi:[0,0,0]
	v_pk_fma_f32 v[124:125], v[152:153], s[4:5], v[124:125] op_sel:[0,0,0] op_sel_hi:[0,1,1] neg_lo:[0,1,0] neg_hi:[0,0,0]
	v_pk_add_f32 v[100:101], v[90:91], v[74:75] neg_lo:[0,1] neg_hi:[0,1]
	v_pk_add_f32 v[94:95], v[148:149], v[76:77] neg_lo:[0,1] neg_hi:[0,1]
	v_pk_add_f32 v[152:153], v[102:103], v[124:125] neg_lo:[0,1] neg_hi:[0,1]
	v_pk_add_f32 v[90:91], v[90:91], v[74:75]
	v_pk_add_f32 v[148:149], v[148:149], v[76:77]
	v_pk_add_f32 v[102:103], v[102:103], v[124:125]
	ds_write2_b64 v147, v[128:129], v[132:133] offset1:1
	ds_write2_b64 v147, v[122:123], v[126:127] offset0:2 offset1:3
	ds_write2_b64 v147, v[110:111], v[90:91] offset0:4 offset1:5
	ds_write2_b64 v147, v[148:149], v[102:103] offset0:6 offset1:7
	ds_write2_b64 v147, v[82:83], v[118:119] offset0:8 offset1:9
	ds_write2_b64 v147, v[104:105], v[92:93] offset0:10 offset1:11
	ds_write2_b64 v147, v[96:97], v[100:101] offset0:12 offset1:13
	ds_write2_b64 v147, v[94:95], v[152:153] offset0:14 offset1:15
	v_mov_b32_e32 v68, v195
	s_waitcnt lgkmcnt(0)
	s_mov_b32 s0, 0
	v_and_b32_e32 v73, 15, v68
	v_lshlrev_b32_e32 v72, 4, v68
	v_lshlrev_b32_e32 v75, 9, v73
	v_and_b32_e32 v72, 0xfffffc00, v72
	v_lshlrev_b32_e32 v74, 3, v68
	v_add_u32_e32 v75, 0, v75
	v_and_b32_e32 v69, 63, v68
	v_lshl_add_u32 v73, v73, 3, 0
	v_and_or_b32 v74, v74, s90, v72
; #define LAS __attribute__((address_space(3)))
; __device__ __forceinline__ cf twc(cf ws, int k16) { if (k16 == 0) return ws; if (k16 == 4) return cf{ws.y, -ws.x}; return cmul(ws, cf{c16(k16), -s16(k16)}); }
; template <int LR> __device__ __forceinline__ void dit_reg(cf (&x)[1 << LR], cf w) {
;     constexpr int R = 1 << LR; cf wsv[LR]; wsv[0] = w;
; #pragma unroll
;     for (int s = 1; s < LR; ++s) wsv[s] = cmul(wsv[s - 1], wsv[s - 1]);
; #pragma unroll
;     for (int s = LR - 1; s >= 0; --s) { const int half = R >> (s + 1);
; #pragma unroll
;         for (int m0 = 0; m0 < R; m0 += 2 * half)
; #pragma unroll
;             for (int mm = 0; mm < half; ++mm) { const int ia = m0 + mm, ib = ia + half; const cf a = x[ia];
;                 const cf b = cmulc(x[ib], twc(wsv[s], (mm << s) * (16 / R)));
;                 x[ia] = cf{a.x + b.x, a.y + b.y}; x[ib] = cf{a.x - b.x, a.y - b.y}; } }
; template <int LR, bool INV> __device__ __forceinline__ void fft_pass(ldsf2 buf, int base, int stride, int twi) {
;     constexpr int R = 1 << LR; cf x[R];
;     const v2f wv = ((ldsf2)((LAS unsigned char*)buf + 139264))[twi];
; #pragma unroll
;     for (int m = 0; m < R; ++m) { const v2f v = buf[base + m * stride]; x[m] = cf{v.x, v.y}; }
;     const cf w{wv.x, wv.y};
;     if (INV) dit_reg<LR>(x, w); else dif_reg<LR>(x, w);
; #pragma unroll
;     for (int m = 0; m < R; ++m) buf[base + m * stride] = mkv2(x[m].x, x[m].y);
; }
.LBB0_353:
	v_or_b32_e32 v76, s0, v74
	v_lshlrev_b32_e32 v77, 3, v76
	v_ashrrev_i32_e32 v76, 1, v76
	v_add3_u32 v122, v73, v77, v76
	ds_read2_b64 v[76:79], v122 offset1:17
	ds_read2_b64 v[80:83], v122 offset0:34 offset1:51
	ds_read2_b64 v[84:87], v122 offset0:68 offset1:85
	ds_read2_b64 v[88:91], v122 offset0:102 offset1:119
	s_movk_i32 s0, 0x200
	v_or_b32_e32 v126, s0, v74
	v_lshlrev_b32_e32 v128, 3, v126
	v_ashrrev_i32_e32 v126, 1, v126
	v_add3_u32 v130, v73, v128, v126
	ds_read2_b64 v[132:135], v130 offset1:17
	ds_read2_b64 v[148:151], v130 offset0:34 offset1:51
	ds_read2_b64 v[152:155], v130 offset0:68 offset1:85
	ds_read2_b64 v[156:159], v130 offset0:102 offset1:119
	s_waitcnt lgkmcnt(4)
	v_pk_mul_f32 v[104:105], v[78:79], v[208:209] op_sel:[1,1] op_sel_hi:[1,0]
	v_pk_mul_f32 v[106:107], v[82:83], v[208:209] op_sel:[1,1] op_sel_hi:[1,0]
	v_pk_mul_f32 v[108:109], v[86:87], v[208:209] op_sel:[1,1] op_sel_hi:[1,0]
	v_pk_mul_f32 v[110:111], v[90:91], v[208:209] op_sel:[1,1] op_sel_hi:[1,0]
	v_pk_fma_f32 v[104:105], v[78:79], v[208:209], v[104:105] op_sel:[0,0,0] op_sel_hi:[0,1,1] neg_lo:[0,0,0] neg_hi:[0,1,0]
	v_pk_fma_f32 v[106:107], v[82:83], v[208:209], v[106:107] op_sel:[0,0,0] op_sel_hi:[0,1,1] neg_lo:[0,0,0] neg_hi:[0,1,0]
	v_pk_fma_f32 v[108:109], v[86:87], v[208:209], v[108:109] op_sel:[0,0,0] op_sel_hi:[0,1,1] neg_lo:[0,0,0] neg_hi:[0,1,0]
	v_pk_fma_f32 v[110:111], v[90:91], v[208:209], v[110:111] op_sel:[0,0,0] op_sel_hi:[0,1,1] neg_lo:[0,0,0] neg_hi:[0,1,0]
	v_pk_add_f32 v[78:79], v[76:77], v[104:105] neg_lo:[0,1] neg_hi:[0,1]
	v_pk_add_f32 v[82:83], v[80:81], v[106:107] neg_lo:[0,1] neg_hi:[0,1]
	v_pk_add_f32 v[86:87], v[84:85], v[108:109] neg_lo:[0,1] neg_hi:[0,1]
	v_pk_add_f32 v[90:91], v[88:89], v[110:111] neg_lo:[0,1] neg_hi:[0,1]
	v_pk_add_f32 v[76:77], v[76:77], v[104:105]
	v_pk_add_f32 v[80:81], v[80:81], v[106:107]
	v_pk_add_f32 v[84:85], v[84:85], v[108:109]
	v_pk_add_f32 v[88:89], v[88:89], v[110:111]
	v_pk_mul_f32 v[104:105], v[80:81], v[206:207] op_sel:[1,1] op_sel_hi:[1,0]
	v_pk_mul_f32 v[106:107], v[82:83], v[206:207] op_sel:[1,0] op_sel_hi:[1,1]
	v_pk_mul_f32 v[108:109], v[88:89], v[206:207] op_sel:[1,1] op_sel_hi:[1,0]
	v_pk_mul_f32 v[110:111], v[90:91], v[206:207] op_sel:[1,0] op_sel_hi:[1,1]
	v_pk_fma_f32 v[104:105], v[80:81], v[206:207], v[104:105] op_sel:[0,0,0] op_sel_hi:[0,1,1] neg_lo:[0,0,0] neg_hi:[0,1,0]
	v_pk_fma_f32 v[106:107], v[82:83], v[206:207], v[106:107] op_sel:[0,1,0] op_sel_hi:[0,0,1] neg_lo:[0,0,1] neg_hi:[0,0,0]
	v_pk_fma_f32 v[108:109], v[88:89], v[206:207], v[108:109] op_sel:[0,0,0] op_sel_hi:[0,1,1] neg_lo:[0,0,0] neg_hi:[0,1,0]
	v_pk_fma_f32 v[110:111], v[90:91], v[206:207], v[110:111] op_sel:[0,1,0] op_sel_hi:[0,0,1] neg_lo:[0,0,1] neg_hi:[0,0,0]
	v_pk_add_f32 v[80:81], v[76:77], v[104:105] neg_lo:[0,1] neg_hi:[0,1]
	v_pk_add_f32 v[82:83], v[78:79], v[106:107] neg_lo:[0,1] neg_hi:[0,1]
	v_pk_add_f32 v[88:89], v[84:85], v[108:109] neg_lo:[0,1] neg_hi:[0,1]
	v_pk_add_f32 v[90:91], v[86:87], v[110:111] neg_lo:[0,1] neg_hi:[0,1]
	v_pk_add_f32 v[76:77], v[76:77], v[104:105]
	v_pk_add_f32 v[78:79], v[78:79], v[106:107]
	v_pk_add_f32 v[84:85], v[84:85], v[108:109]
	v_pk_add_f32 v[86:87], v[86:87], v[110:111]
	v_pk_mul_f32 v[104:105], v[84:85], v[204:205] op_sel:[1,1] op_sel_hi:[1,0]
	v_pk_mul_f32 v[106:107], v[86:87], v[210:211] op_sel:[1,1] op_sel_hi:[1,0]
	v_pk_mul_f32 v[108:109], v[88:89], v[204:205] op_sel:[1,0] op_sel_hi:[1,1]
	v_pk_mul_f32 v[110:111], v[90:91], v[212:213] op_sel:[1,1] op_sel_hi:[1,0]
	v_pk_fma_f32 v[104:105], v[84:85], v[204:205], v[104:105] op_sel:[0,0,0] op_sel_hi:[0,1,1] neg_lo:[0,0,0] neg_hi:[0,1,0]
	v_pk_fma_f32 v[106:107], v[86:87], v[210:211], v[106:107] op_sel:[0,0,0] op_sel_hi:[0,1,1] neg_lo:[0,0,0] neg_hi:[0,1,0]
	v_pk_fma_f32 v[108:109], v[88:89], v[204:205], v[108:109] op_sel:[0,1,0] op_sel_hi:[0,0,1] neg_lo:[0,0,1] neg_hi:[0,0,0]
	v_pk_fma_f32 v[110:111], v[90:91], v[212:213], v[110:111] op_sel:[0,0,0] op_sel_hi:[0,1,1] neg_lo:[0,0,0] neg_hi:[0,1,0]
	v_pk_add_f32 v[84:85], v[76:77], v[104:105] neg_lo:[0,1] neg_hi:[0,1]
	v_pk_add_f32 v[86:87], v[78:79], v[106:107] neg_lo:[0,1] neg_hi:[0,1]
	v_pk_add_f32 v[88:89], v[80:81], v[108:109] neg_lo:[0,1] neg_hi:[0,1]
	v_pk_add_f32 v[90:91], v[82:83], v[110:111] neg_lo:[0,1] neg_hi:[0,1]
	v_pk_add_f32 v[76:77], v[76:77], v[104:105]
	v_pk_add_f32 v[78:79], v[78:79], v[106:107]
	v_pk_add_f32 v[80:81], v[80:81], v[108:109]
	v_pk_add_f32 v[82:83], v[82:83], v[110:111]
	ds_write2_b64 v122, v[76:77], v[78:79] offset1:17
	ds_write2_b64 v122, v[80:81], v[82:83] offset0:34 offset1:51
	ds_write2_b64 v122, v[84:85], v[86:87] offset0:68 offset1:85
	ds_write2_b64 v122, v[88:89], v[90:91] offset0:102 offset1:119
	s_waitcnt lgkmcnt(4)
; #define LAS __attribute__((address_space(3)))
; __device__ __forceinline__ cf twc(cf ws, int k16) { if (k16 == 0) return ws; if (k16 == 4) return cf{ws.y, -ws.x}; return cmul(ws, cf{c16(k16), -s16(k16)}); }
; template <int LR> __device__ __forceinline__ void dit_reg(cf (&x)[1 << LR], cf w) {
;     constexpr int R = 1 << LR; cf wsv[LR]; wsv[0] = w;
; #pragma unroll
;     for (int s = 1; s < LR; ++s) wsv[s] = cmul(wsv[s - 1], wsv[s - 1]);
; #pragma unroll
;     for (int s = LR - 1; s >= 0; --s) { const int half = R >> (s + 1);
; #pragma unroll
;         for (int m0 = 0; m0 < R; m0 += 2 * half)
; #pragma unroll
;             for (int mm = 0; mm < half; ++mm) { const int ia = m0 + mm, ib = ia + half; const cf a = x[ia];
;                 const cf b = cmulc(x[ib], twc(wsv[s], (mm << s) * (16 / R)));
;                 x[ia] = cf{a.x + b.x, a.y + b.y}; x[ib] = cf{a.x - b.x, a.y - b.y}; } }
; template <int LR, bool INV> __device__ __forceinline__ void fft_pass(ldsf2 buf, int base, int stride, int twi) {
;     constexpr int R = 1 << LR; cf x[R];
;     const v2f wv = ((ldsf2)((LAS unsigned char*)buf + 139264))[twi];
; #pragma unroll
;     for (int m = 0; m < R; ++m) { const v2f v = buf[base + m * stride]; x[m] = cf{v.x, v.y}; }
;     const cf w{wv.x, wv.y};
;     if (INV) dit_reg<LR>(x, w); else dif_reg<LR>(x, w);
; #pragma unroll
;     for (int m = 0; m < R; ++m) buf[base + m * stride] = mkv2(x[m].x, x[m].y);
; }
	v_pk_mul_f32 v[170:171], v[134:135], v[208:209] op_sel:[1,1] op_sel_hi:[1,0]
	v_pk_mul_f32 v[172:173], v[150:151], v[208:209] op_sel:[1,1] op_sel_hi:[1,0]
	v_pk_mul_f32 v[174:175], v[154:155], v[208:209] op_sel:[1,1] op_sel_hi:[1,0]
	v_pk_mul_f32 v[188:189], v[158:159], v[208:209] op_sel:[1,1] op_sel_hi:[1,0]
	v_pk_fma_f32 v[170:171], v[134:135], v[208:209], v[170:171] op_sel:[0,0,0] op_sel_hi:[0,1,1] neg_lo:[0,0,0] neg_hi:[0,1,0]
	v_pk_fma_f32 v[172:173], v[150:151], v[208:209], v[172:173] op_sel:[0,0,0] op_sel_hi:[0,1,1] neg_lo:[0,0,0] neg_hi:[0,1,0]
	v_pk_fma_f32 v[174:175], v[154:155], v[208:209], v[174:175] op_sel:[0,0,0] op_sel_hi:[0,1,1] neg_lo:[0,0,0] neg_hi:[0,1,0]
	v_pk_fma_f32 v[188:189], v[158:159], v[208:209], v[188:189] op_sel:[0,0,0] op_sel_hi:[0,1,1] neg_lo:[0,0,0] neg_hi:[0,1,0]
	v_pk_add_f32 v[134:135], v[132:133], v[170:171] neg_lo:[0,1] neg_hi:[0,1]
	v_pk_add_f32 v[150:151], v[148:149], v[172:173] neg_lo:[0,1] neg_hi:[0,1]
	v_pk_add_f32 v[154:155], v[152:153], v[174:175] neg_lo:[0,1] neg_hi:[0,1]
	v_pk_add_f32 v[158:159], v[156:157], v[188:189] neg_lo:[0,1] neg_hi:[0,1]
	v_pk_add_f32 v[132:133], v[132:133], v[170:171]
	v_pk_add_f32 v[148:149], v[148:149], v[172:173]
	v_pk_add_f32 v[152:153], v[152:153], v[174:175]
	v_pk_add_f32 v[156:157], v[156:157], v[188:189]
	v_pk_mul_f32 v[170:171], v[148:149], v[206:207] op_sel:[1,1] op_sel_hi:[1,0]
	v_pk_mul_f32 v[172:173], v[150:151], v[206:207] op_sel:[1,0] op_sel_hi:[1,1]
	v_pk_mul_f32 v[174:175], v[156:157], v[206:207] op_sel:[1,1] op_sel_hi:[1,0]
	v_pk_mul_f32 v[188:189], v[158:159], v[206:207] op_sel:[1,0] op_sel_hi:[1,1]
	v_pk_fma_f32 v[170:171], v[148:149], v[206:207], v[170:171] op_sel:[0,0,0] op_sel_hi:[0,1,1] neg_lo:[0,0,0] neg_hi:[0,1,0]
	v_pk_fma_f32 v[172:173], v[150:151], v[206:207], v[172:173] op_sel:[0,1,0] op_sel_hi:[0,0,1] neg_lo:[0,0,1] neg_hi:[0,0,0]
	v_pk_fma_f32 v[174:175], v[156:157], v[206:207], v[174:175] op_sel:[0,0,0] op_sel_hi:[0,1,1] neg_lo:[0,0,0] neg_hi:[0,1,0]
	v_pk_fma_f32 v[188:189], v[158:159], v[206:207], v[188:189] op_sel:[0,1,0] op_sel_hi:[0,0,1] neg_lo:[0,0,1] neg_hi:[0,0,0]
	v_pk_add_f32 v[148:149], v[132:133], v[170:171] neg_lo:[0,1] neg_hi:[0,1]
	v_pk_add_f32 v[150:151], v[134:135], v[172:173] neg_lo:[0,1] neg_hi:[0,1]
	v_pk_add_f32 v[156:157], v[152:153], v[174:175] neg_lo:[0,1] neg_hi:[0,1]
	v_pk_add_f32 v[158:159], v[154:155], v[188:189] neg_lo:[0,1] neg_hi:[0,1]
	v_pk_add_f32 v[132:133], v[132:133], v[170:171]
	v_pk_add_f32 v[134:135], v[134:135], v[172:173]
	v_pk_add_f32 v[152:153], v[152:153], v[174:175]
	v_pk_add_f32 v[154:155], v[154:155], v[188:189]
	v_pk_mul_f32 v[170:171], v[152:153], v[204:205] op_sel:[1,1] op_sel_hi:[1,0]
	v_pk_mul_f32 v[172:173], v[154:155], v[210:211] op_sel:[1,1] op_sel_hi:[1,0]
	v_pk_mul_f32 v[174:175], v[156:157], v[204:205] op_sel:[1,0] op_sel_hi:[1,1]
	v_pk_mul_f32 v[188:189], v[158:159], v[212:213] op_sel:[1,1] op_sel_hi:[1,0]
	v_pk_fma_f32 v[170:171], v[152:153], v[204:205], v[170:171] op_sel:[0,0,0] op_sel_hi:[0,1,1] neg_lo:[0,0,0] neg_hi:[0,1,0]
	v_pk_fma_f32 v[172:173], v[154:155], v[210:211], v[172:173] op_sel:[0,0,0] op_sel_hi:[0,1,1] neg_lo:[0,0,0] neg_hi:[0,1,0]
	v_pk_fma_f32 v[174:175], v[156:157], v[204:205], v[174:175] op_sel:[0,1,0] op_sel_hi:[0,0,1] neg_lo:[0,0,1] neg_hi:[0,0,0]
	v_pk_fma_f32 v[188:189], v[158:159], v[212:213], v[188:189] op_sel:[0,0,0] op_sel_hi:[0,1,1] neg_lo:[0,0,0] neg_hi:[0,1,0]
	v_pk_add_f32 v[152:153], v[132:133], v[170:171] neg_lo:[0,1] neg_hi:[0,1]
	v_pk_add_f32 v[154:155], v[134:135], v[172:173] neg_lo:[0,1] neg_hi:[0,1]
	v_pk_add_f32 v[156:157], v[148:149], v[174:175] neg_lo:[0,1] neg_hi:[0,1]
	v_pk_add_f32 v[158:159], v[150:151], v[188:189] neg_lo:[0,1] neg_hi:[0,1]
	v_pk_add_f32 v[132:133], v[132:133], v[170:171]
	v_pk_add_f32 v[134:135], v[134:135], v[172:173]
	v_pk_add_f32 v[148:149], v[148:149], v[174:175]
	v_pk_add_f32 v[150:151], v[150:151], v[188:189]
	ds_write2_b64 v130, v[132:133], v[134:135] offset1:17
	ds_write2_b64 v130, v[148:149], v[150:151] offset0:34 offset1:51
	ds_write2_b64 v130, v[152:153], v[154:155] offset0:68 offset1:85
	ds_write2_b64 v130, v[156:157], v[158:159] offset0:102 offset1:119
	s_mov_b64 s[6:7], 0
	s_waitcnt lgkmcnt(0)
	s_mov_b32 s0, 0
	s_mov_b64 s[6:7], -1
; #define LAS __attribute__((address_space(3)))
; __device__ __forceinline__ cf twc(cf ws, int k16) { if (k16 == 0) return ws; if (k16 == 4) return cf{ws.y, -ws.x}; return cmul(ws, cf{c16(k16), -s16(k16)}); }
; template <int LR> __device__ __forceinline__ void dit_reg(cf (&x)[1 << LR], cf w) {
;     constexpr int R = 1 << LR; cf wsv[LR]; wsv[0] = w;
; #pragma unroll
;     for (int s = 1; s < LR; ++s) wsv[s] = cmul(wsv[s - 1], wsv[s - 1]);
; #pragma unroll
;     for (int s = LR - 1; s >= 0; --s) { const int half = R >> (s + 1);
; #pragma unroll
;         for (int m0 = 0; m0 < R; m0 += 2 * half)
; #pragma unroll
;             for (int mm = 0; mm < half; ++mm) { const int ia = m0 + mm, ib = ia + half; const cf a = x[ia];
;                 const cf b = cmulc(x[ib], twc(wsv[s], (mm << s) * (16 / R)));
;                 x[ia] = cf{a.x + b.x, a.y + b.y}; x[ib] = cf{a.x - b.x, a.y - b.y}; } }
; template <int LR, bool INV> __device__ __forceinline__ void fft_pass(ldsf2 buf, int base, int stride, int twi) {
;     constexpr int R = 1 << LR; cf x[R];
;     const v2f wv = ((ldsf2)((LAS unsigned char*)buf + 139264))[twi];
; #pragma unroll
;     for (int m = 0; m < R; ++m) { const v2f v = buf[base + m * stride]; x[m] = cf{v.x, v.y}; }
;     const cf w{wv.x, wv.y};
;     if (INV) dit_reg<LR>(x, w); else dif_reg<LR>(x, w);
; #pragma unroll
;     for (int m = 0; m < R; ++m) buf[base + m * stride] = mkv2(x[m].x, x[m].y);
; }
.LBB0_355:
	v_or_b32_e32 v73, s0, v69
	v_or_b32_e32 v74, v73, v72
	v_ashrrev_i32_e32 v75, 4, v74
	v_lshlrev_b32_e32 v73, 3, v74
	v_lshlrev_b32_e32 v74, 3, v75
	v_add3_u32 v73, 0, v73, v74
	v_add_u32_e32 v122, 0x1800, v73
	v_add_u32_e32 v121, 0x1000, v73
	ds_read2_b64 v[86:89], v122 offset0:48 offset1:184
	ds_read2_b64 v[82:85], v121 offset0:32 offset1:168
	v_add_u32_e32 v120, 0x800, v73
	ds_read2_b64 v[74:77], v73 offset1:136
	ds_read2_b64 v[78:81], v120 offset0:16 offset1:152
	s_mov_b32 s0, 64
	v_or_b32_e32 v124, s0, v69
	v_or_b32_e32 v126, v124, v72
	v_ashrrev_i32_e32 v130, 4, v126
	v_lshlrev_b32_e32 v124, 3, v126
	v_lshlrev_b32_e32 v126, 3, v130
	v_add3_u32 v124, 0, v124, v126
	v_add_u32_e32 v132, 0x1800, v124
	v_add_u32_e32 v134, 0x1000, v124
	ds_read2_b64 v[148:151], v132 offset0:48 offset1:184
	ds_read2_b64 v[152:155], v134 offset0:32 offset1:168
	v_add_u32_e32 v156, 0x800, v124
	ds_read2_b64 v[158:161], v124 offset1:136
	ds_read2_b64 v[162:165], v156 offset0:16 offset1:152
	s_waitcnt lgkmcnt(4)
	v_pk_add_f32 v[92:93], v[214:215], v[214:215] op_sel:[0,1] op_sel_hi:[1,0] neg_lo:[0,0] neg_hi:[0,1]
	s_nop 0
	v_pk_mul_f32 v[94:95], v[92:93], s[16:17] op_sel:[0,0] op_sel_hi:[1,0]
	v_pk_mul_f32 v[96:97], v[92:93], s[16:17] op_sel:[1,0] op_sel_hi:[0,0] neg_lo:[0,0] neg_hi:[1,0]
	v_pk_mul_f32 v[102:103], v[76:77], v[218:219] op_sel:[1,1] op_sel_hi:[1,0]
	v_pk_mul_f32 v[104:105], v[80:81], v[218:219] op_sel:[1,1] op_sel_hi:[1,0]
	v_pk_mul_f32 v[106:107], v[84:85], v[218:219] op_sel:[1,1] op_sel_hi:[1,0]
	v_pk_mul_f32 v[108:109], v[88:89], v[218:219] op_sel:[1,1] op_sel_hi:[1,0]
	v_pk_fma_f32 v[102:103], v[76:77], v[218:219], v[102:103] op_sel:[0,0,0] op_sel_hi:[0,1,1] neg_lo:[0,0,0] neg_hi:[0,1,0]
	v_pk_fma_f32 v[104:105], v[80:81], v[218:219], v[104:105] op_sel:[0,0,0] op_sel_hi:[0,1,1] neg_lo:[0,0,0] neg_hi:[0,1,0]
	v_pk_fma_f32 v[106:107], v[84:85], v[218:219], v[106:107] op_sel:[0,0,0] op_sel_hi:[0,1,1] neg_lo:[0,0,0] neg_hi:[0,1,0]
	v_pk_fma_f32 v[108:109], v[88:89], v[218:219], v[108:109] op_sel:[0,0,0] op_sel_hi:[0,1,1] neg_lo:[0,0,0] neg_hi:[0,1,0]
	v_pk_add_f32 v[76:77], v[74:75], v[102:103] neg_lo:[0,1] neg_hi:[0,1]
	v_pk_add_f32 v[80:81], v[78:79], v[104:105] neg_lo:[0,1] neg_hi:[0,1]
	v_pk_add_f32 v[84:85], v[82:83], v[106:107] neg_lo:[0,1] neg_hi:[0,1]
	v_pk_add_f32 v[88:89], v[86:87], v[108:109] neg_lo:[0,1] neg_hi:[0,1]
	v_pk_add_f32 v[74:75], v[74:75], v[102:103]
	v_pk_add_f32 v[78:79], v[78:79], v[104:105]
	v_pk_add_f32 v[82:83], v[82:83], v[106:107]
	v_pk_add_f32 v[86:87], v[86:87], v[108:109]
	v_pk_mul_f32 v[102:103], v[78:79], v[216:217] op_sel:[1,1] op_sel_hi:[1,0]
	v_pk_mul_f32 v[104:105], v[80:81], v[216:217] op_sel:[1,0] op_sel_hi:[1,1]
	v_pk_mul_f32 v[106:107], v[86:87], v[216:217] op_sel:[1,1] op_sel_hi:[1,0]
	v_pk_mul_f32 v[108:109], v[88:89], v[216:217] op_sel:[1,0] op_sel_hi:[1,1]
	v_pk_fma_f32 v[102:103], v[78:79], v[216:217], v[102:103] op_sel:[0,0,0] op_sel_hi:[0,1,1] neg_lo:[0,0,0] neg_hi:[0,1,0]
	v_pk_fma_f32 v[104:105], v[80:81], v[216:217], v[104:105] op_sel:[0,1,0] op_sel_hi:[0,0,1] neg_lo:[0,0,1] neg_hi:[0,0,0]
	v_pk_fma_f32 v[106:107], v[86:87], v[216:217], v[106:107] op_sel:[0,0,0] op_sel_hi:[0,1,1] neg_lo:[0,0,0] neg_hi:[0,1,0]
	v_pk_fma_f32 v[108:109], v[88:89], v[216:217], v[108:109] op_sel:[0,1,0] op_sel_hi:[0,0,1] neg_lo:[0,0,1] neg_hi:[0,0,0]
	v_pk_add_f32 v[78:79], v[74:75], v[102:103] neg_lo:[0,1] neg_hi:[0,1]
	v_pk_add_f32 v[80:81], v[76:77], v[104:105] neg_lo:[0,1] neg_hi:[0,1]
	v_pk_add_f32 v[86:87], v[82:83], v[106:107] neg_lo:[0,1] neg_hi:[0,1]
	v_pk_add_f32 v[88:89], v[84:85], v[108:109] neg_lo:[0,1] neg_hi:[0,1]
	v_pk_add_f32 v[74:75], v[74:75], v[102:103]
	v_pk_add_f32 v[76:77], v[76:77], v[104:105]
	v_pk_add_f32 v[82:83], v[82:83], v[106:107]
	v_pk_add_f32 v[84:85], v[84:85], v[108:109]
	v_pk_mul_f32 v[102:103], v[82:83], v[214:215] op_sel:[1,1] op_sel_hi:[1,0]
	v_pk_mul_f32 v[104:105], v[84:85], v[94:95] op_sel:[1,1] op_sel_hi:[1,0]
	v_pk_mul_f32 v[106:107], v[86:87], v[214:215] op_sel:[1,0] op_sel_hi:[1,1]
	v_pk_mul_f32 v[108:109], v[88:89], v[96:97] op_sel:[1,1] op_sel_hi:[1,0]
	v_pk_fma_f32 v[102:103], v[82:83], v[214:215], v[102:103] op_sel:[0,0,0] op_sel_hi:[0,1,1] neg_lo:[0,0,0] neg_hi:[0,1,0]
	v_pk_fma_f32 v[104:105], v[84:85], v[94:95], v[104:105] op_sel:[0,0,0] op_sel_hi:[0,1,1] neg_lo:[0,0,0] neg_hi:[0,1,0]
	v_pk_fma_f32 v[106:107], v[86:87], v[214:215], v[106:107] op_sel:[0,1,0] op_sel_hi:[0,0,1] neg_lo:[0,0,1] neg_hi:[0,0,0]
	v_pk_fma_f32 v[108:109], v[88:89], v[96:97], v[108:109] op_sel:[0,0,0] op_sel_hi:[0,1,1] neg_lo:[0,0,0] neg_hi:[0,1,0]
	v_pk_add_f32 v[82:83], v[74:75], v[102:103] neg_lo:[0,1] neg_hi:[0,1]
	v_pk_add_f32 v[84:85], v[76:77], v[104:105] neg_lo:[0,1] neg_hi:[0,1]
	v_pk_add_f32 v[86:87], v[78:79], v[106:107] neg_lo:[0,1] neg_hi:[0,1]
	v_pk_add_f32 v[88:89], v[80:81], v[108:109] neg_lo:[0,1] neg_hi:[0,1]
	v_pk_add_f32 v[74:75], v[74:75], v[102:103]
	v_pk_add_f32 v[76:77], v[76:77], v[104:105]
	v_pk_add_f32 v[78:79], v[78:79], v[106:107]
	v_pk_add_f32 v[80:81], v[80:81], v[108:109]
	ds_write2_b64 v73, v[74:75], v[76:77] offset1:136
	ds_write2_b64 v120, v[78:79], v[80:81] offset0:16 offset1:152
	ds_write2_b64 v121, v[82:83], v[84:85] offset0:32 offset1:168
	ds_write2_b64 v122, v[86:87], v[88:89] offset0:48 offset1:184
	s_waitcnt lgkmcnt(4)
; #define LAS __attribute__((address_space(3)))
; __device__ __forceinline__ cf twc(cf ws, int k16) { if (k16 == 0) return ws; if (k16 == 4) return cf{ws.y, -ws.x}; return cmul(ws, cf{c16(k16), -s16(k16)}); }
; __device__ __forceinline__ void lds_barrier() { asm volatile("s_waitcnt lgkmcnt(0)\n\ts_barrier" ::: "memory"); }
; template <int LR> __device__ __forceinline__ void dit_reg(cf (&x)[1 << LR], cf w) {
;     constexpr int R = 1 << LR; cf wsv[LR]; wsv[0] = w;
; #pragma unroll
;     for (int s = 1; s < LR; ++s) wsv[s] = cmul(wsv[s - 1], wsv[s - 1]);
; #pragma unroll
;     for (int s = LR - 1; s >= 0; --s) { const int half = R >> (s + 1);
; #pragma unroll
;         for (int m0 = 0; m0 < R; m0 += 2 * half)
; #pragma unroll
;             for (int mm = 0; mm < half; ++mm) { const int ia = m0 + mm, ib = ia + half; const cf a = x[ia];
;                 const cf b = cmulc(x[ib], twc(wsv[s], (mm << s) * (16 / R)));
;                 x[ia] = cf{a.x + b.x, a.y + b.y}; x[ib] = cf{a.x - b.x, a.y - b.y}; } }
; template <int LR, bool INV> __device__ __forceinline__ void fft_pass(ldsf2 buf, int base, int stride, int twi) {
;     constexpr int R = 1 << LR; cf x[R];
;     const v2f wv = ((ldsf2)((LAS unsigned char*)buf + 139264))[twi];
; #pragma unroll
;     for (int m = 0; m < R; ++m) { const v2f v = buf[base + m * stride]; x[m] = cf{v.x, v.y}; }
;     const cf w{wv.x, wv.y};
;     if (INV) dit_reg<LR>(x, w); else dif_reg<LR>(x, w);
; #pragma unroll
;     for (int m = 0; m < R; ++m) buf[base + m * stride] = mkv2(x[m].x, x[m].y);
; }
; __device__ __forceinline__ void fft_inv_cba(ldsf2 buf) {
;     ...
;     lds_barrier();
	v_pk_add_f32 v[166:167], v[220:221], v[220:221] op_sel:[0,1] op_sel_hi:[1,0] neg_lo:[0,0] neg_hi:[0,1]
	s_nop 0
	v_pk_mul_f32 v[168:169], v[166:167], s[16:17] op_sel:[0,0] op_sel_hi:[1,0]
	v_pk_mul_f32 v[170:171], v[166:167], s[16:17] op_sel:[1,0] op_sel_hi:[0,0] neg_lo:[0,0] neg_hi:[1,0]
	v_pk_mul_f32 v[188:189], v[160:161], v[224:225] op_sel:[1,1] op_sel_hi:[1,0]
	v_pk_mul_f32 v[190:191], v[164:165], v[224:225] op_sel:[1,1] op_sel_hi:[1,0]
	v_pk_mul_f32 v[196:197], v[154:155], v[224:225] op_sel:[1,1] op_sel_hi:[1,0]
	v_pk_mul_f32 v[198:199], v[150:151], v[224:225] op_sel:[1,1] op_sel_hi:[1,0]
	v_pk_fma_f32 v[188:189], v[160:161], v[224:225], v[188:189] op_sel:[0,0,0] op_sel_hi:[0,1,1] neg_lo:[0,0,0] neg_hi:[0,1,0]
	v_pk_fma_f32 v[190:191], v[164:165], v[224:225], v[190:191] op_sel:[0,0,0] op_sel_hi:[0,1,1] neg_lo:[0,0,0] neg_hi:[0,1,0]
	v_pk_fma_f32 v[196:197], v[154:155], v[224:225], v[196:197] op_sel:[0,0,0] op_sel_hi:[0,1,1] neg_lo:[0,0,0] neg_hi:[0,1,0]
	v_pk_fma_f32 v[198:199], v[150:151], v[224:225], v[198:199] op_sel:[0,0,0] op_sel_hi:[0,1,1] neg_lo:[0,0,0] neg_hi:[0,1,0]
	v_pk_add_f32 v[160:161], v[158:159], v[188:189] neg_lo:[0,1] neg_hi:[0,1]
	v_pk_add_f32 v[164:165], v[162:163], v[190:191] neg_lo:[0,1] neg_hi:[0,1]
	v_pk_add_f32 v[154:155], v[152:153], v[196:197] neg_lo:[0,1] neg_hi:[0,1]
	v_pk_add_f32 v[150:151], v[148:149], v[198:199] neg_lo:[0,1] neg_hi:[0,1]
	v_pk_add_f32 v[158:159], v[158:159], v[188:189]
	v_pk_add_f32 v[162:163], v[162:163], v[190:191]
	v_pk_add_f32 v[152:153], v[152:153], v[196:197]
	v_pk_add_f32 v[148:149], v[148:149], v[198:199]
	v_pk_mul_f32 v[188:189], v[162:163], v[222:223] op_sel:[1,1] op_sel_hi:[1,0]
	v_pk_mul_f32 v[190:191], v[164:165], v[222:223] op_sel:[1,0] op_sel_hi:[1,1]
	v_pk_mul_f32 v[196:197], v[148:149], v[222:223] op_sel:[1,1] op_sel_hi:[1,0]
	v_pk_mul_f32 v[198:199], v[150:151], v[222:223] op_sel:[1,0] op_sel_hi:[1,1]
	v_pk_fma_f32 v[188:189], v[162:163], v[222:223], v[188:189] op_sel:[0,0,0] op_sel_hi:[0,1,1] neg_lo:[0,0,0] neg_hi:[0,1,0]
	v_pk_fma_f32 v[190:191], v[164:165], v[222:223], v[190:191] op_sel:[0,1,0] op_sel_hi:[0,0,1] neg_lo:[0,0,1] neg_hi:[0,0,0]
	v_pk_fma_f32 v[196:197], v[148:149], v[222:223], v[196:197] op_sel:[0,0,0] op_sel_hi:[0,1,1] neg_lo:[0,0,0] neg_hi:[0,1,0]
	v_pk_fma_f32 v[198:199], v[150:151], v[222:223], v[198:199] op_sel:[0,1,0] op_sel_hi:[0,0,1] neg_lo:[0,0,1] neg_hi:[0,0,0]
	v_pk_add_f32 v[162:163], v[158:159], v[188:189] neg_lo:[0,1] neg_hi:[0,1]
	v_pk_add_f32 v[164:165], v[160:161], v[190:191] neg_lo:[0,1] neg_hi:[0,1]
	v_pk_add_f32 v[148:149], v[152:153], v[196:197] neg_lo:[0,1] neg_hi:[0,1]
	v_pk_add_f32 v[150:151], v[154:155], v[198:199] neg_lo:[0,1] neg_hi:[0,1]
	v_pk_add_f32 v[158:159], v[158:159], v[188:189]
	v_pk_add_f32 v[160:161], v[160:161], v[190:191]
	v_pk_add_f32 v[152:153], v[152:153], v[196:197]
	v_pk_add_f32 v[154:155], v[154:155], v[198:199]
	v_pk_mul_f32 v[188:189], v[152:153], v[220:221] op_sel:[1,1] op_sel_hi:[1,0]
	v_pk_mul_f32 v[190:191], v[154:155], v[168:169] op_sel:[1,1] op_sel_hi:[1,0]
	v_pk_mul_f32 v[196:197], v[148:149], v[220:221] op_sel:[1,0] op_sel_hi:[1,1]
	v_pk_mul_f32 v[198:199], v[150:151], v[170:171] op_sel:[1,1] op_sel_hi:[1,0]
	v_pk_fma_f32 v[188:189], v[152:153], v[220:221], v[188:189] op_sel:[0,0,0] op_sel_hi:[0,1,1] neg_lo:[0,0,0] neg_hi:[0,1,0]
	v_pk_fma_f32 v[190:191], v[154:155], v[168:169], v[190:191] op_sel:[0,0,0] op_sel_hi:[0,1,1] neg_lo:[0,0,0] neg_hi:[0,1,0]
	v_pk_fma_f32 v[196:197], v[148:149], v[220:221], v[196:197] op_sel:[0,1,0] op_sel_hi:[0,0,1] neg_lo:[0,0,1] neg_hi:[0,0,0]
	v_pk_fma_f32 v[198:199], v[150:151], v[170:171], v[198:199] op_sel:[0,0,0] op_sel_hi:[0,1,1] neg_lo:[0,0,0] neg_hi:[0,1,0]
	v_pk_add_f32 v[152:153], v[158:159], v[188:189] neg_lo:[0,1] neg_hi:[0,1]
	v_pk_add_f32 v[154:155], v[160:161], v[190:191] neg_lo:[0,1] neg_hi:[0,1]
	v_pk_add_f32 v[148:149], v[162:163], v[196:197] neg_lo:[0,1] neg_hi:[0,1]
	v_pk_add_f32 v[150:151], v[164:165], v[198:199] neg_lo:[0,1] neg_hi:[0,1]
	v_pk_add_f32 v[158:159], v[158:159], v[188:189]
	v_pk_add_f32 v[160:161], v[160:161], v[190:191]
	v_pk_add_f32 v[162:163], v[162:163], v[196:197]
	v_pk_add_f32 v[164:165], v[164:165], v[198:199]
	ds_write2_b64 v124, v[158:159], v[160:161] offset1:136
	ds_write2_b64 v156, v[162:163], v[164:165] offset0:16 offset1:152
	ds_write2_b64 v134, v[152:153], v[154:155] offset0:32 offset1:168
	ds_write2_b64 v132, v[148:149], v[150:151] offset0:48 offset1:184
	s_mov_b64 s[6:7], 0
	s_waitcnt lgkmcnt(0)
	s_barrier
	s_mov_b32 s0, 0
	s_mov_b64 s[6:7], -1
; #define LAS __attribute__((address_space(3)))
; __device__ __forceinline__ cf twc(cf ws, int k16) { if (k16 == 0) return ws; if (k16 == 4) return cf{ws.y, -ws.x}; return cmul(ws, cf{c16(k16), -s16(k16)}); }
; template <int LR> __device__ __forceinline__ void dit_reg(cf (&x)[1 << LR], cf w) {
;     constexpr int R = 1 << LR; cf wsv[LR]; wsv[0] = w;
; #pragma unroll
;     for (int s = 1; s < LR; ++s) wsv[s] = cmul(wsv[s - 1], wsv[s - 1]);
; #pragma unroll
;     for (int s = LR - 1; s >= 0; --s) { const int half = R >> (s + 1);
; #pragma unroll
;         for (int m0 = 0; m0 < R; m0 += 2 * half)
; #pragma unroll
;             for (int mm = 0; mm < half; ++mm) { const int ia = m0 + mm, ib = ia + half; const cf a = x[ia];
;                 const cf b = cmulc(x[ib], twc(wsv[s], (mm << s) * (16 / R)));
;                 x[ia] = cf{a.x + b.x, a.y + b.y}; x[ib] = cf{a.x - b.x, a.y - b.y}; } }
; template <int LR, bool INV> __device__ __forceinline__ void fft_pass(ldsf2 buf, int base, int stride, int twi) {
;     constexpr int R = 1 << LR; cf x[R];
;     const v2f wv = ((ldsf2)((LAS unsigned char*)buf + 139264))[twi];
; #pragma unroll
;     for (int m = 0; m < R; ++m) { const v2f v = buf[base + m * stride]; x[m] = cf{v.x, v.y}; }
;     const cf w{wv.x, wv.y};
;     if (INV) dit_reg<LR>(x, w); else dif_reg<LR>(x, w);
; #pragma unroll
;     for (int m = 0; m < R; ++m) buf[base + m * stride] = mkv2(x[m].x, x[m].y);
; }
.LBB0_357:
	v_add_u32_e32 v69, s0, v68
	v_ashrrev_i32_e32 v72, 4, v69
	v_lshl_add_u32 v69, v69, 3, 0
	v_lshl_add_u32 v69, v72, 3, v69
	ds_read2st64_b64 v[72:75], v69 offset1:17
	ds_read2st64_b64 v[76:79], v69 offset0:34 offset1:51
	ds_read2st64_b64 v[80:83], v69 offset0:68 offset1:85
	ds_read2st64_b64 v[84:87], v69 offset0:102 offset1:119
	s_movk_i32 s0, 0x200
	v_add_u32_e32 v118, s0, v68
	v_ashrrev_i32_e32 v120, 4, v118
	v_lshl_add_u32 v118, v118, 3, 0
	v_lshl_add_u32 v118, v120, 3, v118
	ds_read2st64_b64 v[126:129], v118 offset1:17
	ds_read2st64_b64 v[130:133], v118 offset0:34 offset1:51
	ds_read2st64_b64 v[148:151], v118 offset0:68 offset1:85
	ds_read2st64_b64 v[152:155], v118 offset0:102 offset1:119
	s_waitcnt lgkmcnt(4)
	v_pk_add_f32 v[90:91], v[232:233], v[232:233] op_sel:[0,1] op_sel_hi:[1,0] neg_lo:[0,0] neg_hi:[0,1]
	s_nop 0
	v_pk_mul_f32 v[92:93], v[90:91], s[16:17] op_sel:[0,0] op_sel_hi:[1,0]
	v_pk_mul_f32 v[94:95], v[90:91], s[16:17] op_sel:[1,0] op_sel_hi:[0,0] neg_lo:[0,0] neg_hi:[1,0]
	v_pk_mul_f32 v[100:101], v[74:75], v[236:237] op_sel:[1,1] op_sel_hi:[1,0]
	v_pk_mul_f32 v[102:103], v[78:79], v[236:237] op_sel:[1,1] op_sel_hi:[1,0]
	v_pk_mul_f32 v[104:105], v[82:83], v[236:237] op_sel:[1,1] op_sel_hi:[1,0]
	v_pk_mul_f32 v[106:107], v[86:87], v[236:237] op_sel:[1,1] op_sel_hi:[1,0]
	v_pk_fma_f32 v[100:101], v[74:75], v[236:237], v[100:101] op_sel:[0,0,0] op_sel_hi:[0,1,1] neg_lo:[0,0,0] neg_hi:[0,1,0]
	v_pk_fma_f32 v[102:103], v[78:79], v[236:237], v[102:103] op_sel:[0,0,0] op_sel_hi:[0,1,1] neg_lo:[0,0,0] neg_hi:[0,1,0]
	v_pk_fma_f32 v[104:105], v[82:83], v[236:237], v[104:105] op_sel:[0,0,0] op_sel_hi:[0,1,1] neg_lo:[0,0,0] neg_hi:[0,1,0]
	v_pk_fma_f32 v[106:107], v[86:87], v[236:237], v[106:107] op_sel:[0,0,0] op_sel_hi:[0,1,1] neg_lo:[0,0,0] neg_hi:[0,1,0]
	v_pk_add_f32 v[74:75], v[72:73], v[100:101] neg_lo:[0,1] neg_hi:[0,1]
	v_pk_add_f32 v[78:79], v[76:77], v[102:103] neg_lo:[0,1] neg_hi:[0,1]
	v_pk_add_f32 v[82:83], v[80:81], v[104:105] neg_lo:[0,1] neg_hi:[0,1]
	v_pk_add_f32 v[86:87], v[84:85], v[106:107] neg_lo:[0,1] neg_hi:[0,1]
	v_pk_add_f32 v[72:73], v[72:73], v[100:101]
	v_pk_add_f32 v[76:77], v[76:77], v[102:103]
	v_pk_add_f32 v[80:81], v[80:81], v[104:105]
	v_pk_add_f32 v[84:85], v[84:85], v[106:107]
	v_pk_mul_f32 v[100:101], v[76:77], v[234:235] op_sel:[1,1] op_sel_hi:[1,0]
	v_pk_mul_f32 v[102:103], v[78:79], v[234:235] op_sel:[1,0] op_sel_hi:[1,1]
	v_pk_mul_f32 v[104:105], v[84:85], v[234:235] op_sel:[1,1] op_sel_hi:[1,0]
	v_pk_mul_f32 v[106:107], v[86:87], v[234:235] op_sel:[1,0] op_sel_hi:[1,1]
	v_pk_fma_f32 v[100:101], v[76:77], v[234:235], v[100:101] op_sel:[0,0,0] op_sel_hi:[0,1,1] neg_lo:[0,0,0] neg_hi:[0,1,0]
	v_pk_fma_f32 v[102:103], v[78:79], v[234:235], v[102:103] op_sel:[0,1,0] op_sel_hi:[0,0,1] neg_lo:[0,0,1] neg_hi:[0,0,0]
	v_pk_fma_f32 v[104:105], v[84:85], v[234:235], v[104:105] op_sel:[0,0,0] op_sel_hi:[0,1,1] neg_lo:[0,0,0] neg_hi:[0,1,0]
	v_pk_fma_f32 v[106:107], v[86:87], v[234:235], v[106:107] op_sel:[0,1,0] op_sel_hi:[0,0,1] neg_lo:[0,0,1] neg_hi:[0,0,0]
	v_pk_add_f32 v[76:77], v[72:73], v[100:101] neg_lo:[0,1] neg_hi:[0,1]
	v_pk_add_f32 v[78:79], v[74:75], v[102:103] neg_lo:[0,1] neg_hi:[0,1]
	v_pk_add_f32 v[84:85], v[80:81], v[104:105] neg_lo:[0,1] neg_hi:[0,1]
	v_pk_add_f32 v[86:87], v[82:83], v[106:107] neg_lo:[0,1] neg_hi:[0,1]
	v_pk_add_f32 v[72:73], v[72:73], v[100:101]
	v_pk_add_f32 v[74:75], v[74:75], v[102:103]
	v_pk_add_f32 v[80:81], v[80:81], v[104:105]
	v_pk_add_f32 v[82:83], v[82:83], v[106:107]
	v_pk_mul_f32 v[100:101], v[80:81], v[232:233] op_sel:[1,1] op_sel_hi:[1,0]
	v_pk_mul_f32 v[102:103], v[82:83], v[92:93] op_sel:[1,1] op_sel_hi:[1,0]
	v_pk_mul_f32 v[104:105], v[84:85], v[232:233] op_sel:[1,0] op_sel_hi:[1,1]
	v_pk_mul_f32 v[106:107], v[86:87], v[94:95] op_sel:[1,1] op_sel_hi:[1,0]
	v_pk_fma_f32 v[100:101], v[80:81], v[232:233], v[100:101] op_sel:[0,0,0] op_sel_hi:[0,1,1] neg_lo:[0,0,0] neg_hi:[0,1,0]
	v_pk_fma_f32 v[102:103], v[82:83], v[92:93], v[102:103] op_sel:[0,0,0] op_sel_hi:[0,1,1] neg_lo:[0,0,0] neg_hi:[0,1,0]
	v_pk_fma_f32 v[104:105], v[84:85], v[232:233], v[104:105] op_sel:[0,1,0] op_sel_hi:[0,0,1] neg_lo:[0,0,1] neg_hi:[0,0,0]
	v_pk_fma_f32 v[106:107], v[86:87], v[94:95], v[106:107] op_sel:[0,0,0] op_sel_hi:[0,1,1] neg_lo:[0,0,0] neg_hi:[0,1,0]
	v_pk_add_f32 v[80:81], v[72:73], v[100:101] neg_lo:[0,1] neg_hi:[0,1]
	v_pk_add_f32 v[82:83], v[74:75], v[102:103] neg_lo:[0,1] neg_hi:[0,1]
	v_pk_add_f32 v[84:85], v[76:77], v[104:105] neg_lo:[0,1] neg_hi:[0,1]
	v_pk_add_f32 v[86:87], v[78:79], v[106:107] neg_lo:[0,1] neg_hi:[0,1]
	v_pk_add_f32 v[72:73], v[72:73], v[100:101]
	v_pk_add_f32 v[74:75], v[74:75], v[102:103]
	v_pk_add_f32 v[76:77], v[76:77], v[104:105]
	v_pk_add_f32 v[78:79], v[78:79], v[106:107]
	ds_write2st64_b64 v69, v[72:73], v[74:75] offset1:17
	ds_write2st64_b64 v69, v[76:77], v[78:79] offset0:34 offset1:51
	ds_write2st64_b64 v69, v[80:81], v[82:83] offset0:68 offset1:85
	ds_write2st64_b64 v69, v[84:85], v[86:87] offset0:102 offset1:119
	s_waitcnt lgkmcnt(4)
; __device__ __forceinline__ float bf2f(bf16_t b) { return __uint_as_float(((unsigned)b) << 16); }
; __device__ __forceinline__ cf twc(cf ws, int k16) { if (k16 == 0) return ws; if (k16 == 4) return cf{ws.y, -ws.x}; return cmul(ws, cf{c16(k16), -s16(k16)}); }
; template <int LR> __device__ __forceinline__ void dit_reg(cf (&x)[1 << LR], cf w) {
;     constexpr int R = 1 << LR; cf wsv[LR]; wsv[0] = w;
; #pragma unroll
;     for (int s = 1; s < LR; ++s) wsv[s] = cmul(wsv[s - 1], wsv[s - 1]);
; #pragma unroll
;     for (int s = LR - 1; s >= 0; --s) { const int half = R >> (s + 1);
; #pragma unroll
;         for (int m0 = 0; m0 < R; m0 += 2 * half)
; #pragma unroll
;             for (int mm = 0; mm < half; ++mm) { const int ia = m0 + mm, ib = ia + half; const cf a = x[ia];
;                 const cf b = cmulc(x[ib], twc(wsv[s], (mm << s) * (16 / R)));
;                 x[ia] = cf{a.x + b.x, a.y + b.y}; x[ib] = cf{a.x - b.x, a.y - b.y}; } }
; __device__ __forceinline__ void sconv8(const Raw8& r, int n0, float w0, float w1, float w2, float b, float (&out)[8]) {
;     float a[10]; a[0] = n0 > 0 ? bf2f(r.eL) : 0.f; a[9] = n0 + 8 < SEQ ? bf2f(r.eR) : 0.f;
;     a[1] = __uint_as_float(r.body.x << 16); a[2] = __uint_as_float(r.body.x & 0xffff0000u); a[3] = __uint_as_float(r.body.y << 16); a[4] = __uint_as_float(r.body.y & 0xffff0000u);
;     a[5] = __uint_as_float(r.body.z << 16); a[6] = __uint_as_float(r.body.z & 0xffff0000u); a[7] = __uint_as_float(r.body.w << 16); a[8] = __uint_as_float(r.body.w & 0xffff0000u);
; #pragma unroll
;     for (int k = 0; k < 8; ++k) out[k] = w0 * a[k] + w1 * a[k + 1] + w2 * a[k + 2] + b;
; }
	v_pk_add_f32 v[134:135], v[240:241], v[240:241] op_sel:[0,1] op_sel_hi:[1,0] neg_lo:[0,0] neg_hi:[0,1]
	s_nop 0
	v_pk_mul_f32 v[156:157], v[134:135], s[16:17] op_sel:[0,0] op_sel_hi:[1,0]
	v_pk_mul_f32 v[158:159], v[134:135], s[16:17] op_sel:[1,0] op_sel_hi:[0,0] neg_lo:[0,0] neg_hi:[1,0]
	v_pk_mul_f32 v[164:165], v[128:129], v[244:245] op_sel:[1,1] op_sel_hi:[1,0]
	v_pk_mul_f32 v[166:167], v[132:133], v[244:245] op_sel:[1,1] op_sel_hi:[1,0]
	v_pk_mul_f32 v[168:169], v[150:151], v[244:245] op_sel:[1,1] op_sel_hi:[1,0]
	v_pk_mul_f32 v[170:171], v[154:155], v[244:245] op_sel:[1,1] op_sel_hi:[1,0]
	v_pk_fma_f32 v[164:165], v[128:129], v[244:245], v[164:165] op_sel:[0,0,0] op_sel_hi:[0,1,1] neg_lo:[0,0,0] neg_hi:[0,1,0]
	v_pk_fma_f32 v[166:167], v[132:133], v[244:245], v[166:167] op_sel:[0,0,0] op_sel_hi:[0,1,1] neg_lo:[0,0,0] neg_hi:[0,1,0]
	v_pk_fma_f32 v[168:169], v[150:151], v[244:245], v[168:169] op_sel:[0,0,0] op_sel_hi:[0,1,1] neg_lo:[0,0,0] neg_hi:[0,1,0]
	v_pk_fma_f32 v[170:171], v[154:155], v[244:245], v[170:171] op_sel:[0,0,0] op_sel_hi:[0,1,1] neg_lo:[0,0,0] neg_hi:[0,1,0]
	v_pk_add_f32 v[128:129], v[126:127], v[164:165] neg_lo:[0,1] neg_hi:[0,1]
	v_pk_add_f32 v[132:133], v[130:131], v[166:167] neg_lo:[0,1] neg_hi:[0,1]
	v_pk_add_f32 v[150:151], v[148:149], v[168:169] neg_lo:[0,1] neg_hi:[0,1]
	v_pk_add_f32 v[154:155], v[152:153], v[170:171] neg_lo:[0,1] neg_hi:[0,1]
	v_pk_add_f32 v[126:127], v[126:127], v[164:165]
	v_pk_add_f32 v[130:131], v[130:131], v[166:167]
	v_pk_add_f32 v[148:149], v[148:149], v[168:169]
	v_pk_add_f32 v[152:153], v[152:153], v[170:171]
	v_pk_mul_f32 v[164:165], v[130:131], v[242:243] op_sel:[1,1] op_sel_hi:[1,0]
	v_pk_mul_f32 v[166:167], v[132:133], v[242:243] op_sel:[1,0] op_sel_hi:[1,1]
	v_pk_mul_f32 v[168:169], v[152:153], v[242:243] op_sel:[1,1] op_sel_hi:[1,0]
	v_pk_mul_f32 v[170:171], v[154:155], v[242:243] op_sel:[1,0] op_sel_hi:[1,1]
	v_pk_fma_f32 v[164:165], v[130:131], v[242:243], v[164:165] op_sel:[0,0,0] op_sel_hi:[0,1,1] neg_lo:[0,0,0] neg_hi:[0,1,0]
	v_pk_fma_f32 v[166:167], v[132:133], v[242:243], v[166:167] op_sel:[0,1,0] op_sel_hi:[0,0,1] neg_lo:[0,0,1] neg_hi:[0,0,0]
	v_pk_fma_f32 v[168:169], v[152:153], v[242:243], v[168:169] op_sel:[0,0,0] op_sel_hi:[0,1,1] neg_lo:[0,0,0] neg_hi:[0,1,0]
	v_pk_fma_f32 v[170:171], v[154:155], v[242:243], v[170:171] op_sel:[0,1,0] op_sel_hi:[0,0,1] neg_lo:[0,0,1] neg_hi:[0,0,0]
	v_pk_add_f32 v[130:131], v[126:127], v[164:165] neg_lo:[0,1] neg_hi:[0,1]
	v_pk_add_f32 v[132:133], v[128:129], v[166:167] neg_lo:[0,1] neg_hi:[0,1]
	v_pk_add_f32 v[152:153], v[148:149], v[168:169] neg_lo:[0,1] neg_hi:[0,1]
	v_pk_add_f32 v[154:155], v[150:151], v[170:171] neg_lo:[0,1] neg_hi:[0,1]
	v_pk_add_f32 v[126:127], v[126:127], v[164:165]
	v_pk_add_f32 v[128:129], v[128:129], v[166:167]
	v_pk_add_f32 v[148:149], v[148:149], v[168:169]
	v_pk_add_f32 v[150:151], v[150:151], v[170:171]
	v_pk_mul_f32 v[164:165], v[148:149], v[240:241] op_sel:[1,1] op_sel_hi:[1,0]
	v_pk_mul_f32 v[166:167], v[150:151], v[156:157] op_sel:[1,1] op_sel_hi:[1,0]
	v_pk_mul_f32 v[168:169], v[152:153], v[240:241] op_sel:[1,0] op_sel_hi:[1,1]
	v_pk_mul_f32 v[170:171], v[154:155], v[158:159] op_sel:[1,1] op_sel_hi:[1,0]
	v_pk_fma_f32 v[164:165], v[148:149], v[240:241], v[164:165] op_sel:[0,0,0] op_sel_hi:[0,1,1] neg_lo:[0,0,0] neg_hi:[0,1,0]
	v_pk_fma_f32 v[166:167], v[150:151], v[156:157], v[166:167] op_sel:[0,0,0] op_sel_hi:[0,1,1] neg_lo:[0,0,0] neg_hi:[0,1,0]
	v_pk_fma_f32 v[168:169], v[152:153], v[240:241], v[168:169] op_sel:[0,1,0] op_sel_hi:[0,0,1] neg_lo:[0,0,1] neg_hi:[0,0,0]
	v_pk_fma_f32 v[170:171], v[154:155], v[158:159], v[170:171] op_sel:[0,0,0] op_sel_hi:[0,1,1] neg_lo:[0,0,0] neg_hi:[0,1,0]
	v_pk_add_f32 v[148:149], v[126:127], v[164:165] neg_lo:[0,1] neg_hi:[0,1]
	v_pk_add_f32 v[150:151], v[128:129], v[166:167] neg_lo:[0,1] neg_hi:[0,1]
	v_pk_add_f32 v[152:153], v[130:131], v[168:169] neg_lo:[0,1] neg_hi:[0,1]
	v_pk_add_f32 v[154:155], v[132:133], v[170:171] neg_lo:[0,1] neg_hi:[0,1]
	v_pk_add_f32 v[126:127], v[126:127], v[164:165]
	v_pk_add_f32 v[128:129], v[128:129], v[166:167]
	v_pk_add_f32 v[130:131], v[130:131], v[168:169]
	v_pk_add_f32 v[132:133], v[132:133], v[170:171]
	ds_write2st64_b64 v118, v[126:127], v[128:129] offset1:17
	ds_write2st64_b64 v118, v[130:131], v[132:133] offset0:34 offset1:51
	ds_write2st64_b64 v118, v[148:149], v[150:151] offset0:68 offset1:85
	ds_write2st64_b64 v118, v[152:153], v[154:155] offset0:102 offset1:119
	s_mov_b64 s[6:7], 0
	s_waitcnt vmcnt(5)
	v_lshlrev_b32_e32 v68, 16, v143
	v_cndmask_b32_e64 v69, 0, v68, s[42:43]
	s_waitcnt vmcnt(3)
	v_lshlrev_b32_e32 v68, 16, v144
	v_lshlrev_b32_e32 v75, 16, v5
	v_cndmask_b32_e64 v73, 0, v68, s[44:45]
	v_lshlrev_b32_e32 v74, 16, v4
	v_and_b32_e32 v76, 0xffff0000, v4
	v_mov_b32_e32 v68, v75
	v_and_b32_e32 v77, 0xffff0000, v5
	v_mov_b32_e32 v80, v74
	v_mov_b32_e32 v81, v76
	v_pk_mul_f32 v[68:69], v[56:57], v[68:69]
	v_lshlrev_b32_e32 v79, 16, v6
	v_pk_fma_f32 v[68:69], v[56:57], v[80:81], v[68:69] op_sel:[0,0,1] op_sel_hi:[1,1,0]
	v_pk_mul_f32 v[80:81], v[32:33], v[76:77]
	v_and_b32_e32 v5, 0xffff0000, v7
	v_mov_b32_e32 v78, v75
	v_pk_fma_f32 v[74:75], v[30:31], v[74:75], v[80:81]
	v_and_b32_e32 v81, 16, v7
	v_and_b32_e32 v80, 0xffff0000, v6
	v_lshlrev_b32_e32 v7, 16, v7
	v_pk_fma_f32 v[68:69], v[34:35], v[76:77], v[68:69]
	v_mov_b32_e32 v6, v80
	v_mov_b32_e32 v4, v80
	v_pk_mov_b32 v[76:77], v[76:77], v[80:81] op_sel:[1,0]
	v_mov_b32_e32 v80, v79
	v_mov_b32_e32 v81, v7
	v_pk_mul_f32 v[80:81], v[32:33], v[80:81]
	v_pk_fma_f32 v[74:75], v[34:35], v[78:79], v[74:75]
	v_pk_fma_f32 v[76:77], v[30:31], v[76:77], v[80:81]
	v_mov_b32_e32 v78, v5
	v_pk_fma_f32 v[80:81], v[34:35], v[4:5], v[76:77]
	v_pk_mul_f32 v[4:5], v[56:57], v[78:79]
	v_mov_b32_e32 v72, v7
	v_pk_fma_f32 v[4:5], v[56:57], v[6:7], v[4:5] op_sel:[0,0,1] op_sel_hi:[1,1,0]
	s_waitcnt vmcnt(1)
; __device__ __forceinline__ uint4 ntld_u4(const void* p) { const ntu4_t v = __builtin_nontemporal_load((const ntu4_t*)p); return make_uint4(v.x, v.y, v.z, v.w); }
; __device__ __forceinline__ void lds_barrier() { asm volatile("s_waitcnt lgkmcnt(0)\n\ts_barrier" ::: "memory"); }
; __device__ void ph_hyena_fft(const Params& P, int j, const bf16_t* __restrict__ projAT, const float* __restrict__ kf, bf16_t* __restrict__ yaT, unsigned char* lds_raw) {
;     ...
;             { const Raw8 r0 = load_raw8(vrow + o0, n0), r1 = load_raw8(vrow + o1, n0); sconv8(r0, n0, wv0, wv1, wv2, bv, va); sconv8(r1, n0, wv0, wv1, wv2, bv, vb); }
; #pragma unroll
;             for (int k = 0; k < 8; ++k) { buf[ph0 + k] = mkv2(va[k], vb[k]); buf[ph0 + 4352 + k] = mkv2(0.f, 0.f); }
;             const Raw8 xa0 = load_raw8(x1row + o0, n0), xa1 = load_raw8(x1row + o1, n0);
;             lds_barrier();
;             fft_conv(buf, spec1);
;             { float xa[8], xb[8]; sconv8(xa0, n0, wa0, wa1, wa2, ba, xa); sconv8(xa1, n0, wa0, wa1, wa2, ba, xb);
; #pragma unroll
;               for (int k = 0; k < 8; ++k) { const v2f y = buf[ph0 + k]; va[k] = xa[k] * (y.x * invN + sk0 * va[k]); vb[k] = xb[k] * (y.y * invN + sk0 * vb[k]);
;                   buf[ph0 + k] = mkv2(va[k], vb[k]); buf[ph0 + 4352 + k] = mkv2(0.f, 0.f); } }
;             const Raw8 xb0 = load_raw8(x2row + o0, n0), xb1 = load_raw8(x2row + o1, n0);
;             const uint4 g0 = ntld_u4(grow + o0 + n0), g1 = ntld_u4(grow + o1 + n0);
	v_lshlrev_b32_e32 v77, 16, v1
	v_pk_fma_f32 v[72:73], v[34:35], v[72:73], v[4:5]
	v_lshlrev_b32_e32 v4, 16, v139
	v_cndmask_b32_e64 v5, 0, v4, s[42:43]
	s_waitcnt vmcnt(0)
	v_lshlrev_b32_e32 v4, 16, v141
	v_cndmask_b32_e64 v7, 0, v4, s[44:45]
	v_lshlrev_b32_e32 v76, 16, v0
	v_and_b32_e32 v78, 0xffff0000, v0
	v_mov_b32_e32 v4, v77
	v_mov_b32_e32 v84, v76
	v_mov_b32_e32 v85, v78
	v_pk_mul_f32 v[4:5], v[56:57], v[4:5]
	v_and_b32_e32 v79, 0xffff0000, v1
	v_pk_fma_f32 v[4:5], v[56:57], v[84:85], v[4:5] op_sel:[0,0,1] op_sel_hi:[1,1,0]
	v_lshlrev_b32_e32 v83, 16, v2
	v_pk_fma_f32 v[84:85], v[34:35], v[78:79], v[4:5]
	v_pk_mul_f32 v[4:5], v[32:33], v[78:79]
	v_mov_b32_e32 v82, v77
	v_pk_fma_f32 v[4:5], v[30:31], v[76:77], v[4:5]
	v_and_b32_e32 v1, 0xffff0000, v3
	v_pk_fma_f32 v[86:87], v[34:35], v[82:83], v[4:5]
	v_and_b32_e32 v5, 16, v3
	v_lshlrev_b32_e32 v3, 16, v3
	v_and_b32_e32 v4, 0xffff0000, v2
	v_mov_b32_e32 v76, v83
	v_mov_b32_e32 v77, v3
	v_mov_b32_e32 v2, v4
	v_mov_b32_e32 v0, v4
	v_pk_mov_b32 v[4:5], v[78:79], v[4:5] op_sel:[1,0]
	v_pk_mul_f32 v[76:77], v[32:33], v[76:77]
	v_mov_b32_e32 v82, v1
	v_pk_fma_f32 v[4:5], v[30:31], v[4:5], v[76:77]
	s_waitcnt lgkmcnt(0)
	s_barrier
	v_mov_b32_e32 v6, v3
	v_pk_fma_f32 v[78:79], v[34:35], v[0:1], v[4:5]
	v_pk_mul_f32 v[0:1], v[56:57], v[82:83]
	v_pk_add_f32 v[74:75], v[36:37], v[74:75]
	v_pk_fma_f32 v[0:1], v[56:57], v[2:3], v[0:1] op_sel:[0,0,1] op_sel_hi:[1,1,0]
	v_pk_add_f32 v[68:69], v[36:37], v[68:69]
	v_pk_fma_f32 v[82:83], v[34:35], v[6:7], v[0:1]
	ds_read2_b64 v[0:3], v145 offset1:1
	ds_read2_b64 v[4:7], v145 offset0:2 offset1:3
	s_mov_b32 s14, 0
	s_mov_b32 s15, s14
	s_mov_b32 s0, s14
	s_waitcnt lgkmcnt(1)
	v_mov_b32_e32 v76, v0
	s_waitcnt lgkmcnt(0)
	v_mov_b32_e32 v77, v4
	v_mov_b32_e32 v4, v1
	v_pk_mul_f32 v[0:1], v[4:5], s[80:81] op_sel_hi:[1,0]
	v_mov_b32_e32 v4, v2
	v_mov_b32_e32 v5, v6
	v_pk_mul_f32 v[4:5], v[4:5], s[80:81] op_sel_hi:[1,0]
	v_pk_mul_f32 v[76:77], v[76:77], s[80:81] op_sel_hi:[1,0]
	v_pk_fma_f32 v[4:5], v[44:45], v[62:63], v[4:5]
	v_mov_b32_e32 v6, v3
	v_pk_fma_f32 v[64:65], v[44:45], v[64:65], v[76:77]
	v_pk_mul_f32 v[74:75], v[74:75], v[4:5]
	v_pk_mul_f32 v[2:3], v[6:7], s[80:81] op_sel_hi:[1,0]
	v_pk_add_f32 v[4:5], v[36:37], v[84:85]
	v_pk_fma_f32 v[0:1], v[44:45], v[66:67], v[0:1]
	v_pk_mul_f32 v[76:77], v[68:69], v[64:65]
	v_pk_add_f32 v[6:7], v[36:37], v[86:87]
	v_pk_mul_f32 v[68:69], v[4:5], v[0:1]
	v_pk_fma_f32 v[0:1], v[44:45], v[70:71], v[2:3]
	s_mov_b32 s1, s14
	v_pk_mul_f32 v[66:67], v[6:7], v[0:1]
	v_mov_b32_e32 v0, v76
	v_mov_b32_e32 v1, v68
	v_mov_b32_e32 v2, v74
	v_mov_b32_e32 v3, v66
	v_mov_b64_e32 v[88:89], s[14:15]
	v_mov_b64_e32 v[90:91], s[0:1]
	ds_write2_b64 v145, v[0:1], v[2:3] offset1:1
	v_mov_b32_e32 v0, v77
	v_mov_b32_e32 v1, v69
	v_mov_b32_e32 v2, v75
	v_mov_b32_e32 v3, v67
	ds_write2_b64 v142, v[88:89], v[90:91] offset1:1
	ds_write2_b64 v145, v[0:1], v[2:3] offset0:2 offset1:3
	ds_write2_b64 v138, v[88:89], v[90:91] offset1:1
	ds_read2_b64 v[0:3], v145 offset0:4 offset1:5
	ds_read2_b64 v[4:7], v145 offset0:6 offset1:7
	v_pk_add_f32 v[70:71], v[36:37], v[72:73]
	v_pk_add_f32 v[64:65], v[36:37], v[80:81]
	s_lshl_b32 s62, s11, 1
	s_waitcnt lgkmcnt(1)
	v_mov_b32_e32 v62, v0
	s_waitcnt lgkmcnt(0)
	v_mov_b32_e32 v63, v4
	v_mov_b32_e32 v4, v1
	v_pk_mul_f32 v[0:1], v[4:5], s[80:81] op_sel_hi:[1,0]
	v_mov_b32_e32 v4, v2
	v_mov_b32_e32 v5, v6
	v_pk_mul_f32 v[4:5], v[4:5], s[80:81] op_sel_hi:[1,0]
	v_pk_mul_f32 v[62:63], v[62:63], s[80:81] op_sel_hi:[1,0]
	v_pk_fma_f32 v[4:5], v[44:45], v[10:11], v[4:5]
	v_mov_b32_e32 v6, v3
	v_pk_fma_f32 v[8:9], v[44:45], v[8:9], v[62:63]
	v_pk_mul_f32 v[70:71], v[70:71], v[4:5]
	v_pk_mul_f32 v[2:3], v[6:7], s[80:81] op_sel_hi:[1,0]
	v_pk_add_f32 v[4:5], v[36:37], v[78:79]
	v_pk_fma_f32 v[0:1], v[44:45], v[12:13], v[0:1]
	v_pk_mul_f32 v[72:73], v[64:65], v[8:9]
	v_pk_add_f32 v[6:7], v[36:37], v[82:83]
	v_pk_mul_f32 v[64:65], v[4:5], v[0:1]
	v_pk_fma_f32 v[0:1], v[44:45], v[14:15], v[2:3]
	v_mov_b32_e32 v2, v70
	v_pk_mul_f32 v[62:63], v[6:7], v[0:1]
	v_mov_b32_e32 v0, v72
	v_mov_b32_e32 v1, v64
	v_mov_b32_e32 v3, v62
	s_add_u32 s0, s61, s62
	ds_write2_b64 v145, v[0:1], v[2:3] offset0:4 offset1:5
	v_mov_b32_e32 v0, v73
	v_mov_b32_e32 v1, v65
	v_mov_b32_e32 v2, v71
	v_mov_b32_e32 v3, v63
	s_addc_u32 s1, s52, 0
	ds_write2_b64 v140, v[88:89], v[90:91] offset1:1
	ds_write2_b64 v145, v[0:1], v[2:3] offset0:6 offset1:7
	ds_write2_b64 v137, v[88:89], v[90:91] offset1:1
	v_lshl_add_u64 v[0:1], s[0:1], 0, v[16:17]
	s_lshl_b32 s6, s10, 1
	global_load_dwordx4 v[4:7], v[0:1], off nt
	global_load_ushort v147, v146, s[0:1] offset:-2
	v_lshl_add_u64 v[0:1], s[0:1], 0, v[22:23]
	s_add_u32 s0, s61, s6
	s_addc_u32 s1, s52, 0
	global_load_ushort v148, v[0:1], off offset:16
	v_lshl_add_u64 v[0:1], s[0:1], 0, v[16:17]
	global_load_dwordx4 v[8:11], v[0:1], off nt
	global_load_ushort v149, v146, s[0:1] offset:-2
	v_lshl_add_u64 v[0:1], s[0:1], 0, v[22:23]
	s_mov_b32 s7, s63
	global_load_ushort v150, v[0:1], off offset:16
	v_lshl_add_u64 v[0:1], v[48:49], 0, s[62:63]
	global_load_dwordx4 v[12:15], v[0:1], off nt
	v_lshl_add_u64 v[0:1], v[48:49], 0, s[6:7]
	global_load_dwordx4 v[0:3], v[0:1], off nt
	s_cmp_eq_u32 s53, 3
	s_cbranch_scc1 .Lhy_nopf
	s_add_i32 s100, s53, 1
	s_lshl_b32 s100, s100, 14
	s_add_u32 s100, s47, s100
	s_addc_u32 s101, s58, 0
	v_lshl_add_u64 v[188:189], s[100:101], 0, v[16:17]
	v_lshl_add_u64 v[190:191], s[100:101], 0, v[22:23]
	global_load_ushort v184, v146, s[100:101] offset:-2
	global_load_dwordx4 v[176:179], v[188:189], off nt
	s_add_u32 s100, s100, 0x2000
	s_addc_u32 s101, s101, 0
	v_lshl_add_u64 v[188:189], s[100:101], 0, v[22:23]
	global_load_ushort v185, v146, s[100:101] offset:-2
	global_load_ushort v186, v[188:189], off offset:16
	global_load_ushort v187, v[190:191], off offset:16
	v_lshl_add_u64 v[188:189], s[100:101], 0, v[16:17]
	global_load_dwordx4 v[180:183], v[188:189], off nt

; #define LAS __attribute__((address_space(3)))
; __device__ __forceinline__ cf twc(cf ws, int k16) { if (k16 == 0) return ws; if (k16 == 4) return cf{ws.y, -ws.x}; return cmul(ws, cf{c16(k16), -s16(k16)}); }
; template <int LR> __device__ __forceinline__ void dif_reg(cf (&x)[1 << LR], cf w) {
;     constexpr int R = 1 << LR; cf ws = w;
; #pragma unroll
;     for (int s = 0; s < LR; ++s) { const int half = R >> (s + 1);
; #pragma unroll
;         for (int m0 = 0; m0 < R; m0 += 2 * half)
; #pragma unroll
;             for (int mm = 0; mm < half; ++mm) { const int ia = m0 + mm, ib = ia + half; const cf a = x[ia], b = x[ib];
;                 x[ia] = cf{a.x + b.x, a.y + b.y}; const cf d{a.x - b.x, a.y - b.y};
;                 x[ib] = cmul(d, twc(ws, (mm << s) * (16 / R))); }
;         ws = cmul(ws, ws); }
; }
; template <int LR, bool INV> __device__ __forceinline__ void fft_pass(ldsf2 buf, int base, int stride, int twi) {
;     constexpr int R = 1 << LR; cf x[R];
;     const v2f wv = ((ldsf2)((LAS unsigned char*)buf + 139264))[twi];
; #pragma unroll
;     for (int m = 0; m < R; ++m) { const v2f v = buf[base + m * stride]; x[m] = cf{v.x, v.y}; }
;     const cf w{wv.x, wv.y};
;     if (INV) dit_reg<LR>(x, w); else dif_reg<LR>(x, w);
; #pragma unroll
;     for (int m = 0; m < R; ++m) buf[base + m * stride] = mkv2(x[m].x, x[m].y);
; }
.LBB0_359:
	v_add_u32_e32 v80, s14, v78
	v_ashrrev_i32_e32 v79, 4, v80
	v_lshl_add_u32 v80, v80, 3, 0
	v_lshl_add_u32 v79, v79, 3, v80
	ds_read2st64_b64 v[80:83], v79 offset1:17
	ds_read2st64_b64 v[84:87], v79 offset0:68 offset1:85
	ds_read2st64_b64 v[88:91], v79 offset0:34 offset1:51
	ds_read2st64_b64 v[92:95], v79 offset0:102 offset1:119
	s_movk_i32 s14, 0x200
	v_add_u32_e32 v120, s14, v78
	v_ashrrev_i32_e32 v122, 4, v120
	v_lshl_add_u32 v120, v120, 3, 0
	v_lshl_add_u32 v122, v122, 3, v120
	ds_read2st64_b64 v[128:131], v122 offset1:17
	ds_read2st64_b64 v[132:135], v122 offset0:68 offset1:85
	ds_read2st64_b64 v[136:139], v122 offset0:34 offset1:51
	ds_read2st64_b64 v[140:143], v122 offset0:102 offset1:119
	s_waitcnt lgkmcnt(4)
	v_pk_add_f32 v[98:99], v[232:233], v[232:233] op_sel:[0,1] op_sel_hi:[1,0] neg_lo:[0,0] neg_hi:[0,1]
	s_nop 0
	v_pk_mul_f32 v[100:101], v[98:99], s[16:17] op_sel:[0,0] op_sel_hi:[1,0]
	v_pk_mul_f32 v[102:103], v[98:99], s[16:17] op_sel:[1,0] op_sel_hi:[0,0] neg_lo:[0,0] neg_hi:[1,0]
	v_pk_add_f32 v[108:109], v[80:81], v[84:85] neg_lo:[0,1] neg_hi:[0,1]
	v_pk_add_f32 v[110:111], v[82:83], v[86:87] neg_lo:[0,1] neg_hi:[0,1]
	v_pk_add_f32 v[112:113], v[88:89], v[92:93] neg_lo:[0,1] neg_hi:[0,1]
	v_pk_add_f32 v[114:115], v[90:91], v[94:95] neg_lo:[0,1] neg_hi:[0,1]
	v_pk_add_f32 v[80:81], v[80:81], v[84:85]
	v_pk_add_f32 v[82:83], v[82:83], v[86:87]
	v_pk_add_f32 v[88:89], v[88:89], v[92:93]
	v_pk_add_f32 v[90:91], v[90:91], v[94:95]
	v_pk_mul_f32 v[84:85], v[108:109], v[232:233] op_sel:[1,1] op_sel_hi:[1,0]
	v_pk_mul_f32 v[86:87], v[110:111], v[100:101] op_sel:[1,1] op_sel_hi:[1,0]
	v_pk_mul_f32 v[92:93], v[112:113], v[232:233] op_sel:[1,0] op_sel_hi:[1,1]
	v_pk_mul_f32 v[94:95], v[114:115], v[102:103] op_sel:[1,1] op_sel_hi:[1,0]
	v_pk_fma_f32 v[84:85], v[108:109], v[232:233], v[84:85] op_sel:[0,0,0] op_sel_hi:[0,1,1] neg_lo:[0,0,1] neg_hi:[0,0,0]
	v_pk_fma_f32 v[86:87], v[110:111], v[100:101], v[86:87] op_sel:[0,0,0] op_sel_hi:[0,1,1] neg_lo:[0,0,1] neg_hi:[0,0,0]
	v_pk_fma_f32 v[92:93], v[112:113], v[232:233], v[92:93] op_sel:[0,1,0] op_sel_hi:[0,0,1] neg_lo:[0,0,0] neg_hi:[0,1,0]
	v_pk_fma_f32 v[94:95], v[114:115], v[102:103], v[94:95] op_sel:[0,0,0] op_sel_hi:[0,1,1] neg_lo:[0,0,1] neg_hi:[0,0,0]
	v_pk_add_f32 v[108:109], v[80:81], v[88:89] neg_lo:[0,1] neg_hi:[0,1]
	v_pk_add_f32 v[110:111], v[82:83], v[90:91] neg_lo:[0,1] neg_hi:[0,1]
	v_pk_add_f32 v[112:113], v[84:85], v[92:93] neg_lo:[0,1] neg_hi:[0,1]
	v_pk_add_f32 v[114:115], v[86:87], v[94:95] neg_lo:[0,1] neg_hi:[0,1]
	v_pk_add_f32 v[80:81], v[80:81], v[88:89]
	v_pk_add_f32 v[82:83], v[82:83], v[90:91]
	v_pk_add_f32 v[84:85], v[84:85], v[92:93]
	v_pk_add_f32 v[86:87], v[86:87], v[94:95]
	v_pk_mul_f32 v[88:89], v[108:109], v[234:235] op_sel:[1,1] op_sel_hi:[1,0]
	v_pk_mul_f32 v[90:91], v[110:111], v[234:235] op_sel:[1,0] op_sel_hi:[1,1]
	v_pk_mul_f32 v[92:93], v[112:113], v[234:235] op_sel:[1,1] op_sel_hi:[1,0]
	v_pk_mul_f32 v[94:95], v[114:115], v[234:235] op_sel:[1,0] op_sel_hi:[1,1]
	v_pk_fma_f32 v[88:89], v[108:109], v[234:235], v[88:89] op_sel:[0,0,0] op_sel_hi:[0,1,1] neg_lo:[0,0,1] neg_hi:[0,0,0]
	v_pk_fma_f32 v[90:91], v[110:111], v[234:235], v[90:91] op_sel:[0,1,0] op_sel_hi:[0,0,1] neg_lo:[0,0,0] neg_hi:[0,1,0]
	v_pk_fma_f32 v[92:93], v[112:113], v[234:235], v[92:93] op_sel:[0,0,0] op_sel_hi:[0,1,1] neg_lo:[0,0,1] neg_hi:[0,0,0]
	v_pk_fma_f32 v[94:95], v[114:115], v[234:235], v[94:95] op_sel:[0,1,0] op_sel_hi:[0,0,1] neg_lo:[0,0,0] neg_hi:[0,1,0]
	v_pk_add_f32 v[108:109], v[80:81], v[82:83] neg_lo:[0,1] neg_hi:[0,1]
	v_pk_add_f32 v[110:111], v[88:89], v[90:91] neg_lo:[0,1] neg_hi:[0,1]
	v_pk_add_f32 v[112:113], v[84:85], v[86:87] neg_lo:[0,1] neg_hi:[0,1]
	v_pk_add_f32 v[114:115], v[92:93], v[94:95] neg_lo:[0,1] neg_hi:[0,1]
	v_pk_add_f32 v[80:81], v[80:81], v[82:83]
	v_pk_add_f32 v[88:89], v[88:89], v[90:91]
	v_pk_add_f32 v[84:85], v[84:85], v[86:87]
	v_pk_add_f32 v[92:93], v[92:93], v[94:95]
	v_pk_mul_f32 v[82:83], v[108:109], v[236:237] op_sel:[1,1] op_sel_hi:[1,0]
	v_pk_mul_f32 v[90:91], v[110:111], v[236:237] op_sel:[1,1] op_sel_hi:[1,0]
	v_pk_mul_f32 v[86:87], v[112:113], v[236:237] op_sel:[1,1] op_sel_hi:[1,0]
	v_pk_mul_f32 v[94:95], v[114:115], v[236:237] op_sel:[1,1] op_sel_hi:[1,0]
	v_pk_fma_f32 v[82:83], v[108:109], v[236:237], v[82:83] op_sel:[0,0,0] op_sel_hi:[0,1,1] neg_lo:[0,0,1] neg_hi:[0,0,0]
	v_pk_fma_f32 v[90:91], v[110:111], v[236:237], v[90:91] op_sel:[0,0,0] op_sel_hi:[0,1,1] neg_lo:[0,0,1] neg_hi:[0,0,0]
	v_pk_fma_f32 v[86:87], v[112:113], v[236:237], v[86:87] op_sel:[0,0,0] op_sel_hi:[0,1,1] neg_lo:[0,0,1] neg_hi:[0,0,0]
	v_pk_fma_f32 v[94:95], v[114:115], v[236:237], v[94:95] op_sel:[0,0,0] op_sel_hi:[0,1,1] neg_lo:[0,0,1] neg_hi:[0,0,0]
	ds_write2st64_b64 v79, v[80:81], v[82:83] offset1:17
	ds_write2st64_b64 v79, v[88:89], v[90:91] offset0:34 offset1:51
	ds_write2st64_b64 v79, v[84:85], v[86:87] offset0:68 offset1:85
	ds_write2st64_b64 v79, v[92:93], v[94:95] offset0:102 offset1:119
	s_waitcnt lgkmcnt(4)
; #define LAS __attribute__((address_space(3)))
; __device__ __forceinline__ cf twc(cf ws, int k16) { if (k16 == 0) return ws; if (k16 == 4) return cf{ws.y, -ws.x}; return cmul(ws, cf{c16(k16), -s16(k16)}); }
; __device__ __forceinline__ void lds_barrier() { asm volatile("s_waitcnt lgkmcnt(0)\n\ts_barrier" ::: "memory"); }
; template <int LR> __device__ __forceinline__ void dif_reg(cf (&x)[1 << LR], cf w) {
;     constexpr int R = 1 << LR; cf ws = w;
; #pragma unroll
;     for (int s = 0; s < LR; ++s) { const int half = R >> (s + 1);
; #pragma unroll
;         for (int m0 = 0; m0 < R; m0 += 2 * half)
; #pragma unroll
;             for (int mm = 0; mm < half; ++mm) { const int ia = m0 + mm, ib = ia + half; const cf a = x[ia], b = x[ib];
;                 x[ia] = cf{a.x + b.x, a.y + b.y}; const cf d{a.x - b.x, a.y - b.y};
;                 x[ib] = cmul(d, twc(ws, (mm << s) * (16 / R))); }
;         ws = cmul(ws, ws); }
; }
; template <int LR, bool INV> __device__ __forceinline__ void fft_pass(ldsf2 buf, int base, int stride, int twi) {
;     constexpr int R = 1 << LR; cf x[R];
;     const v2f wv = ((ldsf2)((LAS unsigned char*)buf + 139264))[twi];
; #pragma unroll
;     for (int m = 0; m < R; ++m) { const v2f v = buf[base + m * stride]; x[m] = cf{v.x, v.y}; }
;     const cf w{wv.x, wv.y};
;     if (INV) dit_reg<LR>(x, w); else dif_reg<LR>(x, w);
; #pragma unroll
;     for (int m = 0; m < R; ++m) buf[base + m * stride] = mkv2(x[m].x, x[m].y);
; }
; __device__ __forceinline__ void fft_fwd_abc(ldsf2 buf) {
;     ...
;     lds_barrier();
; #pragma unroll 1
;     for (int u = 0; u < 2; ++u) { const int o = l + 64 * u, e0 = wv * 1024 + o; fft_pass<3, false>(buf, e0 + (e0 >> 4), 136, o * 8); }
	v_pk_add_f32 v[152:153], v[240:241], v[240:241] op_sel:[0,1] op_sel_hi:[1,0] neg_lo:[0,0] neg_hi:[0,1]
	s_nop 0
	v_pk_mul_f32 v[154:155], v[152:153], s[16:17] op_sel:[0,0] op_sel_hi:[1,0]
	v_pk_mul_f32 v[156:157], v[152:153], s[16:17] op_sel:[1,0] op_sel_hi:[0,0] neg_lo:[0,0] neg_hi:[1,0]
	v_pk_add_f32 v[162:163], v[128:129], v[132:133] neg_lo:[0,1] neg_hi:[0,1]
	v_pk_add_f32 v[164:165], v[130:131], v[134:135] neg_lo:[0,1] neg_hi:[0,1]
	v_pk_add_f32 v[166:167], v[136:137], v[140:141] neg_lo:[0,1] neg_hi:[0,1]
	v_pk_add_f32 v[168:169], v[138:139], v[142:143] neg_lo:[0,1] neg_hi:[0,1]
	v_pk_add_f32 v[128:129], v[128:129], v[132:133]
	v_pk_add_f32 v[130:131], v[130:131], v[134:135]
	v_pk_add_f32 v[136:137], v[136:137], v[140:141]
	v_pk_add_f32 v[138:139], v[138:139], v[142:143]
	v_pk_mul_f32 v[132:133], v[162:163], v[240:241] op_sel:[1,1] op_sel_hi:[1,0]
	v_pk_mul_f32 v[134:135], v[164:165], v[154:155] op_sel:[1,1] op_sel_hi:[1,0]
	v_pk_mul_f32 v[140:141], v[166:167], v[240:241] op_sel:[1,0] op_sel_hi:[1,1]
	v_pk_mul_f32 v[142:143], v[168:169], v[156:157] op_sel:[1,1] op_sel_hi:[1,0]
	v_pk_fma_f32 v[132:133], v[162:163], v[240:241], v[132:133] op_sel:[0,0,0] op_sel_hi:[0,1,1] neg_lo:[0,0,1] neg_hi:[0,0,0]
	v_pk_fma_f32 v[134:135], v[164:165], v[154:155], v[134:135] op_sel:[0,0,0] op_sel_hi:[0,1,1] neg_lo:[0,0,1] neg_hi:[0,0,0]
	v_pk_fma_f32 v[140:141], v[166:167], v[240:241], v[140:141] op_sel:[0,1,0] op_sel_hi:[0,0,1] neg_lo:[0,0,0] neg_hi:[0,1,0]
	v_pk_fma_f32 v[142:143], v[168:169], v[156:157], v[142:143] op_sel:[0,0,0] op_sel_hi:[0,1,1] neg_lo:[0,0,1] neg_hi:[0,0,0]
	v_pk_add_f32 v[162:163], v[128:129], v[136:137] neg_lo:[0,1] neg_hi:[0,1]
	v_pk_add_f32 v[164:165], v[130:131], v[138:139] neg_lo:[0,1] neg_hi:[0,1]
	v_pk_add_f32 v[166:167], v[132:133], v[140:141] neg_lo:[0,1] neg_hi:[0,1]
	v_pk_add_f32 v[168:169], v[134:135], v[142:143] neg_lo:[0,1] neg_hi:[0,1]
	v_pk_add_f32 v[128:129], v[128:129], v[136:137]
	v_pk_add_f32 v[130:131], v[130:131], v[138:139]
	v_pk_add_f32 v[132:133], v[132:133], v[140:141]
	v_pk_add_f32 v[134:135], v[134:135], v[142:143]
	v_pk_mul_f32 v[136:137], v[162:163], v[242:243] op_sel:[1,1] op_sel_hi:[1,0]
	v_pk_mul_f32 v[138:139], v[164:165], v[242:243] op_sel:[1,0] op_sel_hi:[1,1]
	v_pk_mul_f32 v[140:141], v[166:167], v[242:243] op_sel:[1,1] op_sel_hi:[1,0]
	v_pk_mul_f32 v[142:143], v[168:169], v[242:243] op_sel:[1,0] op_sel_hi:[1,1]
	v_pk_fma_f32 v[136:137], v[162:163], v[242:243], v[136:137] op_sel:[0,0,0] op_sel_hi:[0,1,1] neg_lo:[0,0,1] neg_hi:[0,0,0]
	v_pk_fma_f32 v[138:139], v[164:165], v[242:243], v[138:139] op_sel:[0,1,0] op_sel_hi:[0,0,1] neg_lo:[0,0,0] neg_hi:[0,1,0]
	v_pk_fma_f32 v[140:141], v[166:167], v[242:243], v[140:141] op_sel:[0,0,0] op_sel_hi:[0,1,1] neg_lo:[0,0,1] neg_hi:[0,0,0]
	v_pk_fma_f32 v[142:143], v[168:169], v[242:243], v[142:143] op_sel:[0,1,0] op_sel_hi:[0,0,1] neg_lo:[0,0,0] neg_hi:[0,1,0]
	v_pk_add_f32 v[162:163], v[128:129], v[130:131] neg_lo:[0,1] neg_hi:[0,1]
	v_pk_add_f32 v[164:165], v[136:137], v[138:139] neg_lo:[0,1] neg_hi:[0,1]
	v_pk_add_f32 v[166:167], v[132:133], v[134:135] neg_lo:[0,1] neg_hi:[0,1]
	v_pk_add_f32 v[168:169], v[140:141], v[142:143] neg_lo:[0,1] neg_hi:[0,1]
	v_pk_add_f32 v[128:129], v[128:129], v[130:131]
	v_pk_add_f32 v[136:137], v[136:137], v[138:139]
	v_pk_add_f32 v[132:133], v[132:133], v[134:135]
	v_pk_add_f32 v[140:141], v[140:141], v[142:143]
	v_pk_mul_f32 v[130:131], v[162:163], v[244:245] op_sel:[1,1] op_sel_hi:[1,0]
	v_pk_mul_f32 v[138:139], v[164:165], v[244:245] op_sel:[1,1] op_sel_hi:[1,0]
	v_pk_mul_f32 v[134:135], v[166:167], v[244:245] op_sel:[1,1] op_sel_hi:[1,0]
	v_pk_mul_f32 v[142:143], v[168:169], v[244:245] op_sel:[1,1] op_sel_hi:[1,0]
	v_pk_fma_f32 v[130:131], v[162:163], v[244:245], v[130:131] op_sel:[0,0,0] op_sel_hi:[0,1,1] neg_lo:[0,0,1] neg_hi:[0,0,0]
	v_pk_fma_f32 v[138:139], v[164:165], v[244:245], v[138:139] op_sel:[0,0,0] op_sel_hi:[0,1,1] neg_lo:[0,0,1] neg_hi:[0,0,0]
	v_pk_fma_f32 v[134:135], v[166:167], v[244:245], v[134:135] op_sel:[0,0,0] op_sel_hi:[0,1,1] neg_lo:[0,0,1] neg_hi:[0,0,0]
	v_pk_fma_f32 v[142:143], v[168:169], v[244:245], v[142:143] op_sel:[0,0,0] op_sel_hi:[0,1,1] neg_lo:[0,0,1] neg_hi:[0,0,0]
	ds_write2st64_b64 v122, v[128:129], v[130:131] offset1:17
	ds_write2st64_b64 v122, v[136:137], v[138:139] offset0:34 offset1:51
	ds_write2st64_b64 v122, v[132:133], v[134:135] offset0:68 offset1:85
	ds_write2st64_b64 v122, v[140:141], v[142:143] offset0:102 offset1:119
	s_mov_b64 s[10:11], 0
	s_waitcnt lgkmcnt(0)
	s_barrier
	v_lshlrev_b32_e32 v80, 4, v78
	v_and_b32_e32 v79, 63, v78
	v_and_b32_e32 v80, 0xfffffc00, v80
	s_mov_b32 s0, 0
	s_mov_b64 s[10:11], -1
; #define LAS __attribute__((address_space(3)))
; __device__ __forceinline__ cf twc(cf ws, int k16) { if (k16 == 0) return ws; if (k16 == 4) return cf{ws.y, -ws.x}; return cmul(ws, cf{c16(k16), -s16(k16)}); }
; template <int LR> __device__ __forceinline__ void dif_reg(cf (&x)[1 << LR], cf w) {
;     constexpr int R = 1 << LR; cf ws = w;
; #pragma unroll
;     for (int s = 0; s < LR; ++s) { const int half = R >> (s + 1);
; #pragma unroll
;         for (int m0 = 0; m0 < R; m0 += 2 * half)
; #pragma unroll
;             for (int mm = 0; mm < half; ++mm) { const int ia = m0 + mm, ib = ia + half; const cf a = x[ia], b = x[ib];
;                 x[ia] = cf{a.x + b.x, a.y + b.y}; const cf d{a.x - b.x, a.y - b.y};
;                 x[ib] = cmul(d, twc(ws, (mm << s) * (16 / R))); }
;         ws = cmul(ws, ws); }
; }
; template <int LR, bool INV> __device__ __forceinline__ void fft_pass(ldsf2 buf, int base, int stride, int twi) {
;     constexpr int R = 1 << LR; cf x[R];
;     const v2f wv = ((ldsf2)((LAS unsigned char*)buf + 139264))[twi];
; #pragma unroll
;     for (int m = 0; m < R; ++m) { const v2f v = buf[base + m * stride]; x[m] = cf{v.x, v.y}; }
;     const cf w{wv.x, wv.y};
;     if (INV) dit_reg<LR>(x, w); else dif_reg<LR>(x, w);
; #pragma unroll
;     for (int m = 0; m < R; ++m) buf[base + m * stride] = mkv2(x[m].x, x[m].y);
; }
.LBB0_361:
	v_or_b32_e32 v82, s0, v79
	v_or_b32_e32 v81, v82, v80
	v_ashrrev_i32_e32 v83, 4, v81
	v_lshlrev_b32_e32 v81, 3, v81
	v_lshlrev_b32_e32 v82, 3, v83
	v_add3_u32 v81, 0, v81, v82
	v_add_u32_e32 v121, 0x800, v81
	ds_read2_b64 v[82:85], v81 offset1:136
	v_add_u32_e32 v126, 0x1000, v81
	v_add_u32_e32 v127, 0x1800, v81
	ds_read2_b64 v[86:89], v121 offset0:16 offset1:152
	ds_read2_b64 v[90:93], v126 offset0:32 offset1:168
	ds_read2_b64 v[94:97], v127 offset0:48 offset1:184
	s_mov_b32 s0, 64
	v_or_b32_e32 v128, s0, v79
	v_or_b32_e32 v130, v128, v80
	v_ashrrev_i32_e32 v132, 4, v130
	v_lshlrev_b32_e32 v130, 3, v130
	v_lshlrev_b32_e32 v128, 3, v132
	v_add3_u32 v130, 0, v130, v128
	v_add_u32_e32 v136, 0x800, v130
	ds_read2_b64 v[138:141], v130 offset1:136
	v_add_u32_e32 v142, 0x1000, v130
	v_add_u32_e32 v152, 0x1800, v130
	ds_read2_b64 v[154:157], v136 offset0:16 offset1:152
	ds_read2_b64 v[158:161], v142 offset0:32 offset1:168
	ds_read2_b64 v[162:165], v152 offset0:48 offset1:184
	s_waitcnt lgkmcnt(4)
	v_pk_add_f32 v[100:101], v[214:215], v[214:215] op_sel:[0,1] op_sel_hi:[1,0] neg_lo:[0,0] neg_hi:[0,1]
	s_nop 0
	v_pk_mul_f32 v[102:103], v[100:101], s[16:17] op_sel:[0,0] op_sel_hi:[1,0]
	v_pk_mul_f32 v[104:105], v[100:101], s[16:17] op_sel:[1,0] op_sel_hi:[0,0] neg_lo:[0,0] neg_hi:[1,0]
	v_pk_add_f32 v[110:111], v[82:83], v[90:91] neg_lo:[0,1] neg_hi:[0,1]
	v_pk_add_f32 v[112:113], v[84:85], v[92:93] neg_lo:[0,1] neg_hi:[0,1]
	v_pk_add_f32 v[114:115], v[86:87], v[94:95] neg_lo:[0,1] neg_hi:[0,1]
	v_pk_add_f32 v[116:117], v[88:89], v[96:97] neg_lo:[0,1] neg_hi:[0,1]
	v_pk_add_f32 v[82:83], v[82:83], v[90:91]
	v_pk_add_f32 v[84:85], v[84:85], v[92:93]
	v_pk_add_f32 v[86:87], v[86:87], v[94:95]
	v_pk_add_f32 v[88:89], v[88:89], v[96:97]
	v_pk_mul_f32 v[90:91], v[110:111], v[214:215] op_sel:[1,1] op_sel_hi:[1,0]
	v_pk_mul_f32 v[92:93], v[112:113], v[102:103] op_sel:[1,1] op_sel_hi:[1,0]
	v_pk_mul_f32 v[94:95], v[114:115], v[214:215] op_sel:[1,0] op_sel_hi:[1,1]
	v_pk_mul_f32 v[96:97], v[116:117], v[104:105] op_sel:[1,1] op_sel_hi:[1,0]
	v_pk_fma_f32 v[90:91], v[110:111], v[214:215], v[90:91] op_sel:[0,0,0] op_sel_hi:[0,1,1] neg_lo:[0,0,1] neg_hi:[0,0,0]
	v_pk_fma_f32 v[92:93], v[112:113], v[102:103], v[92:93] op_sel:[0,0,0] op_sel_hi:[0,1,1] neg_lo:[0,0,1] neg_hi:[0,0,0]
	v_pk_fma_f32 v[94:95], v[114:115], v[214:215], v[94:95] op_sel:[0,1,0] op_sel_hi:[0,0,1] neg_lo:[0,0,0] neg_hi:[0,1,0]
	v_pk_fma_f32 v[96:97], v[116:117], v[104:105], v[96:97] op_sel:[0,0,0] op_sel_hi:[0,1,1] neg_lo:[0,0,1] neg_hi:[0,0,0]
	v_pk_add_f32 v[110:111], v[82:83], v[86:87] neg_lo:[0,1] neg_hi:[0,1]
	v_pk_add_f32 v[112:113], v[84:85], v[88:89] neg_lo:[0,1] neg_hi:[0,1]
	v_pk_add_f32 v[114:115], v[90:91], v[94:95] neg_lo:[0,1] neg_hi:[0,1]
	v_pk_add_f32 v[116:117], v[92:93], v[96:97] neg_lo:[0,1] neg_hi:[0,1]
	v_pk_add_f32 v[82:83], v[82:83], v[86:87]
	v_pk_add_f32 v[84:85], v[84:85], v[88:89]
	v_pk_add_f32 v[90:91], v[90:91], v[94:95]
	v_pk_add_f32 v[92:93], v[92:93], v[96:97]
	v_pk_mul_f32 v[86:87], v[110:111], v[216:217] op_sel:[1,1] op_sel_hi:[1,0]
	v_pk_mul_f32 v[88:89], v[112:113], v[216:217] op_sel:[1,0] op_sel_hi:[1,1]
	v_pk_mul_f32 v[94:95], v[114:115], v[216:217] op_sel:[1,1] op_sel_hi:[1,0]
	v_pk_mul_f32 v[96:97], v[116:117], v[216:217] op_sel:[1,0] op_sel_hi:[1,1]
	v_pk_fma_f32 v[86:87], v[110:111], v[216:217], v[86:87] op_sel:[0,0,0] op_sel_hi:[0,1,1] neg_lo:[0,0,1] neg_hi:[0,0,0]
	v_pk_fma_f32 v[88:89], v[112:113], v[216:217], v[88:89] op_sel:[0,1,0] op_sel_hi:[0,0,1] neg_lo:[0,0,0] neg_hi:[0,1,0]
	v_pk_fma_f32 v[94:95], v[114:115], v[216:217], v[94:95] op_sel:[0,0,0] op_sel_hi:[0,1,1] neg_lo:[0,0,1] neg_hi:[0,0,0]
	v_pk_fma_f32 v[96:97], v[116:117], v[216:217], v[96:97] op_sel:[0,1,0] op_sel_hi:[0,0,1] neg_lo:[0,0,0] neg_hi:[0,1,0]
	v_pk_add_f32 v[110:111], v[82:83], v[84:85] neg_lo:[0,1] neg_hi:[0,1]
	v_pk_add_f32 v[112:113], v[86:87], v[88:89] neg_lo:[0,1] neg_hi:[0,1]
	v_pk_add_f32 v[114:115], v[90:91], v[92:93] neg_lo:[0,1] neg_hi:[0,1]
	v_pk_add_f32 v[116:117], v[94:95], v[96:97] neg_lo:[0,1] neg_hi:[0,1]
	v_pk_add_f32 v[82:83], v[82:83], v[84:85]
	v_pk_add_f32 v[86:87], v[86:87], v[88:89]
	v_pk_add_f32 v[90:91], v[90:91], v[92:93]
	v_pk_add_f32 v[94:95], v[94:95], v[96:97]
	v_pk_mul_f32 v[84:85], v[110:111], v[218:219] op_sel:[1,1] op_sel_hi:[1,0]
	v_pk_mul_f32 v[88:89], v[112:113], v[218:219] op_sel:[1,1] op_sel_hi:[1,0]
	v_pk_mul_f32 v[92:93], v[114:115], v[218:219] op_sel:[1,1] op_sel_hi:[1,0]
	v_pk_mul_f32 v[96:97], v[116:117], v[218:219] op_sel:[1,1] op_sel_hi:[1,0]
	v_pk_fma_f32 v[84:85], v[110:111], v[218:219], v[84:85] op_sel:[0,0,0] op_sel_hi:[0,1,1] neg_lo:[0,0,1] neg_hi:[0,0,0]
	v_pk_fma_f32 v[88:89], v[112:113], v[218:219], v[88:89] op_sel:[0,0,0] op_sel_hi:[0,1,1] neg_lo:[0,0,1] neg_hi:[0,0,0]
	v_pk_fma_f32 v[92:93], v[114:115], v[218:219], v[92:93] op_sel:[0,0,0] op_sel_hi:[0,1,1] neg_lo:[0,0,1] neg_hi:[0,0,0]
	v_pk_fma_f32 v[96:97], v[116:117], v[218:219], v[96:97] op_sel:[0,0,0] op_sel_hi:[0,1,1] neg_lo:[0,0,1] neg_hi:[0,0,0]
	ds_write2_b64 v81, v[82:83], v[84:85] offset1:136
	ds_write2_b64 v121, v[86:87], v[88:89] offset0:16 offset1:152
	ds_write2_b64 v126, v[90:91], v[92:93] offset0:32 offset1:168
	ds_write2_b64 v127, v[94:95], v[96:97] offset0:48 offset1:184
	s_waitcnt lgkmcnt(4)
; #define LAS __attribute__((address_space(3)))
; __device__ __forceinline__ cf twc(cf ws, int k16) { if (k16 == 0) return ws; if (k16 == 4) return cf{ws.y, -ws.x}; return cmul(ws, cf{c16(k16), -s16(k16)}); }
; __device__ __forceinline__ void wave_lds_fence() { asm volatile("s_waitcnt lgkmcnt(0)" ::: "memory"); }
; template <int LR> __device__ __forceinline__ void dif_reg(cf (&x)[1 << LR], cf w) {
;     constexpr int R = 1 << LR; cf ws = w;
; #pragma unroll
;     for (int s = 0; s < LR; ++s) { const int half = R >> (s + 1);
; #pragma unroll
;         for (int m0 = 0; m0 < R; m0 += 2 * half)
; #pragma unroll
;             for (int mm = 0; mm < half; ++mm) { const int ia = m0 + mm, ib = ia + half; const cf a = x[ia], b = x[ib];
;                 x[ia] = cf{a.x + b.x, a.y + b.y}; const cf d{a.x - b.x, a.y - b.y};
;                 x[ib] = cmul(d, twc(ws, (mm << s) * (16 / R))); }
;         ws = cmul(ws, ws); }
; }
; template <int LR, bool INV> __device__ __forceinline__ void fft_pass(ldsf2 buf, int base, int stride, int twi) {
;     constexpr int R = 1 << LR; cf x[R];
;     const v2f wv = ((ldsf2)((LAS unsigned char*)buf + 139264))[twi];
; #pragma unroll
;     for (int m = 0; m < R; ++m) { const v2f v = buf[base + m * stride]; x[m] = cf{v.x, v.y}; }
;     const cf w{wv.x, wv.y};
;     if (INV) dit_reg<LR>(x, w); else dif_reg<LR>(x, w);
; #pragma unroll
;     for (int m = 0; m < R; ++m) buf[base + m * stride] = mkv2(x[m].x, x[m].y);
; }
; __device__ __forceinline__ void fft_fwd_abc(ldsf2 buf) {
;     ...
;     wave_lds_fence();
; #pragma unroll 1
;     for (int u = 0; u < 2; ++u) { const int j = l + 64 * u, o = j & 15, e0 = wv * 1024 + (j >> 4) * 128 + o; fft_pass<3, false>(buf, e0 + (e0 >> 4), 17, o * 64); }
	v_pk_add_f32 v[166:167], v[220:221], v[220:221] op_sel:[0,1] op_sel_hi:[1,0] neg_lo:[0,0] neg_hi:[0,1]
	s_nop 0
	v_pk_mul_f32 v[168:169], v[166:167], s[16:17] op_sel:[0,0] op_sel_hi:[1,0]
	v_pk_mul_f32 v[170:171], v[166:167], s[16:17] op_sel:[1,0] op_sel_hi:[0,0] neg_lo:[0,0] neg_hi:[1,0]
	v_pk_add_f32 v[188:189], v[138:139], v[158:159] neg_lo:[0,1] neg_hi:[0,1]
	v_pk_add_f32 v[190:191], v[140:141], v[160:161] neg_lo:[0,1] neg_hi:[0,1]
	v_pk_add_f32 v[196:197], v[154:155], v[162:163] neg_lo:[0,1] neg_hi:[0,1]
	v_pk_add_f32 v[198:199], v[156:157], v[164:165] neg_lo:[0,1] neg_hi:[0,1]
	v_pk_add_f32 v[138:139], v[138:139], v[158:159]
	v_pk_add_f32 v[140:141], v[140:141], v[160:161]
	v_pk_add_f32 v[154:155], v[154:155], v[162:163]
	v_pk_add_f32 v[156:157], v[156:157], v[164:165]
	v_pk_mul_f32 v[158:159], v[188:189], v[220:221] op_sel:[1,1] op_sel_hi:[1,0]
	v_pk_mul_f32 v[160:161], v[190:191], v[168:169] op_sel:[1,1] op_sel_hi:[1,0]
	v_pk_mul_f32 v[162:163], v[196:197], v[220:221] op_sel:[1,0] op_sel_hi:[1,1]
	v_pk_mul_f32 v[164:165], v[198:199], v[170:171] op_sel:[1,1] op_sel_hi:[1,0]
	v_pk_fma_f32 v[158:159], v[188:189], v[220:221], v[158:159] op_sel:[0,0,0] op_sel_hi:[0,1,1] neg_lo:[0,0,1] neg_hi:[0,0,0]
	v_pk_fma_f32 v[160:161], v[190:191], v[168:169], v[160:161] op_sel:[0,0,0] op_sel_hi:[0,1,1] neg_lo:[0,0,1] neg_hi:[0,0,0]
	v_pk_fma_f32 v[162:163], v[196:197], v[220:221], v[162:163] op_sel:[0,1,0] op_sel_hi:[0,0,1] neg_lo:[0,0,0] neg_hi:[0,1,0]
	v_pk_fma_f32 v[164:165], v[198:199], v[170:171], v[164:165] op_sel:[0,0,0] op_sel_hi:[0,1,1] neg_lo:[0,0,1] neg_hi:[0,0,0]
	v_pk_add_f32 v[188:189], v[138:139], v[154:155] neg_lo:[0,1] neg_hi:[0,1]
	v_pk_add_f32 v[190:191], v[140:141], v[156:157] neg_lo:[0,1] neg_hi:[0,1]
	v_pk_add_f32 v[196:197], v[158:159], v[162:163] neg_lo:[0,1] neg_hi:[0,1]
	v_pk_add_f32 v[198:199], v[160:161], v[164:165] neg_lo:[0,1] neg_hi:[0,1]
	v_pk_add_f32 v[138:139], v[138:139], v[154:155]
	v_pk_add_f32 v[140:141], v[140:141], v[156:157]
	v_pk_add_f32 v[158:159], v[158:159], v[162:163]
	v_pk_add_f32 v[160:161], v[160:161], v[164:165]
	v_pk_mul_f32 v[154:155], v[188:189], v[222:223] op_sel:[1,1] op_sel_hi:[1,0]
	v_pk_mul_f32 v[156:157], v[190:191], v[222:223] op_sel:[1,0] op_sel_hi:[1,1]
	v_pk_mul_f32 v[162:163], v[196:197], v[222:223] op_sel:[1,1] op_sel_hi:[1,0]
	v_pk_mul_f32 v[164:165], v[198:199], v[222:223] op_sel:[1,0] op_sel_hi:[1,1]
	v_pk_fma_f32 v[154:155], v[188:189], v[222:223], v[154:155] op_sel:[0,0,0] op_sel_hi:[0,1,1] neg_lo:[0,0,1] neg_hi:[0,0,0]
	v_pk_fma_f32 v[156:157], v[190:191], v[222:223], v[156:157] op_sel:[0,1,0] op_sel_hi:[0,0,1] neg_lo:[0,0,0] neg_hi:[0,1,0]
	v_pk_fma_f32 v[162:163], v[196:197], v[222:223], v[162:163] op_sel:[0,0,0] op_sel_hi:[0,1,1] neg_lo:[0,0,1] neg_hi:[0,0,0]
	v_pk_fma_f32 v[164:165], v[198:199], v[222:223], v[164:165] op_sel:[0,1,0] op_sel_hi:[0,0,1] neg_lo:[0,0,0] neg_hi:[0,1,0]
	v_pk_add_f32 v[188:189], v[138:139], v[140:141] neg_lo:[0,1] neg_hi:[0,1]
	v_pk_add_f32 v[190:191], v[154:155], v[156:157] neg_lo:[0,1] neg_hi:[0,1]
	v_pk_add_f32 v[196:197], v[158:159], v[160:161] neg_lo:[0,1] neg_hi:[0,1]
	v_pk_add_f32 v[198:199], v[162:163], v[164:165] neg_lo:[0,1] neg_hi:[0,1]
	v_pk_add_f32 v[138:139], v[138:139], v[140:141]
	v_pk_add_f32 v[154:155], v[154:155], v[156:157]
	v_pk_add_f32 v[158:159], v[158:159], v[160:161]
	v_pk_add_f32 v[162:163], v[162:163], v[164:165]
	v_pk_mul_f32 v[140:141], v[188:189], v[224:225] op_sel:[1,1] op_sel_hi:[1,0]
	v_pk_mul_f32 v[156:157], v[190:191], v[224:225] op_sel:[1,1] op_sel_hi:[1,0]
	v_pk_mul_f32 v[160:161], v[196:197], v[224:225] op_sel:[1,1] op_sel_hi:[1,0]
	v_pk_mul_f32 v[164:165], v[198:199], v[224:225] op_sel:[1,1] op_sel_hi:[1,0]
	v_pk_fma_f32 v[140:141], v[188:189], v[224:225], v[140:141] op_sel:[0,0,0] op_sel_hi:[0,1,1] neg_lo:[0,0,1] neg_hi:[0,0,0]
	v_pk_fma_f32 v[156:157], v[190:191], v[224:225], v[156:157] op_sel:[0,0,0] op_sel_hi:[0,1,1] neg_lo:[0,0,1] neg_hi:[0,0,0]
	v_pk_fma_f32 v[160:161], v[196:197], v[224:225], v[160:161] op_sel:[0,0,0] op_sel_hi:[0,1,1] neg_lo:[0,0,1] neg_hi:[0,0,0]
	v_pk_fma_f32 v[164:165], v[198:199], v[224:225], v[164:165] op_sel:[0,0,0] op_sel_hi:[0,1,1] neg_lo:[0,0,1] neg_hi:[0,0,0]
	ds_write2_b64 v130, v[138:139], v[140:141] offset1:136
	ds_write2_b64 v136, v[154:155], v[156:157] offset0:16 offset1:152
	ds_write2_b64 v142, v[158:159], v[160:161] offset0:32 offset1:168
	ds_write2_b64 v152, v[162:163], v[164:165] offset0:48 offset1:184
	s_mov_b64 s[10:11], 0
	v_and_b32_e32 v78, 15, v78
	s_waitcnt lgkmcnt(0)
	v_lshlrev_b32_e32 v79, 3, v79
	v_lshlrev_b32_e32 v81, 9, v78
	v_and_or_b32 v79, v79, s90, v80
	v_add_u32_e32 v80, 0, v81
	v_lshl_add_u32 v78, v78, 3, 0
	s_mov_b32 s0, 0
	s_mov_b64 s[10:11], -1
; #define LAS __attribute__((address_space(3)))
; __device__ __forceinline__ cf twc(cf ws, int k16) { if (k16 == 0) return ws; if (k16 == 4) return cf{ws.y, -ws.x}; return cmul(ws, cf{c16(k16), -s16(k16)}); }
; template <int LR> __device__ __forceinline__ void dif_reg(cf (&x)[1 << LR], cf w) {
;     constexpr int R = 1 << LR; cf ws = w;
; #pragma unroll
;     for (int s = 0; s < LR; ++s) { const int half = R >> (s + 1);
; #pragma unroll
;         for (int m0 = 0; m0 < R; m0 += 2 * half)
; #pragma unroll
;             for (int mm = 0; mm < half; ++mm) { const int ia = m0 + mm, ib = ia + half; const cf a = x[ia], b = x[ib];
;                 x[ia] = cf{a.x + b.x, a.y + b.y}; const cf d{a.x - b.x, a.y - b.y};
;                 x[ib] = cmul(d, twc(ws, (mm << s) * (16 / R))); }
;         ws = cmul(ws, ws); }
; }
; template <int LR, bool INV> __device__ __forceinline__ void fft_pass(ldsf2 buf, int base, int stride, int twi) {
;     constexpr int R = 1 << LR; cf x[R];
;     const v2f wv = ((ldsf2)((LAS unsigned char*)buf + 139264))[twi];
; #pragma unroll
;     for (int m = 0; m < R; ++m) { const v2f v = buf[base + m * stride]; x[m] = cf{v.x, v.y}; }
;     const cf w{wv.x, wv.y};
;     if (INV) dit_reg<LR>(x, w); else dif_reg<LR>(x, w);
; #pragma unroll
;     for (int m = 0; m < R; ++m) buf[base + m * stride] = mkv2(x[m].x, x[m].y);
; }
.LBB0_363:
	v_or_b32_e32 v81, s0, v79
	v_lshlrev_b32_e32 v82, 3, v81
	v_ashrrev_i32_e32 v81, 1, v81
	v_add3_u32 v81, v78, v82, v81
	ds_read2_b64 v[82:85], v81 offset1:17
	ds_read2_b64 v[86:89], v81 offset0:34 offset1:51
	ds_read2_b64 v[90:93], v81 offset0:68 offset1:85
	ds_read2_b64 v[94:97], v81 offset0:102 offset1:119
	s_movk_i32 s0, 0x200
	v_or_b32_e32 v126, s0, v79
	v_lshlrev_b32_e32 v130, 3, v126
	v_ashrrev_i32_e32 v126, 1, v126
	v_add3_u32 v126, v78, v130, v126
	ds_read2_b64 v[132:135], v126 offset1:17
	ds_read2_b64 v[136:139], v126 offset0:34 offset1:51
	ds_read2_b64 v[140:143], v126 offset0:68 offset1:85
	ds_read2_b64 v[152:155], v126 offset0:102 offset1:119
	s_waitcnt lgkmcnt(4)
	v_pk_add_f32 v[110:111], v[82:83], v[90:91] neg_lo:[0,1] neg_hi:[0,1]
	v_pk_add_f32 v[112:113], v[84:85], v[92:93] neg_lo:[0,1] neg_hi:[0,1]
	v_pk_add_f32 v[114:115], v[86:87], v[94:95] neg_lo:[0,1] neg_hi:[0,1]
	v_pk_add_f32 v[116:117], v[88:89], v[96:97] neg_lo:[0,1] neg_hi:[0,1]
	v_pk_add_f32 v[82:83], v[82:83], v[90:91]
	v_pk_add_f32 v[84:85], v[84:85], v[92:93]
	v_pk_add_f32 v[86:87], v[86:87], v[94:95]
	v_pk_add_f32 v[88:89], v[88:89], v[96:97]
	v_pk_mul_f32 v[90:91], v[110:111], v[204:205] op_sel:[1,1] op_sel_hi:[1,0]
	v_pk_mul_f32 v[92:93], v[112:113], v[210:211] op_sel:[1,1] op_sel_hi:[1,0]
	v_pk_mul_f32 v[94:95], v[114:115], v[204:205] op_sel:[1,0] op_sel_hi:[1,1]
	v_pk_mul_f32 v[96:97], v[116:117], v[212:213] op_sel:[1,1] op_sel_hi:[1,0]
	v_pk_fma_f32 v[90:91], v[110:111], v[204:205], v[90:91] op_sel:[0,0,0] op_sel_hi:[0,1,1] neg_lo:[0,0,1] neg_hi:[0,0,0]
	v_pk_fma_f32 v[92:93], v[112:113], v[210:211], v[92:93] op_sel:[0,0,0] op_sel_hi:[0,1,1] neg_lo:[0,0,1] neg_hi:[0,0,0]
	v_pk_fma_f32 v[94:95], v[114:115], v[204:205], v[94:95] op_sel:[0,1,0] op_sel_hi:[0,0,1] neg_lo:[0,0,0] neg_hi:[0,1,0]
	v_pk_fma_f32 v[96:97], v[116:117], v[212:213], v[96:97] op_sel:[0,0,0] op_sel_hi:[0,1,1] neg_lo:[0,0,1] neg_hi:[0,0,0]
	v_pk_add_f32 v[110:111], v[82:83], v[86:87] neg_lo:[0,1] neg_hi:[0,1]
	v_pk_add_f32 v[112:113], v[84:85], v[88:89] neg_lo:[0,1] neg_hi:[0,1]
	v_pk_add_f32 v[114:115], v[90:91], v[94:95] neg_lo:[0,1] neg_hi:[0,1]
	v_pk_add_f32 v[116:117], v[92:93], v[96:97] neg_lo:[0,1] neg_hi:[0,1]
	v_pk_add_f32 v[82:83], v[82:83], v[86:87]
	v_pk_add_f32 v[84:85], v[84:85], v[88:89]
	v_pk_add_f32 v[90:91], v[90:91], v[94:95]
	v_pk_add_f32 v[92:93], v[92:93], v[96:97]
	v_pk_mul_f32 v[86:87], v[110:111], v[206:207] op_sel:[1,1] op_sel_hi:[1,0]
	v_pk_mul_f32 v[88:89], v[112:113], v[206:207] op_sel:[1,0] op_sel_hi:[1,1]
	v_pk_mul_f32 v[94:95], v[114:115], v[206:207] op_sel:[1,1] op_sel_hi:[1,0]
	v_pk_mul_f32 v[96:97], v[116:117], v[206:207] op_sel:[1,0] op_sel_hi:[1,1]
	v_pk_fma_f32 v[86:87], v[110:111], v[206:207], v[86:87] op_sel:[0,0,0] op_sel_hi:[0,1,1] neg_lo:[0,0,1] neg_hi:[0,0,0]
	v_pk_fma_f32 v[88:89], v[112:113], v[206:207], v[88:89] op_sel:[0,1,0] op_sel_hi:[0,0,1] neg_lo:[0,0,0] neg_hi:[0,1,0]
	v_pk_fma_f32 v[94:95], v[114:115], v[206:207], v[94:95] op_sel:[0,0,0] op_sel_hi:[0,1,1] neg_lo:[0,0,1] neg_hi:[0,0,0]
	v_pk_fma_f32 v[96:97], v[116:117], v[206:207], v[96:97] op_sel:[0,1,0] op_sel_hi:[0,0,1] neg_lo:[0,0,0] neg_hi:[0,1,0]
	v_pk_add_f32 v[110:111], v[82:83], v[84:85] neg_lo:[0,1] neg_hi:[0,1]
	v_pk_add_f32 v[112:113], v[86:87], v[88:89] neg_lo:[0,1] neg_hi:[0,1]
	v_pk_add_f32 v[114:115], v[90:91], v[92:93] neg_lo:[0,1] neg_hi:[0,1]
	v_pk_add_f32 v[116:117], v[94:95], v[96:97] neg_lo:[0,1] neg_hi:[0,1]
	v_pk_add_f32 v[82:83], v[82:83], v[84:85]
	v_pk_add_f32 v[86:87], v[86:87], v[88:89]
	v_pk_add_f32 v[90:91], v[90:91], v[92:93]
	v_pk_add_f32 v[94:95], v[94:95], v[96:97]
	v_pk_mul_f32 v[84:85], v[110:111], v[208:209] op_sel:[1,1] op_sel_hi:[1,0]
	v_pk_mul_f32 v[88:89], v[112:113], v[208:209] op_sel:[1,1] op_sel_hi:[1,0]
	v_pk_mul_f32 v[92:93], v[114:115], v[208:209] op_sel:[1,1] op_sel_hi:[1,0]
	v_pk_mul_f32 v[96:97], v[116:117], v[208:209] op_sel:[1,1] op_sel_hi:[1,0]
	v_pk_fma_f32 v[84:85], v[110:111], v[208:209], v[84:85] op_sel:[0,0,0] op_sel_hi:[0,1,1] neg_lo:[0,0,1] neg_hi:[0,0,0]
	v_pk_fma_f32 v[88:89], v[112:113], v[208:209], v[88:89] op_sel:[0,0,0] op_sel_hi:[0,1,1] neg_lo:[0,0,1] neg_hi:[0,0,0]
	v_pk_fma_f32 v[92:93], v[114:115], v[208:209], v[92:93] op_sel:[0,0,0] op_sel_hi:[0,1,1] neg_lo:[0,0,1] neg_hi:[0,0,0]
	v_pk_fma_f32 v[96:97], v[116:117], v[208:209], v[96:97] op_sel:[0,0,0] op_sel_hi:[0,1,1] neg_lo:[0,0,1] neg_hi:[0,0,0]
	ds_write2_b64 v81, v[82:83], v[84:85] offset1:17
	ds_write2_b64 v81, v[86:87], v[88:89] offset0:34 offset1:51
	ds_write2_b64 v81, v[90:91], v[92:93] offset0:68 offset1:85
	ds_write2_b64 v81, v[94:95], v[96:97] offset0:102 offset1:119
	s_waitcnt lgkmcnt(4)
; __device__ __forceinline__ int otid() { int t = threadIdx.x; asm volatile("" : "+v"(t)); return t; }
; __device__ __forceinline__ cf twc(cf ws, int k16) { if (k16 == 0) return ws; if (k16 == 4) return cf{ws.y, -ws.x}; return cmul(ws, cf{c16(k16), -s16(k16)}); }
; template <int LR> __device__ __forceinline__ void dif_reg(cf (&x)[1 << LR], cf w) {
;     constexpr int R = 1 << LR; cf ws = w;
; #pragma unroll
;     for (int s = 0; s < LR; ++s) { const int half = R >> (s + 1);
; #pragma unroll
;         for (int m0 = 0; m0 < R; m0 += 2 * half)
; #pragma unroll
;             for (int mm = 0; mm < half; ++mm) { const int ia = m0 + mm, ib = ia + half; const cf a = x[ia], b = x[ib];
;                 x[ia] = cf{a.x + b.x, a.y + b.y}; const cf d{a.x - b.x, a.y - b.y};
;                 x[ib] = cmul(d, twc(ws, (mm << s) * (16 / R))); }
;         ws = cmul(ws, ws); }
; }
; __device__ __forceinline__ void fft_conv(ldsf2 buf, const LAS unsigned* spec) {
;     ...
;     { const int tid = otid(); cf x[16];
; #pragma unroll
;       for (int m = 0; m < 16; ++m) { const v2f v = buf[tid * 17 + m]; x[m] = cf{v.x, v.y}; }
;       dif_reg<4>(x, cf{1.0f, 0.0f});
; #pragma unroll
;       for (int m = 0; m < 16; ++m) { const h2_t hv = __builtin_bit_cast(h2_t, spec[tid * 17 + m]); x[m] = cmul(x[m], cf{(float)hv.x, (float)hv.y}); }
	v_pk_add_f32 v[166:167], v[132:133], v[140:141] neg_lo:[0,1] neg_hi:[0,1]
	v_pk_add_f32 v[168:169], v[134:135], v[142:143] neg_lo:[0,1] neg_hi:[0,1]
	v_pk_add_f32 v[170:171], v[136:137], v[152:153] neg_lo:[0,1] neg_hi:[0,1]
	v_pk_add_f32 v[172:173], v[138:139], v[154:155] neg_lo:[0,1] neg_hi:[0,1]
	v_pk_add_f32 v[132:133], v[132:133], v[140:141]
	v_pk_add_f32 v[134:135], v[134:135], v[142:143]
	v_pk_add_f32 v[136:137], v[136:137], v[152:153]
	v_pk_add_f32 v[138:139], v[138:139], v[154:155]
	v_pk_mul_f32 v[140:141], v[166:167], v[204:205] op_sel:[1,1] op_sel_hi:[1,0]
	v_pk_mul_f32 v[142:143], v[168:169], v[210:211] op_sel:[1,1] op_sel_hi:[1,0]
	v_pk_mul_f32 v[152:153], v[170:171], v[204:205] op_sel:[1,0] op_sel_hi:[1,1]
	v_pk_mul_f32 v[154:155], v[172:173], v[212:213] op_sel:[1,1] op_sel_hi:[1,0]
	v_pk_fma_f32 v[140:141], v[166:167], v[204:205], v[140:141] op_sel:[0,0,0] op_sel_hi:[0,1,1] neg_lo:[0,0,1] neg_hi:[0,0,0]
	v_pk_fma_f32 v[142:143], v[168:169], v[210:211], v[142:143] op_sel:[0,0,0] op_sel_hi:[0,1,1] neg_lo:[0,0,1] neg_hi:[0,0,0]
	v_pk_fma_f32 v[152:153], v[170:171], v[204:205], v[152:153] op_sel:[0,1,0] op_sel_hi:[0,0,1] neg_lo:[0,0,0] neg_hi:[0,1,0]
	v_pk_fma_f32 v[154:155], v[172:173], v[212:213], v[154:155] op_sel:[0,0,0] op_sel_hi:[0,1,1] neg_lo:[0,0,1] neg_hi:[0,0,0]
	v_pk_add_f32 v[166:167], v[132:133], v[136:137] neg_lo:[0,1] neg_hi:[0,1]
	v_pk_add_f32 v[168:169], v[134:135], v[138:139] neg_lo:[0,1] neg_hi:[0,1]
	v_pk_add_f32 v[170:171], v[140:141], v[152:153] neg_lo:[0,1] neg_hi:[0,1]
	v_pk_add_f32 v[172:173], v[142:143], v[154:155] neg_lo:[0,1] neg_hi:[0,1]
	v_pk_add_f32 v[132:133], v[132:133], v[136:137]
	v_pk_add_f32 v[134:135], v[134:135], v[138:139]
	v_pk_add_f32 v[140:141], v[140:141], v[152:153]
	v_pk_add_f32 v[142:143], v[142:143], v[154:155]
	v_pk_mul_f32 v[136:137], v[166:167], v[206:207] op_sel:[1,1] op_sel_hi:[1,0]
	v_pk_mul_f32 v[138:139], v[168:169], v[206:207] op_sel:[1,0] op_sel_hi:[1,1]
	v_pk_mul_f32 v[152:153], v[170:171], v[206:207] op_sel:[1,1] op_sel_hi:[1,0]
	v_pk_mul_f32 v[154:155], v[172:173], v[206:207] op_sel:[1,0] op_sel_hi:[1,1]
	v_pk_fma_f32 v[136:137], v[166:167], v[206:207], v[136:137] op_sel:[0,0,0] op_sel_hi:[0,1,1] neg_lo:[0,0,1] neg_hi:[0,0,0]
	v_pk_fma_f32 v[138:139], v[168:169], v[206:207], v[138:139] op_sel:[0,1,0] op_sel_hi:[0,0,1] neg_lo:[0,0,0] neg_hi:[0,1,0]
	v_pk_fma_f32 v[152:153], v[170:171], v[206:207], v[152:153] op_sel:[0,0,0] op_sel_hi:[0,1,1] neg_lo:[0,0,1] neg_hi:[0,0,0]
	v_pk_fma_f32 v[154:155], v[172:173], v[206:207], v[154:155] op_sel:[0,1,0] op_sel_hi:[0,0,1] neg_lo:[0,0,0] neg_hi:[0,1,0]
	v_pk_add_f32 v[166:167], v[132:133], v[134:135] neg_lo:[0,1] neg_hi:[0,1]
	v_pk_add_f32 v[168:169], v[136:137], v[138:139] neg_lo:[0,1] neg_hi:[0,1]
	v_pk_add_f32 v[170:171], v[140:141], v[142:143] neg_lo:[0,1] neg_hi:[0,1]
	v_pk_add_f32 v[172:173], v[152:153], v[154:155] neg_lo:[0,1] neg_hi:[0,1]
	v_pk_add_f32 v[132:133], v[132:133], v[134:135]
	v_pk_add_f32 v[136:137], v[136:137], v[138:139]
	v_pk_add_f32 v[140:141], v[140:141], v[142:143]
	v_pk_add_f32 v[152:153], v[152:153], v[154:155]
	v_pk_mul_f32 v[134:135], v[166:167], v[208:209] op_sel:[1,1] op_sel_hi:[1,0]
	v_pk_mul_f32 v[138:139], v[168:169], v[208:209] op_sel:[1,1] op_sel_hi:[1,0]
	v_pk_mul_f32 v[142:143], v[170:171], v[208:209] op_sel:[1,1] op_sel_hi:[1,0]
	v_pk_mul_f32 v[154:155], v[172:173], v[208:209] op_sel:[1,1] op_sel_hi:[1,0]
	v_pk_fma_f32 v[134:135], v[166:167], v[208:209], v[134:135] op_sel:[0,0,0] op_sel_hi:[0,1,1] neg_lo:[0,0,1] neg_hi:[0,0,0]
	v_pk_fma_f32 v[138:139], v[168:169], v[208:209], v[138:139] op_sel:[0,0,0] op_sel_hi:[0,1,1] neg_lo:[0,0,1] neg_hi:[0,0,0]
	v_pk_fma_f32 v[142:143], v[170:171], v[208:209], v[142:143] op_sel:[0,0,0] op_sel_hi:[0,1,1] neg_lo:[0,0,1] neg_hi:[0,0,0]
	v_pk_fma_f32 v[154:155], v[172:173], v[208:209], v[154:155] op_sel:[0,0,0] op_sel_hi:[0,1,1] neg_lo:[0,0,1] neg_hi:[0,0,0]
	ds_write2_b64 v126, v[132:133], v[134:135] offset1:17
	ds_write2_b64 v126, v[136:137], v[138:139] offset0:34 offset1:51
	ds_write2_b64 v126, v[140:141], v[142:143] offset0:68 offset1:85
	ds_write2_b64 v126, v[152:153], v[154:155] offset0:102 offset1:119
	s_mov_b64 s[10:11], 0
	v_mov_b32_e32 v162, v195
	s_movk_i32 s0, 0x88
	s_waitcnt lgkmcnt(0)
	s_mov_b32 s86, s63
	v_mul_lo_u32 v78, v162, s0
	v_add_u32_e32 v151, 0, v78
	ds_read2_b64 v[80:83], v151 offset1:1
	ds_read2_b64 v[84:87], v151 offset0:2 offset1:3
	ds_read2_b64 v[98:101], v151 offset0:4 offset1:5
	ds_read2_b64 v[102:105], v151 offset0:6 offset1:7
	ds_read2_b64 v[106:109], v151 offset0:8 offset1:9
	ds_read2_b64 v[110:113], v151 offset0:10 offset1:11
	ds_read2_b64 v[126:129], v151 offset0:12 offset1:13
	ds_read2_b64 v[134:137], v151 offset0:14 offset1:15
	s_mov_b32 s10, s63
	s_mov_b32 s11, s16
	s_mov_b32 s17, s5
	s_mov_b32 s0, s16
	s_mov_b32 s1, s4
	s_mov_b32 s0, s63
	s_mov_b32 s1, s5
	s_mov_b32 s0, s87
	s_mov_b32 s1, s4
	s_mov_b32 s1, s5
	s_mov_b32 s35, s4
	s_mov_b32 s12, s63
	s_movk_i32 s0, 0x44
	v_mul_lo_u32 v114, v162, s0
	v_add_u32_e32 v114, 0, v114
	v_add_u32_e32 v114, 0x19800, v114
	ds_read2_b32 v[160:161], v114 offset1:1
	ds_read2_b32 v[162:163], v114 offset0:2 offset1:3
	ds_read2_b32 v[164:165], v114 offset0:4 offset1:5
	ds_read2_b32 v[166:167], v114 offset0:6 offset1:7
	ds_read2_b32 v[168:169], v114 offset0:8 offset1:9
	ds_read2_b32 v[142:143], v114 offset0:10 offset1:11
	ds_read2_b32 v[138:139], v114 offset0:12 offset1:13
	ds_read2_b32 v[172:173], v114 offset0:14 offset1:15
	s_mov_b32 s0, s5
	s_mov_b64 s[14:15], -1
	s_mov_b32 s35, s13
	s_mov_b32 s0, s13
	s_waitcnt lgkmcnt(8)
; __device__ __forceinline__ cf twc(cf ws, int k16) { if (k16 == 0) return ws; if (k16 == 4) return cf{ws.y, -ws.x}; return cmul(ws, cf{c16(k16), -s16(k16)}); }
; template <int LR> __device__ __forceinline__ void dif_reg(cf (&x)[1 << LR], cf w) {
;     constexpr int R = 1 << LR; cf ws = w;
; #pragma unroll
;     for (int s = 0; s < LR; ++s) { const int half = R >> (s + 1);
; #pragma unroll
;         for (int m0 = 0; m0 < R; m0 += 2 * half)
; #pragma unroll
;             for (int mm = 0; mm < half; ++mm) { const int ia = m0 + mm, ib = ia + half; const cf a = x[ia], b = x[ib];
;                 x[ia] = cf{a.x + b.x, a.y + b.y}; const cf d{a.x - b.x, a.y - b.y};
;                 x[ib] = cmul(d, twc(ws, (mm << s) * (16 / R))); }
;         ws = cmul(ws, ws); }
; }
; __device__ __forceinline__ void fft_conv(ldsf2 buf, const LAS unsigned* spec) {
;     ...
;       dif_reg<4>(x, cf{1.0f, 0.0f});
	v_pk_add_f32 v[88:89], v[80:81], v[106:107]
	v_pk_add_f32 v[90:91], v[82:83], v[108:109]
	v_pk_add_f32 v[92:93], v[84:85], v[110:111]
	v_pk_add_f32 v[94:95], v[86:87], v[112:113]
	v_pk_add_f32 v[80:81], v[80:81], v[106:107] neg_lo:[0,1] neg_hi:[0,1]
	v_pk_add_f32 v[82:83], v[82:83], v[108:109] neg_lo:[0,1] neg_hi:[0,1]
	v_pk_add_f32 v[84:85], v[84:85], v[110:111] neg_lo:[0,1] neg_hi:[0,1]
	v_pk_add_f32 v[86:87], v[86:87], v[112:113] neg_lo:[0,1] neg_hi:[0,1]
	v_pk_mul_f32 v[108:109], v[82:83], s[4:5] op_sel:[1,1] op_sel_hi:[1,0] neg_lo:[0,1] neg_hi:[0,0]
	v_pk_mul_f32 v[110:111], v[84:85], s[16:17] op_sel:[1,0] op_sel_hi:[1,0] neg_lo:[0,1] neg_hi:[0,0]
	v_pk_mul_f32 v[112:113], v[86:87], s[4:5] op_sel:[1,0] op_sel_hi:[1,1] neg_lo:[0,1] neg_hi:[0,0]
	v_pk_fma_f32 v[108:109], v[82:83], s[4:5], v[108:109] op_sel:[0,0,0] op_sel_hi:[0,1,1] neg_lo:[0,0,1] neg_hi:[0,1,0]
	v_pk_fma_f32 v[110:111], v[84:85], s[16:17], v[110:111] op_sel:[0,0,0] op_sel_hi:[0,0,1] neg_lo:[0,0,1] neg_hi:[0,1,0]
	v_pk_fma_f32 v[112:113], v[86:87], s[4:5], v[112:113] op_sel:[0,1,0] op_sel_hi:[0,0,1] neg_lo:[0,0,1] neg_hi:[0,1,0]
	v_pk_add_f32 v[96:97], v[98:99], v[126:127]
	v_pk_add_f32 v[116:117], v[100:101], v[128:129]
	v_pk_add_f32 v[118:119], v[102:103], v[134:135]
	v_pk_add_f32 v[120:121], v[104:105], v[136:137]
	v_pk_add_f32 v[98:99], v[98:99], v[126:127] op_sel:[1,1] op_sel_hi:[0,0] neg_lo:[0,1] neg_hi:[1,0]
	v_pk_add_f32 v[100:101], v[100:101], v[128:129] neg_lo:[0,1] neg_hi:[0,1]
	v_pk_add_f32 v[102:103], v[102:103], v[134:135] neg_lo:[0,1] neg_hi:[0,1]
	v_pk_add_f32 v[104:105], v[104:105], v[136:137] neg_lo:[0,1] neg_hi:[0,1]
	v_pk_mul_f32 v[128:129], v[100:101], s[4:5] op_sel:[1,0] op_sel_hi:[1,1] neg_lo:[0,1] neg_hi:[0,1]
	v_pk_mul_f32 v[134:135], v[102:103], s[16:17] op_sel:[1,0] op_sel_hi:[1,0] neg_lo:[0,1] neg_hi:[0,1]
	v_pk_mul_f32 v[136:137], v[104:105], s[4:5] op_sel:[1,1] op_sel_hi:[1,0] neg_lo:[0,1] neg_hi:[0,1]
	v_pk_fma_f32 v[128:129], v[100:101], s[4:5], v[128:129] op_sel:[0,1,0] op_sel_hi:[0,0,1] neg_lo:[0,1,1] neg_hi:[0,1,0]
	v_pk_fma_f32 v[134:135], v[102:103], s[16:17], v[134:135] op_sel:[0,0,0] op_sel_hi:[0,0,1] neg_lo:[0,1,1] neg_hi:[0,1,0]
	v_pk_fma_f32 v[136:137], v[104:105], s[4:5], v[136:137] op_sel:[0,0,0] op_sel_hi:[0,1,1] neg_lo:[0,1,1] neg_hi:[0,1,0]
	v_pk_add_f32 v[122:123], v[88:89], v[96:97]
	v_pk_add_f32 v[124:125], v[90:91], v[116:117]
	v_pk_add_f32 v[130:131], v[92:93], v[118:119]
	v_pk_add_f32 v[132:133], v[94:95], v[120:121]
	v_pk_add_f32 v[88:89], v[88:89], v[96:97] neg_lo:[0,1] neg_hi:[0,1]
	v_pk_add_f32 v[90:91], v[90:91], v[116:117] neg_lo:[0,1] neg_hi:[0,1]
	v_pk_add_f32 v[92:93], v[92:93], v[118:119] op_sel:[1,1] op_sel_hi:[0,0] neg_lo:[0,1] neg_hi:[1,0]
	v_pk_add_f32 v[94:95], v[94:95], v[120:121] neg_lo:[0,1] neg_hi:[0,1]
	v_pk_mul_f32 v[116:117], v[90:91], s[16:17] op_sel:[1,0] op_sel_hi:[1,0] neg_lo:[0,1] neg_hi:[0,0]
	v_pk_mul_f32 v[120:121], v[94:95], s[16:17] op_sel:[1,0] op_sel_hi:[1,0] neg_lo:[0,1] neg_hi:[0,1]
	v_pk_fma_f32 v[116:117], v[90:91], s[16:17], v[116:117] op_sel:[0,0,0] op_sel_hi:[0,0,1] neg_lo:[0,0,1] neg_hi:[0,1,0]
	v_pk_fma_f32 v[120:121], v[94:95], s[16:17], v[120:121] op_sel:[0,0,0] op_sel_hi:[0,0,1] neg_lo:[0,1,1] neg_hi:[0,1,0]
	v_pk_add_f32 v[140:141], v[80:81], v[98:99]
	v_pk_add_f32 v[152:153], v[108:109], v[128:129]
	v_pk_add_f32 v[154:155], v[110:111], v[134:135]
	v_pk_add_f32 v[156:157], v[112:113], v[136:137]
	v_pk_add_f32 v[80:81], v[80:81], v[98:99] neg_lo:[0,1] neg_hi:[0,1]
	v_pk_add_f32 v[108:109], v[108:109], v[128:129] neg_lo:[0,1] neg_hi:[0,1]
	v_pk_add_f32 v[110:111], v[110:111], v[134:135] op_sel:[1,1] op_sel_hi:[0,0] neg_lo:[0,1] neg_hi:[1,0]
	v_pk_add_f32 v[112:113], v[112:113], v[136:137] neg_lo:[0,1] neg_hi:[0,1]
	v_pk_mul_f32 v[128:129], v[108:109], s[16:17] op_sel:[1,0] op_sel_hi:[1,0] neg_lo:[0,1] neg_hi:[0,0]
	v_pk_mul_f32 v[136:137], v[112:113], s[16:17] op_sel:[1,0] op_sel_hi:[1,0] neg_lo:[0,1] neg_hi:[0,1]
	v_pk_fma_f32 v[128:129], v[108:109], s[16:17], v[128:129] op_sel:[0,0,0] op_sel_hi:[0,0,1] neg_lo:[0,0,1] neg_hi:[0,1,0]
	v_pk_fma_f32 v[136:137], v[112:113], s[16:17], v[136:137] op_sel:[0,0,0] op_sel_hi:[0,0,1] neg_lo:[0,1,1] neg_hi:[0,1,0]
	v_pk_add_f32 v[158:159], v[122:123], v[130:131]
	v_pk_add_f32 v[170:171], v[124:125], v[132:133]
	v_pk_add_f32 v[106:107], v[88:89], v[92:93]
	v_pk_add_f32 v[82:83], v[116:117], v[120:121]
	v_pk_add_f32 v[122:123], v[122:123], v[130:131] neg_lo:[0,1] neg_hi:[0,1]
	v_pk_add_f32 v[124:125], v[124:125], v[132:133] op_sel:[1,1] op_sel_hi:[0,0] neg_lo:[0,1] neg_hi:[1,0]
	v_pk_add_f32 v[88:89], v[88:89], v[92:93] neg_lo:[0,1] neg_hi:[0,1]
	v_pk_add_f32 v[116:117], v[116:117], v[120:121] op_sel:[1,1] op_sel_hi:[0,0] neg_lo:[0,1] neg_hi:[1,0]
	v_pk_add_f32 v[84:85], v[140:141], v[154:155]
	v_pk_add_f32 v[86:87], v[152:153], v[156:157]
	v_pk_add_f32 v[126:127], v[80:81], v[110:111]
	v_pk_add_f32 v[100:101], v[128:129], v[136:137]
	v_pk_add_f32 v[140:141], v[140:141], v[154:155] neg_lo:[0,1] neg_hi:[0,1]
	v_pk_add_f32 v[152:153], v[152:153], v[156:157] op_sel:[1,1] op_sel_hi:[0,0] neg_lo:[0,1] neg_hi:[1,0]
	v_pk_add_f32 v[80:81], v[80:81], v[110:111] neg_lo:[0,1] neg_hi:[0,1]
	v_pk_add_f32 v[128:129], v[128:129], v[136:137] op_sel:[1,1] op_sel_hi:[0,0] neg_lo:[0,1] neg_hi:[1,0]
	v_pk_add_f32 v[102:103], v[158:159], v[170:171]
	v_pk_add_f32 v[104:105], v[122:123], v[124:125]
	v_pk_add_f32 v[96:97], v[106:107], v[82:83]
	v_pk_add_f32 v[90:91], v[88:89], v[116:117]
	v_pk_add_f32 v[158:159], v[158:159], v[170:171] neg_lo:[0,1] neg_hi:[0,1]
	v_pk_add_f32 v[122:123], v[122:123], v[124:125] neg_lo:[0,1] neg_hi:[0,1]
	v_pk_add_f32 v[106:107], v[106:107], v[82:83] neg_lo:[0,1] neg_hi:[0,1]
	v_pk_add_f32 v[88:89], v[88:89], v[116:117] neg_lo:[0,1] neg_hi:[0,1]
	v_pk_add_f32 v[118:119], v[84:85], v[86:87]
	v_pk_add_f32 v[94:95], v[140:141], v[152:153]
	v_pk_add_f32 v[98:99], v[126:127], v[100:101]
	v_pk_add_f32 v[108:109], v[80:81], v[128:129]
	v_pk_add_f32 v[84:85], v[84:85], v[86:87] neg_lo:[0,1] neg_hi:[0,1]
	v_pk_add_f32 v[140:141], v[140:141], v[152:153] neg_lo:[0,1] neg_hi:[0,1]
	v_pk_add_f32 v[126:127], v[126:127], v[100:101] neg_lo:[0,1] neg_hi:[0,1]
	v_pk_add_f32 v[80:81], v[80:81], v[128:129] neg_lo:[0,1] neg_hi:[0,1]
	s_waitcnt lgkmcnt(0)
; __device__ __forceinline__ cf twc(cf ws, int k16) { if (k16 == 0) return ws; if (k16 == 4) return cf{ws.y, -ws.x}; return cmul(ws, cf{c16(k16), -s16(k16)}); }
; template <int LR> __device__ __forceinline__ void dit_reg(cf (&x)[1 << LR], cf w) {
;     constexpr int R = 1 << LR; cf wsv[LR]; wsv[0] = w;
; #pragma unroll
;     for (int s = 1; s < LR; ++s) wsv[s] = cmul(wsv[s - 1], wsv[s - 1]);
; #pragma unroll
;     for (int s = LR - 1; s >= 0; --s) { const int half = R >> (s + 1);
; #pragma unroll
;         for (int m0 = 0; m0 < R; m0 += 2 * half)
; #pragma unroll
;             for (int mm = 0; mm < half; ++mm) { const int ia = m0 + mm, ib = ia + half; const cf a = x[ia];
;                 const cf b = cmulc(x[ib], twc(wsv[s], (mm << s) * (16 / R)));
;                 x[ia] = cf{a.x + b.x, a.y + b.y}; x[ib] = cf{a.x - b.x, a.y - b.y}; } }
; __device__ __forceinline__ void fft_conv(ldsf2 buf, const LAS unsigned* spec) {
;     ...
;       for (int m = 0; m < 16; ++m) { const h2_t hv = __builtin_bit_cast(h2_t, spec[tid * 17 + m]); x[m] = cmul(x[m], cf{(float)hv.x, (float)hv.y}); }
;       dit_reg<4>(x, cf{1.0f, 0.0f});
	v_cvt_f32_f16_e32 v134, v160
	v_cvt_f32_f16_e32 v130, v161
	v_cvt_f32_f16_e32 v92, v162
	v_cvt_f32_f16_e32 v154, v163
	v_cvt_f32_f16_sdwa v135, v160 dst_sel:DWORD dst_unused:UNUSED_PAD src0_sel:WORD_1
	v_cvt_f32_f16_sdwa v131, v161 dst_sel:DWORD dst_unused:UNUSED_PAD src0_sel:WORD_1
	v_cvt_f32_f16_sdwa v93, v162 dst_sel:DWORD dst_unused:UNUSED_PAD src0_sel:WORD_1
	v_cvt_f32_f16_sdwa v155, v163 dst_sel:DWORD dst_unused:UNUSED_PAD src0_sel:WORD_1
	v_pk_mul_f32 v[112:113], v[102:103], v[134:135] op_sel:[1,1] op_sel_hi:[1,0]
	v_pk_mul_f32 v[132:133], v[158:159], v[130:131] op_sel:[1,1] op_sel_hi:[1,0]
	v_pk_mul_f32 v[120:121], v[104:105], v[92:93] op_sel:[1,1] op_sel_hi:[1,0]
	v_pk_mul_f32 v[156:157], v[122:123], v[154:155] op_sel:[1,1] op_sel_hi:[1,0]
	v_pk_fma_f32 v[134:135], v[102:103], v[134:135], v[112:113] op_sel:[0,0,0] op_sel_hi:[0,1,1] neg_lo:[0,0,1] neg_hi:[0,0,0]
	v_pk_fma_f32 v[130:131], v[158:159], v[130:131], v[132:133] op_sel:[0,0,0] op_sel_hi:[0,1,1] neg_lo:[0,0,1] neg_hi:[0,0,0]
	v_pk_fma_f32 v[92:93], v[104:105], v[92:93], v[120:121] op_sel:[0,0,0] op_sel_hi:[0,1,1] neg_lo:[0,0,1] neg_hi:[0,0,0]
	v_pk_fma_f32 v[154:155], v[122:123], v[154:155], v[156:157] op_sel:[0,0,0] op_sel_hi:[0,1,1] neg_lo:[0,0,1] neg_hi:[0,0,0]
	v_cvt_f32_f16_e32 v110, v164
	v_cvt_f32_f16_e32 v170, v165
	v_cvt_f32_f16_e32 v82, v166
	v_cvt_f32_f16_e32 v86, v167
	v_cvt_f32_f16_sdwa v111, v164 dst_sel:DWORD dst_unused:UNUSED_PAD src0_sel:WORD_1
	v_cvt_f32_f16_sdwa v171, v165 dst_sel:DWORD dst_unused:UNUSED_PAD src0_sel:WORD_1
	v_cvt_f32_f16_sdwa v83, v166 dst_sel:DWORD dst_unused:UNUSED_PAD src0_sel:WORD_1
	v_cvt_f32_f16_sdwa v87, v167 dst_sel:DWORD dst_unused:UNUSED_PAD src0_sel:WORD_1
	v_pk_mul_f32 v[136:137], v[96:97], v[110:111] op_sel:[1,1] op_sel_hi:[1,0]
	v_pk_mul_f32 v[124:125], v[106:107], v[170:171] op_sel:[1,1] op_sel_hi:[1,0]
	v_pk_mul_f32 v[116:117], v[90:91], v[82:83] op_sel:[1,1] op_sel_hi:[1,0]
	v_pk_mul_f32 v[152:153], v[88:89], v[86:87] op_sel:[1,1] op_sel_hi:[1,0]
	v_pk_fma_f32 v[110:111], v[96:97], v[110:111], v[136:137] op_sel:[0,0,0] op_sel_hi:[0,1,1] neg_lo:[0,0,1] neg_hi:[0,0,0]
	v_pk_fma_f32 v[170:171], v[106:107], v[170:171], v[124:125] op_sel:[0,0,0] op_sel_hi:[0,1,1] neg_lo:[0,0,1] neg_hi:[0,0,0]
	v_pk_fma_f32 v[82:83], v[90:91], v[82:83], v[116:117] op_sel:[0,0,0] op_sel_hi:[0,1,1] neg_lo:[0,0,1] neg_hi:[0,0,0]
	v_pk_fma_f32 v[86:87], v[88:89], v[86:87], v[152:153] op_sel:[0,0,0] op_sel_hi:[0,1,1] neg_lo:[0,0,1] neg_hi:[0,0,0]
	v_cvt_f32_f16_e32 v100, v168
	v_cvt_f32_f16_e32 v112, v169
	v_cvt_f32_f16_e32 v132, v142
	v_cvt_f32_f16_e32 v120, v143
	v_cvt_f32_f16_sdwa v101, v168 dst_sel:DWORD dst_unused:UNUSED_PAD src0_sel:WORD_1
	v_cvt_f32_f16_sdwa v113, v169 dst_sel:DWORD dst_unused:UNUSED_PAD src0_sel:WORD_1
	v_cvt_f32_f16_sdwa v133, v142 dst_sel:DWORD dst_unused:UNUSED_PAD src0_sel:WORD_1
	v_cvt_f32_f16_sdwa v121, v143 dst_sel:DWORD dst_unused:UNUSED_PAD src0_sel:WORD_1
	v_pk_mul_f32 v[128:129], v[118:119], v[100:101] op_sel:[1,1] op_sel_hi:[1,0]
	v_pk_mul_f32 v[102:103], v[84:85], v[112:113] op_sel:[1,1] op_sel_hi:[1,0]
	v_pk_mul_f32 v[158:159], v[94:95], v[132:133] op_sel:[1,1] op_sel_hi:[1,0]
	v_pk_mul_f32 v[104:105], v[140:141], v[120:121] op_sel:[1,1] op_sel_hi:[1,0]
	v_pk_fma_f32 v[100:101], v[118:119], v[100:101], v[128:129] op_sel:[0,0,0] op_sel_hi:[0,1,1] neg_lo:[0,0,1] neg_hi:[0,0,0]
	v_pk_fma_f32 v[112:113], v[84:85], v[112:113], v[102:103] op_sel:[0,0,0] op_sel_hi:[0,1,1] neg_lo:[0,0,1] neg_hi:[0,0,0]
	v_pk_fma_f32 v[132:133], v[94:95], v[132:133], v[158:159] op_sel:[0,0,0] op_sel_hi:[0,1,1] neg_lo:[0,0,1] neg_hi:[0,0,0]
	v_pk_fma_f32 v[120:121], v[140:141], v[120:121], v[104:105] op_sel:[0,0,0] op_sel_hi:[0,1,1] neg_lo:[0,0,1] neg_hi:[0,0,0]
	v_cvt_f32_f16_e32 v156, v138
	v_cvt_f32_f16_e32 v136, v139
	v_cvt_f32_f16_e32 v124, v172
	v_cvt_f32_f16_e32 v116, v173
	v_cvt_f32_f16_sdwa v157, v138 dst_sel:DWORD dst_unused:UNUSED_PAD src0_sel:WORD_1
	v_cvt_f32_f16_sdwa v137, v139 dst_sel:DWORD dst_unused:UNUSED_PAD src0_sel:WORD_1
	v_cvt_f32_f16_sdwa v125, v172 dst_sel:DWORD dst_unused:UNUSED_PAD src0_sel:WORD_1
	v_cvt_f32_f16_sdwa v117, v173 dst_sel:DWORD dst_unused:UNUSED_PAD src0_sel:WORD_1
	v_pk_mul_f32 v[122:123], v[98:99], v[156:157] op_sel:[1,1] op_sel_hi:[1,0]
	v_pk_mul_f32 v[96:97], v[126:127], v[136:137] op_sel:[1,1] op_sel_hi:[1,0]
	v_pk_mul_f32 v[106:107], v[108:109], v[124:125] op_sel:[1,1] op_sel_hi:[1,0]
	v_pk_mul_f32 v[90:91], v[80:81], v[116:117] op_sel:[1,1] op_sel_hi:[1,0]
	v_pk_fma_f32 v[156:157], v[98:99], v[156:157], v[122:123] op_sel:[0,0,0] op_sel_hi:[0,1,1] neg_lo:[0,0,1] neg_hi:[0,0,0]
	v_pk_fma_f32 v[136:137], v[126:127], v[136:137], v[96:97] op_sel:[0,0,0] op_sel_hi:[0,1,1] neg_lo:[0,0,1] neg_hi:[0,0,0]
	v_pk_fma_f32 v[124:125], v[108:109], v[124:125], v[106:107] op_sel:[0,0,0] op_sel_hi:[0,1,1] neg_lo:[0,0,1] neg_hi:[0,0,0]
	v_pk_fma_f32 v[116:117], v[80:81], v[116:117], v[90:91] op_sel:[0,0,0] op_sel_hi:[0,1,1] neg_lo:[0,0,1] neg_hi:[0,0,0]
	v_pk_add_f32 v[152:153], v[134:135], v[130:131]
	v_pk_add_f32 v[88:89], v[92:93], v[154:155]
	v_pk_add_f32 v[128:129], v[110:111], v[170:171]
	v_pk_add_f32 v[118:119], v[82:83], v[86:87]
	v_pk_add_f32 v[134:135], v[134:135], v[130:131] neg_lo:[0,1] neg_hi:[0,1]
	v_pk_add_f32 v[92:93], v[92:93], v[154:155] neg_lo:[0,1] neg_hi:[0,1]
	v_pk_add_f32 v[110:111], v[110:111], v[170:171] neg_lo:[0,1] neg_hi:[0,1]
	v_pk_add_f32 v[82:83], v[82:83], v[86:87] neg_lo:[0,1] neg_hi:[0,1]
	v_pk_add_f32 v[102:103], v[100:101], v[112:113]
	v_pk_add_f32 v[84:85], v[132:133], v[120:121]
	v_pk_add_f32 v[158:159], v[156:157], v[136:137]
	v_pk_add_f32 v[94:95], v[124:125], v[116:117]
; __device__ __forceinline__ cf twc(cf ws, int k16) { if (k16 == 0) return ws; if (k16 == 4) return cf{ws.y, -ws.x}; return cmul(ws, cf{c16(k16), -s16(k16)}); }
; __device__ __forceinline__ void wave_lds_fence() { asm volatile("s_waitcnt lgkmcnt(0)" ::: "memory"); }
; template <int LR> __device__ __forceinline__ void dit_reg(cf (&x)[1 << LR], cf w) {
;     constexpr int R = 1 << LR; cf wsv[LR]; wsv[0] = w;
; #pragma unroll
;     for (int s = 1; s < LR; ++s) wsv[s] = cmul(wsv[s - 1], wsv[s - 1]);
; #pragma unroll
;     for (int s = LR - 1; s >= 0; --s) { const int half = R >> (s + 1);
; #pragma unroll
;         for (int m0 = 0; m0 < R; m0 += 2 * half)
; #pragma unroll
;             for (int mm = 0; mm < half; ++mm) { const int ia = m0 + mm, ib = ia + half; const cf a = x[ia];
;                 const cf b = cmulc(x[ib], twc(wsv[s], (mm << s) * (16 / R)));
;                 x[ia] = cf{a.x + b.x, a.y + b.y}; x[ib] = cf{a.x - b.x, a.y - b.y}; } }
; __device__ __forceinline__ void fft_conv(ldsf2 buf, const LAS unsigned* spec) {
;     ...
; #pragma unroll
;       for (int m = 0; m < 16; ++m) buf[tid * 17 + m] = mkv2(x[m].x, x[m].y); }
;     wave_lds_fence();
	v_pk_add_f32 v[100:101], v[100:101], v[112:113] neg_lo:[0,1] neg_hi:[0,1]
	v_pk_add_f32 v[132:133], v[132:133], v[120:121] neg_lo:[0,1] neg_hi:[0,1]
	v_pk_add_f32 v[156:157], v[156:157], v[136:137] neg_lo:[0,1] neg_hi:[0,1]
	v_pk_add_f32 v[124:125], v[124:125], v[116:117] neg_lo:[0,1] neg_hi:[0,1]
	v_pk_add_f32 v[104:105], v[152:153], v[88:89]
	v_pk_add_f32 v[140:141], v[134:135], v[92:93] op_sel:[0,1] op_sel_hi:[1,0] neg_lo:[0,1] neg_hi:[0,0]
	v_pk_add_f32 v[122:123], v[128:129], v[118:119]
	v_pk_add_f32 v[98:99], v[110:111], v[82:83] op_sel:[0,1] op_sel_hi:[1,0] neg_lo:[0,1] neg_hi:[0,0]
	v_pk_add_f32 v[152:153], v[152:153], v[88:89] neg_lo:[0,1] neg_hi:[0,1]
	v_pk_add_f32 v[134:135], v[134:135], v[92:93] op_sel:[0,1] op_sel_hi:[1,0] neg_lo:[0,0] neg_hi:[0,1]
	v_pk_add_f32 v[128:129], v[128:129], v[118:119] neg_lo:[0,1] neg_hi:[0,1]
	v_pk_add_f32 v[110:111], v[110:111], v[82:83] op_sel:[0,1] op_sel_hi:[1,0] neg_lo:[0,0] neg_hi:[0,1]
	v_pk_add_f32 v[96:97], v[102:103], v[84:85]
	v_pk_add_f32 v[126:127], v[100:101], v[132:133] op_sel:[0,1] op_sel_hi:[1,0] neg_lo:[0,1] neg_hi:[0,0]
	v_pk_add_f32 v[106:107], v[158:159], v[94:95]
	v_pk_add_f32 v[108:109], v[156:157], v[124:125] op_sel:[0,1] op_sel_hi:[1,0] neg_lo:[0,1] neg_hi:[0,0]
	v_pk_add_f32 v[102:103], v[102:103], v[84:85] neg_lo:[0,1] neg_hi:[0,1]
	v_pk_add_f32 v[100:101], v[100:101], v[132:133] op_sel:[0,1] op_sel_hi:[1,0] neg_lo:[0,0] neg_hi:[0,1]
	v_pk_add_f32 v[158:159], v[158:159], v[94:95] neg_lo:[0,1] neg_hi:[0,1]
	v_pk_add_f32 v[156:157], v[156:157], v[124:125] op_sel:[0,1] op_sel_hi:[1,0] neg_lo:[0,0] neg_hi:[0,1]
	v_pk_add_f32 v[90:91], v[104:105], v[122:123]
	v_pk_mul_f32 v[80:81], v[98:99], s[16:17] op_sel:[1,0] op_sel_hi:[1,0] neg_lo:[0,1] neg_hi:[0,0]
	v_pk_add_f32 v[130:131], v[152:153], v[128:129] op_sel:[0,1] op_sel_hi:[1,0] neg_lo:[0,1] neg_hi:[0,0]
	v_pk_mul_f32 v[154:155], v[110:111], s[16:17] op_sel:[1,0] op_sel_hi:[1,0] neg_lo:[0,1] neg_hi:[0,1]
	v_pk_add_f32 v[104:105], v[104:105], v[122:123] neg_lo:[0,1] neg_hi:[0,1]
	v_pk_fma_f32 v[80:81], v[98:99], s[16:17], v[80:81] op_sel:[0,0,0] op_sel_hi:[0,0,1] neg_lo:[0,0,0] neg_hi:[0,0,0]
	v_pk_add_f32 v[152:153], v[152:153], v[128:129] op_sel:[0,1] op_sel_hi:[1,0] neg_lo:[0,0] neg_hi:[0,1]
	v_pk_fma_f32 v[154:155], v[110:111], s[16:17], v[154:155] op_sel:[0,0,0] op_sel_hi:[0,0,1] neg_lo:[0,1,0] neg_hi:[0,0,0]
	v_pk_add_f32 v[98:99], v[140:141], v[80:81] neg_lo:[0,1] neg_hi:[0,1]
	v_pk_add_f32 v[110:111], v[134:135], v[154:155] neg_lo:[0,1] neg_hi:[0,1]
	v_pk_add_f32 v[140:141], v[140:141], v[80:81]
	v_pk_add_f32 v[134:135], v[134:135], v[154:155]
	v_pk_add_f32 v[170:171], v[96:97], v[106:107]
	v_pk_mul_f32 v[86:87], v[108:109], s[16:17] op_sel:[1,0] op_sel_hi:[1,0] neg_lo:[0,1] neg_hi:[0,0]
	v_pk_add_f32 v[112:113], v[102:103], v[158:159] op_sel:[0,1] op_sel_hi:[1,0] neg_lo:[0,1] neg_hi:[0,0]
	v_pk_mul_f32 v[120:121], v[156:157], s[16:17] op_sel:[1,0] op_sel_hi:[1,0] neg_lo:[0,1] neg_hi:[0,1]
	v_pk_add_f32 v[96:97], v[96:97], v[106:107] neg_lo:[0,1] neg_hi:[0,1]
	v_pk_fma_f32 v[86:87], v[108:109], s[16:17], v[86:87] op_sel:[0,0,0] op_sel_hi:[0,0,1] neg_lo:[0,0,0] neg_hi:[0,0,0]
	v_pk_add_f32 v[102:103], v[102:103], v[158:159] op_sel:[0,1] op_sel_hi:[1,0] neg_lo:[0,0] neg_hi:[0,1]
	v_pk_fma_f32 v[120:121], v[156:157], s[16:17], v[120:121] op_sel:[0,0,0] op_sel_hi:[0,0,1] neg_lo:[0,1,0] neg_hi:[0,0,0]
	v_pk_add_f32 v[108:109], v[126:127], v[86:87] neg_lo:[0,1] neg_hi:[0,1]
	v_pk_add_f32 v[156:157], v[100:101], v[120:121] neg_lo:[0,1] neg_hi:[0,1]
	v_pk_add_f32 v[126:127], v[126:127], v[86:87]
	v_pk_add_f32 v[100:101], v[100:101], v[120:121]
	v_pk_add_f32 v[136:137], v[90:91], v[170:171]
	v_pk_mul_f32 v[116:117], v[126:127], s[4:5] op_sel:[1,1] op_sel_hi:[1,0] neg_lo:[0,1] neg_hi:[0,0]
	v_pk_mul_f32 v[88:89], v[112:113], s[16:17] op_sel:[1,0] op_sel_hi:[1,0] neg_lo:[0,1] neg_hi:[0,0]
	v_pk_mul_f32 v[92:93], v[100:101], s[4:5] op_sel:[1,0] op_sel_hi:[1,1] neg_lo:[0,1] neg_hi:[0,0]
	v_pk_add_f32 v[90:91], v[90:91], v[170:171] neg_lo:[0,1] neg_hi:[0,1]
	v_pk_fma_f32 v[116:117], v[126:127], s[4:5], v[116:117] op_sel:[0,0,0] op_sel_hi:[0,1,1] neg_lo:[0,0,0] neg_hi:[0,0,0]
	v_pk_fma_f32 v[88:89], v[112:113], s[16:17], v[88:89] op_sel:[0,0,0] op_sel_hi:[0,0,1] neg_lo:[0,0,0] neg_hi:[0,0,0]
	v_pk_fma_f32 v[92:93], v[100:101], s[4:5], v[92:93] op_sel:[0,1,0] op_sel_hi:[0,0,1] neg_lo:[0,0,0] neg_hi:[0,0,0]
	v_pk_add_f32 v[126:127], v[140:141], v[116:117] neg_lo:[0,1] neg_hi:[0,1]
	v_pk_add_f32 v[112:113], v[130:131], v[88:89] neg_lo:[0,1] neg_hi:[0,1]
	v_pk_add_f32 v[100:101], v[134:135], v[92:93] neg_lo:[0,1] neg_hi:[0,1]
	v_pk_add_f32 v[140:141], v[140:141], v[116:117]
	v_pk_add_f32 v[130:131], v[130:131], v[88:89]
	v_pk_add_f32 v[134:135], v[134:135], v[92:93]
	v_pk_add_f32 v[118:119], v[104:105], v[96:97] op_sel:[0,1] op_sel_hi:[1,0] neg_lo:[0,1] neg_hi:[0,0]
	v_pk_mul_f32 v[82:83], v[108:109], s[4:5] op_sel:[1,0] op_sel_hi:[1,1] neg_lo:[0,1] neg_hi:[0,1]
	v_pk_mul_f32 v[84:85], v[102:103], s[16:17] op_sel:[1,0] op_sel_hi:[1,0] neg_lo:[0,1] neg_hi:[0,1]
	v_pk_mul_f32 v[132:133], v[156:157], s[4:5] op_sel:[1,1] op_sel_hi:[1,0] neg_lo:[0,1] neg_hi:[0,1]
	v_pk_add_f32 v[104:105], v[104:105], v[96:97] op_sel:[0,1] op_sel_hi:[1,0] neg_lo:[0,0] neg_hi:[0,1]
	v_pk_fma_f32 v[82:83], v[108:109], s[4:5], v[82:83] op_sel:[0,1,0] op_sel_hi:[0,0,1] neg_lo:[0,1,0] neg_hi:[0,0,0]
	v_pk_fma_f32 v[84:85], v[102:103], s[16:17], v[84:85] op_sel:[0,0,0] op_sel_hi:[0,0,1] neg_lo:[0,1,0] neg_hi:[0,0,0]
	v_pk_fma_f32 v[132:133], v[156:157], s[4:5], v[132:133] op_sel:[0,0,0] op_sel_hi:[0,1,1] neg_lo:[0,1,0] neg_hi:[0,0,0]
	v_pk_add_f32 v[108:109], v[98:99], v[82:83] neg_lo:[0,1] neg_hi:[0,1]
	v_pk_add_f32 v[102:103], v[152:153], v[84:85] neg_lo:[0,1] neg_hi:[0,1]
	v_pk_add_f32 v[156:157], v[110:111], v[132:133] neg_lo:[0,1] neg_hi:[0,1]
	v_pk_add_f32 v[98:99], v[98:99], v[82:83]
	v_pk_add_f32 v[152:153], v[152:153], v[84:85]
	v_pk_add_f32 v[110:111], v[110:111], v[132:133]
	ds_write2_b64 v151, v[136:137], v[140:141] offset1:1
	ds_write2_b64 v151, v[130:131], v[134:135] offset0:2 offset1:3
	ds_write2_b64 v151, v[118:119], v[98:99] offset0:4 offset1:5
	ds_write2_b64 v151, v[152:153], v[110:111] offset0:6 offset1:7
	ds_write2_b64 v151, v[90:91], v[126:127] offset0:8 offset1:9
	ds_write2_b64 v151, v[112:113], v[100:101] offset0:10 offset1:11
	ds_write2_b64 v151, v[104:105], v[108:109] offset0:12 offset1:13
	ds_write2_b64 v151, v[102:103], v[156:157] offset0:14 offset1:15
	v_mov_b32_e32 v78, v195
	s_waitcnt lgkmcnt(0)
	s_mov_b32 s0, 0
	v_and_b32_e32 v81, 15, v78
	v_lshlrev_b32_e32 v80, 4, v78
	v_lshlrev_b32_e32 v83, 9, v81
	v_and_b32_e32 v80, 0xfffffc00, v80
	v_lshlrev_b32_e32 v82, 3, v78
	v_add_u32_e32 v83, 0, v83
	v_and_b32_e32 v79, 63, v78
	v_lshl_add_u32 v81, v81, 3, 0
	v_and_or_b32 v82, v82, s90, v80
; #define LAS __attribute__((address_space(3)))
; __device__ __forceinline__ cf twc(cf ws, int k16) { if (k16 == 0) return ws; if (k16 == 4) return cf{ws.y, -ws.x}; return cmul(ws, cf{c16(k16), -s16(k16)}); }
; template <int LR> __device__ __forceinline__ void dit_reg(cf (&x)[1 << LR], cf w) {
;     constexpr int R = 1 << LR; cf wsv[LR]; wsv[0] = w;
; #pragma unroll
;     for (int s = 1; s < LR; ++s) wsv[s] = cmul(wsv[s - 1], wsv[s - 1]);
; #pragma unroll
;     for (int s = LR - 1; s >= 0; --s) { const int half = R >> (s + 1);
; #pragma unroll
;         for (int m0 = 0; m0 < R; m0 += 2 * half)
; #pragma unroll
;             for (int mm = 0; mm < half; ++mm) { const int ia = m0 + mm, ib = ia + half; const cf a = x[ia];
;                 const cf b = cmulc(x[ib], twc(wsv[s], (mm << s) * (16 / R)));
;                 x[ia] = cf{a.x + b.x, a.y + b.y}; x[ib] = cf{a.x - b.x, a.y - b.y}; } }
; template <int LR, bool INV> __device__ __forceinline__ void fft_pass(ldsf2 buf, int base, int stride, int twi) {
;     constexpr int R = 1 << LR; cf x[R];
;     const v2f wv = ((ldsf2)((LAS unsigned char*)buf + 139264))[twi];
; #pragma unroll
;     for (int m = 0; m < R; ++m) { const v2f v = buf[base + m * stride]; x[m] = cf{v.x, v.y}; }
;     const cf w{wv.x, wv.y};
;     if (INV) dit_reg<LR>(x, w); else dif_reg<LR>(x, w);
; #pragma unroll
;     for (int m = 0; m < R; ++m) buf[base + m * stride] = mkv2(x[m].x, x[m].y);
; }
.LBB0_365:
	v_or_b32_e32 v84, s0, v82
	v_lshlrev_b32_e32 v85, 3, v84
	v_ashrrev_i32_e32 v84, 1, v84
	v_add3_u32 v130, v81, v85, v84
	ds_read2_b64 v[84:87], v130 offset1:17
	ds_read2_b64 v[88:91], v130 offset0:34 offset1:51
	ds_read2_b64 v[92:95], v130 offset0:68 offset1:85
	ds_read2_b64 v[96:99], v130 offset0:102 offset1:119
	s_movk_i32 s0, 0x200
	v_or_b32_e32 v134, s0, v82
	v_lshlrev_b32_e32 v136, 3, v134
	v_ashrrev_i32_e32 v134, 1, v134
	v_add3_u32 v138, v81, v136, v134
	ds_read2_b64 v[140:143], v138 offset1:17
	ds_read2_b64 v[152:155], v138 offset0:34 offset1:51
	ds_read2_b64 v[156:159], v138 offset0:68 offset1:85
	ds_read2_b64 v[160:163], v138 offset0:102 offset1:119
	s_waitcnt lgkmcnt(4)
	v_pk_mul_f32 v[112:113], v[86:87], v[208:209] op_sel:[1,1] op_sel_hi:[1,0]
	v_pk_mul_f32 v[114:115], v[90:91], v[208:209] op_sel:[1,1] op_sel_hi:[1,0]
	v_pk_mul_f32 v[116:117], v[94:95], v[208:209] op_sel:[1,1] op_sel_hi:[1,0]
	v_pk_mul_f32 v[118:119], v[98:99], v[208:209] op_sel:[1,1] op_sel_hi:[1,0]
	v_pk_fma_f32 v[112:113], v[86:87], v[208:209], v[112:113] op_sel:[0,0,0] op_sel_hi:[0,1,1] neg_lo:[0,0,0] neg_hi:[0,1,0]
	v_pk_fma_f32 v[114:115], v[90:91], v[208:209], v[114:115] op_sel:[0,0,0] op_sel_hi:[0,1,1] neg_lo:[0,0,0] neg_hi:[0,1,0]
	v_pk_fma_f32 v[116:117], v[94:95], v[208:209], v[116:117] op_sel:[0,0,0] op_sel_hi:[0,1,1] neg_lo:[0,0,0] neg_hi:[0,1,0]
	v_pk_fma_f32 v[118:119], v[98:99], v[208:209], v[118:119] op_sel:[0,0,0] op_sel_hi:[0,1,1] neg_lo:[0,0,0] neg_hi:[0,1,0]
	v_pk_add_f32 v[86:87], v[84:85], v[112:113] neg_lo:[0,1] neg_hi:[0,1]
	v_pk_add_f32 v[90:91], v[88:89], v[114:115] neg_lo:[0,1] neg_hi:[0,1]
	v_pk_add_f32 v[94:95], v[92:93], v[116:117] neg_lo:[0,1] neg_hi:[0,1]
	v_pk_add_f32 v[98:99], v[96:97], v[118:119] neg_lo:[0,1] neg_hi:[0,1]
	v_pk_add_f32 v[84:85], v[84:85], v[112:113]
	v_pk_add_f32 v[88:89], v[88:89], v[114:115]
	v_pk_add_f32 v[92:93], v[92:93], v[116:117]
	v_pk_add_f32 v[96:97], v[96:97], v[118:119]
	v_pk_mul_f32 v[112:113], v[88:89], v[206:207] op_sel:[1,1] op_sel_hi:[1,0]
	v_pk_mul_f32 v[114:115], v[90:91], v[206:207] op_sel:[1,0] op_sel_hi:[1,1]
	v_pk_mul_f32 v[116:117], v[96:97], v[206:207] op_sel:[1,1] op_sel_hi:[1,0]
	v_pk_mul_f32 v[118:119], v[98:99], v[206:207] op_sel:[1,0] op_sel_hi:[1,1]
	v_pk_fma_f32 v[112:113], v[88:89], v[206:207], v[112:113] op_sel:[0,0,0] op_sel_hi:[0,1,1] neg_lo:[0,0,0] neg_hi:[0,1,0]
	v_pk_fma_f32 v[114:115], v[90:91], v[206:207], v[114:115] op_sel:[0,1,0] op_sel_hi:[0,0,1] neg_lo:[0,0,1] neg_hi:[0,0,0]
	v_pk_fma_f32 v[116:117], v[96:97], v[206:207], v[116:117] op_sel:[0,0,0] op_sel_hi:[0,1,1] neg_lo:[0,0,0] neg_hi:[0,1,0]
	v_pk_fma_f32 v[118:119], v[98:99], v[206:207], v[118:119] op_sel:[0,1,0] op_sel_hi:[0,0,1] neg_lo:[0,0,1] neg_hi:[0,0,0]
	v_pk_add_f32 v[88:89], v[84:85], v[112:113] neg_lo:[0,1] neg_hi:[0,1]
	v_pk_add_f32 v[90:91], v[86:87], v[114:115] neg_lo:[0,1] neg_hi:[0,1]
	v_pk_add_f32 v[96:97], v[92:93], v[116:117] neg_lo:[0,1] neg_hi:[0,1]
	v_pk_add_f32 v[98:99], v[94:95], v[118:119] neg_lo:[0,1] neg_hi:[0,1]
	v_pk_add_f32 v[84:85], v[84:85], v[112:113]
	v_pk_add_f32 v[86:87], v[86:87], v[114:115]
	v_pk_add_f32 v[92:93], v[92:93], v[116:117]
	v_pk_add_f32 v[94:95], v[94:95], v[118:119]
	v_pk_mul_f32 v[112:113], v[92:93], v[204:205] op_sel:[1,1] op_sel_hi:[1,0]
	v_pk_mul_f32 v[114:115], v[94:95], v[210:211] op_sel:[1,1] op_sel_hi:[1,0]
	v_pk_mul_f32 v[116:117], v[96:97], v[204:205] op_sel:[1,0] op_sel_hi:[1,1]
	v_pk_mul_f32 v[118:119], v[98:99], v[212:213] op_sel:[1,1] op_sel_hi:[1,0]
	v_pk_fma_f32 v[112:113], v[92:93], v[204:205], v[112:113] op_sel:[0,0,0] op_sel_hi:[0,1,1] neg_lo:[0,0,0] neg_hi:[0,1,0]
	v_pk_fma_f32 v[114:115], v[94:95], v[210:211], v[114:115] op_sel:[0,0,0] op_sel_hi:[0,1,1] neg_lo:[0,0,0] neg_hi:[0,1,0]
	v_pk_fma_f32 v[116:117], v[96:97], v[204:205], v[116:117] op_sel:[0,1,0] op_sel_hi:[0,0,1] neg_lo:[0,0,1] neg_hi:[0,0,0]
	v_pk_fma_f32 v[118:119], v[98:99], v[212:213], v[118:119] op_sel:[0,0,0] op_sel_hi:[0,1,1] neg_lo:[0,0,0] neg_hi:[0,1,0]
	v_pk_add_f32 v[92:93], v[84:85], v[112:113] neg_lo:[0,1] neg_hi:[0,1]
	v_pk_add_f32 v[94:95], v[86:87], v[114:115] neg_lo:[0,1] neg_hi:[0,1]
	v_pk_add_f32 v[96:97], v[88:89], v[116:117] neg_lo:[0,1] neg_hi:[0,1]
	v_pk_add_f32 v[98:99], v[90:91], v[118:119] neg_lo:[0,1] neg_hi:[0,1]
	v_pk_add_f32 v[84:85], v[84:85], v[112:113]
	v_pk_add_f32 v[86:87], v[86:87], v[114:115]
	v_pk_add_f32 v[88:89], v[88:89], v[116:117]
	v_pk_add_f32 v[90:91], v[90:91], v[118:119]
	ds_write2_b64 v130, v[84:85], v[86:87] offset1:17
	ds_write2_b64 v130, v[88:89], v[90:91] offset0:34 offset1:51
	ds_write2_b64 v130, v[92:93], v[94:95] offset0:68 offset1:85
	ds_write2_b64 v130, v[96:97], v[98:99] offset0:102 offset1:119
	s_waitcnt lgkmcnt(4)
; #define LAS __attribute__((address_space(3)))
; __device__ __forceinline__ cf twc(cf ws, int k16) { if (k16 == 0) return ws; if (k16 == 4) return cf{ws.y, -ws.x}; return cmul(ws, cf{c16(k16), -s16(k16)}); }
; template <int LR> __device__ __forceinline__ void dit_reg(cf (&x)[1 << LR], cf w) {
;     constexpr int R = 1 << LR; cf wsv[LR]; wsv[0] = w;
; #pragma unroll
;     for (int s = 1; s < LR; ++s) wsv[s] = cmul(wsv[s - 1], wsv[s - 1]);
; #pragma unroll
;     for (int s = LR - 1; s >= 0; --s) { const int half = R >> (s + 1);
; #pragma unroll
;         for (int m0 = 0; m0 < R; m0 += 2 * half)
; #pragma unroll
;             for (int mm = 0; mm < half; ++mm) { const int ia = m0 + mm, ib = ia + half; const cf a = x[ia];
;                 const cf b = cmulc(x[ib], twc(wsv[s], (mm << s) * (16 / R)));
;                 x[ia] = cf{a.x + b.x, a.y + b.y}; x[ib] = cf{a.x - b.x, a.y - b.y}; } }
; template <int LR, bool INV> __device__ __forceinline__ void fft_pass(ldsf2 buf, int base, int stride, int twi) {
;     constexpr int R = 1 << LR; cf x[R];
;     const v2f wv = ((ldsf2)((LAS unsigned char*)buf + 139264))[twi];
; #pragma unroll
;     for (int m = 0; m < R; ++m) { const v2f v = buf[base + m * stride]; x[m] = cf{v.x, v.y}; }
;     const cf w{wv.x, wv.y};
;     if (INV) dit_reg<LR>(x, w); else dif_reg<LR>(x, w);
; #pragma unroll
;     for (int m = 0; m < R; ++m) buf[base + m * stride] = mkv2(x[m].x, x[m].y);
; }
	v_pk_mul_f32 v[174:175], v[142:143], v[208:209] op_sel:[1,1] op_sel_hi:[1,0]
	v_pk_mul_f32 v[188:189], v[154:155], v[208:209] op_sel:[1,1] op_sel_hi:[1,0]
	v_pk_mul_f32 v[190:191], v[158:159], v[208:209] op_sel:[1,1] op_sel_hi:[1,0]
	v_pk_mul_f32 v[196:197], v[162:163], v[208:209] op_sel:[1,1] op_sel_hi:[1,0]
	v_pk_fma_f32 v[174:175], v[142:143], v[208:209], v[174:175] op_sel:[0,0,0] op_sel_hi:[0,1,1] neg_lo:[0,0,0] neg_hi:[0,1,0]
	v_pk_fma_f32 v[188:189], v[154:155], v[208:209], v[188:189] op_sel:[0,0,0] op_sel_hi:[0,1,1] neg_lo:[0,0,0] neg_hi:[0,1,0]
	v_pk_fma_f32 v[190:191], v[158:159], v[208:209], v[190:191] op_sel:[0,0,0] op_sel_hi:[0,1,1] neg_lo:[0,0,0] neg_hi:[0,1,0]
	v_pk_fma_f32 v[196:197], v[162:163], v[208:209], v[196:197] op_sel:[0,0,0] op_sel_hi:[0,1,1] neg_lo:[0,0,0] neg_hi:[0,1,0]
	v_pk_add_f32 v[142:143], v[140:141], v[174:175] neg_lo:[0,1] neg_hi:[0,1]
	v_pk_add_f32 v[154:155], v[152:153], v[188:189] neg_lo:[0,1] neg_hi:[0,1]
	v_pk_add_f32 v[158:159], v[156:157], v[190:191] neg_lo:[0,1] neg_hi:[0,1]
	v_pk_add_f32 v[162:163], v[160:161], v[196:197] neg_lo:[0,1] neg_hi:[0,1]
	v_pk_add_f32 v[140:141], v[140:141], v[174:175]
	v_pk_add_f32 v[152:153], v[152:153], v[188:189]
	v_pk_add_f32 v[156:157], v[156:157], v[190:191]
	v_pk_add_f32 v[160:161], v[160:161], v[196:197]
	v_pk_mul_f32 v[174:175], v[152:153], v[206:207] op_sel:[1,1] op_sel_hi:[1,0]
	v_pk_mul_f32 v[188:189], v[154:155], v[206:207] op_sel:[1,0] op_sel_hi:[1,1]
	v_pk_mul_f32 v[190:191], v[160:161], v[206:207] op_sel:[1,1] op_sel_hi:[1,0]
	v_pk_mul_f32 v[196:197], v[162:163], v[206:207] op_sel:[1,0] op_sel_hi:[1,1]
	v_pk_fma_f32 v[174:175], v[152:153], v[206:207], v[174:175] op_sel:[0,0,0] op_sel_hi:[0,1,1] neg_lo:[0,0,0] neg_hi:[0,1,0]
	v_pk_fma_f32 v[188:189], v[154:155], v[206:207], v[188:189] op_sel:[0,1,0] op_sel_hi:[0,0,1] neg_lo:[0,0,1] neg_hi:[0,0,0]
	v_pk_fma_f32 v[190:191], v[160:161], v[206:207], v[190:191] op_sel:[0,0,0] op_sel_hi:[0,1,1] neg_lo:[0,0,0] neg_hi:[0,1,0]
	v_pk_fma_f32 v[196:197], v[162:163], v[206:207], v[196:197] op_sel:[0,1,0] op_sel_hi:[0,0,1] neg_lo:[0,0,1] neg_hi:[0,0,0]
	v_pk_add_f32 v[152:153], v[140:141], v[174:175] neg_lo:[0,1] neg_hi:[0,1]
	v_pk_add_f32 v[154:155], v[142:143], v[188:189] neg_lo:[0,1] neg_hi:[0,1]
	v_pk_add_f32 v[160:161], v[156:157], v[190:191] neg_lo:[0,1] neg_hi:[0,1]
	v_pk_add_f32 v[162:163], v[158:159], v[196:197] neg_lo:[0,1] neg_hi:[0,1]
	v_pk_add_f32 v[140:141], v[140:141], v[174:175]
	v_pk_add_f32 v[142:143], v[142:143], v[188:189]
	v_pk_add_f32 v[156:157], v[156:157], v[190:191]
	v_pk_add_f32 v[158:159], v[158:159], v[196:197]
	v_pk_mul_f32 v[174:175], v[156:157], v[204:205] op_sel:[1,1] op_sel_hi:[1,0]
	v_pk_mul_f32 v[188:189], v[158:159], v[210:211] op_sel:[1,1] op_sel_hi:[1,0]
	v_pk_mul_f32 v[190:191], v[160:161], v[204:205] op_sel:[1,0] op_sel_hi:[1,1]
	v_pk_mul_f32 v[196:197], v[162:163], v[212:213] op_sel:[1,1] op_sel_hi:[1,0]
	v_pk_fma_f32 v[174:175], v[156:157], v[204:205], v[174:175] op_sel:[0,0,0] op_sel_hi:[0,1,1] neg_lo:[0,0,0] neg_hi:[0,1,0]
	v_pk_fma_f32 v[188:189], v[158:159], v[210:211], v[188:189] op_sel:[0,0,0] op_sel_hi:[0,1,1] neg_lo:[0,0,0] neg_hi:[0,1,0]
	v_pk_fma_f32 v[190:191], v[160:161], v[204:205], v[190:191] op_sel:[0,1,0] op_sel_hi:[0,0,1] neg_lo:[0,0,1] neg_hi:[0,0,0]
	v_pk_fma_f32 v[196:197], v[162:163], v[212:213], v[196:197] op_sel:[0,0,0] op_sel_hi:[0,1,1] neg_lo:[0,0,0] neg_hi:[0,1,0]
	v_pk_add_f32 v[156:157], v[140:141], v[174:175] neg_lo:[0,1] neg_hi:[0,1]
	v_pk_add_f32 v[158:159], v[142:143], v[188:189] neg_lo:[0,1] neg_hi:[0,1]
	v_pk_add_f32 v[160:161], v[152:153], v[190:191] neg_lo:[0,1] neg_hi:[0,1]
	v_pk_add_f32 v[162:163], v[154:155], v[196:197] neg_lo:[0,1] neg_hi:[0,1]
	v_pk_add_f32 v[140:141], v[140:141], v[174:175]
	v_pk_add_f32 v[142:143], v[142:143], v[188:189]
	v_pk_add_f32 v[152:153], v[152:153], v[190:191]
	v_pk_add_f32 v[154:155], v[154:155], v[196:197]
	ds_write2_b64 v138, v[140:141], v[142:143] offset1:17
	ds_write2_b64 v138, v[152:153], v[154:155] offset0:34 offset1:51
	ds_write2_b64 v138, v[156:157], v[158:159] offset0:68 offset1:85
	ds_write2_b64 v138, v[160:161], v[162:163] offset0:102 offset1:119
	s_mov_b64 s[14:15], 0
	s_waitcnt lgkmcnt(0)
	s_mov_b32 s0, 0
	s_mov_b64 s[14:15], -1
; #define LAS __attribute__((address_space(3)))
; __device__ __forceinline__ cf twc(cf ws, int k16) { if (k16 == 0) return ws; if (k16 == 4) return cf{ws.y, -ws.x}; return cmul(ws, cf{c16(k16), -s16(k16)}); }
; template <int LR> __device__ __forceinline__ void dit_reg(cf (&x)[1 << LR], cf w) {
;     constexpr int R = 1 << LR; cf wsv[LR]; wsv[0] = w;
; #pragma unroll
;     for (int s = 1; s < LR; ++s) wsv[s] = cmul(wsv[s - 1], wsv[s - 1]);
; #pragma unroll
;     for (int s = LR - 1; s >= 0; --s) { const int half = R >> (s + 1);
; #pragma unroll
;         for (int m0 = 0; m0 < R; m0 += 2 * half)
; #pragma unroll
;             for (int mm = 0; mm < half; ++mm) { const int ia = m0 + mm, ib = ia + half; const cf a = x[ia];
;                 const cf b = cmulc(x[ib], twc(wsv[s], (mm << s) * (16 / R)));
;                 x[ia] = cf{a.x + b.x, a.y + b.y}; x[ib] = cf{a.x - b.x, a.y - b.y}; } }
; template <int LR, bool INV> __device__ __forceinline__ void fft_pass(ldsf2 buf, int base, int stride, int twi) {
;     constexpr int R = 1 << LR; cf x[R];
;     const v2f wv = ((ldsf2)((LAS unsigned char*)buf + 139264))[twi];
; #pragma unroll
;     for (int m = 0; m < R; ++m) { const v2f v = buf[base + m * stride]; x[m] = cf{v.x, v.y}; }
;     const cf w{wv.x, wv.y};
;     if (INV) dit_reg<LR>(x, w); else dif_reg<LR>(x, w);
; #pragma unroll
;     for (int m = 0; m < R; ++m) buf[base + m * stride] = mkv2(x[m].x, x[m].y);
; }
.LBB0_367:
	v_or_b32_e32 v81, s0, v79
	v_or_b32_e32 v82, v81, v80
	v_ashrrev_i32_e32 v83, 4, v82
	v_lshlrev_b32_e32 v81, 3, v82
	v_lshlrev_b32_e32 v82, 3, v83
	v_add3_u32 v81, 0, v81, v82
	v_add_u32_e32 v130, 0x1800, v81
	v_add_u32_e32 v129, 0x1000, v81
	ds_read2_b64 v[94:97], v130 offset0:48 offset1:184
	ds_read2_b64 v[90:93], v129 offset0:32 offset1:168
	v_add_u32_e32 v128, 0x800, v81
	ds_read2_b64 v[82:85], v81 offset1:136
	ds_read2_b64 v[86:89], v128 offset0:16 offset1:152
	s_mov_b32 s0, 64
	v_or_b32_e32 v132, s0, v79
	v_or_b32_e32 v134, v132, v80
	v_ashrrev_i32_e32 v138, 4, v134
	v_lshlrev_b32_e32 v132, 3, v134
	v_lshlrev_b32_e32 v134, 3, v138
	v_add3_u32 v132, 0, v132, v134
	v_add_u32_e32 v140, 0x1800, v132
	v_add_u32_e32 v142, 0x1000, v132
	ds_read2_b64 v[152:155], v140 offset0:48 offset1:184
	ds_read2_b64 v[156:159], v142 offset0:32 offset1:168
	v_add_u32_e32 v160, 0x800, v132
	ds_read2_b64 v[162:165], v132 offset1:136
	ds_read2_b64 v[166:169], v160 offset0:16 offset1:152
	s_waitcnt lgkmcnt(4)
	v_pk_add_f32 v[100:101], v[214:215], v[214:215] op_sel:[0,1] op_sel_hi:[1,0] neg_lo:[0,0] neg_hi:[0,1]
	s_nop 0
	v_pk_mul_f32 v[102:103], v[100:101], s[16:17] op_sel:[0,0] op_sel_hi:[1,0]
	v_pk_mul_f32 v[104:105], v[100:101], s[16:17] op_sel:[1,0] op_sel_hi:[0,0] neg_lo:[0,0] neg_hi:[1,0]
	v_pk_mul_f32 v[110:111], v[84:85], v[218:219] op_sel:[1,1] op_sel_hi:[1,0]
	v_pk_mul_f32 v[112:113], v[88:89], v[218:219] op_sel:[1,1] op_sel_hi:[1,0]
	v_pk_mul_f32 v[114:115], v[92:93], v[218:219] op_sel:[1,1] op_sel_hi:[1,0]
	v_pk_mul_f32 v[116:117], v[96:97], v[218:219] op_sel:[1,1] op_sel_hi:[1,0]
	v_pk_fma_f32 v[110:111], v[84:85], v[218:219], v[110:111] op_sel:[0,0,0] op_sel_hi:[0,1,1] neg_lo:[0,0,0] neg_hi:[0,1,0]
	v_pk_fma_f32 v[112:113], v[88:89], v[218:219], v[112:113] op_sel:[0,0,0] op_sel_hi:[0,1,1] neg_lo:[0,0,0] neg_hi:[0,1,0]
	v_pk_fma_f32 v[114:115], v[92:93], v[218:219], v[114:115] op_sel:[0,0,0] op_sel_hi:[0,1,1] neg_lo:[0,0,0] neg_hi:[0,1,0]
	v_pk_fma_f32 v[116:117], v[96:97], v[218:219], v[116:117] op_sel:[0,0,0] op_sel_hi:[0,1,1] neg_lo:[0,0,0] neg_hi:[0,1,0]
	v_pk_add_f32 v[84:85], v[82:83], v[110:111] neg_lo:[0,1] neg_hi:[0,1]
	v_pk_add_f32 v[88:89], v[86:87], v[112:113] neg_lo:[0,1] neg_hi:[0,1]
	v_pk_add_f32 v[92:93], v[90:91], v[114:115] neg_lo:[0,1] neg_hi:[0,1]
	v_pk_add_f32 v[96:97], v[94:95], v[116:117] neg_lo:[0,1] neg_hi:[0,1]
	v_pk_add_f32 v[82:83], v[82:83], v[110:111]
	v_pk_add_f32 v[86:87], v[86:87], v[112:113]
	v_pk_add_f32 v[90:91], v[90:91], v[114:115]
	v_pk_add_f32 v[94:95], v[94:95], v[116:117]
	v_pk_mul_f32 v[110:111], v[86:87], v[216:217] op_sel:[1,1] op_sel_hi:[1,0]
	v_pk_mul_f32 v[112:113], v[88:89], v[216:217] op_sel:[1,0] op_sel_hi:[1,1]
	v_pk_mul_f32 v[114:115], v[94:95], v[216:217] op_sel:[1,1] op_sel_hi:[1,0]
	v_pk_mul_f32 v[116:117], v[96:97], v[216:217] op_sel:[1,0] op_sel_hi:[1,1]
	v_pk_fma_f32 v[110:111], v[86:87], v[216:217], v[110:111] op_sel:[0,0,0] op_sel_hi:[0,1,1] neg_lo:[0,0,0] neg_hi:[0,1,0]
	v_pk_fma_f32 v[112:113], v[88:89], v[216:217], v[112:113] op_sel:[0,1,0] op_sel_hi:[0,0,1] neg_lo:[0,0,1] neg_hi:[0,0,0]
	v_pk_fma_f32 v[114:115], v[94:95], v[216:217], v[114:115] op_sel:[0,0,0] op_sel_hi:[0,1,1] neg_lo:[0,0,0] neg_hi:[0,1,0]
	v_pk_fma_f32 v[116:117], v[96:97], v[216:217], v[116:117] op_sel:[0,1,0] op_sel_hi:[0,0,1] neg_lo:[0,0,1] neg_hi:[0,0,0]
	v_pk_add_f32 v[86:87], v[82:83], v[110:111] neg_lo:[0,1] neg_hi:[0,1]
	v_pk_add_f32 v[88:89], v[84:85], v[112:113] neg_lo:[0,1] neg_hi:[0,1]
	v_pk_add_f32 v[94:95], v[90:91], v[114:115] neg_lo:[0,1] neg_hi:[0,1]
	v_pk_add_f32 v[96:97], v[92:93], v[116:117] neg_lo:[0,1] neg_hi:[0,1]
	v_pk_add_f32 v[82:83], v[82:83], v[110:111]
	v_pk_add_f32 v[84:85], v[84:85], v[112:113]
	v_pk_add_f32 v[90:91], v[90:91], v[114:115]
	v_pk_add_f32 v[92:93], v[92:93], v[116:117]
	v_pk_mul_f32 v[110:111], v[90:91], v[214:215] op_sel:[1,1] op_sel_hi:[1,0]
	v_pk_mul_f32 v[112:113], v[92:93], v[102:103] op_sel:[1,1] op_sel_hi:[1,0]
	v_pk_mul_f32 v[114:115], v[94:95], v[214:215] op_sel:[1,0] op_sel_hi:[1,1]
	v_pk_mul_f32 v[116:117], v[96:97], v[104:105] op_sel:[1,1] op_sel_hi:[1,0]
	v_pk_fma_f32 v[110:111], v[90:91], v[214:215], v[110:111] op_sel:[0,0,0] op_sel_hi:[0,1,1] neg_lo:[0,0,0] neg_hi:[0,1,0]
	v_pk_fma_f32 v[112:113], v[92:93], v[102:103], v[112:113] op_sel:[0,0,0] op_sel_hi:[0,1,1] neg_lo:[0,0,0] neg_hi:[0,1,0]
	v_pk_fma_f32 v[114:115], v[94:95], v[214:215], v[114:115] op_sel:[0,1,0] op_sel_hi:[0,0,1] neg_lo:[0,0,1] neg_hi:[0,0,0]
	v_pk_fma_f32 v[116:117], v[96:97], v[104:105], v[116:117] op_sel:[0,0,0] op_sel_hi:[0,1,1] neg_lo:[0,0,0] neg_hi:[0,1,0]
	v_pk_add_f32 v[90:91], v[82:83], v[110:111] neg_lo:[0,1] neg_hi:[0,1]
	v_pk_add_f32 v[92:93], v[84:85], v[112:113] neg_lo:[0,1] neg_hi:[0,1]
	v_pk_add_f32 v[94:95], v[86:87], v[114:115] neg_lo:[0,1] neg_hi:[0,1]
	v_pk_add_f32 v[96:97], v[88:89], v[116:117] neg_lo:[0,1] neg_hi:[0,1]
	v_pk_add_f32 v[82:83], v[82:83], v[110:111]
	v_pk_add_f32 v[84:85], v[84:85], v[112:113]
	v_pk_add_f32 v[86:87], v[86:87], v[114:115]
	v_pk_add_f32 v[88:89], v[88:89], v[116:117]
	ds_write2_b64 v81, v[82:83], v[84:85] offset1:136
	ds_write2_b64 v128, v[86:87], v[88:89] offset0:16 offset1:152
	ds_write2_b64 v129, v[90:91], v[92:93] offset0:32 offset1:168
	ds_write2_b64 v130, v[94:95], v[96:97] offset0:48 offset1:184
	s_waitcnt lgkmcnt(4)
; #define LAS __attribute__((address_space(3)))
; __device__ __forceinline__ cf twc(cf ws, int k16) { if (k16 == 0) return ws; if (k16 == 4) return cf{ws.y, -ws.x}; return cmul(ws, cf{c16(k16), -s16(k16)}); }
; __device__ __forceinline__ void lds_barrier() { asm volatile("s_waitcnt lgkmcnt(0)\n\ts_barrier" ::: "memory"); }
; template <int LR> __device__ __forceinline__ void dit_reg(cf (&x)[1 << LR], cf w) {
;     constexpr int R = 1 << LR; cf wsv[LR]; wsv[0] = w;
; #pragma unroll
;     for (int s = 1; s < LR; ++s) wsv[s] = cmul(wsv[s - 1], wsv[s - 1]);
; #pragma unroll
;     for (int s = LR - 1; s >= 0; --s) { const int half = R >> (s + 1);
; #pragma unroll
;         for (int m0 = 0; m0 < R; m0 += 2 * half)
; #pragma unroll
;             for (int mm = 0; mm < half; ++mm) { const int ia = m0 + mm, ib = ia + half; const cf a = x[ia];
;                 const cf b = cmulc(x[ib], twc(wsv[s], (mm << s) * (16 / R)));
;                 x[ia] = cf{a.x + b.x, a.y + b.y}; x[ib] = cf{a.x - b.x, a.y - b.y}; } }
; template <int LR, bool INV> __device__ __forceinline__ void fft_pass(ldsf2 buf, int base, int stride, int twi) {
;     constexpr int R = 1 << LR; cf x[R];
;     const v2f wv = ((ldsf2)((LAS unsigned char*)buf + 139264))[twi];
; #pragma unroll
;     for (int m = 0; m < R; ++m) { const v2f v = buf[base + m * stride]; x[m] = cf{v.x, v.y}; }
;     const cf w{wv.x, wv.y};
;     if (INV) dit_reg<LR>(x, w); else dif_reg<LR>(x, w);
; #pragma unroll
;     for (int m = 0; m < R; ++m) buf[base + m * stride] = mkv2(x[m].x, x[m].y);
; }
; __device__ __forceinline__ void fft_inv_cba(ldsf2 buf) {
;     ...
;     lds_barrier();
	v_pk_add_f32 v[170:171], v[220:221], v[220:221] op_sel:[0,1] op_sel_hi:[1,0] neg_lo:[0,0] neg_hi:[0,1]
	s_nop 0
	v_pk_mul_f32 v[172:173], v[170:171], s[16:17] op_sel:[0,0] op_sel_hi:[1,0]
	v_pk_mul_f32 v[174:175], v[170:171], s[16:17] op_sel:[1,0] op_sel_hi:[0,0] neg_lo:[0,0] neg_hi:[1,0]
	v_pk_mul_f32 v[196:197], v[164:165], v[224:225] op_sel:[1,1] op_sel_hi:[1,0]
	v_pk_mul_f32 v[198:199], v[168:169], v[224:225] op_sel:[1,1] op_sel_hi:[1,0]
	v_pk_mul_f32 v[200:201], v[158:159], v[224:225] op_sel:[1,1] op_sel_hi:[1,0]
	v_pk_mul_f32 v[202:203], v[154:155], v[224:225] op_sel:[1,1] op_sel_hi:[1,0]
	v_pk_fma_f32 v[196:197], v[164:165], v[224:225], v[196:197] op_sel:[0,0,0] op_sel_hi:[0,1,1] neg_lo:[0,0,0] neg_hi:[0,1,0]
	v_pk_fma_f32 v[198:199], v[168:169], v[224:225], v[198:199] op_sel:[0,0,0] op_sel_hi:[0,1,1] neg_lo:[0,0,0] neg_hi:[0,1,0]
	v_pk_fma_f32 v[200:201], v[158:159], v[224:225], v[200:201] op_sel:[0,0,0] op_sel_hi:[0,1,1] neg_lo:[0,0,0] neg_hi:[0,1,0]
	v_pk_fma_f32 v[202:203], v[154:155], v[224:225], v[202:203] op_sel:[0,0,0] op_sel_hi:[0,1,1] neg_lo:[0,0,0] neg_hi:[0,1,0]
	v_pk_add_f32 v[164:165], v[162:163], v[196:197] neg_lo:[0,1] neg_hi:[0,1]
	v_pk_add_f32 v[168:169], v[166:167], v[198:199] neg_lo:[0,1] neg_hi:[0,1]
	v_pk_add_f32 v[158:159], v[156:157], v[200:201] neg_lo:[0,1] neg_hi:[0,1]
	v_pk_add_f32 v[154:155], v[152:153], v[202:203] neg_lo:[0,1] neg_hi:[0,1]
	v_pk_add_f32 v[162:163], v[162:163], v[196:197]
	v_pk_add_f32 v[166:167], v[166:167], v[198:199]
	v_pk_add_f32 v[156:157], v[156:157], v[200:201]
	v_pk_add_f32 v[152:153], v[152:153], v[202:203]
	v_pk_mul_f32 v[196:197], v[166:167], v[222:223] op_sel:[1,1] op_sel_hi:[1,0]
	v_pk_mul_f32 v[198:199], v[168:169], v[222:223] op_sel:[1,0] op_sel_hi:[1,1]
	v_pk_mul_f32 v[200:201], v[152:153], v[222:223] op_sel:[1,1] op_sel_hi:[1,0]
	v_pk_mul_f32 v[202:203], v[154:155], v[222:223] op_sel:[1,0] op_sel_hi:[1,1]
	v_pk_fma_f32 v[196:197], v[166:167], v[222:223], v[196:197] op_sel:[0,0,0] op_sel_hi:[0,1,1] neg_lo:[0,0,0] neg_hi:[0,1,0]
	v_pk_fma_f32 v[198:199], v[168:169], v[222:223], v[198:199] op_sel:[0,1,0] op_sel_hi:[0,0,1] neg_lo:[0,0,1] neg_hi:[0,0,0]
	v_pk_fma_f32 v[200:201], v[152:153], v[222:223], v[200:201] op_sel:[0,0,0] op_sel_hi:[0,1,1] neg_lo:[0,0,0] neg_hi:[0,1,0]
	v_pk_fma_f32 v[202:203], v[154:155], v[222:223], v[202:203] op_sel:[0,1,0] op_sel_hi:[0,0,1] neg_lo:[0,0,1] neg_hi:[0,0,0]
	v_pk_add_f32 v[166:167], v[162:163], v[196:197] neg_lo:[0,1] neg_hi:[0,1]
	v_pk_add_f32 v[168:169], v[164:165], v[198:199] neg_lo:[0,1] neg_hi:[0,1]
	v_pk_add_f32 v[152:153], v[156:157], v[200:201] neg_lo:[0,1] neg_hi:[0,1]
	v_pk_add_f32 v[154:155], v[158:159], v[202:203] neg_lo:[0,1] neg_hi:[0,1]
	v_pk_add_f32 v[162:163], v[162:163], v[196:197]
	v_pk_add_f32 v[164:165], v[164:165], v[198:199]
	v_pk_add_f32 v[156:157], v[156:157], v[200:201]
	v_pk_add_f32 v[158:159], v[158:159], v[202:203]
	v_pk_mul_f32 v[196:197], v[156:157], v[220:221] op_sel:[1,1] op_sel_hi:[1,0]
	v_pk_mul_f32 v[198:199], v[158:159], v[172:173] op_sel:[1,1] op_sel_hi:[1,0]
	v_pk_mul_f32 v[200:201], v[152:153], v[220:221] op_sel:[1,0] op_sel_hi:[1,1]
	v_pk_mul_f32 v[202:203], v[154:155], v[174:175] op_sel:[1,1] op_sel_hi:[1,0]
	v_pk_fma_f32 v[196:197], v[156:157], v[220:221], v[196:197] op_sel:[0,0,0] op_sel_hi:[0,1,1] neg_lo:[0,0,0] neg_hi:[0,1,0]
	v_pk_fma_f32 v[198:199], v[158:159], v[172:173], v[198:199] op_sel:[0,0,0] op_sel_hi:[0,1,1] neg_lo:[0,0,0] neg_hi:[0,1,0]
	v_pk_fma_f32 v[200:201], v[152:153], v[220:221], v[200:201] op_sel:[0,1,0] op_sel_hi:[0,0,1] neg_lo:[0,0,1] neg_hi:[0,0,0]
	v_pk_fma_f32 v[202:203], v[154:155], v[174:175], v[202:203] op_sel:[0,0,0] op_sel_hi:[0,1,1] neg_lo:[0,0,0] neg_hi:[0,1,0]
	v_pk_add_f32 v[156:157], v[162:163], v[196:197] neg_lo:[0,1] neg_hi:[0,1]
	v_pk_add_f32 v[158:159], v[164:165], v[198:199] neg_lo:[0,1] neg_hi:[0,1]
	v_pk_add_f32 v[152:153], v[166:167], v[200:201] neg_lo:[0,1] neg_hi:[0,1]
	v_pk_add_f32 v[154:155], v[168:169], v[202:203] neg_lo:[0,1] neg_hi:[0,1]
	v_pk_add_f32 v[162:163], v[162:163], v[196:197]
	v_pk_add_f32 v[164:165], v[164:165], v[198:199]
	v_pk_add_f32 v[166:167], v[166:167], v[200:201]
	v_pk_add_f32 v[168:169], v[168:169], v[202:203]
	ds_write2_b64 v132, v[162:163], v[164:165] offset1:136
	ds_write2_b64 v160, v[166:167], v[168:169] offset0:16 offset1:152
	ds_write2_b64 v142, v[156:157], v[158:159] offset0:32 offset1:168
	ds_write2_b64 v140, v[152:153], v[154:155] offset0:48 offset1:184
	s_mov_b64 s[14:15], 0
	s_waitcnt lgkmcnt(0)
	s_barrier
	s_mov_b32 s0, 0
	s_mov_b64 s[30:31], -1
; #define LAS __attribute__((address_space(3)))
; __device__ __forceinline__ cf twc(cf ws, int k16) { if (k16 == 0) return ws; if (k16 == 4) return cf{ws.y, -ws.x}; return cmul(ws, cf{c16(k16), -s16(k16)}); }
; template <int LR> __device__ __forceinline__ void dit_reg(cf (&x)[1 << LR], cf w) {
;     constexpr int R = 1 << LR; cf wsv[LR]; wsv[0] = w;
; #pragma unroll
;     for (int s = 1; s < LR; ++s) wsv[s] = cmul(wsv[s - 1], wsv[s - 1]);
; #pragma unroll
;     for (int s = LR - 1; s >= 0; --s) { const int half = R >> (s + 1);
; #pragma unroll
;         for (int m0 = 0; m0 < R; m0 += 2 * half)
; #pragma unroll
;             for (int mm = 0; mm < half; ++mm) { const int ia = m0 + mm, ib = ia + half; const cf a = x[ia];
;                 const cf b = cmulc(x[ib], twc(wsv[s], (mm << s) * (16 / R)));
;                 x[ia] = cf{a.x + b.x, a.y + b.y}; x[ib] = cf{a.x - b.x, a.y - b.y}; } }
; template <int LR, bool INV> __device__ __forceinline__ void fft_pass(ldsf2 buf, int base, int stride, int twi) {
;     constexpr int R = 1 << LR; cf x[R];
;     const v2f wv = ((ldsf2)((LAS unsigned char*)buf + 139264))[twi];
; #pragma unroll
;     for (int m = 0; m < R; ++m) { const v2f v = buf[base + m * stride]; x[m] = cf{v.x, v.y}; }
;     const cf w{wv.x, wv.y};
;     if (INV) dit_reg<LR>(x, w); else dif_reg<LR>(x, w);
; #pragma unroll
;     for (int m = 0; m < R; ++m) buf[base + m * stride] = mkv2(x[m].x, x[m].y);
; }
.LBB0_369:
	v_add_u32_e32 v79, s0, v78
	v_ashrrev_i32_e32 v80, 4, v79
	v_lshl_add_u32 v79, v79, 3, 0
	v_lshl_add_u32 v79, v80, 3, v79
	ds_read2st64_b64 v[80:83], v79 offset1:17
	ds_read2st64_b64 v[84:87], v79 offset0:34 offset1:51
	ds_read2st64_b64 v[88:91], v79 offset0:68 offset1:85
	ds_read2st64_b64 v[92:95], v79 offset0:102 offset1:119
	s_movk_i32 s0, 0x200
	v_add_u32_e32 v126, s0, v78
	v_ashrrev_i32_e32 v128, 4, v126
	v_lshl_add_u32 v126, v126, 3, 0
	v_lshl_add_u32 v126, v128, 3, v126
	ds_read2st64_b64 v[134:137], v126 offset1:17
	ds_read2st64_b64 v[138:141], v126 offset0:34 offset1:51
	ds_read2st64_b64 v[152:155], v126 offset0:68 offset1:85
	ds_read2st64_b64 v[156:159], v126 offset0:102 offset1:119
	s_waitcnt lgkmcnt(4)
	v_pk_add_f32 v[98:99], v[232:233], v[232:233] op_sel:[0,1] op_sel_hi:[1,0] neg_lo:[0,0] neg_hi:[0,1]
	s_nop 0
	v_pk_mul_f32 v[100:101], v[98:99], s[16:17] op_sel:[0,0] op_sel_hi:[1,0]
	v_pk_mul_f32 v[102:103], v[98:99], s[16:17] op_sel:[1,0] op_sel_hi:[0,0] neg_lo:[0,0] neg_hi:[1,0]
	v_pk_mul_f32 v[108:109], v[82:83], v[236:237] op_sel:[1,1] op_sel_hi:[1,0]
	v_pk_mul_f32 v[110:111], v[86:87], v[236:237] op_sel:[1,1] op_sel_hi:[1,0]
	v_pk_mul_f32 v[112:113], v[90:91], v[236:237] op_sel:[1,1] op_sel_hi:[1,0]
	v_pk_mul_f32 v[114:115], v[94:95], v[236:237] op_sel:[1,1] op_sel_hi:[1,0]
	v_pk_fma_f32 v[108:109], v[82:83], v[236:237], v[108:109] op_sel:[0,0,0] op_sel_hi:[0,1,1] neg_lo:[0,0,0] neg_hi:[0,1,0]
	v_pk_fma_f32 v[110:111], v[86:87], v[236:237], v[110:111] op_sel:[0,0,0] op_sel_hi:[0,1,1] neg_lo:[0,0,0] neg_hi:[0,1,0]
	v_pk_fma_f32 v[112:113], v[90:91], v[236:237], v[112:113] op_sel:[0,0,0] op_sel_hi:[0,1,1] neg_lo:[0,0,0] neg_hi:[0,1,0]
	v_pk_fma_f32 v[114:115], v[94:95], v[236:237], v[114:115] op_sel:[0,0,0] op_sel_hi:[0,1,1] neg_lo:[0,0,0] neg_hi:[0,1,0]
	v_pk_add_f32 v[82:83], v[80:81], v[108:109] neg_lo:[0,1] neg_hi:[0,1]
	v_pk_add_f32 v[86:87], v[84:85], v[110:111] neg_lo:[0,1] neg_hi:[0,1]
	v_pk_add_f32 v[90:91], v[88:89], v[112:113] neg_lo:[0,1] neg_hi:[0,1]
	v_pk_add_f32 v[94:95], v[92:93], v[114:115] neg_lo:[0,1] neg_hi:[0,1]
	v_pk_add_f32 v[80:81], v[80:81], v[108:109]
	v_pk_add_f32 v[84:85], v[84:85], v[110:111]
	v_pk_add_f32 v[88:89], v[88:89], v[112:113]
	v_pk_add_f32 v[92:93], v[92:93], v[114:115]
	v_pk_mul_f32 v[108:109], v[84:85], v[234:235] op_sel:[1,1] op_sel_hi:[1,0]
	v_pk_mul_f32 v[110:111], v[86:87], v[234:235] op_sel:[1,0] op_sel_hi:[1,1]
	v_pk_mul_f32 v[112:113], v[92:93], v[234:235] op_sel:[1,1] op_sel_hi:[1,0]
	v_pk_mul_f32 v[114:115], v[94:95], v[234:235] op_sel:[1,0] op_sel_hi:[1,1]
	v_pk_fma_f32 v[108:109], v[84:85], v[234:235], v[108:109] op_sel:[0,0,0] op_sel_hi:[0,1,1] neg_lo:[0,0,0] neg_hi:[0,1,0]
	v_pk_fma_f32 v[110:111], v[86:87], v[234:235], v[110:111] op_sel:[0,1,0] op_sel_hi:[0,0,1] neg_lo:[0,0,1] neg_hi:[0,0,0]
	v_pk_fma_f32 v[112:113], v[92:93], v[234:235], v[112:113] op_sel:[0,0,0] op_sel_hi:[0,1,1] neg_lo:[0,0,0] neg_hi:[0,1,0]
	v_pk_fma_f32 v[114:115], v[94:95], v[234:235], v[114:115] op_sel:[0,1,0] op_sel_hi:[0,0,1] neg_lo:[0,0,1] neg_hi:[0,0,0]
	v_pk_add_f32 v[84:85], v[80:81], v[108:109] neg_lo:[0,1] neg_hi:[0,1]
	v_pk_add_f32 v[86:87], v[82:83], v[110:111] neg_lo:[0,1] neg_hi:[0,1]
	v_pk_add_f32 v[92:93], v[88:89], v[112:113] neg_lo:[0,1] neg_hi:[0,1]
	v_pk_add_f32 v[94:95], v[90:91], v[114:115] neg_lo:[0,1] neg_hi:[0,1]
	v_pk_add_f32 v[80:81], v[80:81], v[108:109]
	v_pk_add_f32 v[82:83], v[82:83], v[110:111]
	v_pk_add_f32 v[88:89], v[88:89], v[112:113]
	v_pk_add_f32 v[90:91], v[90:91], v[114:115]
	v_pk_mul_f32 v[108:109], v[88:89], v[232:233] op_sel:[1,1] op_sel_hi:[1,0]
	v_pk_mul_f32 v[110:111], v[90:91], v[100:101] op_sel:[1,1] op_sel_hi:[1,0]
	v_pk_mul_f32 v[112:113], v[92:93], v[232:233] op_sel:[1,0] op_sel_hi:[1,1]
	v_pk_mul_f32 v[114:115], v[94:95], v[102:103] op_sel:[1,1] op_sel_hi:[1,0]
	v_pk_fma_f32 v[108:109], v[88:89], v[232:233], v[108:109] op_sel:[0,0,0] op_sel_hi:[0,1,1] neg_lo:[0,0,0] neg_hi:[0,1,0]
	v_pk_fma_f32 v[110:111], v[90:91], v[100:101], v[110:111] op_sel:[0,0,0] op_sel_hi:[0,1,1] neg_lo:[0,0,0] neg_hi:[0,1,0]
	v_pk_fma_f32 v[112:113], v[92:93], v[232:233], v[112:113] op_sel:[0,1,0] op_sel_hi:[0,0,1] neg_lo:[0,0,1] neg_hi:[0,0,0]
	v_pk_fma_f32 v[114:115], v[94:95], v[102:103], v[114:115] op_sel:[0,0,0] op_sel_hi:[0,1,1] neg_lo:[0,0,0] neg_hi:[0,1,0]
	v_pk_add_f32 v[88:89], v[80:81], v[108:109] neg_lo:[0,1] neg_hi:[0,1]
	v_pk_add_f32 v[90:91], v[82:83], v[110:111] neg_lo:[0,1] neg_hi:[0,1]
	v_pk_add_f32 v[92:93], v[84:85], v[112:113] neg_lo:[0,1] neg_hi:[0,1]
	v_pk_add_f32 v[94:95], v[86:87], v[114:115] neg_lo:[0,1] neg_hi:[0,1]
	v_pk_add_f32 v[80:81], v[80:81], v[108:109]
	v_pk_add_f32 v[82:83], v[82:83], v[110:111]
	v_pk_add_f32 v[84:85], v[84:85], v[112:113]
	v_pk_add_f32 v[86:87], v[86:87], v[114:115]
	ds_write2st64_b64 v79, v[80:81], v[82:83] offset1:17
	ds_write2st64_b64 v79, v[84:85], v[86:87] offset0:34 offset1:51
	ds_write2st64_b64 v79, v[88:89], v[90:91] offset0:68 offset1:85
	ds_write2st64_b64 v79, v[92:93], v[94:95] offset0:102 offset1:119
	s_waitcnt lgkmcnt(4)
; #define LAS __attribute__((address_space(3)))
; template <int LR> __device__ __forceinline__ void dit_reg(cf (&x)[1 << LR], cf w) {
;     constexpr int R = 1 << LR; cf wsv[LR]; wsv[0] = w;
; #pragma unroll
;     for (int s = 1; s < LR; ++s) wsv[s] = cmul(wsv[s - 1], wsv[s - 1]);
; #pragma unroll
;     for (int s = LR - 1; s >= 0; --s) { const int half = R >> (s + 1);
; #pragma unroll
;         for (int m0 = 0; m0 < R; m0 += 2 * half)
; #pragma unroll
;             for (int mm = 0; mm < half; ++mm) { const int ia = m0 + mm, ib = ia + half; const cf a = x[ia];
;                 const cf b = cmulc(x[ib], twc(wsv[s], (mm << s) * (16 / R)));
;                 x[ia] = cf{a.x + b.x, a.y + b.y}; x[ib] = cf{a.x - b.x, a.y - b.y}; } }
; }
; __device__ __forceinline__ void lds_barrier() { asm volatile("s_waitcnt lgkmcnt(0)\n\ts_barrier" ::: "memory"); }
; template <int LR, bool INV> __device__ __forceinline__ void fft_pass(ldsf2 buf, int base, int stride, int twi) {
;     constexpr int R = 1 << LR; cf x[R];
;     const v2f wv = ((ldsf2)((LAS unsigned char*)buf + 139264))[twi];
; #pragma unroll
;     for (int m = 0; m < R; ++m) { const v2f v = buf[base + m * stride]; x[m] = cf{v.x, v.y}; }
;     const cf w{wv.x, wv.y};
;     if (INV) dit_reg<LR>(x, w); else dif_reg<LR>(x, w);
; #pragma unroll
;     for (int m = 0; m < R; ++m) buf[base + m * stride] = mkv2(x[m].x, x[m].y);
; __device__ void ph_hyena_fft(const Params& P, int j, const bf16_t* __restrict__ projAT, const float* __restrict__ kf, bf16_t* __restrict__ yaT, unsigned char* lds_raw) {
;     ...
;             { float xa[8], xb[8]; sconv8(xb0, n0, wb0, wb1, wb2, bb, xa); sconv8(xb1, n0, wb0, wb1, wb2, bb, xb);
;               const unsigned gw0[4] = {g0.x, g0.y, g0.z, g0.w}, gw1[4] = {g1.x, g1.y, g1.z, g1.w}; unsigned w0[4], w1[4];
; #pragma unroll
;               for (int k2 = 0; k2 < 4; ++k2) { const v2f ya = buf[ph0 + 2 * k2], yb = buf[ph0 + 2 * k2 + 1];
;                   const float ra = xa[2 * k2] * (ya.x * invN + sk1 * va[2 * k2]) * silu(__uint_as_float(gw0[k2] << 16));
;                   const float rb = xa[2 * k2 + 1] * (yb.x * invN + sk1 * va[2 * k2 + 1]) * silu(__uint_as_float(gw0[k2] & 0xffff0000u));
;                   const float rc = xb[2 * k2] * (ya.y * invN + sk1 * vb[2 * k2]) * silu(__uint_as_float(gw1[k2] << 16));
	v_pk_add_f32 v[142:143], v[240:241], v[240:241] op_sel:[0,1] op_sel_hi:[1,0] neg_lo:[0,0] neg_hi:[0,1]
	s_nop 0
	v_pk_mul_f32 v[160:161], v[142:143], s[16:17] op_sel:[0,0] op_sel_hi:[1,0]
	v_pk_mul_f32 v[162:163], v[142:143], s[16:17] op_sel:[1,0] op_sel_hi:[0,0] neg_lo:[0,0] neg_hi:[1,0]
	v_pk_mul_f32 v[168:169], v[136:137], v[244:245] op_sel:[1,1] op_sel_hi:[1,0]
	v_pk_mul_f32 v[170:171], v[140:141], v[244:245] op_sel:[1,1] op_sel_hi:[1,0]
	v_pk_mul_f32 v[172:173], v[154:155], v[244:245] op_sel:[1,1] op_sel_hi:[1,0]
	v_pk_mul_f32 v[174:175], v[158:159], v[244:245] op_sel:[1,1] op_sel_hi:[1,0]
	v_pk_fma_f32 v[168:169], v[136:137], v[244:245], v[168:169] op_sel:[0,0,0] op_sel_hi:[0,1,1] neg_lo:[0,0,0] neg_hi:[0,1,0]
	v_pk_fma_f32 v[170:171], v[140:141], v[244:245], v[170:171] op_sel:[0,0,0] op_sel_hi:[0,1,1] neg_lo:[0,0,0] neg_hi:[0,1,0]
	v_pk_fma_f32 v[172:173], v[154:155], v[244:245], v[172:173] op_sel:[0,0,0] op_sel_hi:[0,1,1] neg_lo:[0,0,0] neg_hi:[0,1,0]
	v_pk_fma_f32 v[174:175], v[158:159], v[244:245], v[174:175] op_sel:[0,0,0] op_sel_hi:[0,1,1] neg_lo:[0,0,0] neg_hi:[0,1,0]
	v_pk_add_f32 v[136:137], v[134:135], v[168:169] neg_lo:[0,1] neg_hi:[0,1]
	v_pk_add_f32 v[140:141], v[138:139], v[170:171] neg_lo:[0,1] neg_hi:[0,1]
	v_pk_add_f32 v[154:155], v[152:153], v[172:173] neg_lo:[0,1] neg_hi:[0,1]
	v_pk_add_f32 v[158:159], v[156:157], v[174:175] neg_lo:[0,1] neg_hi:[0,1]
	v_pk_add_f32 v[134:135], v[134:135], v[168:169]
	v_pk_add_f32 v[138:139], v[138:139], v[170:171]
	v_pk_add_f32 v[152:153], v[152:153], v[172:173]
	v_pk_add_f32 v[156:157], v[156:157], v[174:175]
	v_pk_mul_f32 v[168:169], v[138:139], v[242:243] op_sel:[1,1] op_sel_hi:[1,0]
	v_pk_mul_f32 v[170:171], v[140:141], v[242:243] op_sel:[1,0] op_sel_hi:[1,1]
	v_pk_mul_f32 v[172:173], v[156:157], v[242:243] op_sel:[1,1] op_sel_hi:[1,0]
	v_pk_mul_f32 v[174:175], v[158:159], v[242:243] op_sel:[1,0] op_sel_hi:[1,1]
	v_pk_fma_f32 v[168:169], v[138:139], v[242:243], v[168:169] op_sel:[0,0,0] op_sel_hi:[0,1,1] neg_lo:[0,0,0] neg_hi:[0,1,0]
	v_pk_fma_f32 v[170:171], v[140:141], v[242:243], v[170:171] op_sel:[0,1,0] op_sel_hi:[0,0,1] neg_lo:[0,0,1] neg_hi:[0,0,0]
	v_pk_fma_f32 v[172:173], v[156:157], v[242:243], v[172:173] op_sel:[0,0,0] op_sel_hi:[0,1,1] neg_lo:[0,0,0] neg_hi:[0,1,0]
	v_pk_fma_f32 v[174:175], v[158:159], v[242:243], v[174:175] op_sel:[0,1,0] op_sel_hi:[0,0,1] neg_lo:[0,0,1] neg_hi:[0,0,0]
	v_pk_add_f32 v[138:139], v[134:135], v[168:169] neg_lo:[0,1] neg_hi:[0,1]
	v_pk_add_f32 v[140:141], v[136:137], v[170:171] neg_lo:[0,1] neg_hi:[0,1]
	v_pk_add_f32 v[156:157], v[152:153], v[172:173] neg_lo:[0,1] neg_hi:[0,1]
	v_pk_add_f32 v[158:159], v[154:155], v[174:175] neg_lo:[0,1] neg_hi:[0,1]
	v_pk_add_f32 v[134:135], v[134:135], v[168:169]
	v_pk_add_f32 v[136:137], v[136:137], v[170:171]
	v_pk_add_f32 v[152:153], v[152:153], v[172:173]
	v_pk_add_f32 v[154:155], v[154:155], v[174:175]
	v_pk_mul_f32 v[168:169], v[152:153], v[240:241] op_sel:[1,1] op_sel_hi:[1,0]
	v_pk_mul_f32 v[170:171], v[154:155], v[160:161] op_sel:[1,1] op_sel_hi:[1,0]
	v_pk_mul_f32 v[172:173], v[156:157], v[240:241] op_sel:[1,0] op_sel_hi:[1,1]
	v_pk_mul_f32 v[174:175], v[158:159], v[162:163] op_sel:[1,1] op_sel_hi:[1,0]
	v_pk_fma_f32 v[168:169], v[152:153], v[240:241], v[168:169] op_sel:[0,0,0] op_sel_hi:[0,1,1] neg_lo:[0,0,0] neg_hi:[0,1,0]
	v_pk_fma_f32 v[170:171], v[154:155], v[160:161], v[170:171] op_sel:[0,0,0] op_sel_hi:[0,1,1] neg_lo:[0,0,0] neg_hi:[0,1,0]
	v_pk_fma_f32 v[172:173], v[156:157], v[240:241], v[172:173] op_sel:[0,1,0] op_sel_hi:[0,0,1] neg_lo:[0,0,1] neg_hi:[0,0,0]
	v_pk_fma_f32 v[174:175], v[158:159], v[162:163], v[174:175] op_sel:[0,0,0] op_sel_hi:[0,1,1] neg_lo:[0,0,0] neg_hi:[0,1,0]
	v_pk_add_f32 v[152:153], v[134:135], v[168:169] neg_lo:[0,1] neg_hi:[0,1]
	v_pk_add_f32 v[154:155], v[136:137], v[170:171] neg_lo:[0,1] neg_hi:[0,1]
	v_pk_add_f32 v[156:157], v[138:139], v[172:173] neg_lo:[0,1] neg_hi:[0,1]
	v_pk_add_f32 v[158:159], v[140:141], v[174:175] neg_lo:[0,1] neg_hi:[0,1]
	v_pk_add_f32 v[134:135], v[134:135], v[168:169]
	v_pk_add_f32 v[136:137], v[136:137], v[170:171]
	v_pk_add_f32 v[138:139], v[138:139], v[172:173]
	v_pk_add_f32 v[140:141], v[140:141], v[174:175]
	ds_write2st64_b64 v126, v[134:135], v[136:137] offset1:17
	ds_write2st64_b64 v126, v[138:139], v[140:141] offset0:34 offset1:51
	ds_write2st64_b64 v126, v[152:153], v[154:155] offset0:68 offset1:85
	ds_write2st64_b64 v126, v[156:157], v[158:159] offset0:102 offset1:119
	s_mov_b64 s[30:31], 0
	s_waitcnt vmcnt(6)
	v_lshlrev_b32_e32 v78, 16, v147
	v_cndmask_b32_e64 v97, 0, v78, s[42:43]
	s_waitcnt vmcnt(5)
	v_lshlrev_b32_e32 v78, 16, v148
	s_waitcnt vmcnt(1)
	v_lshlrev_b32_e32 v114, 16, v12
	v_cndmask_b32_e64 v99, 0, v78, s[44:45]
	v_and_b32_e32 v12, 0xffff0000, v12
	v_mul_f32_e32 v78, 0xbfb8aa3b, v114
	v_exp_f32_e32 v78, v78
	v_mul_f32_e32 v82, 0xbfb8aa3b, v12
	v_lshlrev_b32_e32 v104, 16, v5
	v_exp_f32_e32 v82, v82
	v_and_b32_e32 v102, 0xffff0000, v4
	v_mov_b32_e32 v96, v104
	v_lshlrev_b32_e32 v100, 16, v4
	v_and_b32_e32 v103, 0xffff0000, v5
	v_mov_b32_e32 v101, v102
	v_pk_mul_f32 v[96:97], v[38:39], v[96:97]
	v_lshlrev_b32_e32 v115, 16, v13
	v_pk_fma_f32 v[96:97], v[38:39], v[100:101], v[96:97] op_sel:[0,0,1] op_sel_hi:[1,1,0]
	v_mov_b32_e32 v101, v104
	v_pk_mul_f32 v[122:123], v[54:55], v[102:103]
	v_add_f32_e32 v78, 1.0, v78
	v_pk_fma_f32 v[100:101], v[52:53], v[100:101], v[122:123]
	v_rcp_f32_e32 v122, v78
	v_add_f32_e32 v78, 1.0, v82
	v_mul_f32_e32 v82, 0xbfb8aa3b, v115
	v_exp_f32_e32 v82, v82
	s_waitcnt lgkmcnt(0)
	s_barrier
; __device__ __forceinline__ bf16_t f2bf(float f) { unsigned u = __float_as_uint(f); u += 0x7FFFu + ((u >> 16) & 1u); return (bf16_t)(u >> 16); }
; __device__ __forceinline__ float silu(float x) { return x * __builtin_amdgcn_rcpf(1.0f + __expf(-x)); }
; __device__ void ph_hyena_fft(const Params& P, int j, const bf16_t* __restrict__ projAT, const float* __restrict__ kf, bf16_t* __restrict__ yaT, unsigned char* lds_raw) {
;     ...
;             { float xa[8], xb[8]; sconv8(xb0, n0, wb0, wb1, wb2, bb, xa); sconv8(xb1, n0, wb0, wb1, wb2, bb, xb);
;               const unsigned gw0[4] = {g0.x, g0.y, g0.z, g0.w}, gw1[4] = {g1.x, g1.y, g1.z, g1.w}; unsigned w0[4], w1[4];
; #pragma unroll
;               for (int k2 = 0; k2 < 4; ++k2) { const v2f ya = buf[ph0 + 2 * k2], yb = buf[ph0 + 2 * k2 + 1];
;                   const float ra = xa[2 * k2] * (ya.x * invN + sk1 * va[2 * k2]) * silu(__uint_as_float(gw0[k2] << 16));
;                   const float rb = xa[2 * k2 + 1] * (yb.x * invN + sk1 * va[2 * k2 + 1]) * silu(__uint_as_float(gw0[k2] & 0xffff0000u));
;                   const float rc = xb[2 * k2] * (ya.y * invN + sk1 * vb[2 * k2]) * silu(__uint_as_float(gw1[k2] << 16));
;                   const float rd = xb[2 * k2 + 1] * (yb.y * invN + sk1 * vb[2 * k2 + 1]) * silu(__uint_as_float(gw1[k2] & 0xffff0000u));
;                   w0[k2] = (unsigned)f2bf(ra) | ((unsigned)f2bf(rb) << 16); w1[k2] = (unsigned)f2bf(rc) | ((unsigned)f2bf(rd) << 16); }
	ds_read2_b64 v[88:91], v145 offset1:1
	ds_read2_b64 v[92:95], v145 offset0:2 offset1:3
	v_and_b32_e32 v13, 0xffff0000, v13
	v_rcp_f32_e32 v124, v78
	v_add_f32_e32 v78, 1.0, v82
	v_rcp_f32_e32 v123, v78
	v_mul_f32_e32 v78, 0xbfb8aa3b, v13
	v_exp_f32_e32 v78, v78
	s_waitcnt lgkmcnt(1)
	v_mov_b32_e32 v126, v88
	s_waitcnt lgkmcnt(0)
	v_mov_b32_e32 v127, v92
	v_pk_fma_f32 v[96:97], v[40:41], v[102:103], v[96:97]
	v_pk_mul_f32 v[126:127], v[126:127], s[80:81] op_sel_hi:[1,0]
	v_pk_add_f32 v[96:97], v[42:43], v[96:97]
	v_pk_fma_f32 v[76:77], v[46:47], v[76:77], v[126:127]
	v_add_f32_e32 v78, 1.0, v78
	v_pk_mul_f32 v[76:77], v[96:97], v[76:77]
	v_pk_mul_f32 v[96:97], v[122:123], v[114:115]
	v_rcp_f32_e32 v125, v78
	v_lshlrev_b32_e32 v105, 16, v6
	v_pk_mul_f32 v[76:77], v[96:97], v[76:77]
	v_mov_b32_e32 v96, v90
	v_mov_b32_e32 v97, v94
	v_pk_fma_f32 v[100:101], v[40:41], v[104:105], v[100:101]
	v_pk_mul_f32 v[96:97], v[96:97], s[80:81] op_sel_hi:[1,0]
	v_pk_add_f32 v[100:101], v[42:43], v[100:101]
	v_pk_fma_f32 v[74:75], v[46:47], v[74:75], v[96:97]
	v_pk_mul_f32 v[12:13], v[124:125], v[12:13]
	v_pk_mul_f32 v[74:75], v[100:101], v[74:75]
	v_lshlrev_b32_e32 v118, 16, v14
	v_pk_mul_f32 v[12:13], v[12:13], v[74:75]
	v_and_b32_sdwa v74, v77, v229 dst_sel:DWORD dst_unused:UNUSED_PAD src0_sel:WORD_1 src1_sel:DWORD
	v_add3_u32 v74, v77, v74, s33
	v_and_b32_sdwa v77, v12, v229 dst_sel:DWORD dst_unused:UNUSED_PAD src0_sel:WORD_1 src1_sel:DWORD
	v_and_b32_sdwa v75, v76, v229 dst_sel:DWORD dst_unused:UNUSED_PAD src0_sel:WORD_1 src1_sel:DWORD
	v_add3_u32 v12, v12, v77, s33
	v_and_b32_e32 v14, 0xffff0000, v14
	v_add3_u32 v75, v76, v75, s33
	v_and_b32_e32 v12, 0xffff0000, v12
	v_or_b32_sdwa v12, v12, v75 dst_sel:DWORD dst_unused:UNUSED_PAD src0_sel:DWORD src1_sel:WORD_1
	v_mul_f32_e32 v75, 0xbfb8aa3b, v14
	v_exp_f32_e32 v75, v75
	v_lshlrev_b32_e32 v4, 16, v149
	v_lshlrev_b32_e32 v119, 16, v15
	v_and_b32_sdwa v76, v13, v229 dst_sel:DWORD dst_unused:UNUSED_PAD src0_sel:WORD_1 src1_sel:DWORD
	v_add_f32_e32 v75, 1.0, v75
	v_cndmask_b32_e64 v111, 0, v4, s[42:43]
	v_lshlrev_b32_e32 v4, 16, v150
	v_add3_u32 v13, v13, v76, s33
	v_rcp_f32_e32 v76, v75
	v_mul_f32_e32 v75, 0xbfb8aa3b, v119
	v_and_b32_e32 v106, 0xffff0000, v6
	v_lshlrev_b32_e32 v109, 16, v7
	v_and_b32_e32 v107, 0xffff0000, v7
	v_cndmask_b32_e64 v79, 0, v4, s[44:45]
	v_lshlrev_b32_e32 v112, 16, v8
	v_and_b32_e32 v86, 0xffff0000, v8
	v_lshlrev_b32_e32 v80, 16, v9
	v_and_b32_e32 v87, 0xffff0000, v9
	v_lshlrev_b32_e32 v81, 16, v10
	v_and_b32_e32 v84, 0xffff0000, v10
	v_lshlrev_b32_e32 v83, 16, v11
	v_and_b32_e32 v85, 0xffff0000, v11
	ds_read2_b64 v[4:7], v145 offset0:4 offset1:5
	ds_read2_b64 v[8:11], v145 offset0:6 offset1:7
	v_exp_f32_e32 v75, v75
	v_and_b32_e32 v15, 0xffff0000, v15
	v_and_b32_e32 v13, 0xffff0000, v13
	s_waitcnt lgkmcnt(1)
	v_mov_b32_e32 v96, v4
	v_add_f32_e32 v4, 1.0, v75
	v_rcp_f32_e32 v75, v4
	v_mul_f32_e32 v4, 0xbfb8aa3b, v15
	v_exp_f32_e32 v4, v4
	s_waitcnt lgkmcnt(0)
	v_mov_b32_e32 v97, v8
	v_or_b32_sdwa v13, v13, v74 dst_sel:DWORD dst_unused:UNUSED_PAD src0_sel:DWORD src1_sel:WORD_1
	v_mul_f32_e32 v74, 0xbfb8aa3b, v118
	v_add_f32_e32 v4, 1.0, v4
	v_pk_mul_f32 v[96:97], v[96:97], s[80:81] op_sel_hi:[1,0]
	v_rcp_f32_e32 v77, v4
	v_exp_f32_e32 v74, v74
	v_pk_fma_f32 v[72:73], v[46:47], v[72:73], v[96:97]
	v_mov_b32_e32 v96, v6
	v_mov_b32_e32 v97, v10
	v_pk_mul_f32 v[96:97], v[96:97], s[80:81] op_sel_hi:[1,0]
	v_pk_mul_f32 v[14:15], v[76:77], v[14:15]
	v_pk_fma_f32 v[70:71], v[46:47], v[70:71], v[96:97]
	v_mov_b32_e32 v96, v105
	v_mov_b32_e32 v97, v109
	v_pk_mov_b32 v[76:77], v[102:103], v[106:107] op_sel:[1,0]
	v_pk_mul_f32 v[96:97], v[54:55], v[96:97]
	v_mov_b32_e32 v104, v107
	v_mov_b32_e32 v108, v106
	v_add_f32_e32 v74, 1.0, v74
	v_pk_fma_f32 v[76:77], v[52:53], v[76:77], v[96:97]
	v_pk_mul_f32 v[96:97], v[38:39], v[104:105]
	v_mov_b32_e32 v98, v109
	v_rcp_f32_e32 v74, v74
	v_pk_fma_f32 v[96:97], v[38:39], v[108:109], v[96:97] op_sel:[0,0,1] op_sel_hi:[1,1,0]
	v_pk_fma_f32 v[76:77], v[40:41], v[106:107], v[76:77]
	v_pk_fma_f32 v[96:97], v[40:41], v[98:99], v[96:97]
	v_pk_add_f32 v[76:77], v[42:43], v[76:77]
	v_pk_add_f32 v[96:97], v[42:43], v[96:97]
	v_pk_mul_f32 v[74:75], v[74:75], v[118:119]
	v_pk_mul_f32 v[70:71], v[96:97], v[70:71]
	v_pk_mul_f32 v[72:73], v[76:77], v[72:73]
	v_pk_mul_f32 v[14:15], v[14:15], v[70:71]
	v_pk_mul_f32 v[72:73], v[74:75], v[72:73]
	v_and_b32_sdwa v8, v15, v229 dst_sel:DWORD dst_unused:UNUSED_PAD src0_sel:WORD_1 src1_sel:DWORD
	v_and_b32_sdwa v4, v73, v229 dst_sel:DWORD dst_unused:UNUSED_PAD src0_sel:WORD_1 src1_sel:DWORD
	v_and_b32_sdwa v10, v14, v229 dst_sel:DWORD dst_unused:UNUSED_PAD src0_sel:WORD_1 src1_sel:DWORD
	v_add3_u32 v8, v15, v8, s33
	s_waitcnt vmcnt(0)
; __device__ __forceinline__ bf16_t f2bf(float f) { unsigned u = __float_as_uint(f); u += 0x7FFFu + ((u >> 16) & 1u); return (bf16_t)(u >> 16); }
; __device__ __forceinline__ float silu(float x) { return x * __builtin_amdgcn_rcpf(1.0f + __expf(-x)); }
; __device__ __forceinline__ void lds_barrier() { asm volatile("s_waitcnt lgkmcnt(0)\n\ts_barrier" ::: "memory"); }
; __device__ void ph_hyena_fft(const Params& P, int j, const bf16_t* __restrict__ projAT, const float* __restrict__ kf, bf16_t* __restrict__ yaT, unsigned char* lds_raw) {
;     ...
;             { float xa[8], xb[8]; sconv8(xb0, n0, wb0, wb1, wb2, bb, xa); sconv8(xb1, n0, wb0, wb1, wb2, bb, xb);
;               const unsigned gw0[4] = {g0.x, g0.y, g0.z, g0.w}, gw1[4] = {g1.x, g1.y, g1.z, g1.w}; unsigned w0[4], w1[4];
; #pragma unroll
;               for (int k2 = 0; k2 < 4; ++k2) { const v2f ya = buf[ph0 + 2 * k2], yb = buf[ph0 + 2 * k2 + 1];
;                   const float ra = xa[2 * k2] * (ya.x * invN + sk1 * va[2 * k2]) * silu(__uint_as_float(gw0[k2] << 16));
;                   const float rb = xa[2 * k2 + 1] * (yb.x * invN + sk1 * va[2 * k2 + 1]) * silu(__uint_as_float(gw0[k2] & 0xffff0000u));
;                   const float rc = xb[2 * k2] * (ya.y * invN + sk1 * vb[2 * k2]) * silu(__uint_as_float(gw1[k2] << 16));
;                   const float rd = xb[2 * k2 + 1] * (yb.y * invN + sk1 * vb[2 * k2 + 1]) * silu(__uint_as_float(gw1[k2] & 0xffff0000u));
;                   w0[k2] = (unsigned)f2bf(ra) | ((unsigned)f2bf(rb) << 16); w1[k2] = (unsigned)f2bf(rc) | ((unsigned)f2bf(rd) << 16); }
;               *(uint4*)(yaT + (size_t)c * T_TOK + o0 + n0) = make_uint4(w0[0], w0[1], w0[2], w0[3]);
;               *(uint4*)(yaT + (size_t)c * T_TOK + o1 + n0) = make_uint4(w1[0], w1[1], w1[2], w1[3]); }
;             lds_barrier();
;         }
	v_lshlrev_b32_e32 v116, 16, v0
	v_and_b32_sdwa v6, v72, v229 dst_sel:DWORD dst_unused:UNUSED_PAD src0_sel:WORD_1 src1_sel:DWORD
	v_add3_u32 v4, v73, v4, s33
	v_add3_u32 v10, v14, v10, s33
	v_and_b32_e32 v8, 0xffff0000, v8
	v_and_b32_e32 v0, 0xffff0000, v0
	v_add3_u32 v6, v72, v6, s33
	v_and_b32_e32 v10, 0xffff0000, v10
	v_or_b32_sdwa v15, v8, v4 dst_sel:DWORD dst_unused:UNUSED_PAD src0_sel:DWORD src1_sel:WORD_1
	v_mul_f32_e32 v4, 0xbfb8aa3b, v116
	v_or_b32_sdwa v14, v10, v6 dst_sel:DWORD dst_unused:UNUSED_PAD src0_sel:DWORD src1_sel:WORD_1
	v_exp_f32_e32 v4, v4
	v_mul_f32_e32 v6, 0xbfb8aa3b, v0
	v_exp_f32_e32 v6, v6
	v_lshlrev_b32_e32 v117, 16, v1
	v_add_f32_e32 v4, 1.0, v4
	v_rcp_f32_e32 v72, v4
	v_add_f32_e32 v4, 1.0, v6
	v_rcp_f32_e32 v74, v4
	v_mul_f32_e32 v4, 0xbfb8aa3b, v117
	v_exp_f32_e32 v4, v4
	v_and_b32_e32 v1, 0xffff0000, v1
	v_lshl_add_u64 v[120:121], v[50:51], 0, s[62:63]
	v_mov_b32_e32 v110, v80
	v_add_f32_e32 v4, 1.0, v4
	v_rcp_f32_e32 v73, v4
	v_mul_f32_e32 v4, 0xbfb8aa3b, v1
	v_exp_f32_e32 v4, v4
	global_store_dwordx4 v[120:121], v[12:15], off
	v_mov_b32_e32 v113, v86
	v_mov_b32_e32 v92, v89
	v_pk_mul_f32 v[14:15], v[38:39], v[110:111]
	v_pk_mul_f32 v[76:77], v[92:93], s[80:81] op_sel_hi:[1,0]
	v_pk_fma_f32 v[14:15], v[38:39], v[112:113], v[14:15] op_sel:[0,0,1] op_sel_hi:[1,1,0]
	v_add_f32_e32 v4, 1.0, v4
	v_pk_fma_f32 v[14:15], v[40:41], v[86:87], v[14:15]
	v_mov_b32_e32 v113, v80
	v_pk_add_f32 v[14:15], v[42:43], v[14:15]
	v_pk_mul_f32 v[70:71], v[54:55], v[86:87]
	v_pk_fma_f32 v[68:69], v[46:47], v[68:69], v[76:77]
	v_rcp_f32_e32 v75, v4
	v_pk_fma_f32 v[70:71], v[52:53], v[112:113], v[70:71]
	v_pk_mul_f32 v[14:15], v[14:15], v[68:69]
	v_pk_mul_f32 v[68:69], v[72:73], v[116:117]
	v_mov_b32_e32 v94, v91
	v_pk_fma_f32 v[70:71], v[40:41], v[80:81], v[70:71]
	v_pk_mul_f32 v[14:15], v[68:69], v[14:15]
	v_pk_mul_f32 v[68:69], v[94:95], s[80:81] op_sel_hi:[1,0]
	v_pk_add_f32 v[70:71], v[42:43], v[70:71]
	v_pk_fma_f32 v[66:67], v[46:47], v[66:67], v[68:69]
	v_pk_mul_f32 v[0:1], v[74:75], v[0:1]
	v_pk_mul_f32 v[66:67], v[70:71], v[66:67]
	v_and_b32_sdwa v6, v14, v229 dst_sel:DWORD dst_unused:UNUSED_PAD src0_sel:WORD_1 src1_sel:DWORD
	v_pk_mul_f32 v[0:1], v[0:1], v[66:67]
	v_and_b32_sdwa v4, v15, v229 dst_sel:DWORD dst_unused:UNUSED_PAD src0_sel:WORD_1 src1_sel:DWORD
	v_and_b32_sdwa v10, v0, v229 dst_sel:DWORD dst_unused:UNUSED_PAD src0_sel:WORD_1 src1_sel:DWORD
	v_and_b32_sdwa v8, v1, v229 dst_sel:DWORD dst_unused:UNUSED_PAD src0_sel:WORD_1 src1_sel:DWORD
	v_add3_u32 v0, v0, v10, s33
	v_add3_u32 v6, v14, v6, s33
	v_add3_u32 v1, v1, v8, s33
	v_and_b32_e32 v0, 0xffff0000, v0
	v_lshlrev_b32_e32 v14, 16, v2
	v_and_b32_e32 v2, 0xffff0000, v2
	v_add3_u32 v4, v15, v4, s33
	v_and_b32_e32 v1, 0xffff0000, v1
	v_or_b32_sdwa v0, v0, v6 dst_sel:DWORD dst_unused:UNUSED_PAD src0_sel:DWORD src1_sel:WORD_1
	v_lshlrev_b32_e32 v15, 16, v3
	v_mul_f32_e32 v6, 0xbfb8aa3b, v2
	v_or_b32_sdwa v1, v1, v4 dst_sel:DWORD dst_unused:UNUSED_PAD src0_sel:DWORD src1_sel:WORD_1
	v_mul_f32_e32 v4, 0xbfb8aa3b, v14
	v_exp_f32_e32 v6, v6
	v_mul_f32_e32 v8, 0xbfb8aa3b, v15
	v_exp_f32_e32 v4, v4
	v_exp_f32_e32 v10, v8
	v_and_b32_e32 v3, 0xffff0000, v3
	v_add_f32_e32 v6, 1.0, v6
	v_add_f32_e32 v4, 1.0, v4
	v_rcp_f32_e32 v66, v6
	v_mov_b32_e32 v8, v5
	v_add_f32_e32 v5, 1.0, v10
	v_mul_f32_e32 v6, 0xbfb8aa3b, v3
	v_rcp_f32_e32 v4, v4
	v_rcp_f32_e32 v5, v5
	v_exp_f32_e32 v6, v6
	v_mov_b32_e32 v10, v7
	v_mov_b32_e32 v80, v85
	v_pk_mul_f32 v[4:5], v[4:5], v[14:15]
	v_add_f32_e32 v6, 1.0, v6
	v_mov_b32_e32 v14, v81
	v_mov_b32_e32 v15, v83
	v_rcp_f32_e32 v67, v6
	v_pk_mul_f32 v[6:7], v[10:11], s[80:81] op_sel_hi:[1,0]
	v_pk_mov_b32 v[10:11], v[86:87], v[84:85] op_sel:[1,0]
	v_pk_mul_f32 v[14:15], v[54:55], v[14:15]
	v_mov_b32_e32 v82, v84
	v_pk_fma_f32 v[10:11], v[52:53], v[10:11], v[14:15]
	v_pk_mul_f32 v[14:15], v[38:39], v[80:81]
	v_mov_b32_e32 v78, v83
	v_pk_mul_f32 v[8:9], v[8:9], s[80:81] op_sel_hi:[1,0]
	v_pk_fma_f32 v[10:11], v[40:41], v[84:85], v[10:11]
	v_pk_fma_f32 v[14:15], v[38:39], v[82:83], v[14:15] op_sel:[0,0,1] op_sel_hi:[1,1,0]
	v_pk_fma_f32 v[8:9], v[46:47], v[64:65], v[8:9]
	v_pk_add_f32 v[10:11], v[42:43], v[10:11]
	v_pk_fma_f32 v[14:15], v[40:41], v[78:79], v[14:15]
	v_pk_fma_f32 v[6:7], v[46:47], v[62:63], v[6:7]
	v_pk_add_f32 v[14:15], v[42:43], v[14:15]
	v_pk_mul_f32 v[8:9], v[10:11], v[8:9]
	v_pk_mul_f32 v[2:3], v[66:67], v[2:3]
	v_pk_mul_f32 v[4:5], v[4:5], v[8:9]
	v_pk_mul_f32 v[6:7], v[14:15], v[6:7]
	s_mov_b32 s7, s63
	v_pk_mul_f32 v[2:3], v[2:3], v[6:7]
	v_and_b32_sdwa v6, v5, v229 dst_sel:DWORD dst_unused:UNUSED_PAD src0_sel:WORD_1 src1_sel:DWORD
	v_and_b32_sdwa v7, v4, v229 dst_sel:DWORD dst_unused:UNUSED_PAD src0_sel:WORD_1 src1_sel:DWORD
	v_add3_u32 v4, v4, v7, s33
	v_add3_u32 v5, v5, v6, s33
	v_and_b32_sdwa v6, v3, v229 dst_sel:DWORD dst_unused:UNUSED_PAD src0_sel:WORD_1 src1_sel:DWORD
	v_and_b32_sdwa v7, v2, v229 dst_sel:DWORD dst_unused:UNUSED_PAD src0_sel:WORD_1 src1_sel:DWORD
	v_add3_u32 v3, v3, v6, s33
	v_add3_u32 v2, v2, v7, s33
	v_and_b32_e32 v3, 0xffff0000, v3
	v_and_b32_e32 v2, 0xffff0000, v2
	v_lshl_add_u64 v[12:13], v[50:51], 0, s[6:7]
	v_or_b32_sdwa v3, v3, v5 dst_sel:DWORD dst_unused:UNUSED_PAD src0_sel:DWORD src1_sel:WORD_1
	v_or_b32_sdwa v2, v2, v4 dst_sel:DWORD dst_unused:UNUSED_PAD src0_sel:DWORD src1_sel:WORD_1
	global_store_dwordx4 v[12:13], v[0:3], off
	s_waitcnt lgkmcnt(0)
	s_barrier
	s_add_i32 s53, s53, 1
	s_cmp_eq_u32 s53, 4
	s_cbranch_scc0 .LBB0_346
	s_add_i32 s46, s46, s22
	v_readlane_b32 s60, v255, 27
	s_cmpk_gt_i32 s46, 0x3ff
	v_readlane_b32 s61, v255, 28
	s_movk_i32 s59, 0xffd0
	s_cbranch_scc0 .LBB0_333

; template <class Pol> ...
;     f32x16 sc;
; #pragma unroll
;     for (int i = 0; i < 16; ++i) sc[i] = 0.f;
; #pragma unroll
;     for (int s = 0; s < 4; ++s) sc = __builtin_amdgcn_mfma_f32_32x32x16_bf16(kf[s], qf[s], sc, 0, 0, 0);
;     attn_loadk<Pol>(kbase, pol, fbn, r, hh, kf);
;     pol.scores(fb, r, hh, sc);
;     if (first) { float bm = sc[0];
; #pragma unroll
;         for (int i = 1; i < 16; ++i) bm = fmaxf(bm, sc[i]);
;         bm = fmaxf(bm, bperm_f(xaddr, bm)); m_run = fmaxf(bm, -40.0f); }
;     float psum = 0.f;
; #pragma unroll
;     for (int i = 0; i < 16; ++i) { const float p = __builtin_amdgcn_exp2f(sc[i] - m_run); sc[i] = p; psum += p; }
;     l_run += psum;
;     { const int lane = hh * 32 + r;
;       asm volatile("" ::: "memory");
; #pragma unroll
;       for (int j = 0; j < 4; ++j) *(LAS u32x4a*)(wl + (8 * j + (lane >> 3)) * 144 + (lane & 7) * 16) = vg[j];
;       asm volatile("" ::: "memory"); }
;     attn_loadv<Pol>(vbase, pol, fbn, r, hh, vg);
;     u32x4a va[2], vb[2];
;     { const LAS unsigned short* rp = (const LAS unsigned short*)(wl + (4 * hh) * 144 + r * 2);
; #pragma unroll
;       for (int s = 0; s < 2; ++s)
; #pragma unroll
;         for (int jx = 0; jx < 4; ++jx) { const int k0 = 16 * s + 8 * ((2 * jx) >> 2) + ((2 * jx) & 3), k1 = k0 + 1;
;             va[s][jx] = (unsigned)rp[k0 * 72] | ((unsigned)rp[k1 * 72] << 16); vb[s][jx] = (unsigned)rp[k0 * 72 + 32] | ((unsigned)rp[k1 * 72 + 32] << 16); } }
; #pragma unroll
;     for (int s = 0; s < 2; ++s) { f32x8v t;
; #pragma unroll
;         for (int jx = 0; jx < 8; ++jx) t[jx] = sc[8 * s + jx];
;         const bf16x8s pf = __builtin_bit_cast(bf16x8s, __builtin_convertvector(t, bf16x8n));
;         o0 = __builtin_amdgcn_mfma_f32_32x32x16_bf16(__builtin_bit_cast(bf16x8s, va[s]), pf, o0, 0, 0, 0);
;         o1 = __builtin_amdgcn_mfma_f32_32x32x16_bf16(__builtin_bit_cast(bf16x8s, vb[s]), pf, o1, 0, 0, 0); }
; template <class Pol, int MODE>
; __device__ __forceinline__ void attn_wave_task(const bf16_t* __restrict__ proj, int b, int h, Pol pol, bf16_t* __restrict__ yout, int lane, float* __restrict__ X, LAS unsigned char* wl) {
;     ...
;     constexpr int NB = Pol::NB;
;     bf16x8s kf[4]; u32x4a vfA[4];
;     attn_loadk<Pol>(kbase, pol, 0, r, hh, kf);
;     attn_loadv<Pol>(vbase, pol, 0, r, hh, vfA);
; #pragma unroll 1
;     for (int fb = 0; fb < NB; ++fb)
.LBB0_599:
	s_or_b64 exec, exec, s[6:7]
	v_subrev_u32_e32 v34, 64, v173
	v_or_b32_e32 v175, v34, v151
	v_med3_i32 v32, v175, 0, v248
	v_lshlrev_b32_e32 v192, 7, v32
	v_lshl_add_u64 v[32:33], v[122:123], 0, v[192:193]
	global_load_dwordx4 v[92:95], v[32:33], off
	global_load_dwordx4 v[72:75], v[32:33], off offset:32
	global_load_dwordx4 v[68:71], v[32:33], off offset:64
	global_load_dwordx4 v[64:67], v[32:33], off offset:96
	v_or_b32_e32 v32, v34, v156
	v_med3_i32 v32, v32, 0, v248
	v_add_u32_e32 v34, v163, v173
	v_lshlrev_b32_e32 v192, 7, v32
	v_med3_i32 v34, v34, 0, v248
	v_lshl_add_u64 v[32:33], v[124:125], 0, v[192:193]
	v_lshlrev_b32_e32 v192, 7, v34
	v_lshl_add_u64 v[34:35], v[124:125], 0, v[192:193]
	global_load_dwordx4 v[76:79], v[32:33], off
	global_load_dwordx4 v[80:83], v[34:35], off
	v_add_u32_e32 v32, v164, v173
	v_med3_i32 v32, v32, 0, v248
	v_add_u32_e32 v34, v165, v173
	v_lshlrev_b32_e32 v192, 7, v32
	v_med3_i32 v34, v34, 0, v248
	v_lshl_add_u64 v[32:33], v[124:125], 0, v[192:193]
	v_lshlrev_b32_e32 v192, 7, v34
	v_lshl_add_u64 v[34:35], v[124:125], 0, v[192:193]
	global_load_dwordx4 v[84:87], v[32:33], off
	global_load_dwordx4 v[88:91], v[34:35], off
	s_xor_b64 s[6:7], s[10:11], -1
	v_or_b32_e32 v176, 8, v173
	v_or_b32_e32 v177, 16, v173
	v_or_b32_e32 v178, 24, v173
	v_add_u32_e32 v179, s0, v117
	s_movk_i32 s0, 0xffc0
	v_mov_b32_e32 v180, v169
	v_lshl_add_u64 v[236:237], v[132:133], 1, v[128:129]
	global_load_dwordx2 v[214:215], v[236:237], off
	global_load_dwordx2 v[216:217], v[236:237], off offset:16
	global_load_dwordx2 v[218:219], v[236:237], off offset:32
	global_load_dwordx2 v[220:221], v[236:237], off offset:48
	global_load_dwordx2 v[222:223], v[236:237], off offset:64
	global_load_dwordx2 v[224:225], v[236:237], off offset:80
	global_load_dwordx2 v[232:233], v[236:237], off offset:96
	global_load_dwordx2 v[234:235], v[236:237], off offset:112
.LBB0_600:
	s_waitcnt vmcnt(7)
	v_mfma_f32_32x32x16_bf16 v[32:47], v[92:95], v[60:63], 0
	s_add_i32 s1, s0, 0x60
	s_cmp_lg_u32 s0, 64
	s_cselect_b32 s1, s1, 0x80
	v_add_u32_e32 v92, s1, v175
	v_add_u32_e32 v93, s1, v161
	v_med3_i32 v92, v92, 0, v248
	v_add_u32_e32 v94, v93, v173
	s_waitcnt vmcnt(6)
	v_mfma_f32_32x32x16_bf16 v[32:47], v[72:75], v[48:51], v[32:47]
	v_add_u32_e32 v95, v176, v93
	v_add_u32_e32 v96, v177, v93
	v_lshlrev_b32_e32 v192, 7, v92
	v_med3_i32 v92, v94, 0, v248
	v_med3_i32 v100, v95, 0, v248
	v_med3_i32 v102, v96, 0, v248
	v_lshl_add_u64 v[96:97], v[122:123], 0, v[192:193]
	s_waitcnt vmcnt(5)
	v_mfma_f32_32x32x16_bf16 v[32:47], v[68:71], v[52:55], v[32:47]
	v_lshlrev_b32_e32 v192, 7, v92
	v_add_u32_e32 v93, v178, v93
	v_lshl_add_u64 v[98:99], v[124:125], 0, v[192:193]
	v_lshlrev_b32_e32 v192, 7, v100
	ds_read2_b32 v[134:135], v180 offset1:1
	ds_read2_b32 v[136:137], v180 offset0:2 offset1:3
	ds_read2_b32 v[138:139], v180 offset0:8 offset1:9
	ds_read2_b32 v[140:141], v180 offset0:10 offset1:11
	ds_read2_b32 v[142:143], v180 offset0:16 offset1:17
	ds_read2_b32 v[144:145], v180 offset0:18 offset1:19
	ds_read2_b32 v[146:147], v180 offset0:24 offset1:25
	ds_read2_b32 v[148:149], v180 offset0:26 offset1:27
	v_med3_i32 v104, v93, 0, v248
	global_load_dwordx4 v[92:95], v[96:97], off
	global_load_dwordx4 v[72:75], v[96:97], off offset:32
	v_lshl_add_u64 v[100:101], v[124:125], 0, v[192:193]
	v_lshlrev_b32_e32 v192, 7, v102
	global_load_dwordx4 v[68:71], v[96:97], off offset:64
	s_waitcnt vmcnt(7)
	v_mfma_f32_32x32x16_bf16 v[32:47], v[64:67], v[56:59], v[32:47]
	global_load_dwordx4 v[64:67], v[96:97], off offset:96
	s_waitcnt vmcnt(7)
	ds_write_b128 v171, v[76:79] offset:32768
	s_waitcnt vmcnt(6)
	ds_write_b128 v171, v[80:83] offset:33920
	s_waitcnt vmcnt(5)
	ds_write_b128 v171, v[84:87] offset:35072
	s_waitcnt vmcnt(4)
	ds_write_b128 v171, v[88:91] offset:36224
	v_lshl_add_u64 v[102:103], v[124:125], 0, v[192:193]
	v_lshlrev_b32_e32 v192, 7, v104
	v_lshl_add_u64 v[104:105], v[124:125], 0, v[192:193]
	global_load_dwordx4 v[76:79], v[98:99], off
	global_load_dwordx4 v[80:83], v[100:101], off
	global_load_dwordx4 v[84:87], v[102:103], off
	global_load_dwordx4 v[88:91], v[104:105], off
	v_add_u32_e32 v181, s0, v179
	s_waitcnt lgkmcnt(11)
	v_fmamk_f32 v32, v32, 0x3e38aa3b, v134
	v_fmac_f32_e32 v135, 0x3e38aa3b, v33
	s_waitcnt lgkmcnt(10)
	v_fmamk_f32 v33, v34, 0x3e38aa3b, v136
	v_fmac_f32_e32 v137, 0x3e38aa3b, v35
	s_waitcnt lgkmcnt(9)
	v_fmamk_f32 v34, v36, 0x3e38aa3b, v138
	v_fmac_f32_e32 v139, 0x3e38aa3b, v37
	s_waitcnt lgkmcnt(8)
	v_fmamk_f32 v35, v38, 0x3e38aa3b, v140
	v_fmac_f32_e32 v141, 0x3e38aa3b, v39
	s_waitcnt lgkmcnt(7)
	v_fmamk_f32 v36, v40, 0x3e38aa3b, v142
	v_fmac_f32_e32 v143, 0x3e38aa3b, v41
	s_waitcnt lgkmcnt(6)
	v_fmamk_f32 v37, v42, 0x3e38aa3b, v144
	v_fmac_f32_e32 v145, 0x3e38aa3b, v43
	s_waitcnt lgkmcnt(5)
	v_fmamk_f32 v38, v44, 0x3e38aa3b, v146
	v_fmac_f32_e32 v147, 0x3e38aa3b, v45
	s_waitcnt lgkmcnt(4)
; #define LAS __attribute__((address_space(3)))
; __device__ __forceinline__ float bperm_f(int addr, float v) { return __uint_as_float((unsigned)__builtin_amdgcn_ds_bpermute(addr, (int)__float_as_uint(v))); }
; template <class Pol> ...
;     ...
;     if (first) { float bm = sc[0];
; #pragma unroll
;         for (int i = 1; i < 16; ++i) bm = fmaxf(bm, sc[i]);
;         bm = fmaxf(bm, bperm_f(xaddr, bm)); m_run = fmaxf(bm, -40.0f); }
;     float psum = 0.f;
; #pragma unroll
;     for (int i = 0; i < 16; ++i) { const float p = __builtin_amdgcn_exp2f(sc[i] - m_run); sc[i] = p; psum += p; }
;     l_run += psum;
;     { const int lane = hh * 32 + r;
;       asm volatile("" ::: "memory");
; #pragma unroll
;       for (int j = 0; j < 4; ++j) *(LAS u32x4a*)(wl + (8 * j + (lane >> 3)) * 144 + (lane & 7) * 16) = vg[j];
;       asm volatile("" ::: "memory"); }
;     attn_loadv<Pol>(vbase, pol, fbn, r, hh, vg);
;     u32x4a va[2], vb[2];
;     { const LAS unsigned short* rp = (const LAS unsigned short*)(wl + (4 * hh) * 144 + r * 2);
; #pragma unroll
;       for (int s = 0; s < 2; ++s)
; #pragma unroll
;         for (int jx = 0; jx < 4; ++jx) { const int k0 = 16 * s + 8 * ((2 * jx) >> 2) + ((2 * jx) & 3), k1 = k0 + 1;
;             va[s][jx] = (unsigned)rp[k0 * 72] | ((unsigned)rp[k1 * 72] << 16); vb[s][jx] = (unsigned)rp[k0 * 72 + 32] | ((unsigned)rp[k1 * 72 + 32] << 16); } }
; #pragma unroll
;     for (int s = 0; s < 2; ++s) { f32x8v t;
; #pragma unroll
;         for (int jx = 0; jx < 8; ++jx) t[jx] = sc[8 * s + jx];
;         const bf16x8s pf = __builtin_bit_cast(bf16x8s, __builtin_convertvector(t, bf16x8n));
;         o0 = __builtin_amdgcn_mfma_f32_32x32x16_bf16(__builtin_bit_cast(bf16x8s, va[s]), pf, o0, 0, 0, 0);
;         o1 = __builtin_amdgcn_mfma_f32_32x32x16_bf16(__builtin_bit_cast(bf16x8s, vb[s]), pf, o1, 0, 0, 0); }
	v_fmamk_f32 v39, v46, 0x3e38aa3b, v148
	v_fmac_f32_e32 v149, 0x3e38aa3b, v47
	v_cmp_gt_u32_e32 vcc, s8, v181
	s_movk_i32 s1, 0xfe0
	ds_read_u16 v96, v172 offset:32768
	ds_read_u16 v97, v172 offset:32912
	ds_read_u16 v98, v172 offset:32976
	ds_read_u16 v99, v172 offset:33056
	ds_read_u16 v100, v172 offset:33200
	ds_read_u16 v101, v172 offset:33264
	ds_read_u16 v102, v172 offset:33120
	ds_read_u16 v103, v172 offset:32832
	ds_read_u16 v106, v172 offset:33920
	ds_read_u16 v107, v172 offset:34064
	ds_read_u16 v111, v172 offset:34128
	ds_read_u16 v182, v172 offset:34208
	ds_read_u16 v183, v172 offset:34352
	ds_read_u16 v184, v172 offset:34416
	ds_read_u16 v185, v172 offset:34272
	ds_read_u16 v186, v172 offset:33984
	ds_read_u16 v187, v172 offset:35072
	ds_read_u16 v188, v172 offset:35216
	ds_read_u16 v189, v172 offset:35280
	ds_read_u16 v190, v172 offset:35360
	ds_read_u16 v191, v172 offset:35504
	ds_read_u16 v192, v172 offset:35568
	ds_read_u16 v204, v172 offset:35424
	ds_read_u16 v205, v172 offset:35136
	ds_read_u16 v206, v172 offset:36224
	ds_read_u16 v207, v172 offset:36368
	ds_read_u16 v208, v172 offset:36432
	ds_read_u16 v209, v172 offset:36512
	ds_read_u16 v210, v172 offset:36656
	ds_read_u16 v211, v172 offset:36720
	ds_read_u16 v212, v172 offset:36576
	ds_read_u16 v213, v172 offset:36288
	v_cndmask_b32_e32 v40, v246, v32, vcc
	v_cndmask_b32_e32 v41, v246, v135, vcc
	v_cndmask_b32_e32 v42, v246, v33, vcc
	v_cndmask_b32_e32 v43, v246, v137, vcc
	v_cndmask_b32_e32 v44, v246, v34, vcc
	v_cndmask_b32_e32 v45, v246, v139, vcc
	v_cndmask_b32_e32 v46, v246, v35, vcc
	v_cndmask_b32_e32 v47, v246, v141, vcc
	v_cndmask_b32_e32 v134, v246, v36, vcc
	v_cndmask_b32_e32 v136, v246, v143, vcc
	v_cndmask_b32_e32 v138, v246, v37, vcc
	v_cndmask_b32_e32 v140, v246, v145, vcc
	v_cndmask_b32_e32 v142, v246, v38, vcc
	v_cndmask_b32_e32 v144, v246, v147, vcc
	v_cndmask_b32_e32 v146, v246, v39, vcc
	v_cndmask_b32_e32 v148, v246, v149, vcc
	v_cmp_lt_u32_e32 vcc, s1, v181
	s_waitcnt lgkmcnt(14)
	v_lshl_or_b32 v104, v98, 16, v103
	v_lshl_or_b32 v105, v101, 16, v102
	v_cndmask_b32_e32 v32, v32, v40, vcc
	v_cndmask_b32_e32 v40, v135, v41, vcc
	v_cndmask_b32_e32 v33, v33, v42, vcc
	v_cndmask_b32_e32 v41, v137, v43, vcc
	v_cndmask_b32_e32 v34, v34, v44, vcc
	v_cndmask_b32_e32 v42, v139, v45, vcc
	v_cndmask_b32_e32 v35, v35, v46, vcc
	v_cndmask_b32_e32 v43, v141, v47, vcc
	v_sub_f32_e32 v32, v32, v127
	v_sub_f32_e32 v40, v40, v127
	v_sub_f32_e32 v33, v33, v127
	v_sub_f32_e32 v41, v41, v127
	v_sub_f32_e32 v34, v34, v127
	v_sub_f32_e32 v42, v42, v127
	v_sub_f32_e32 v35, v35, v127
	v_sub_f32_e32 v43, v43, v127
	v_lshl_or_b32 v110, v107, 16, v106
	v_lshl_or_b32 v106, v111, 16, v186
	v_lshl_or_b32 v107, v184, 16, v185
	v_cndmask_b32_e32 v36, v36, v134, vcc
	v_cndmask_b32_e32 v44, v143, v136, vcc
	v_exp_f32_e32 v134, v32
	v_exp_f32_e32 v40, v40
	v_exp_f32_e32 v135, v33
	v_exp_f32_e32 v136, v34
	v_exp_f32_e32 v137, v35
	v_exp_f32_e32 v43, v43
	v_exp_f32_e32 v42, v42
	v_exp_f32_e32 v41, v41
	v_lshl_or_b32 v108, v97, 16, v96
	v_lshl_or_b32 v109, v100, 16, v99
	v_lshl_or_b32 v111, v183, 16, v182
	v_cvt_pk_bf16_f32 v35, v137, v43
	v_cvt_pk_bf16_f32 v34, v136, v42
	v_cvt_pk_bf16_f32 v33, v135, v41
	v_cvt_pk_bf16_f32 v32, v134, v40
	v_cndmask_b32_e32 v37, v37, v138, vcc
	v_cndmask_b32_e32 v45, v145, v140, vcc
	v_mfma_f32_32x32x16_bf16 v[0:15], v[104:107], v[32:35], v[0:15]
	v_add_f32_e32 v104, 0, v134
	v_add_f32_e32 v40, v104, v40
	v_cndmask_b32_e32 v38, v38, v142, vcc
	v_cndmask_b32_e32 v46, v147, v144, vcc
	v_cndmask_b32_e32 v39, v39, v146, vcc
	v_cndmask_b32_e32 v47, v149, v148, vcc
	v_add_f32_e32 v40, v40, v135
	v_mfma_f32_32x32x16_bf16 v[16:31], v[108:111], v[32:35], v[16:31]
	v_sub_f32_e32 v36, v36, v127
	v_sub_f32_e32 v44, v44, v127
	v_sub_f32_e32 v37, v37, v127
	v_sub_f32_e32 v45, v45, v127
	v_sub_f32_e32 v38, v38, v127
	v_sub_f32_e32 v46, v46, v127
	v_sub_f32_e32 v39, v39, v127
	v_sub_f32_e32 v47, v47, v127
	v_add_f32_e32 v40, v40, v41
	v_lshl_or_b32 v100, v188, 16, v187
	s_waitcnt lgkmcnt(8)
	v_lshl_or_b32 v96, v189, 16, v205
	v_lshl_or_b32 v101, v191, 16, v190
	v_lshl_or_b32 v97, v192, 16, v204
	s_waitcnt lgkmcnt(6)
	v_lshl_or_b32 v102, v207, 16, v206
	s_waitcnt lgkmcnt(0)
	v_lshl_or_b32 v98, v208, 16, v213
	v_lshl_or_b32 v103, v210, 16, v209
	v_lshl_or_b32 v99, v211, 16, v212
	v_exp_f32_e32 v36, v36
	v_exp_f32_e32 v44, v44
	v_exp_f32_e32 v37, v37
	v_exp_f32_e32 v45, v45
	v_exp_f32_e32 v38, v38
	v_exp_f32_e32 v39, v39
	v_exp_f32_e32 v47, v47
	v_exp_f32_e32 v46, v46
	v_add_f32_e32 v40, v40, v136
	v_add_f32_e32 v40, v40, v42
	v_add_f32_e32 v40, v40, v137
	v_add_f32_e32 v40, v40, v43
	v_cvt_pk_bf16_f32 v35, v39, v47
	v_cvt_pk_bf16_f32 v34, v38, v46
	v_cvt_pk_bf16_f32 v33, v37, v45
	v_cvt_pk_bf16_f32 v32, v36, v44
	v_add_f32_e32 v36, v40, v36
	v_add_f32_e32 v36, v36, v44
	v_mfma_f32_32x32x16_bf16 v[16:31], v[100:103], v[32:35], v[16:31]
	s_add_i32 s0, s0, 32
	v_add_u32_e32 v180, 0x80, v180
	s_cmpk_lg_i32 s0, 0x60
	v_mfma_f32_32x32x16_bf16 v[0:15], v[96:99], v[32:35], v[0:15]
	v_add_f32_e32 v32, v36, v37
	v_add_f32_e32 v32, v32, v45
	v_add_f32_e32 v32, v32, v38
	v_add_f32_e32 v32, v32, v46
	v_add_f32_e32 v32, v32, v39
	v_add_f32_e32 v32, v32, v47
	v_add_f32_e32 v174, v174, v32
	s_cbranch_scc1 .LBB0_600
; __device__ __forceinline__ bf16_t f2bf(float f) { unsigned u = __float_as_uint(f); u += 0x7FFFu + ((u >> 16) & 1u); return (bf16_t)(u >> 16); }
; __device__ __forceinline__ float bperm_f(int addr, float v) { return __uint_as_float((unsigned)__builtin_amdgcn_ds_bpermute(addr, (int)__float_as_uint(v))); }
; __device__ __forceinline__ void attn_store_out(const f32x16& o0, const f32x16& o1, float inv, const bf16_t* __restrict__ gbase, int qt, bf16_t* __restrict__ yout, int b, int h, int hh) {
;     uint2 gws[2][4];
; #pragma unroll
;     for (int dt = 0; dt < 2; ++dt)
; #pragma unroll
;         for (int g = 0; g < 4; ++g) gws[dt][g] = *(const uint2*)(gbase + qt * 64 + dt * 32 + 8 * g + 4 * hh);
; #pragma unroll
;     for (int dt = 0; dt < 2; ++dt)
; #pragma unroll
;         for (int g = 0; g < 4; ++g) { const int d0 = dt * 32 + 8 * g + 4 * hh;
;             const uint2 gw = gws[dt][g];
;             const float g0 = __uint_as_float(gw.x << 16), g1 = __uint_as_float(gw.x & 0xffff0000u), g2 = __uint_as_float(gw.y << 16), g3 = __uint_as_float(gw.y & 0xffff0000u);
;             const float v0 = (dt ? o1[4 * g] : o0[4 * g]) * inv, v1 = (dt ? o1[4 * g + 1] : o0[4 * g + 1]) * inv, v2 = (dt ? o1[4 * g + 2] : o0[4 * g + 2]) * inv, v3 = (dt ? o1[4 * g + 3] : o0[4 * g + 3]) * inv;
;             uint2 w; w.x = (unsigned)f2bf(v0 * silu(g0)) | ((unsigned)f2bf(v1 * silu(g1)) << 16); w.y = (unsigned)f2bf(v2 * silu(g2)) | ((unsigned)f2bf(v3 * silu(g3)) << 16);
;             *(uint2*)(yout + (size_t)(b * SEQ + qt) * 1024 + h * 64 + d0) = w; }
; }
; template <class Pol, int MODE>
; __device__ __forceinline__ void attn_wave_task(const bf16_t* __restrict__ proj, int b, int h, Pol pol, bf16_t* __restrict__ yout, int lane, float* __restrict__ X, LAS unsigned char* wl) {
;     ...
;     l_run += bperm_f(xaddr, l_run);
;     if (MODE == 1) { float* xr = X + (size_t)pol.xrow(r) * 68;
; #pragma unroll
;         for (int g = 0; g < 4; ++g) { *(float4*)(xr + 8 * g + 4 * hh) = make_float4(o0[4 * g], o0[4 * g + 1], o0[4 * g + 2], o0[4 * g + 3]);
;             *(float4*)(xr + 32 + 8 * g + 4 * hh) = make_float4(o1[4 * g], o1[4 * g + 1], o1[4 * g + 2], o1[4 * g + 3]); }
;         if (hh == 0) { xr[64] = m_run; xr[65] = l_run; }
;         return; }
;     attn_store_out(o0, o1, 1.0f / l_run, gbase, qt, yout, b, h, hh);
	ds_bpermute_b32 v32, v153, v174
	v_mov_b32_e32 v55, v18
	v_mov_b32_e32 v18, v17
	v_mov_b32_e32 v54, v16
	s_mov_b64 s[10:11], 0
	s_waitcnt lgkmcnt(0)
	v_add_f32_e32 v32, v174, v32
	v_div_scale_f32 v33, s[0:1], v32, v32, 1.0
	v_rcp_f32_e32 v34, v33
	s_mov_b32 s0, 32
	v_fma_f32 v35, -v33, v34, 1.0
	v_fmac_f32_e32 v34, v35, v34
	v_div_scale_f32 v35, vcc, 1.0, v32, 1.0
	v_mul_f32_e32 v36, v35, v34
	v_fma_f32 v37, -v33, v36, v35
	v_fmac_f32_e32 v36, v37, v34
	v_fma_f32 v33, -v33, v36, v35
	v_div_fmas_f32 v33, v33, v34, v36
	v_div_fixup_f32 v34, v33, v32, 1.0
	s_waitcnt vmcnt(8)
	v_mov_b32_e32 v48, v214
	v_mov_b32_e32 v49, v215
	v_mov_b32_e32 v50, v216
	v_mov_b32_e32 v51, v217
	v_mov_b32_e32 v46, v218
	v_mov_b32_e32 v47, v219
	v_mov_b32_e32 v44, v220
	v_mov_b32_e32 v45, v221
	v_mov_b32_e32 v42, v222
	v_mov_b32_e32 v43, v223
	v_mov_b32_e32 v40, v224
	v_mov_b32_e32 v41, v225
	v_mov_b32_e32 v38, v232
	v_mov_b32_e32 v39, v233
	v_mov_b32_e32 v36, v234
	v_mov_b32_e32 v37, v235
	v_pk_mul_f32 v[16:17], v[18:19], v[34:35] op_sel_hi:[1,0]
	v_pk_mul_f32 v[54:55], v[54:55], v[34:35] op_sel_hi:[1,0]
	v_add_u32_e32 v32, s14, v119
	v_ashrrev_i32_e32 v33, 31, v32
	v_lshlrev_b64 v[32:33], 11, v[32:33]
	v_lshl_add_u64 v[32:33], v[130:131], 0, v[32:33]
	s_and_b64 vcc, exec, s[6:7]
	s_waitcnt vmcnt(7)
	v_lshlrev_b32_e32 v52, 16, v48
	v_and_b32_e32 v48, 0xffff0000, v48
	v_mul_f32_e32 v19, 0xbfb8aa3b, v48
	v_exp_f32_e32 v19, v19
	v_lshlrev_b32_e32 v53, 16, v49
	v_mul_f32_e32 v18, 0xbfb8aa3b, v52
	v_exp_f32_e32 v18, v18
	v_add_f32_e32 v19, 1.0, v19
	v_rcp_f32_e32 v56, v19
	v_mul_f32_e32 v19, 0xbfb8aa3b, v53
	v_exp_f32_e32 v19, v19
	v_add_f32_e32 v18, 1.0, v18
	v_rcp_f32_e32 v18, v18
	v_and_b32_e32 v49, 0xffff0000, v49
	v_add_f32_e32 v19, 1.0, v19
	v_rcp_f32_e32 v19, v19
	s_nop 0
	v_pk_mul_f32 v[18:19], v[18:19], v[52:53]
	s_nop 0
	v_pk_mul_f32 v[18:19], v[54:55], v[18:19]
	s_nop 0
	v_and_b32_sdwa v52, v18, v229 dst_sel:DWORD dst_unused:UNUSED_PAD src0_sel:WORD_1 src1_sel:DWORD
	v_add3_u32 v52, v18, v52, s33
	v_mul_f32_e32 v18, 0xbfb8aa3b, v49
	v_exp_f32_e32 v18, v18
	v_and_b32_sdwa v35, v19, v229 dst_sel:DWORD dst_unused:UNUSED_PAD src0_sel:WORD_1 src1_sel:DWORD
	v_add3_u32 v35, v19, v35, s33
	v_add_f32_e32 v18, 1.0, v18
	v_rcp_f32_e32 v57, v18
	s_nop 0
	v_pk_mul_f32 v[18:19], v[56:57], v[48:49]
	s_nop 0
	v_pk_mul_f32 v[16:17], v[16:17], v[18:19]
	v_mov_b32_e32 v49, v22
	v_and_b32_sdwa v18, v17, v229 dst_sel:DWORD dst_unused:UNUSED_PAD src0_sel:WORD_1 src1_sel:DWORD
	v_and_b32_sdwa v19, v16, v229 dst_sel:DWORD dst_unused:UNUSED_PAD src0_sel:WORD_1 src1_sel:DWORD
	v_add3_u32 v17, v17, v18, s33
	v_add3_u32 v16, v16, v19, s33
	v_and_b32_e32 v17, 0xffff0000, v17
	v_and_b32_e32 v16, 0xffff0000, v16
	v_or_b32_sdwa v17, v17, v35 dst_sel:DWORD dst_unused:UNUSED_PAD src0_sel:DWORD src1_sel:WORD_1
	v_or_b32_sdwa v16, v16, v52 dst_sel:DWORD dst_unused:UNUSED_PAD src0_sel:DWORD src1_sel:WORD_1
	global_store_dwordx2 v[32:33], v[16:17], off
	s_waitcnt vmcnt(7)
	v_and_b32_e32 v16, 0xffff0000, v50
	v_mov_b32_e32 v22, v21
	v_mov_b32_e32 v48, v20
	v_pk_mul_f32 v[20:21], v[22:23], v[34:35] op_sel_hi:[1,0]
	v_mul_f32_e32 v23, 0xbfb8aa3b, v16
	v_exp_f32_e32 v23, v23
	v_lshlrev_b32_e32 v19, 16, v51
	v_lshlrev_b32_e32 v18, 16, v50
	v_mul_f32_e32 v22, 0xbfb8aa3b, v18
	v_add_f32_e32 v23, 1.0, v23
	v_rcp_f32_e32 v50, v23
	v_mul_f32_e32 v23, 0xbfb8aa3b, v19
	v_exp_f32_e32 v22, v22
	v_exp_f32_e32 v23, v23
	v_pk_mul_f32 v[48:49], v[48:49], v[34:35] op_sel_hi:[1,0]
	v_and_b32_e32 v17, 0xffff0000, v51
	v_add_f32_e32 v22, 1.0, v22
	v_add_f32_e32 v23, 1.0, v23
	v_rcp_f32_e32 v22, v22
	v_rcp_f32_e32 v23, v23
	s_nop 0
	v_pk_mul_f32 v[18:19], v[22:23], v[18:19]
	s_nop 0
	v_pk_mul_f32 v[18:19], v[48:49], v[18:19]
	s_nop 0
	v_and_b32_sdwa v22, v19, v229 dst_sel:DWORD dst_unused:UNUSED_PAD src0_sel:WORD_1 src1_sel:DWORD
	v_add3_u32 v19, v19, v22, s33
	v_mul_f32_e32 v22, 0xbfb8aa3b, v17
	v_exp_f32_e32 v22, v22
	v_and_b32_sdwa v23, v18, v229 dst_sel:DWORD dst_unused:UNUSED_PAD src0_sel:WORD_1 src1_sel:DWORD
	v_add3_u32 v18, v18, v23, s33
	v_add_f32_e32 v22, 1.0, v22
	v_rcp_f32_e32 v51, v22
	s_nop 0
	v_pk_mul_f32 v[16:17], v[50:51], v[16:17]
	s_nop 0
	v_pk_mul_f32 v[16:17], v[20:21], v[16:17]
	s_nop 0
	v_and_b32_sdwa v21, v16, v229 dst_sel:DWORD dst_unused:UNUSED_PAD src0_sel:WORD_1 src1_sel:DWORD
	v_add3_u32 v16, v16, v21, s33
	v_and_b32_e32 v16, 0xffff0000, v16
	v_or_b32_sdwa v16, v16, v18 dst_sel:DWORD dst_unused:UNUSED_PAD src0_sel:DWORD src1_sel:WORD_1
	s_waitcnt vmcnt(6)
	v_and_b32_e32 v18, 0xffff0000, v46
	v_mov_b32_e32 v21, v26
	v_mov_b32_e32 v26, v25
	v_mul_f32_e32 v25, 0xbfb8aa3b, v18
	v_and_b32_sdwa v20, v17, v229 dst_sel:DWORD dst_unused:UNUSED_PAD src0_sel:WORD_1 src1_sel:DWORD
	v_exp_f32_e32 v25, v25
	v_add3_u32 v17, v17, v20, s33
	v_and_b32_e32 v17, 0xffff0000, v17
	v_or_b32_sdwa v17, v17, v19 dst_sel:DWORD dst_unused:UNUSED_PAD src0_sel:DWORD src1_sel:WORD_1
	global_store_dwordx2 v[32:33], v[16:17], off offset:16
	v_lshlrev_b32_e32 v17, 16, v47
	v_lshlrev_b32_e32 v16, 16, v46
	v_add_f32_e32 v25, 1.0, v25
	v_mov_b32_e32 v20, v24
	v_pk_mul_f32 v[22:23], v[26:27], v[34:35] op_sel_hi:[1,0]
	v_mul_f32_e32 v24, 0xbfb8aa3b, v16
	v_rcp_f32_e32 v26, v25
	v_mul_f32_e32 v25, 0xbfb8aa3b, v17
	v_exp_f32_e32 v24, v24
	v_exp_f32_e32 v25, v25
	v_pk_mul_f32 v[20:21], v[20:21], v[34:35] op_sel_hi:[1,0]
	v_and_b32_e32 v19, 0xffff0000, v47
	v_add_f32_e32 v24, 1.0, v24
	v_add_f32_e32 v25, 1.0, v25
	v_rcp_f32_e32 v24, v24
	v_rcp_f32_e32 v25, v25
	s_nop 0
	v_pk_mul_f32 v[16:17], v[24:25], v[16:17]
	s_nop 0
	v_pk_mul_f32 v[16:17], v[20:21], v[16:17]
	s_nop 0
	v_and_b32_sdwa v21, v16, v229 dst_sel:DWORD dst_unused:UNUSED_PAD src0_sel:WORD_1 src1_sel:DWORD
	v_add3_u32 v21, v16, v21, s33
	v_mul_f32_e32 v16, 0xbfb8aa3b, v19
	v_exp_f32_e32 v16, v16
	v_and_b32_sdwa v20, v17, v229 dst_sel:DWORD dst_unused:UNUSED_PAD src0_sel:WORD_1 src1_sel:DWORD
	v_add3_u32 v20, v17, v20, s33
	v_add_f32_e32 v16, 1.0, v16
	v_rcp_f32_e32 v27, v16
	s_nop 0
	v_pk_mul_f32 v[16:17], v[26:27], v[18:19]
	s_nop 0
	v_pk_mul_f32 v[16:17], v[22:23], v[16:17]
	s_nop 0
	v_and_b32_sdwa v18, v17, v229 dst_sel:DWORD dst_unused:UNUSED_PAD src0_sel:WORD_1 src1_sel:DWORD
	v_add3_u32 v17, v17, v18, s33
	s_waitcnt vmcnt(6)
; __device__ __forceinline__ bf16_t f2bf(float f) { unsigned u = __float_as_uint(f); u += 0x7FFFu + ((u >> 16) & 1u); return (bf16_t)(u >> 16); }
; __device__ __forceinline__ float silu(float x) { return x * __builtin_amdgcn_rcpf(1.0f + __expf(-x)); }
; __device__ __forceinline__ void attn_store_out(const f32x16& o0, const f32x16& o1, float inv, const bf16_t* __restrict__ gbase, int qt, bf16_t* __restrict__ yout, int b, int h, int hh) {
;     ...
;         for (int g = 0; g < 4; ++g) gws[dt][g] = *(const uint2*)(gbase + qt * 64 + dt * 32 + 8 * g + 4 * hh);
; #pragma unroll
;     for (int dt = 0; dt < 2; ++dt)
; #pragma unroll
;         for (int g = 0; g < 4; ++g) { const int d0 = dt * 32 + 8 * g + 4 * hh;
;             const uint2 gw = gws[dt][g];
;             const float g0 = __uint_as_float(gw.x << 16), g1 = __uint_as_float(gw.x & 0xffff0000u), g2 = __uint_as_float(gw.y << 16), g3 = __uint_as_float(gw.y & 0xffff0000u);
;             const float v0 = (dt ? o1[4 * g] : o0[4 * g]) * inv, v1 = (dt ? o1[4 * g + 1] : o0[4 * g + 1]) * inv, v2 = (dt ? o1[4 * g + 2] : o0[4 * g + 2]) * inv, v3 = (dt ? o1[4 * g + 3] : o0[4 * g + 3]) * inv;
;             uint2 w; w.x = (unsigned)f2bf(v0 * silu(g0)) | ((unsigned)f2bf(v1 * silu(g1)) << 16); w.y = (unsigned)f2bf(v2 * silu(g2)) | ((unsigned)f2bf(v3 * silu(g3)) << 16);
;             *(uint2*)(yout + (size_t)(b * SEQ + qt) * 1024 + h * 64 + d0) = w; }
	v_and_b32_e32 v18, 0xffff0000, v44
	v_mul_f32_e32 v25, 0xbfb8aa3b, v18
	v_and_b32_sdwa v19, v16, v229 dst_sel:DWORD dst_unused:UNUSED_PAD src0_sel:WORD_1 src1_sel:DWORD
	v_exp_f32_e32 v25, v25
	v_add3_u32 v16, v16, v19, s33
	v_and_b32_e32 v17, 0xffff0000, v17
	v_and_b32_e32 v16, 0xffff0000, v16
	v_or_b32_sdwa v17, v17, v20 dst_sel:DWORD dst_unused:UNUSED_PAD src0_sel:DWORD src1_sel:WORD_1
	v_or_b32_sdwa v16, v16, v21 dst_sel:DWORD dst_unused:UNUSED_PAD src0_sel:DWORD src1_sel:WORD_1
	global_store_dwordx2 v[32:33], v[16:17], off offset:32
	v_lshlrev_b32_e32 v17, 16, v45
	v_lshlrev_b32_e32 v16, 16, v44
	v_add_f32_e32 v25, 1.0, v25
	v_mul_f32_e32 v24, 0xbfb8aa3b, v16
	v_rcp_f32_e32 v26, v25
	v_mul_f32_e32 v25, 0xbfb8aa3b, v17
	v_exp_f32_e32 v24, v24
	v_exp_f32_e32 v25, v25
	v_mov_b32_e32 v20, v28
	v_mov_b32_e32 v21, v30
	v_add_f32_e32 v24, 1.0, v24
	v_add_f32_e32 v25, 1.0, v25
	v_rcp_f32_e32 v24, v24
	v_rcp_f32_e32 v25, v25
	v_pk_mul_f32 v[20:21], v[20:21], v[34:35] op_sel_hi:[1,0]
	v_and_b32_e32 v19, 0xffff0000, v45
	v_mov_b32_e32 v30, v29
	v_pk_mul_f32 v[16:17], v[24:25], v[16:17]
	v_pk_mul_f32 v[22:23], v[30:31], v[34:35] op_sel_hi:[1,0]
	v_pk_mul_f32 v[16:17], v[20:21], v[16:17]
	s_nop 0
	v_and_b32_sdwa v21, v16, v229 dst_sel:DWORD dst_unused:UNUSED_PAD src0_sel:WORD_1 src1_sel:DWORD
	v_add3_u32 v21, v16, v21, s33
	v_mul_f32_e32 v16, 0xbfb8aa3b, v19
	v_exp_f32_e32 v16, v16
	v_and_b32_sdwa v20, v17, v229 dst_sel:DWORD dst_unused:UNUSED_PAD src0_sel:WORD_1 src1_sel:DWORD
	v_add3_u32 v20, v17, v20, s33
	v_add_f32_e32 v16, 1.0, v16
	v_rcp_f32_e32 v27, v16
	s_nop 0
	v_pk_mul_f32 v[16:17], v[26:27], v[18:19]
	s_nop 0
	v_pk_mul_f32 v[16:17], v[22:23], v[16:17]
	s_nop 0
	v_and_b32_sdwa v19, v16, v229 dst_sel:DWORD dst_unused:UNUSED_PAD src0_sel:WORD_1 src1_sel:DWORD
	v_and_b32_sdwa v18, v17, v229 dst_sel:DWORD dst_unused:UNUSED_PAD src0_sel:WORD_1 src1_sel:DWORD
	v_add3_u32 v16, v16, v19, s33
	v_add3_u32 v17, v17, v18, s33
	v_and_b32_e32 v16, 0xffff0000, v16
	v_and_b32_e32 v17, 0xffff0000, v17
	v_or_b32_sdwa v16, v16, v21 dst_sel:DWORD dst_unused:UNUSED_PAD src0_sel:DWORD src1_sel:WORD_1
	s_waitcnt vmcnt(6)
	v_and_b32_e32 v18, 0xffff0000, v42
	v_mov_b32_e32 v21, v2
	v_mov_b32_e32 v2, v1
	v_or_b32_sdwa v17, v17, v20 dst_sel:DWORD dst_unused:UNUSED_PAD src0_sel:DWORD src1_sel:WORD_1
	v_mov_b32_e32 v20, v0
	v_pk_mul_f32 v[0:1], v[2:3], v[34:35] op_sel_hi:[1,0]
	v_mul_f32_e32 v3, 0xbfb8aa3b, v18
	v_exp_f32_e32 v3, v3
	global_store_dwordx2 v[32:33], v[16:17], off offset:48
	v_lshlrev_b32_e32 v17, 16, v43
	v_lshlrev_b32_e32 v16, 16, v42
	v_add_f32_e32 v3, 1.0, v3
	v_mul_f32_e32 v2, 0xbfb8aa3b, v16
	v_rcp_f32_e32 v22, v3
	v_mul_f32_e32 v3, 0xbfb8aa3b, v17
	v_exp_f32_e32 v2, v2
	v_exp_f32_e32 v3, v3
	v_pk_mul_f32 v[20:21], v[20:21], v[34:35] op_sel_hi:[1,0]
	v_and_b32_e32 v19, 0xffff0000, v43
	v_add_f32_e32 v2, 1.0, v2
	v_add_f32_e32 v3, 1.0, v3
	v_rcp_f32_e32 v2, v2
	v_rcp_f32_e32 v3, v3
	s_nop 0
	v_pk_mul_f32 v[2:3], v[2:3], v[16:17]
	s_nop 0
	v_pk_mul_f32 v[2:3], v[20:21], v[2:3]
	s_nop 0
	v_and_b32_sdwa v17, v2, v229 dst_sel:DWORD dst_unused:UNUSED_PAD src0_sel:WORD_1 src1_sel:DWORD
	v_add3_u32 v17, v2, v17, s33
	v_mul_f32_e32 v2, 0xbfb8aa3b, v19
	v_exp_f32_e32 v2, v2
	v_and_b32_sdwa v16, v3, v229 dst_sel:DWORD dst_unused:UNUSED_PAD src0_sel:WORD_1 src1_sel:DWORD
	v_add3_u32 v16, v3, v16, s33
	v_add_f32_e32 v2, 1.0, v2
	v_rcp_f32_e32 v23, v2
	s_nop 0
	v_pk_mul_f32 v[2:3], v[22:23], v[18:19]
	s_nop 0
	v_pk_mul_f32 v[0:1], v[0:1], v[2:3]
	s_nop 0
	v_and_b32_sdwa v3, v0, v229 dst_sel:DWORD dst_unused:UNUSED_PAD src0_sel:WORD_1 src1_sel:DWORD
	v_and_b32_sdwa v2, v1, v229 dst_sel:DWORD dst_unused:UNUSED_PAD src0_sel:WORD_1 src1_sel:DWORD
	v_add3_u32 v0, v0, v3, s33
	v_add3_u32 v1, v1, v2, s33
	v_and_b32_e32 v0, 0xffff0000, v0
	v_and_b32_e32 v1, 0xffff0000, v1
	v_or_b32_sdwa v0, v0, v17 dst_sel:DWORD dst_unused:UNUSED_PAD src0_sel:DWORD src1_sel:WORD_1
	s_waitcnt vmcnt(6)
	v_and_b32_e32 v2, 0xffff0000, v40
	v_mov_b32_e32 v17, v6
	v_mov_b32_e32 v6, v5
	v_or_b32_sdwa v1, v1, v16 dst_sel:DWORD dst_unused:UNUSED_PAD src0_sel:DWORD src1_sel:WORD_1
	v_mov_b32_e32 v16, v4
	v_pk_mul_f32 v[4:5], v[6:7], v[34:35] op_sel_hi:[1,0]
	v_mul_f32_e32 v7, 0xbfb8aa3b, v2
	v_exp_f32_e32 v7, v7
	global_store_dwordx2 v[32:33], v[0:1], off offset:64
	v_lshlrev_b32_e32 v1, 16, v41
	v_lshlrev_b32_e32 v0, 16, v40
	v_add_f32_e32 v7, 1.0, v7
	v_mul_f32_e32 v6, 0xbfb8aa3b, v0
	v_rcp_f32_e32 v18, v7
	v_mul_f32_e32 v7, 0xbfb8aa3b, v1
	v_exp_f32_e32 v6, v6
	v_exp_f32_e32 v7, v7
	v_pk_mul_f32 v[16:17], v[16:17], v[34:35] op_sel_hi:[1,0]
	v_and_b32_e32 v3, 0xffff0000, v41
	v_add_f32_e32 v6, 1.0, v6
	v_add_f32_e32 v7, 1.0, v7
	v_rcp_f32_e32 v6, v6
	v_rcp_f32_e32 v7, v7
	s_nop 0
	v_pk_mul_f32 v[0:1], v[6:7], v[0:1]
	s_nop 0
	v_pk_mul_f32 v[0:1], v[16:17], v[0:1]
	s_nop 0
	v_and_b32_sdwa v7, v0, v229 dst_sel:DWORD dst_unused:UNUSED_PAD src0_sel:WORD_1 src1_sel:DWORD
	v_add3_u32 v7, v0, v7, s33
	v_mul_f32_e32 v0, 0xbfb8aa3b, v3
	v_exp_f32_e32 v0, v0
	v_and_b32_sdwa v6, v1, v229 dst_sel:DWORD dst_unused:UNUSED_PAD src0_sel:WORD_1 src1_sel:DWORD
	v_add3_u32 v6, v1, v6, s33
	v_add_f32_e32 v0, 1.0, v0
	v_rcp_f32_e32 v19, v0
	s_nop 0
	v_pk_mul_f32 v[0:1], v[18:19], v[2:3]
	s_nop 0
	v_pk_mul_f32 v[0:1], v[4:5], v[0:1]
	v_mov_b32_e32 v5, v10
	v_and_b32_sdwa v2, v1, v229 dst_sel:DWORD dst_unused:UNUSED_PAD src0_sel:WORD_1 src1_sel:DWORD
	v_add3_u32 v1, v1, v2, s33
	s_waitcnt vmcnt(6)
; #define LAS __attribute__((address_space(3)))
; __device__ __forceinline__ void attn_store_out(const f32x16& o0, const f32x16& o1, float inv, const bf16_t* __restrict__ gbase, int qt, bf16_t* __restrict__ yout, int b, int h, int hh) {
;     ...
;         for (int g = 0; g < 4; ++g) gws[dt][g] = *(const uint2*)(gbase + qt * 64 + dt * 32 + 8 * g + 4 * hh);
; #pragma unroll
;     for (int dt = 0; dt < 2; ++dt)
; #pragma unroll
;         for (int g = 0; g < 4; ++g) { const int d0 = dt * 32 + 8 * g + 4 * hh;
;             const uint2 gw = gws[dt][g];
;             const float g0 = __uint_as_float(gw.x << 16), g1 = __uint_as_float(gw.x & 0xffff0000u), g2 = __uint_as_float(gw.y << 16), g3 = __uint_as_float(gw.y & 0xffff0000u);
;             const float v0 = (dt ? o1[4 * g] : o0[4 * g]) * inv, v1 = (dt ? o1[4 * g + 1] : o0[4 * g + 1]) * inv, v2 = (dt ? o1[4 * g + 2] : o0[4 * g + 2]) * inv, v3 = (dt ? o1[4 * g + 3] : o0[4 * g + 3]) * inv;
;             uint2 w; w.x = (unsigned)f2bf(v0 * silu(g0)) | ((unsigned)f2bf(v1 * silu(g1)) << 16); w.y = (unsigned)f2bf(v2 * silu(g2)) | ((unsigned)f2bf(v3 * silu(g3)) << 16);
;             *(uint2*)(yout + (size_t)(b * SEQ + qt) * 1024 + h * 64 + d0) = w; }
; __device__ void ph_dilated_mfma(const Params& P, const bf16_t* __restrict__ proj, bf16_t* __restrict__ yout, unsigned char* lds_raw, float* __restrict__ Xall) {
;     ...
;     for (int bt = vb; bt < 1024; bt += G) {
;         const int p = bt >> 3, chunk = bt & 7, b = p >> 4, h = p & 15;
;         __syncthreads();
;         LAS float* tbl16 = tbl; LAS float* tbl4 = tbl + 3328; LAS float* tblB = tbl + 6656;
;         for (int x = tid; x < 3073; x += NT) { const int rel = x - 1536, ar = rel < 0 ? -rel : rel; const float bv = rel_bias[t5_bucket(rel) * 16 + h] * 1.44269504088896341f;
;             tbl16[x + (x >> 4)] = ((rel & 15) == 0 && ar <= 1024) ? bv : -1e30f; tbl4[x + (x >> 4)] = ((rel & 3) == 0 && ar <= 256) ? bv : -1e30f; }
;         for (int x = tid; x < 256; x += NT) { const int rel = x - 96, ar = rel < 0 ? -rel : rel; tblB[x] = (ar <= 64) ? rel_bias[t5_bucket(rel) * 16 + h] * 1.44269504088896341f : -1e30f; }
;         __syncthreads();
; #pragma unroll 1
;         for (int rr = 0; rr < 2; ++rr) { const int res = wid * 2 + rr; DilPolA pol{chunk * 512 + res, res, tbl16, tbl4}; attn_wave_task<DilPolA, 1>(proj, b, h, pol, yout, lane, X, wl); }
;         __syncthreads();
; #pragma unroll 1
	v_and_b32_e32 v2, 0xffff0000, v38
	v_mov_b32_e32 v10, v9
	v_mul_f32_e32 v9, 0xbfb8aa3b, v2
	v_and_b32_sdwa v3, v0, v229 dst_sel:DWORD dst_unused:UNUSED_PAD src0_sel:WORD_1 src1_sel:DWORD
	v_exp_f32_e32 v9, v9
	v_add3_u32 v0, v0, v3, s33
	v_and_b32_e32 v1, 0xffff0000, v1
	v_and_b32_e32 v0, 0xffff0000, v0
	v_or_b32_sdwa v1, v1, v6 dst_sel:DWORD dst_unused:UNUSED_PAD src0_sel:DWORD src1_sel:WORD_1
	v_or_b32_sdwa v0, v0, v7 dst_sel:DWORD dst_unused:UNUSED_PAD src0_sel:DWORD src1_sel:WORD_1
	global_store_dwordx2 v[32:33], v[0:1], off offset:80
	v_lshlrev_b32_e32 v1, 16, v39
	v_lshlrev_b32_e32 v0, 16, v38
	v_add_f32_e32 v9, 1.0, v9
	v_mov_b32_e32 v4, v8
	v_pk_mul_f32 v[6:7], v[10:11], v[34:35] op_sel_hi:[1,0]
	v_mul_f32_e32 v8, 0xbfb8aa3b, v0
	v_rcp_f32_e32 v10, v9
	v_mul_f32_e32 v9, 0xbfb8aa3b, v1
	v_exp_f32_e32 v8, v8
	v_exp_f32_e32 v9, v9
	v_pk_mul_f32 v[4:5], v[4:5], v[34:35] op_sel_hi:[1,0]
	v_and_b32_e32 v3, 0xffff0000, v39
	v_add_f32_e32 v8, 1.0, v8
	v_add_f32_e32 v9, 1.0, v9
	v_rcp_f32_e32 v8, v8
	v_rcp_f32_e32 v9, v9
	s_nop 0
	v_pk_mul_f32 v[0:1], v[8:9], v[0:1]
	s_nop 0
	v_pk_mul_f32 v[0:1], v[4:5], v[0:1]
	s_nop 0
	v_and_b32_sdwa v5, v0, v229 dst_sel:DWORD dst_unused:UNUSED_PAD src0_sel:WORD_1 src1_sel:DWORD
	v_add3_u32 v5, v0, v5, s33
	v_mul_f32_e32 v0, 0xbfb8aa3b, v3
	v_exp_f32_e32 v0, v0
	v_and_b32_sdwa v4, v1, v229 dst_sel:DWORD dst_unused:UNUSED_PAD src0_sel:WORD_1 src1_sel:DWORD
	v_add3_u32 v4, v1, v4, s33
	v_add_f32_e32 v0, 1.0, v0
	v_rcp_f32_e32 v11, v0
	s_nop 0
	v_pk_mul_f32 v[0:1], v[10:11], v[2:3]
	s_nop 0
	v_pk_mul_f32 v[0:1], v[6:7], v[0:1]
	s_nop 0
	v_and_b32_sdwa v2, v1, v229 dst_sel:DWORD dst_unused:UNUSED_PAD src0_sel:WORD_1 src1_sel:DWORD
	v_add3_u32 v1, v1, v2, s33
	s_waitcnt vmcnt(6)
	v_and_b32_e32 v2, 0xffff0000, v36
	v_mul_f32_e32 v9, 0xbfb8aa3b, v2
	v_exp_f32_e32 v9, v9
	v_and_b32_sdwa v3, v0, v229 dst_sel:DWORD dst_unused:UNUSED_PAD src0_sel:WORD_1 src1_sel:DWORD
	v_add3_u32 v0, v0, v3, s33
	v_and_b32_e32 v1, 0xffff0000, v1
	v_and_b32_e32 v0, 0xffff0000, v0
	v_or_b32_sdwa v1, v1, v4 dst_sel:DWORD dst_unused:UNUSED_PAD src0_sel:DWORD src1_sel:WORD_1
	v_or_b32_sdwa v0, v0, v5 dst_sel:DWORD dst_unused:UNUSED_PAD src0_sel:DWORD src1_sel:WORD_1
	v_lshlrev_b32_e32 v5, 16, v37
	v_lshlrev_b32_e32 v4, 16, v36
	v_add_f32_e32 v9, 1.0, v9
	v_mul_f32_e32 v8, 0xbfb8aa3b, v4
	v_rcp_f32_e32 v10, v9
	v_mul_f32_e32 v9, 0xbfb8aa3b, v5
	v_exp_f32_e32 v8, v8
	v_exp_f32_e32 v9, v9
	global_store_dwordx2 v[32:33], v[0:1], off offset:96
	v_mov_b32_e32 v0, v12
	v_add_f32_e32 v8, 1.0, v8
	v_add_f32_e32 v9, 1.0, v9
	v_rcp_f32_e32 v8, v8
	v_rcp_f32_e32 v9, v9
	v_mov_b32_e32 v1, v14
	v_pk_mul_f32 v[0:1], v[0:1], v[34:35] op_sel_hi:[1,0]
	v_and_b32_e32 v3, 0xffff0000, v37
	v_pk_mul_f32 v[4:5], v[8:9], v[4:5]
	v_mov_b32_e32 v14, v13
	v_pk_mul_f32 v[0:1], v[0:1], v[4:5]
	v_pk_mul_f32 v[6:7], v[14:15], v[34:35] op_sel_hi:[1,0]
	v_and_b32_sdwa v5, v0, v229 dst_sel:DWORD dst_unused:UNUSED_PAD src0_sel:WORD_1 src1_sel:DWORD
	v_add3_u32 v5, v0, v5, s33
	v_mul_f32_e32 v0, 0xbfb8aa3b, v3
	v_exp_f32_e32 v0, v0
	v_and_b32_sdwa v4, v1, v229 dst_sel:DWORD dst_unused:UNUSED_PAD src0_sel:WORD_1 src1_sel:DWORD
	v_add3_u32 v4, v1, v4, s33
	v_add_f32_e32 v0, 1.0, v0
	v_rcp_f32_e32 v11, v0
	s_nop 0
	v_pk_mul_f32 v[0:1], v[10:11], v[2:3]
	s_nop 0
	v_pk_mul_f32 v[0:1], v[6:7], v[0:1]
	s_nop 0
	v_and_b32_sdwa v2, v1, v229 dst_sel:DWORD dst_unused:UNUSED_PAD src0_sel:WORD_1 src1_sel:DWORD
	v_and_b32_sdwa v3, v0, v229 dst_sel:DWORD dst_unused:UNUSED_PAD src0_sel:WORD_1 src1_sel:DWORD
	v_add3_u32 v1, v1, v2, s33
	v_add3_u32 v0, v0, v3, s33
	v_and_b32_e32 v1, 0xffff0000, v1
	v_and_b32_e32 v0, 0xffff0000, v0
	v_or_b32_sdwa v1, v1, v4 dst_sel:DWORD dst_unused:UNUSED_PAD src0_sel:DWORD src1_sel:WORD_1
	v_or_b32_sdwa v0, v0, v5 dst_sel:DWORD dst_unused:UNUSED_PAD src0_sel:DWORD src1_sel:WORD_1
	global_store_dwordx2 v[32:33], v[0:1], off offset:112
	s_cbranch_vccz .LBB0_597
	v_readlane_b32 s0, v255, 20
	s_add_i32 s17, s17, s22
	s_add_i32 s12, s12, s0
	s_cmpk_gt_i32 s17, 0x3ff
	s_cbranch_scc0 .LBB0_580
